# epilogue sigmoids: drop the v_div_scale pair of the IEEE 1/d sequence (d = 1+exp >= 1, scaling is the identity), same fma refinement chain + v_div_fixup, bit-identical in range
# speedup vs baseline: 1.0048x; 1.0048x over previous
; __device__ __forceinline__ unsigned pkbf(float lo, float hi) { f32x2 v = {lo, hi}; bf16x2v b = __builtin_convertvector(v, bf16x2v); return __builtin_bit_cast(unsigned, b); }
; __device__ __forceinline__ float sigmoidf_(float x) { return 1.f / (1.f + __expf(-x)); }
;     __device__ __forceinline__ void operator()(int row, int col, f32x4 v0, f32x4 v1) const { *(u32x4*)(G + (size_t)row * 1024 + col) = pack8(v0, v1); }
;     __device__ __forceinline__ void operator()(const pg8::f32x4 (&acc)[2][2][4][2], const pg8::Unit& u, int wr, int wc, int fr, int fq) const {
;         const int row0 = u.pm * 256 + wr * 64 + fr, col0 = u.pn * 256 + wc * 32 + 8 * fq;
; #pragma unroll
;         for (int ai = 0; ai < 2; ++ai)
; #pragma unroll
;             for (int m = 0; m < 4; ++m)
; #pragma unroll
;                 for (int bj = 0; bj < 2; ++bj) { op(row0 + ai * 128 + m * 16, col0 + bj * 128, acc[ai][bj][m][0], acc[ai][bj][m][1]); asm volatile("" ::: "memory"); }
;     __device__ __forceinline__ void operator()(int row, int col, f32x4 v0, f32x4 v1) const {
;         const float h0 = v0.x * sigmoidf_(v0.x) * v0.y, h1 = v0.z * sigmoidf_(v0.z) * v0.w, h2 = v1.x * sigmoidf_(v1.x) * v1.y, h3 = v1.z * sigmoidf_(v1.z) * v1.w;
;         u32x2 o; o.x = pkbf(h0, h1); o.y = pkbf(h2, h3);
;         *(u32x2*)(HID + (size_t)row * DFF + (col >> 1)) = o;
;     }
.LBB0_38:
	v_mul_f32_e32 v146, 0xbfb8aa3b, v126
	v_mul_f32_e32 v147, 0xbfb8aa3b, v128
	v_exp_f32_e32 v146, v146
	v_exp_f32_e32 v147, v147
	v_lshl_or_b32 v145, s78, 8, v142
	v_lshl_add_u32 v144, s27, 8, v140
	v_pk_add_f32 v[146:147], v[146:147], 1.0 op_sel_hi:[1,0]
	s_nop 0
	v_rcp_f32_e32 v149, v147
	s_nop 0
	v_fma_f32 v150, -v147, v149, 1.0
	v_fmac_f32_e32 v149, v150, v149
	v_fma_f32 v152, -v147, v149, 1.0
	v_fma_f32 v151, v152, v149, v149
	v_fma_f32 v148, -v147, v151, 1.0
	v_fma_f32 v148, v148, v149, v151
	v_div_fixup_f32 v147, v148, v147, 1.0
	v_rcp_f32_e32 v149, v146
	s_nop 0
	v_fma_f32 v150, -v146, v149, 1.0
	v_fmac_f32_e32 v149, v150, v149
	v_fma_f32 v152, -v146, v149, 1.0
	v_fma_f32 v151, v152, v149, v149
	v_fma_f32 v148, -v146, v151, 1.0
	v_fma_f32 v148, v148, v149, v151
	v_div_fixup_f32 v146, v148, v146, 1.0
	v_mov_b32_e32 v148, v126
	v_mov_b32_e32 v149, v128
	v_pk_mul_f32 v[146:147], v[148:149], v[146:147]
	v_mov_b32_e32 v128, v127
	v_pk_mul_f32 v[126:127], v[128:129], v[146:147]
	v_mul_f32_e32 v128, 0xbfb8aa3b, v122
	v_mul_f32_e32 v129, 0xbfb8aa3b, v124
	v_exp_f32_e32 v128, v128
	v_exp_f32_e32 v129, v129
	v_cvt_pk_bf16_f32 v126, v126, v127
	v_pk_add_f32 v[128:129], v[128:129], 1.0 op_sel_hi:[1,0]
	s_nop 0
	v_rcp_f32_e32 v147, v129
	s_nop 0
	v_fma_f32 v148, -v129, v147, 1.0
	v_fmac_f32_e32 v147, v148, v147
	v_fma_f32 v150, -v129, v147, 1.0
	v_fma_f32 v149, v150, v147, v147
	v_fma_f32 v146, -v129, v149, 1.0
	v_fma_f32 v146, v146, v147, v149
	v_div_fixup_f32 v129, v146, v129, 1.0
	v_rcp_f32_e32 v147, v128
	s_nop 0
	v_fma_f32 v148, -v128, v147, 1.0
	v_fmac_f32_e32 v147, v148, v147
	v_fma_f32 v150, -v128, v147, 1.0
	v_fma_f32 v149, v150, v147, v147
	v_fma_f32 v146, -v128, v149, 1.0
	v_fma_f32 v146, v146, v147, v149
	v_div_fixup_f32 v128, v146, v128, 1.0
	v_mov_b32_e32 v146, v122
	v_mov_b32_e32 v147, v124
	v_pk_mul_f32 v[128:129], v[146:147], v[128:129]
	v_mov_b32_e32 v124, v123
	v_pk_mul_f32 v[122:123], v[124:125], v[128:129]
	v_ashrrev_i32_e32 v124, 1, v145
	v_cvt_pk_bf16_f32 v127, v122, v123
	v_mov_b64_e32 v[122:123], s[52:53]
	v_ashrrev_i32_e32 v125, 31, v124
	v_mad_i64_i32 v[128:129], s[4:5], v144, s86, v[122:123]
	v_lshlrev_b64 v[124:125], 1, v[124:125]
	v_lshl_add_u64 v[128:129], v[128:129], 0, v[124:125]
	global_store_dwordx2 v[128:129], v[126:127], off
	v_mul_f32_e32 v126, 0xbfb8aa3b, v118
	v_mul_f32_e32 v127, 0xbfb8aa3b, v120
	v_exp_f32_e32 v126, v126
	v_exp_f32_e32 v127, v127
	s_nop 0
	v_pk_add_f32 v[126:127], v[126:127], 1.0 op_sel_hi:[1,0]
	s_nop 0
	v_rcp_f32_e32 v146, v127
	s_nop 0
	v_fma_f32 v147, -v127, v146, 1.0
	v_fmac_f32_e32 v146, v147, v146
	v_fma_f32 v149, -v127, v146, 1.0
	v_fma_f32 v148, v149, v146, v146
	v_fma_f32 v145, -v127, v148, 1.0
	v_fma_f32 v145, v145, v146, v148
	v_div_fixup_f32 v127, v145, v127, 1.0
	v_rcp_f32_e32 v146, v126
	s_nop 0
	v_fma_f32 v147, -v126, v146, 1.0
	v_fmac_f32_e32 v146, v147, v146
	v_fma_f32 v149, -v126, v146, 1.0
	v_fma_f32 v148, v149, v146, v146
	v_fma_f32 v145, -v126, v148, 1.0
	v_fma_f32 v145, v145, v146, v148
	v_div_fixup_f32 v126, v145, v126, 1.0
	v_mov_b32_e32 v146, v118
	v_mov_b32_e32 v147, v120
	v_pk_mul_f32 v[126:127], v[146:147], v[126:127]
	v_mov_b32_e32 v120, v119
	v_pk_mul_f32 v[118:119], v[120:121], v[126:127]
	v_mul_f32_e32 v120, 0xbfb8aa3b, v114
	v_mul_f32_e32 v121, 0xbfb8aa3b, v116
	v_exp_f32_e32 v120, v120
	v_exp_f32_e32 v121, v121
	s_nop 0
	v_pk_add_f32 v[120:121], v[120:121], 1.0 op_sel_hi:[1,0]
	s_nop 0
	v_rcp_f32_e32 v127, v121
	s_nop 0
	v_fma_f32 v145, -v121, v127, 1.0
	v_fmac_f32_e32 v127, v145, v127
	v_fma_f32 v147, -v121, v127, 1.0
	v_fma_f32 v146, v147, v127, v127
	v_fma_f32 v126, -v121, v146, 1.0
	v_fma_f32 v126, v126, v127, v146
	v_div_fixup_f32 v121, v126, v121, 1.0
	v_rcp_f32_e32 v127, v120
	s_nop 0
	v_fma_f32 v145, -v120, v127, 1.0
	v_fmac_f32_e32 v127, v145, v127
	v_fma_f32 v147, -v120, v127, 1.0
	v_fma_f32 v146, v147, v127, v127
	v_fma_f32 v126, -v120, v146, 1.0
	v_fma_f32 v126, v126, v127, v146
	v_div_fixup_f32 v120, v126, v120, 1.0
	v_mov_b32_e32 v126, v114
	v_mov_b32_e32 v127, v116
	v_pk_mul_f32 v[120:121], v[126:127], v[120:121]
	v_mov_b32_e32 v116, v115
	v_pk_mul_f32 v[114:115], v[116:117], v[120:121]
	v_cvt_pk_bf16_f32 v116, v118, v119
	v_cvt_pk_bf16_f32 v117, v114, v115
	v_mul_f32_e32 v114, 0xbfb8aa3b, v110
	v_mul_f32_e32 v115, 0xbfb8aa3b, v112
	v_exp_f32_e32 v114, v114
	v_exp_f32_e32 v115, v115
	global_store_dwordx2 v[128:129], v[116:117], off offset:128
	v_or_b32_e32 v118, 16, v144
	v_pk_add_f32 v[114:115], v[114:115], 1.0 op_sel_hi:[1,0]
	s_nop 0
	v_rcp_f32_e32 v117, v115
	s_nop 0
	v_fma_f32 v119, -v115, v117, 1.0
	v_fmac_f32_e32 v117, v119, v117
	v_fma_f32 v121, -v115, v117, 1.0
	v_fma_f32 v120, v121, v117, v117
	v_fma_f32 v116, -v115, v120, 1.0
	v_fma_f32 v116, v116, v117, v120
	v_div_fixup_f32 v115, v116, v115, 1.0
	v_rcp_f32_e32 v117, v114
	s_nop 0
	v_fma_f32 v119, -v114, v117, 1.0
	v_fmac_f32_e32 v117, v119, v117
	v_fma_f32 v121, -v114, v117, 1.0
	v_fma_f32 v120, v121, v117, v117
	v_fma_f32 v116, -v114, v120, 1.0
	v_fma_f32 v116, v116, v117, v120
	v_div_fixup_f32 v114, v116, v114, 1.0
	v_mov_b32_e32 v116, v110
	v_mov_b32_e32 v117, v112
	v_pk_mul_f32 v[114:115], v[116:117], v[114:115]
	v_mov_b32_e32 v112, v111
	v_pk_mul_f32 v[110:111], v[112:113], v[114:115]
	v_mul_f32_e32 v112, 0xbfb8aa3b, v106
	v_mul_f32_e32 v113, 0xbfb8aa3b, v108
	v_exp_f32_e32 v112, v112
	v_exp_f32_e32 v113, v113
	s_nop 0
	v_pk_add_f32 v[112:113], v[112:113], 1.0 op_sel_hi:[1,0]
	s_nop 0
	v_rcp_f32_e32 v115, v113
	s_nop 0
	v_fma_f32 v116, -v113, v115, 1.0
	v_fmac_f32_e32 v115, v116, v115
	v_fma_f32 v119, -v113, v115, 1.0
	v_fma_f32 v117, v119, v115, v115
; __device__ __forceinline__ unsigned pkbf(float lo, float hi) { f32x2 v = {lo, hi}; bf16x2v b = __builtin_convertvector(v, bf16x2v); return __builtin_bit_cast(unsigned, b); }
; __device__ __forceinline__ float sigmoidf_(float x) { return 1.f / (1.f + __expf(-x)); }
;     __device__ __forceinline__ void operator()(int row, int col, f32x4 v0, f32x4 v1) const { *(u32x4*)(G + (size_t)row * 1024 + col) = pack8(v0, v1); }
;     __device__ __forceinline__ void operator()(int row, int col, f32x4 v0, f32x4 v1) const {
;         const float h0 = v0.x * sigmoidf_(v0.x) * v0.y, h1 = v0.z * sigmoidf_(v0.z) * v0.w, h2 = v1.x * sigmoidf_(v1.x) * v1.y, h3 = v1.z * sigmoidf_(v1.z) * v1.w;
;         u32x2 o; o.x = pkbf(h0, h1); o.y = pkbf(h2, h3);
;         *(u32x2*)(HID + (size_t)row * DFF + (col >> 1)) = o;
;     }
	v_fma_f32 v114, -v113, v117, 1.0
	v_fma_f32 v114, v114, v115, v117
	v_div_fixup_f32 v113, v114, v113, 1.0
	v_rcp_f32_e32 v115, v112
	s_nop 0
	v_fma_f32 v116, -v112, v115, 1.0
	v_fmac_f32_e32 v115, v116, v115
	v_fma_f32 v119, -v112, v115, 1.0
	v_fma_f32 v117, v119, v115, v115
	v_fma_f32 v114, -v112, v117, 1.0
	v_fma_f32 v114, v114, v115, v117
	v_div_fixup_f32 v112, v114, v112, 1.0
	v_mov_b32_e32 v114, v106
	v_mov_b32_e32 v115, v108
	v_pk_mul_f32 v[112:113], v[114:115], v[112:113]
	v_mov_b32_e32 v108, v107
	v_pk_mul_f32 v[106:107], v[108:109], v[112:113]
	v_cvt_pk_bf16_f32 v108, v110, v111
	v_cvt_pk_bf16_f32 v109, v106, v107
	v_mad_i64_i32 v[106:107], s[4:5], v118, s86, v[122:123]
	v_lshl_add_u64 v[106:107], v[106:107], 0, v[124:125]
	global_store_dwordx2 v[106:107], v[108:109], off
	v_mul_f32_e32 v108, 0xbfb8aa3b, v102
	v_mul_f32_e32 v109, 0xbfb8aa3b, v104
	v_exp_f32_e32 v108, v108
	v_exp_f32_e32 v109, v109
	s_nop 0
	v_pk_add_f32 v[108:109], v[108:109], 1.0 op_sel_hi:[1,0]
	s_nop 0
	v_rcp_f32_e32 v111, v109
	s_nop 0
	v_fma_f32 v112, -v109, v111, 1.0
	v_fmac_f32_e32 v111, v112, v111
	v_fma_f32 v114, -v109, v111, 1.0
	v_fma_f32 v113, v114, v111, v111
	v_fma_f32 v110, -v109, v113, 1.0
	v_fma_f32 v110, v110, v111, v113
	v_div_fixup_f32 v109, v110, v109, 1.0
	v_rcp_f32_e32 v111, v108
	s_nop 0
	v_fma_f32 v112, -v108, v111, 1.0
	v_fmac_f32_e32 v111, v112, v111
	v_fma_f32 v114, -v108, v111, 1.0
	v_fma_f32 v113, v114, v111, v111
	v_fma_f32 v110, -v108, v113, 1.0
	v_fma_f32 v110, v110, v111, v113
	v_div_fixup_f32 v108, v110, v108, 1.0
	v_mov_b32_e32 v110, v102
	v_mov_b32_e32 v111, v104
	v_pk_mul_f32 v[108:109], v[110:111], v[108:109]
	v_mov_b32_e32 v104, v103
	v_pk_mul_f32 v[102:103], v[104:105], v[108:109]
	v_mul_f32_e32 v104, 0xbfb8aa3b, v98
	v_mul_f32_e32 v105, 0xbfb8aa3b, v100
	v_exp_f32_e32 v104, v104
	v_exp_f32_e32 v105, v105
	s_nop 0
	v_pk_add_f32 v[104:105], v[104:105], 1.0 op_sel_hi:[1,0]
	s_nop 0
	v_rcp_f32_e32 v109, v105
	s_nop 0
	v_fma_f32 v110, -v105, v109, 1.0
	v_fmac_f32_e32 v109, v110, v109
	v_fma_f32 v112, -v105, v109, 1.0
	v_fma_f32 v111, v112, v109, v109
	v_fma_f32 v108, -v105, v111, 1.0
	v_fma_f32 v108, v108, v109, v111
	v_div_fixup_f32 v105, v108, v105, 1.0
	v_rcp_f32_e32 v109, v104
	s_nop 0
	v_fma_f32 v110, -v104, v109, 1.0
	v_fmac_f32_e32 v109, v110, v109
	v_fma_f32 v112, -v104, v109, 1.0
	v_fma_f32 v111, v112, v109, v109
	v_fma_f32 v108, -v104, v111, 1.0
	v_fma_f32 v108, v108, v109, v111
	v_div_fixup_f32 v104, v108, v104, 1.0
	v_mov_b32_e32 v108, v98
	v_mov_b32_e32 v109, v100
	v_pk_mul_f32 v[104:105], v[108:109], v[104:105]
	v_mov_b32_e32 v100, v99
	v_pk_mul_f32 v[98:99], v[100:101], v[104:105]
	v_cvt_pk_bf16_f32 v100, v102, v103
	v_cvt_pk_bf16_f32 v101, v98, v99
	v_mul_f32_e32 v98, 0xbfb8aa3b, v94
	v_mul_f32_e32 v99, 0xbfb8aa3b, v96
	v_exp_f32_e32 v98, v98
	v_exp_f32_e32 v99, v99
	global_store_dwordx2 v[106:107], v[100:101], off offset:128
	v_or_b32_e32 v102, 32, v144
	v_pk_add_f32 v[98:99], v[98:99], 1.0 op_sel_hi:[1,0]
	s_nop 0
	v_rcp_f32_e32 v101, v99
	s_nop 0
	v_fma_f32 v103, -v99, v101, 1.0
	v_fmac_f32_e32 v101, v103, v101
	v_fma_f32 v105, -v99, v101, 1.0
	v_fma_f32 v104, v105, v101, v101
	v_fma_f32 v100, -v99, v104, 1.0
	v_fma_f32 v100, v100, v101, v104
	v_div_fixup_f32 v99, v100, v99, 1.0
	v_rcp_f32_e32 v101, v98
	s_nop 0
	v_fma_f32 v103, -v98, v101, 1.0
	v_fmac_f32_e32 v101, v103, v101
	v_fma_f32 v105, -v98, v101, 1.0
	v_fma_f32 v104, v105, v101, v101
	v_fma_f32 v100, -v98, v104, 1.0
	v_fma_f32 v100, v100, v101, v104
	v_div_fixup_f32 v98, v100, v98, 1.0
	v_mov_b32_e32 v100, v94
	v_mov_b32_e32 v101, v96
	v_pk_mul_f32 v[98:99], v[100:101], v[98:99]
	v_mov_b32_e32 v96, v95
	v_pk_mul_f32 v[94:95], v[96:97], v[98:99]
	v_mul_f32_e32 v96, 0xbfb8aa3b, v90
	v_mul_f32_e32 v97, 0xbfb8aa3b, v92
	v_exp_f32_e32 v96, v96
	v_exp_f32_e32 v97, v97
	s_nop 0
	v_pk_add_f32 v[96:97], v[96:97], 1.0 op_sel_hi:[1,0]
	s_nop 0
	v_rcp_f32_e32 v99, v97
	s_nop 0
	v_fma_f32 v100, -v97, v99, 1.0
	v_fmac_f32_e32 v99, v100, v99
	v_fma_f32 v103, -v97, v99, 1.0
	v_fma_f32 v101, v103, v99, v99
	v_fma_f32 v98, -v97, v101, 1.0
	v_fma_f32 v98, v98, v99, v101
	v_div_fixup_f32 v97, v98, v97, 1.0
	v_rcp_f32_e32 v99, v96
	s_nop 0
	v_fma_f32 v100, -v96, v99, 1.0
	v_fmac_f32_e32 v99, v100, v99
	v_fma_f32 v103, -v96, v99, 1.0
	v_fma_f32 v101, v103, v99, v99
	v_fma_f32 v98, -v96, v101, 1.0
	v_fma_f32 v98, v98, v99, v101
	v_div_fixup_f32 v96, v98, v96, 1.0
	v_mov_b32_e32 v98, v90
	v_mov_b32_e32 v99, v92
	v_pk_mul_f32 v[96:97], v[98:99], v[96:97]
	v_mov_b32_e32 v92, v91
	v_pk_mul_f32 v[90:91], v[92:93], v[96:97]
	v_cvt_pk_bf16_f32 v92, v94, v95
	v_cvt_pk_bf16_f32 v93, v90, v91
	v_mad_i64_i32 v[90:91], s[4:5], v102, s86, v[122:123]
	v_lshl_add_u64 v[90:91], v[90:91], 0, v[124:125]
	global_store_dwordx2 v[90:91], v[92:93], off
	v_mul_f32_e32 v92, 0xbfb8aa3b, v86
	v_mul_f32_e32 v93, 0xbfb8aa3b, v88
	v_exp_f32_e32 v92, v92
	v_exp_f32_e32 v93, v93
	s_nop 0
	v_pk_add_f32 v[92:93], v[92:93], 1.0 op_sel_hi:[1,0]
	s_nop 0
	v_rcp_f32_e32 v95, v93
	s_nop 0
	v_fma_f32 v96, -v93, v95, 1.0
	v_fmac_f32_e32 v95, v96, v95
	v_fma_f32 v98, -v93, v95, 1.0
	v_fma_f32 v97, v98, v95, v95
	v_fma_f32 v94, -v93, v97, 1.0
	v_fma_f32 v94, v94, v95, v97
	v_div_fixup_f32 v93, v94, v93, 1.0
	v_rcp_f32_e32 v95, v92
	s_nop 0
	v_fma_f32 v96, -v92, v95, 1.0
	v_fmac_f32_e32 v95, v96, v95
	v_fma_f32 v98, -v92, v95, 1.0
	v_fma_f32 v97, v98, v95, v95
	v_fma_f32 v94, -v92, v97, 1.0
	v_fma_f32 v94, v94, v95, v97
	v_div_fixup_f32 v92, v94, v92, 1.0
	v_mov_b32_e32 v94, v86
	v_mov_b32_e32 v95, v88
	v_pk_mul_f32 v[92:93], v[94:95], v[92:93]
	v_mov_b32_e32 v88, v87
	v_pk_mul_f32 v[86:87], v[88:89], v[92:93]
; __device__ __forceinline__ unsigned pkbf(float lo, float hi) { f32x2 v = {lo, hi}; bf16x2v b = __builtin_convertvector(v, bf16x2v); return __builtin_bit_cast(unsigned, b); }
; __device__ __forceinline__ float sigmoidf_(float x) { return 1.f / (1.f + __expf(-x)); }
;     __device__ __forceinline__ void operator()(int row, int col, f32x4 v0, f32x4 v1) const { *(u32x4*)(G + (size_t)row * 1024 + col) = pack8(v0, v1); }
;     __device__ __forceinline__ void operator()(int row, int col, f32x4 v0, f32x4 v1) const {
;         const float h0 = v0.x * sigmoidf_(v0.x) * v0.y, h1 = v0.z * sigmoidf_(v0.z) * v0.w, h2 = v1.x * sigmoidf_(v1.x) * v1.y, h3 = v1.z * sigmoidf_(v1.z) * v1.w;
;         u32x2 o; o.x = pkbf(h0, h1); o.y = pkbf(h2, h3);
;         *(u32x2*)(HID + (size_t)row * DFF + (col >> 1)) = o;
;     }
	v_mul_f32_e32 v88, 0xbfb8aa3b, v82
	v_mul_f32_e32 v89, 0xbfb8aa3b, v84
	v_exp_f32_e32 v88, v88
	v_exp_f32_e32 v89, v89
	s_nop 0
	v_pk_add_f32 v[88:89], v[88:89], 1.0 op_sel_hi:[1,0]
	s_nop 0
	v_rcp_f32_e32 v93, v89
	s_nop 0
	v_fma_f32 v94, -v89, v93, 1.0
	v_fmac_f32_e32 v93, v94, v93
	v_fma_f32 v96, -v89, v93, 1.0
	v_fma_f32 v95, v96, v93, v93
	v_fma_f32 v92, -v89, v95, 1.0
	v_fma_f32 v92, v92, v93, v95
	v_div_fixup_f32 v89, v92, v89, 1.0
	v_rcp_f32_e32 v93, v88
	s_nop 0
	v_fma_f32 v94, -v88, v93, 1.0
	v_fmac_f32_e32 v93, v94, v93
	v_fma_f32 v96, -v88, v93, 1.0
	v_fma_f32 v95, v96, v93, v93
	v_fma_f32 v92, -v88, v95, 1.0
	v_fma_f32 v92, v92, v93, v95
	v_div_fixup_f32 v88, v92, v88, 1.0
	v_mov_b32_e32 v92, v82
	v_mov_b32_e32 v93, v84
	v_pk_mul_f32 v[88:89], v[92:93], v[88:89]
	v_mov_b32_e32 v84, v83
	v_pk_mul_f32 v[82:83], v[84:85], v[88:89]
	v_cvt_pk_bf16_f32 v84, v86, v87
	v_cvt_pk_bf16_f32 v85, v82, v83
	v_mul_f32_e32 v82, 0xbfb8aa3b, v78
	v_mul_f32_e32 v83, 0xbfb8aa3b, v80
	v_exp_f32_e32 v82, v82
	v_exp_f32_e32 v83, v83
	global_store_dwordx2 v[90:91], v[84:85], off offset:128
	v_or_b32_e32 v86, 48, v144
	v_pk_add_f32 v[82:83], v[82:83], 1.0 op_sel_hi:[1,0]
	s_nop 0
	v_rcp_f32_e32 v85, v83
	s_nop 0
	v_fma_f32 v87, -v83, v85, 1.0
	v_fmac_f32_e32 v85, v87, v85
	v_fma_f32 v89, -v83, v85, 1.0
	v_fma_f32 v88, v89, v85, v85
	v_fma_f32 v84, -v83, v88, 1.0
	v_fma_f32 v84, v84, v85, v88
	v_div_fixup_f32 v83, v84, v83, 1.0
	v_rcp_f32_e32 v85, v82
	s_nop 0
	v_fma_f32 v87, -v82, v85, 1.0
	v_fmac_f32_e32 v85, v87, v85
	v_fma_f32 v89, -v82, v85, 1.0
	v_fma_f32 v88, v89, v85, v85
	v_fma_f32 v84, -v82, v88, 1.0
	v_fma_f32 v84, v84, v85, v88
	v_div_fixup_f32 v82, v84, v82, 1.0
	v_mov_b32_e32 v84, v78
	v_mov_b32_e32 v85, v80
	v_pk_mul_f32 v[82:83], v[84:85], v[82:83]
	v_mov_b32_e32 v80, v79
	v_pk_mul_f32 v[78:79], v[80:81], v[82:83]
	v_mul_f32_e32 v80, 0xbfb8aa3b, v74
	v_mul_f32_e32 v81, 0xbfb8aa3b, v76
	v_exp_f32_e32 v80, v80
	v_exp_f32_e32 v81, v81
	s_nop 0
	v_pk_add_f32 v[80:81], v[80:81], 1.0 op_sel_hi:[1,0]
	s_nop 0
	v_rcp_f32_e32 v83, v81
	s_nop 0
	v_fma_f32 v84, -v81, v83, 1.0
	v_fmac_f32_e32 v83, v84, v83
	v_fma_f32 v87, -v81, v83, 1.0
	v_fma_f32 v85, v87, v83, v83
	v_fma_f32 v82, -v81, v85, 1.0
	v_fma_f32 v82, v82, v83, v85
	v_div_fixup_f32 v81, v82, v81, 1.0
	v_rcp_f32_e32 v83, v80
	s_nop 0
	v_fma_f32 v84, -v80, v83, 1.0
	v_fmac_f32_e32 v83, v84, v83
	v_fma_f32 v87, -v80, v83, 1.0
	v_fma_f32 v85, v87, v83, v83
	v_fma_f32 v82, -v80, v85, 1.0
	v_fma_f32 v82, v82, v83, v85
	v_div_fixup_f32 v80, v82, v80, 1.0
	v_mov_b32_e32 v82, v74
	v_mov_b32_e32 v83, v76
	v_pk_mul_f32 v[80:81], v[82:83], v[80:81]
	v_mov_b32_e32 v76, v75
	v_pk_mul_f32 v[74:75], v[76:77], v[80:81]
	v_cvt_pk_bf16_f32 v76, v78, v79
	v_cvt_pk_bf16_f32 v77, v74, v75
	v_mad_i64_i32 v[74:75], s[4:5], v86, s86, v[122:123]
	v_lshl_add_u64 v[74:75], v[74:75], 0, v[124:125]
	global_store_dwordx2 v[74:75], v[76:77], off
	v_mul_f32_e32 v76, 0xbfb8aa3b, v70
	v_mul_f32_e32 v77, 0xbfb8aa3b, v72
	v_exp_f32_e32 v76, v76
	v_exp_f32_e32 v77, v77
	s_nop 0
	v_pk_add_f32 v[76:77], v[76:77], 1.0 op_sel_hi:[1,0]
	s_nop 0
	v_rcp_f32_e32 v79, v77
	s_nop 0
	v_fma_f32 v80, -v77, v79, 1.0
	v_fmac_f32_e32 v79, v80, v79
	v_fma_f32 v82, -v77, v79, 1.0
	v_fma_f32 v81, v82, v79, v79
	v_fma_f32 v78, -v77, v81, 1.0
	v_fma_f32 v78, v78, v79, v81
	v_div_fixup_f32 v77, v78, v77, 1.0
	v_rcp_f32_e32 v79, v76
	s_nop 0
	v_fma_f32 v80, -v76, v79, 1.0
	v_fmac_f32_e32 v79, v80, v79
	v_fma_f32 v82, -v76, v79, 1.0
	v_fma_f32 v81, v82, v79, v79
	v_fma_f32 v78, -v76, v81, 1.0
	v_fma_f32 v78, v78, v79, v81
	v_div_fixup_f32 v76, v78, v76, 1.0
	v_mov_b32_e32 v78, v70
	v_mov_b32_e32 v79, v72
	v_pk_mul_f32 v[76:77], v[78:79], v[76:77]
	v_mov_b32_e32 v72, v71
	v_pk_mul_f32 v[70:71], v[72:73], v[76:77]
	v_mul_f32_e32 v72, 0xbfb8aa3b, v66
	v_mul_f32_e32 v73, 0xbfb8aa3b, v68
	v_exp_f32_e32 v72, v72
	v_exp_f32_e32 v73, v73
	s_nop 0
	v_pk_add_f32 v[72:73], v[72:73], 1.0 op_sel_hi:[1,0]
	s_nop 0
	v_rcp_f32_e32 v77, v73
	s_nop 0
	v_fma_f32 v78, -v73, v77, 1.0
	v_fmac_f32_e32 v77, v78, v77
	v_fma_f32 v80, -v73, v77, 1.0
	v_fma_f32 v79, v80, v77, v77
	v_fma_f32 v76, -v73, v79, 1.0
	v_fma_f32 v76, v76, v77, v79
	v_div_fixup_f32 v73, v76, v73, 1.0
	v_rcp_f32_e32 v77, v72
	s_nop 0
	v_fma_f32 v78, -v72, v77, 1.0
	v_fmac_f32_e32 v77, v78, v77
	v_fma_f32 v80, -v72, v77, 1.0
	v_fma_f32 v79, v80, v77, v77
	v_fma_f32 v76, -v72, v79, 1.0
	v_fma_f32 v76, v76, v77, v79
	v_div_fixup_f32 v72, v76, v72, 1.0
	v_mov_b32_e32 v76, v66
	v_mov_b32_e32 v77, v68
	v_pk_mul_f32 v[72:73], v[76:77], v[72:73]
	v_mov_b32_e32 v68, v67
	v_pk_mul_f32 v[66:67], v[68:69], v[72:73]
	v_cvt_pk_bf16_f32 v68, v70, v71
	v_cvt_pk_bf16_f32 v69, v66, v67
	v_mul_f32_e32 v66, 0xbfb8aa3b, v62
	v_mul_f32_e32 v67, 0xbfb8aa3b, v64
	v_exp_f32_e32 v66, v66
	v_exp_f32_e32 v67, v67
	global_store_dwordx2 v[74:75], v[68:69], off offset:128
	v_add_u32_e32 v70, 0x80, v144
	v_pk_add_f32 v[66:67], v[66:67], 1.0 op_sel_hi:[1,0]
	s_nop 0
	v_rcp_f32_e32 v69, v67
	s_nop 0
	v_fma_f32 v71, -v67, v69, 1.0
	v_fmac_f32_e32 v69, v71, v69
	v_fma_f32 v73, -v67, v69, 1.0
	v_fma_f32 v72, v73, v69, v69
	v_fma_f32 v68, -v67, v72, 1.0
	v_fma_f32 v68, v68, v69, v72
	v_div_fixup_f32 v67, v68, v67, 1.0
	v_rcp_f32_e32 v69, v66
	s_nop 0
	v_fma_f32 v71, -v66, v69, 1.0
	v_fmac_f32_e32 v69, v71, v69
	v_fma_f32 v73, -v66, v69, 1.0
	v_fma_f32 v72, v73, v69, v69
	v_fma_f32 v68, -v66, v72, 1.0
	v_fma_f32 v68, v68, v69, v72
	v_div_fixup_f32 v66, v68, v66, 1.0
	v_mov_b32_e32 v68, v62
	v_mov_b32_e32 v69, v64
	v_pk_mul_f32 v[66:67], v[68:69], v[66:67]
	v_mov_b32_e32 v64, v63
	v_pk_mul_f32 v[62:63], v[64:65], v[66:67]
; __device__ __forceinline__ unsigned pkbf(float lo, float hi) { f32x2 v = {lo, hi}; bf16x2v b = __builtin_convertvector(v, bf16x2v); return __builtin_bit_cast(unsigned, b); }
; __device__ __forceinline__ float sigmoidf_(float x) { return 1.f / (1.f + __expf(-x)); }
;     __device__ __forceinline__ void operator()(int row, int col, f32x4 v0, f32x4 v1) const { *(u32x4*)(G + (size_t)row * 1024 + col) = pack8(v0, v1); }
;     __device__ __forceinline__ void operator()(int row, int col, f32x4 v0, f32x4 v1) const {
;         const float h0 = v0.x * sigmoidf_(v0.x) * v0.y, h1 = v0.z * sigmoidf_(v0.z) * v0.w, h2 = v1.x * sigmoidf_(v1.x) * v1.y, h3 = v1.z * sigmoidf_(v1.z) * v1.w;
;         u32x2 o; o.x = pkbf(h0, h1); o.y = pkbf(h2, h3);
;         *(u32x2*)(HID + (size_t)row * DFF + (col >> 1)) = o;
;     }
	v_mul_f32_e32 v64, 0xbfb8aa3b, v58
	v_mul_f32_e32 v65, 0xbfb8aa3b, v60
	v_exp_f32_e32 v64, v64
	v_exp_f32_e32 v65, v65
	s_nop 0
	v_pk_add_f32 v[64:65], v[64:65], 1.0 op_sel_hi:[1,0]
	s_nop 0
	v_rcp_f32_e32 v67, v65
	s_nop 0
	v_fma_f32 v68, -v65, v67, 1.0
	v_fmac_f32_e32 v67, v68, v67
	v_fma_f32 v71, -v65, v67, 1.0
	v_fma_f32 v69, v71, v67, v67
	v_fma_f32 v66, -v65, v69, 1.0
	v_fma_f32 v66, v66, v67, v69
	v_div_fixup_f32 v65, v66, v65, 1.0
	v_rcp_f32_e32 v67, v64
	s_nop 0
	v_fma_f32 v68, -v64, v67, 1.0
	v_fmac_f32_e32 v67, v68, v67
	v_fma_f32 v71, -v64, v67, 1.0
	v_fma_f32 v69, v71, v67, v67
	v_fma_f32 v66, -v64, v69, 1.0
	v_fma_f32 v66, v66, v67, v69
	v_div_fixup_f32 v64, v66, v64, 1.0
	v_mov_b32_e32 v66, v58
	v_mov_b32_e32 v67, v60
	v_pk_mul_f32 v[64:65], v[66:67], v[64:65]
	v_mov_b32_e32 v60, v59
	v_pk_mul_f32 v[58:59], v[60:61], v[64:65]
	v_cvt_pk_bf16_f32 v60, v62, v63
	v_cvt_pk_bf16_f32 v61, v58, v59
	v_mad_i64_i32 v[58:59], s[4:5], v70, s86, v[122:123]
	v_lshl_add_u64 v[58:59], v[58:59], 0, v[124:125]
	global_store_dwordx2 v[58:59], v[60:61], off
	v_mul_f32_e32 v60, 0xbfb8aa3b, v54
	v_mul_f32_e32 v61, 0xbfb8aa3b, v56
	v_exp_f32_e32 v60, v60
	v_exp_f32_e32 v61, v61
	s_nop 0
	v_pk_add_f32 v[60:61], v[60:61], 1.0 op_sel_hi:[1,0]
	s_nop 0
	v_rcp_f32_e32 v63, v61
	s_nop 0
	v_fma_f32 v64, -v61, v63, 1.0
	v_fmac_f32_e32 v63, v64, v63
	v_fma_f32 v66, -v61, v63, 1.0
	v_fma_f32 v65, v66, v63, v63
	v_fma_f32 v62, -v61, v65, 1.0
	v_fma_f32 v62, v62, v63, v65
	v_div_fixup_f32 v61, v62, v61, 1.0
	v_rcp_f32_e32 v63, v60
	s_nop 0
	v_fma_f32 v64, -v60, v63, 1.0
	v_fmac_f32_e32 v63, v64, v63
	v_fma_f32 v66, -v60, v63, 1.0
	v_fma_f32 v65, v66, v63, v63
	v_fma_f32 v62, -v60, v65, 1.0
	v_fma_f32 v62, v62, v63, v65
	v_div_fixup_f32 v60, v62, v60, 1.0
	v_mov_b32_e32 v62, v54
	v_mov_b32_e32 v63, v56
	v_pk_mul_f32 v[60:61], v[62:63], v[60:61]
	v_mov_b32_e32 v56, v55
	v_pk_mul_f32 v[54:55], v[56:57], v[60:61]
	v_mul_f32_e32 v56, 0xbfb8aa3b, v50
	v_mul_f32_e32 v57, 0xbfb8aa3b, v52
	v_exp_f32_e32 v56, v56
	v_exp_f32_e32 v57, v57
	s_nop 0
	v_pk_add_f32 v[56:57], v[56:57], 1.0 op_sel_hi:[1,0]
	s_nop 0
	v_rcp_f32_e32 v61, v57
	s_nop 0
	v_fma_f32 v62, -v57, v61, 1.0
	v_fmac_f32_e32 v61, v62, v61
	v_fma_f32 v64, -v57, v61, 1.0
	v_fma_f32 v63, v64, v61, v61
	v_fma_f32 v60, -v57, v63, 1.0
	v_fma_f32 v60, v60, v61, v63
	v_div_fixup_f32 v57, v60, v57, 1.0
	v_rcp_f32_e32 v61, v56
	s_nop 0
	v_fma_f32 v62, -v56, v61, 1.0
	v_fmac_f32_e32 v61, v62, v61
	v_fma_f32 v64, -v56, v61, 1.0
	v_fma_f32 v63, v64, v61, v61
	v_fma_f32 v60, -v56, v63, 1.0
	v_fma_f32 v60, v60, v61, v63
	v_div_fixup_f32 v56, v60, v56, 1.0
	v_mov_b32_e32 v60, v50
	v_mov_b32_e32 v61, v52
	v_pk_mul_f32 v[56:57], v[60:61], v[56:57]
	v_mov_b32_e32 v52, v51
	v_pk_mul_f32 v[50:51], v[52:53], v[56:57]
	v_cvt_pk_bf16_f32 v52, v54, v55
	v_cvt_pk_bf16_f32 v53, v50, v51
	v_mul_f32_e32 v50, 0xbfb8aa3b, v46
	v_mul_f32_e32 v51, 0xbfb8aa3b, v48
	v_exp_f32_e32 v50, v50
	v_exp_f32_e32 v51, v51
	global_store_dwordx2 v[58:59], v[52:53], off offset:128
	v_add_u32_e32 v54, 0x90, v144
	v_pk_add_f32 v[50:51], v[50:51], 1.0 op_sel_hi:[1,0]
	s_nop 0
	v_rcp_f32_e32 v53, v51
	s_nop 0
	v_fma_f32 v55, -v51, v53, 1.0
	v_fmac_f32_e32 v53, v55, v53
	v_fma_f32 v57, -v51, v53, 1.0
	v_fma_f32 v56, v57, v53, v53
	v_fma_f32 v52, -v51, v56, 1.0
	v_fma_f32 v52, v52, v53, v56
	v_div_fixup_f32 v51, v52, v51, 1.0
	v_rcp_f32_e32 v53, v50
	s_nop 0
	v_fma_f32 v55, -v50, v53, 1.0
	v_fmac_f32_e32 v53, v55, v53
	v_fma_f32 v57, -v50, v53, 1.0
	v_fma_f32 v56, v57, v53, v53
	v_fma_f32 v52, -v50, v56, 1.0
	v_fma_f32 v52, v52, v53, v56
	v_div_fixup_f32 v50, v52, v50, 1.0
	v_mov_b32_e32 v52, v46
	v_mov_b32_e32 v53, v48
	v_pk_mul_f32 v[50:51], v[52:53], v[50:51]
	v_mov_b32_e32 v48, v47
	v_pk_mul_f32 v[46:47], v[48:49], v[50:51]
	v_mul_f32_e32 v48, 0xbfb8aa3b, v42
	v_mul_f32_e32 v49, 0xbfb8aa3b, v44
	v_exp_f32_e32 v48, v48
	v_exp_f32_e32 v49, v49
	s_nop 0
	v_pk_add_f32 v[48:49], v[48:49], 1.0 op_sel_hi:[1,0]
	s_nop 0
	v_rcp_f32_e32 v51, v49
	s_nop 0
	v_fma_f32 v52, -v49, v51, 1.0
	v_fmac_f32_e32 v51, v52, v51
	v_fma_f32 v55, -v49, v51, 1.0
	v_fma_f32 v53, v55, v51, v51
	v_fma_f32 v50, -v49, v53, 1.0
	v_fma_f32 v50, v50, v51, v53
	v_div_fixup_f32 v49, v50, v49, 1.0
	v_rcp_f32_e32 v51, v48
	s_nop 0
	v_fma_f32 v52, -v48, v51, 1.0
	v_fmac_f32_e32 v51, v52, v51
	v_fma_f32 v55, -v48, v51, 1.0
	v_fma_f32 v53, v55, v51, v51
	v_fma_f32 v50, -v48, v53, 1.0
	v_fma_f32 v50, v50, v51, v53
	v_div_fixup_f32 v48, v50, v48, 1.0
	v_mov_b32_e32 v50, v42
	v_mov_b32_e32 v51, v44
	v_pk_mul_f32 v[48:49], v[50:51], v[48:49]
	v_mov_b32_e32 v44, v43
	v_pk_mul_f32 v[42:43], v[44:45], v[48:49]
	v_cvt_pk_bf16_f32 v44, v46, v47
	v_cvt_pk_bf16_f32 v45, v42, v43
	v_mad_i64_i32 v[42:43], s[4:5], v54, s86, v[122:123]
	v_lshl_add_u64 v[42:43], v[42:43], 0, v[124:125]
	global_store_dwordx2 v[42:43], v[44:45], off
	v_mul_f32_e32 v44, 0xbfb8aa3b, v38
	v_mul_f32_e32 v45, 0xbfb8aa3b, v40
	v_exp_f32_e32 v44, v44
	v_exp_f32_e32 v45, v45
	s_nop 0
	v_pk_add_f32 v[44:45], v[44:45], 1.0 op_sel_hi:[1,0]
	s_nop 0
	v_rcp_f32_e32 v47, v45
	s_nop 0
	v_fma_f32 v48, -v45, v47, 1.0
	v_fmac_f32_e32 v47, v48, v47
	v_fma_f32 v50, -v45, v47, 1.0
	v_fma_f32 v49, v50, v47, v47
	v_fma_f32 v46, -v45, v49, 1.0
	v_fma_f32 v46, v46, v47, v49
	v_div_fixup_f32 v45, v46, v45, 1.0
	v_rcp_f32_e32 v47, v44
	s_nop 0
	v_fma_f32 v48, -v44, v47, 1.0
	v_fmac_f32_e32 v47, v48, v47
	v_fma_f32 v50, -v44, v47, 1.0
	v_fma_f32 v49, v50, v47, v47
	v_fma_f32 v46, -v44, v49, 1.0
	v_fma_f32 v46, v46, v47, v49
	v_div_fixup_f32 v44, v46, v44, 1.0
	v_mov_b32_e32 v46, v38
	v_mov_b32_e32 v47, v40
	v_pk_mul_f32 v[44:45], v[46:47], v[44:45]
; __device__ __forceinline__ unsigned pkbf(float lo, float hi) { f32x2 v = {lo, hi}; bf16x2v b = __builtin_convertvector(v, bf16x2v); return __builtin_bit_cast(unsigned, b); }
; __device__ __forceinline__ float sigmoidf_(float x) { return 1.f / (1.f + __expf(-x)); }
;     __device__ __forceinline__ void operator()(int row, int col, f32x4 v0, f32x4 v1) const { *(u32x4*)(G + (size_t)row * 1024 + col) = pack8(v0, v1); }
;     __device__ __forceinline__ void operator()(int row, int col, f32x4 v0, f32x4 v1) const {
;         const float h0 = v0.x * sigmoidf_(v0.x) * v0.y, h1 = v0.z * sigmoidf_(v0.z) * v0.w, h2 = v1.x * sigmoidf_(v1.x) * v1.y, h3 = v1.z * sigmoidf_(v1.z) * v1.w;
;         u32x2 o; o.x = pkbf(h0, h1); o.y = pkbf(h2, h3);
;         *(u32x2*)(HID + (size_t)row * DFF + (col >> 1)) = o;
;     }
	v_mov_b32_e32 v40, v39
	v_pk_mul_f32 v[38:39], v[40:41], v[44:45]
	v_mul_f32_e32 v40, 0xbfb8aa3b, v34
	v_mul_f32_e32 v41, 0xbfb8aa3b, v36
	v_exp_f32_e32 v40, v40
	v_exp_f32_e32 v41, v41
	s_nop 0
	v_pk_add_f32 v[40:41], v[40:41], 1.0 op_sel_hi:[1,0]
	s_nop 0
	v_rcp_f32_e32 v45, v41
	s_nop 0
	v_fma_f32 v46, -v41, v45, 1.0
	v_fmac_f32_e32 v45, v46, v45
	v_fma_f32 v48, -v41, v45, 1.0
	v_fma_f32 v47, v48, v45, v45
	v_fma_f32 v44, -v41, v47, 1.0
	v_fma_f32 v44, v44, v45, v47
	v_div_fixup_f32 v41, v44, v41, 1.0
	v_rcp_f32_e32 v45, v40
	s_nop 0
	v_fma_f32 v46, -v40, v45, 1.0
	v_fmac_f32_e32 v45, v46, v45
	v_fma_f32 v48, -v40, v45, 1.0
	v_fma_f32 v47, v48, v45, v45
	v_fma_f32 v44, -v40, v47, 1.0
	v_fma_f32 v44, v44, v45, v47
	v_div_fixup_f32 v40, v44, v40, 1.0
	v_mov_b32_e32 v44, v34
	v_mov_b32_e32 v45, v36
	v_pk_mul_f32 v[40:41], v[44:45], v[40:41]
	v_mov_b32_e32 v36, v35
	v_pk_mul_f32 v[34:35], v[36:37], v[40:41]
	v_cvt_pk_bf16_f32 v36, v38, v39
	v_cvt_pk_bf16_f32 v37, v34, v35
	v_mul_f32_e32 v34, 0xbfb8aa3b, v30
	v_mul_f32_e32 v35, 0xbfb8aa3b, v32
	v_exp_f32_e32 v34, v34
	v_exp_f32_e32 v35, v35
	global_store_dwordx2 v[42:43], v[36:37], off offset:128
	v_add_u32_e32 v38, 0xa0, v144
	v_pk_add_f32 v[34:35], v[34:35], 1.0 op_sel_hi:[1,0]
	s_nop 0
	v_rcp_f32_e32 v37, v35
	s_nop 0
	v_fma_f32 v39, -v35, v37, 1.0
	v_fmac_f32_e32 v37, v39, v37
	v_fma_f32 v41, -v35, v37, 1.0
	v_fma_f32 v40, v41, v37, v37
	v_fma_f32 v36, -v35, v40, 1.0
	v_fma_f32 v36, v36, v37, v40
	v_div_fixup_f32 v35, v36, v35, 1.0
	v_rcp_f32_e32 v37, v34
	s_nop 0
	v_fma_f32 v39, -v34, v37, 1.0
	v_fmac_f32_e32 v37, v39, v37
	v_fma_f32 v41, -v34, v37, 1.0
	v_fma_f32 v40, v41, v37, v37
	v_fma_f32 v36, -v34, v40, 1.0
	v_fma_f32 v36, v36, v37, v40
	v_div_fixup_f32 v34, v36, v34, 1.0
	v_mov_b32_e32 v36, v30
	v_mov_b32_e32 v37, v32
	v_pk_mul_f32 v[34:35], v[36:37], v[34:35]
	v_mov_b32_e32 v32, v31
	v_pk_mul_f32 v[30:31], v[32:33], v[34:35]
	v_mul_f32_e32 v32, 0xbfb8aa3b, v26
	v_mul_f32_e32 v33, 0xbfb8aa3b, v28
	v_exp_f32_e32 v32, v32
	v_exp_f32_e32 v33, v33
	s_nop 0
	v_pk_add_f32 v[32:33], v[32:33], 1.0 op_sel_hi:[1,0]
	s_nop 0
	v_rcp_f32_e32 v35, v33
	s_nop 0
	v_fma_f32 v36, -v33, v35, 1.0
	v_fmac_f32_e32 v35, v36, v35
	v_fma_f32 v39, -v33, v35, 1.0
	v_fma_f32 v37, v39, v35, v35
	v_fma_f32 v34, -v33, v37, 1.0
	v_fma_f32 v34, v34, v35, v37
	v_div_fixup_f32 v33, v34, v33, 1.0
	v_rcp_f32_e32 v35, v32
	s_nop 0
	v_fma_f32 v36, -v32, v35, 1.0
	v_fmac_f32_e32 v35, v36, v35
	v_fma_f32 v39, -v32, v35, 1.0
	v_fma_f32 v37, v39, v35, v35
	v_fma_f32 v34, -v32, v37, 1.0
	v_fma_f32 v34, v34, v35, v37
	v_div_fixup_f32 v32, v34, v32, 1.0
	v_mov_b32_e32 v34, v26
	v_mov_b32_e32 v35, v28
	v_pk_mul_f32 v[32:33], v[34:35], v[32:33]
	v_mov_b32_e32 v28, v27
	v_pk_mul_f32 v[26:27], v[28:29], v[32:33]
	v_cvt_pk_bf16_f32 v28, v30, v31
	v_cvt_pk_bf16_f32 v29, v26, v27
	v_mad_i64_i32 v[26:27], s[4:5], v38, s86, v[122:123]
	v_lshl_add_u64 v[26:27], v[26:27], 0, v[124:125]
	global_store_dwordx2 v[26:27], v[28:29], off
	v_mul_f32_e32 v28, 0xbfb8aa3b, v22
	v_mul_f32_e32 v29, 0xbfb8aa3b, v24
	v_exp_f32_e32 v28, v28
	v_exp_f32_e32 v29, v29
	s_nop 0
	v_pk_add_f32 v[28:29], v[28:29], 1.0 op_sel_hi:[1,0]
	s_nop 0
	v_rcp_f32_e32 v31, v29
	s_nop 0
	v_fma_f32 v32, -v29, v31, 1.0
	v_fmac_f32_e32 v31, v32, v31
	v_fma_f32 v34, -v29, v31, 1.0
	v_fma_f32 v33, v34, v31, v31
	v_fma_f32 v30, -v29, v33, 1.0
	v_fma_f32 v30, v30, v31, v33
	v_div_fixup_f32 v29, v30, v29, 1.0
	v_rcp_f32_e32 v31, v28
	s_nop 0
	v_fma_f32 v32, -v28, v31, 1.0
	v_fmac_f32_e32 v31, v32, v31
	v_fma_f32 v34, -v28, v31, 1.0
	v_fma_f32 v33, v34, v31, v31
	v_fma_f32 v30, -v28, v33, 1.0
	v_fma_f32 v30, v30, v31, v33
	v_div_fixup_f32 v28, v30, v28, 1.0
	v_mov_b32_e32 v30, v22
	v_mov_b32_e32 v31, v24
	v_pk_mul_f32 v[28:29], v[30:31], v[28:29]
	v_mov_b32_e32 v24, v23
	v_pk_mul_f32 v[22:23], v[24:25], v[28:29]
	v_mul_f32_e32 v24, 0xbfb8aa3b, v18
	v_mul_f32_e32 v25, 0xbfb8aa3b, v20
	v_exp_f32_e32 v24, v24
	v_exp_f32_e32 v25, v25
	s_nop 0
	v_pk_add_f32 v[24:25], v[24:25], 1.0 op_sel_hi:[1,0]
	s_nop 0
	v_rcp_f32_e32 v29, v25
	s_nop 0
	v_fma_f32 v30, -v25, v29, 1.0
	v_fmac_f32_e32 v29, v30, v29
	v_fma_f32 v32, -v25, v29, 1.0
	v_fma_f32 v31, v32, v29, v29
	v_fma_f32 v28, -v25, v31, 1.0
	v_fma_f32 v28, v28, v29, v31
	v_div_fixup_f32 v25, v28, v25, 1.0
	v_rcp_f32_e32 v29, v24
	s_nop 0
	v_fma_f32 v30, -v24, v29, 1.0
; #define PG8_BAR __builtin_amdgcn_s_barrier()
; __device__ __forceinline__ unsigned pkbf(float lo, float hi) { f32x2 v = {lo, hi}; bf16x2v b = __builtin_convertvector(v, bf16x2v); return __builtin_bit_cast(unsigned, b); }
; __device__ __forceinline__ float sigmoidf_(float x) { return 1.f / (1.f + __expf(-x)); }
;     __device__ __forceinline__ void operator()(int row, int col, f32x4 v0, f32x4 v1) const { *(u32x4*)(G + (size_t)row * 1024 + col) = pack8(v0, v1); }
; template <class Epi, class Sched, bool ALIGN_EPI = false, bool SP2 = false>
; __device__ __forceinline__ void gemm_phase(PG8_LAS unsigned char* lds, const Gemm g, const Sched& S, const Epi& E, const int tid_in) {
;     ...
;         if (!has_next) break;
; #pragma unroll
;         for (int a = 0; a < 2; ++a)
; #pragma unroll
;             for (int b = 0; b < 2; ++b)
; #pragma unroll
;                 for (int m = 0; m < 4; ++m)
; #pragma unroll
;                     for (int n = 0; n < 2; ++n) acc[a][b][m][n] = (f32x4){0.f, 0.f, 0.f, 0.f};
;         cur = nxt; cA = nA; cB = nB; ++ui;
;         if constexpr (ALIGN_EPI) { if (wr == 1) PG8_BAR; }
;     __device__ __forceinline__ void operator()(int row, int col, f32x4 v0, f32x4 v1) const {
;         const float h0 = v0.x * sigmoidf_(v0.x) * v0.y, h1 = v0.z * sigmoidf_(v0.z) * v0.w, h2 = v1.x * sigmoidf_(v1.x) * v1.y, h3 = v1.z * sigmoidf_(v1.z) * v1.w;
;         u32x2 o; o.x = pkbf(h0, h1); o.y = pkbf(h2, h3);
;         *(u32x2*)(HID + (size_t)row * DFF + (col >> 1)) = o;
;     }
	v_fmac_f32_e32 v29, v30, v29
	v_fma_f32 v32, -v24, v29, 1.0
	v_fma_f32 v31, v32, v29, v29
	v_fma_f32 v28, -v24, v31, 1.0
	v_fma_f32 v28, v28, v29, v31
	v_div_fixup_f32 v24, v28, v24, 1.0
	v_mov_b32_e32 v28, v18
	v_mov_b32_e32 v29, v20
	v_pk_mul_f32 v[24:25], v[28:29], v[24:25]
	v_mov_b32_e32 v20, v19
	v_pk_mul_f32 v[18:19], v[20:21], v[24:25]
	v_cvt_pk_bf16_f32 v20, v22, v23
	v_cvt_pk_bf16_f32 v21, v18, v19
	v_mul_f32_e32 v18, 0xbfb8aa3b, v14
	v_mul_f32_e32 v19, 0xbfb8aa3b, v16
	v_exp_f32_e32 v18, v18
	v_exp_f32_e32 v19, v19
	global_store_dwordx2 v[26:27], v[20:21], off offset:128
	v_add_u32_e32 v22, 0xb0, v144
	v_pk_add_f32 v[18:19], v[18:19], 1.0 op_sel_hi:[1,0]
	s_nop 0
	v_rcp_f32_e32 v21, v19
	s_nop 0
	v_fma_f32 v23, -v19, v21, 1.0
	v_fmac_f32_e32 v21, v23, v21
	v_fma_f32 v25, -v19, v21, 1.0
	v_fma_f32 v24, v25, v21, v21
	v_fma_f32 v20, -v19, v24, 1.0
	v_fma_f32 v20, v20, v21, v24
	v_div_fixup_f32 v19, v20, v19, 1.0
	v_rcp_f32_e32 v21, v18
	s_nop 0
	v_fma_f32 v23, -v18, v21, 1.0
	v_fmac_f32_e32 v21, v23, v21
	v_fma_f32 v25, -v18, v21, 1.0
	v_fma_f32 v24, v25, v21, v21
	v_fma_f32 v20, -v18, v24, 1.0
	v_fma_f32 v20, v20, v21, v24
	v_div_fixup_f32 v18, v20, v18, 1.0
	v_mov_b32_e32 v20, v14
	v_mov_b32_e32 v21, v16
	v_pk_mul_f32 v[18:19], v[20:21], v[18:19]
	v_mov_b32_e32 v16, v15
	v_pk_mul_f32 v[14:15], v[16:17], v[18:19]
	v_mul_f32_e32 v16, 0xbfb8aa3b, v10
	v_mul_f32_e32 v17, 0xbfb8aa3b, v12
	v_exp_f32_e32 v16, v16
	v_exp_f32_e32 v17, v17
	s_nop 0
	v_pk_add_f32 v[16:17], v[16:17], 1.0 op_sel_hi:[1,0]
	s_nop 0
	v_rcp_f32_e32 v19, v17
	s_nop 0
	v_fma_f32 v20, -v17, v19, 1.0
	v_fmac_f32_e32 v19, v20, v19
	v_fma_f32 v23, -v17, v19, 1.0
	v_fma_f32 v21, v23, v19, v19
	v_fma_f32 v18, -v17, v21, 1.0
	v_fma_f32 v18, v18, v19, v21
	v_div_fixup_f32 v17, v18, v17, 1.0
	v_rcp_f32_e32 v19, v16
	s_nop 0
	v_fma_f32 v20, -v16, v19, 1.0
	v_fmac_f32_e32 v19, v20, v19
	v_fma_f32 v23, -v16, v19, 1.0
	v_fma_f32 v21, v23, v19, v19
	v_fma_f32 v18, -v16, v21, 1.0
	v_fma_f32 v18, v18, v19, v21
	v_div_fixup_f32 v16, v18, v16, 1.0
	v_mov_b32_e32 v18, v10
	v_mov_b32_e32 v19, v12
	v_pk_mul_f32 v[16:17], v[18:19], v[16:17]
	v_mov_b32_e32 v12, v11
	v_pk_mul_f32 v[10:11], v[12:13], v[16:17]
	v_cvt_pk_bf16_f32 v12, v14, v15
	v_cvt_pk_bf16_f32 v13, v10, v11
	v_mad_i64_i32 v[10:11], s[4:5], v22, s86, v[122:123]
	v_lshl_add_u64 v[10:11], v[10:11], 0, v[124:125]
	global_store_dwordx2 v[10:11], v[12:13], off
	v_mul_f32_e32 v12, 0xbfb8aa3b, v6
	v_mul_f32_e32 v13, 0xbfb8aa3b, v8
	v_exp_f32_e32 v12, v12
	v_exp_f32_e32 v13, v13
	s_nop 0
	v_pk_add_f32 v[12:13], v[12:13], 1.0 op_sel_hi:[1,0]
	s_nop 0
	v_rcp_f32_e32 v15, v13
	s_nop 0
	v_fma_f32 v16, -v13, v15, 1.0
	v_fmac_f32_e32 v15, v16, v15
	v_fma_f32 v18, -v13, v15, 1.0
	v_fma_f32 v17, v18, v15, v15
	v_fma_f32 v14, -v13, v17, 1.0
	v_fma_f32 v14, v14, v15, v17
	v_div_fixup_f32 v13, v14, v13, 1.0
	v_rcp_f32_e32 v15, v12
	s_nop 0
	v_fma_f32 v16, -v12, v15, 1.0
	v_fmac_f32_e32 v15, v16, v15
	v_fma_f32 v18, -v12, v15, 1.0
	v_fma_f32 v17, v18, v15, v15
	v_fma_f32 v14, -v12, v17, 1.0
	v_fma_f32 v14, v14, v15, v17
	v_div_fixup_f32 v12, v14, v12, 1.0
	v_mov_b32_e32 v14, v6
	v_mov_b32_e32 v15, v8
	v_pk_mul_f32 v[12:13], v[14:15], v[12:13]
	v_mov_b32_e32 v8, v7
	v_pk_mul_f32 v[6:7], v[8:9], v[12:13]
	v_mul_f32_e32 v8, 0xbfb8aa3b, v2
	v_mul_f32_e32 v9, 0xbfb8aa3b, v4
	v_exp_f32_e32 v8, v8
	v_exp_f32_e32 v9, v9
	s_nop 0
	v_pk_add_f32 v[8:9], v[8:9], 1.0 op_sel_hi:[1,0]
	s_nop 0
	v_rcp_f32_e32 v13, v9
	s_nop 0
	v_fma_f32 v14, -v9, v13, 1.0
	v_fmac_f32_e32 v13, v14, v13
	v_fma_f32 v16, -v9, v13, 1.0
	v_fma_f32 v15, v16, v13, v13
	v_fma_f32 v12, -v9, v15, 1.0
	v_fma_f32 v12, v12, v13, v15
	v_div_fixup_f32 v9, v12, v9, 1.0
	v_rcp_f32_e32 v13, v8
	s_mov_b64 s[4:5], -1
	v_fma_f32 v14, -v8, v13, 1.0
	v_fmac_f32_e32 v13, v14, v13
	v_fma_f32 v16, -v8, v13, 1.0
	v_fma_f32 v15, v16, v13, v13
	v_fma_f32 v12, -v8, v15, 1.0
	v_fma_f32 v12, v12, v13, v15
	v_div_fixup_f32 v8, v12, v8, 1.0
	v_mov_b32_e32 v12, v2
	v_mov_b32_e32 v13, v4
	v_pk_mul_f32 v[8:9], v[12:13], v[8:9]
	v_mov_b32_e32 v4, v3
	v_pk_mul_f32 v[2:3], v[4:5], v[8:9]
	v_cvt_pk_bf16_f32 v4, v6, v7
	v_cvt_pk_bf16_f32 v5, v2, v3
	global_store_dwordx2 v[10:11], v[4:5], off offset:128
	s_and_b64 vcc, exec, s[40:41]
	s_cbranch_vccnz .LBB0_25
	s_andn2_b64 vcc, exec, s[50:51]
	s_cbranch_vccnz .LBB0_24
	s_barrier
	s_branch .LBB0_24

; __device__ __forceinline__ u32x4 pack8(f32x4 v0, f32x4 v1) { u32x4 o; o.x = pkbf(v0.x, v0.y); o.y = pkbf(v0.z, v0.w); o.z = pkbf(v1.x, v1.y); o.w = pkbf(v1.z, v1.w); return o; }
;     __device__ __forceinline__ float f(float x) const { return -0.6065306597126334f * sigmoidf_(x); }
;     __device__ __forceinline__ void operator()(int row, int col, f32x4 v0, f32x4 v1) const { *(u32x4*)(G + (size_t)row * 1024 + col) = pack8(v0, v1); }
;     __device__ __forceinline__ void operator()(const pg8::f32x4 (&acc)[2][2][4][2], const pg8::Unit& u, int wr, int wc, int fr, int fq) const {
;         const int row0 = u.pm * 256 + wr * 64 + fr, col0 = u.pn * 256 + wc * 32 + 8 * fq;
; #pragma unroll
;         for (int ai = 0; ai < 2; ++ai)
; #pragma unroll
;             for (int m = 0; m < 4; ++m)
; #pragma unroll
;                 for (int bj = 0; bj < 2; ++bj) { op(row0 + ai * 128 + m * 16, col0 + bj * 128, acc[ai][bj][m][0], acc[ai][bj][m][1]); asm volatile("" ::: "memory"); }
;     __device__ __forceinline__ void operator()(int row, int col, f32x4 v0, f32x4 v1) const {
;         const f32x4 b0 = *(const f32x4*)(w0 + col), b1 = *(const f32x4*)(w0 + col + 4);
;         v0 += b0; v1 += b1;
;         v0 = (f32x4){f(v0.x), f(v0.y), f(v0.z), f(v0.w)}; v1 = (f32x4){f(v1.x), f(v1.y), f(v1.z), f(v1.w)};
;         bf16_t* dst = (col < 1024 ? D0 : D1) + (size_t)row * 1024 + (col & 1023);
;         *(u32x4*)dst = pack8(v0, v1);
.LBB0_384:
	v_lshl_or_b32 v148, s47, 8, v158
	v_ashrrev_i32_e32 v149, 31, v148
	v_lshl_add_u64 v[142:143], v[148:149], 2, s[54:55]
	global_load_dwordx4 v[160:163], v[142:143], off offset:16
	global_load_dwordx4 v[164:167], v[142:143], off
	v_lshl_add_u32 v146, s27, 8, v152
	v_ashrrev_i32_e32 v147, 31, v146
	v_lshlrev_b64 v[144:145], 11, v[146:147]
	s_waitcnt vmcnt(0)
	v_pk_add_f32 v[122:123], v[122:123], v[160:161]
	v_pk_add_f32 v[150:151], v[126:127], v[164:165]
	v_pk_add_f32 v[126:127], v[124:125], v[162:163]
	v_mul_f32_e32 v0, 0xbfb8aa3b, v150
	v_exp_f32_e32 v124, v0
	v_mul_f32_e32 v0, 0xbfb8aa3b, v151
	v_exp_f32_e32 v125, v0
	v_pk_add_f32 v[128:129], v[128:129], v[166:167]
	v_pk_add_f32 v[124:125], v[124:125], 1.0 op_sel_hi:[1,0]
	s_nop 0
	v_rcp_f32_e32 v147, v125
	s_nop 0
	v_fma_f32 v149, -v125, v147, 1.0
	v_fmac_f32_e32 v147, v149, v147
	v_fma_f32 v151, -v125, v147, 1.0
	v_fma_f32 v150, v151, v147, v147
	v_fma_f32 v0, -v125, v150, 1.0
	v_fma_f32 v0, v0, v147, v150
	v_div_fixup_f32 v125, v0, v125, 1.0
	v_rcp_f32_e32 v147, v124
	s_nop 0
	v_fma_f32 v149, -v124, v147, 1.0
	v_fmac_f32_e32 v147, v149, v147
	v_fma_f32 v151, -v124, v147, 1.0
	v_fma_f32 v150, v151, v147, v147
	v_fma_f32 v0, -v124, v150, 1.0
	v_fma_f32 v0, v0, v147, v150
	v_div_fixup_f32 v124, v0, v124, 1.0
	v_mul_f32_e32 v0, 0xbfb8aa3b, v128
	v_exp_f32_e32 v128, v0
	v_mul_f32_e32 v0, 0xbfb8aa3b, v129
	v_exp_f32_e32 v129, v0
	v_pk_mul_f32 v[124:125], v[124:125], s[20:21] op_sel_hi:[1,0]
	v_pk_add_f32 v[128:129], v[128:129], 1.0 op_sel_hi:[1,0]
	s_nop 0
	v_rcp_f32_e32 v147, v129
	s_nop 0
	v_fma_f32 v149, -v129, v147, 1.0
	v_fmac_f32_e32 v147, v149, v147
	v_fma_f32 v151, -v129, v147, 1.0
	v_fma_f32 v150, v151, v147, v147
	v_fma_f32 v0, -v129, v150, 1.0
	v_fma_f32 v0, v0, v147, v150
	v_div_fixup_f32 v129, v0, v129, 1.0
	v_rcp_f32_e32 v147, v128
	s_nop 0
	v_fma_f32 v149, -v128, v147, 1.0
	v_fmac_f32_e32 v147, v149, v147
	v_fma_f32 v151, -v128, v147, 1.0
	v_fma_f32 v150, v151, v147, v147
	v_fma_f32 v0, -v128, v150, 1.0
	v_fma_f32 v0, v0, v147, v150
	v_div_fixup_f32 v128, v0, v128, 1.0
	v_mul_f32_e32 v0, 0xbfb8aa3b, v122
	v_exp_f32_e32 v122, v0
	v_mul_f32_e32 v0, 0xbfb8aa3b, v123
	v_exp_f32_e32 v123, v0
	v_pk_mul_f32 v[128:129], v[128:129], s[20:21] op_sel_hi:[1,0]
	v_pk_add_f32 v[122:123], v[122:123], 1.0 op_sel_hi:[1,0]
	s_nop 0
	v_rcp_f32_e32 v147, v123
	s_nop 0
	v_fma_f32 v149, -v123, v147, 1.0
	v_fmac_f32_e32 v147, v149, v147
	v_fma_f32 v151, -v123, v147, 1.0
	v_fma_f32 v150, v151, v147, v147
	v_fma_f32 v0, -v123, v150, 1.0
	v_fma_f32 v0, v0, v147, v150
	v_div_fixup_f32 v123, v0, v123, 1.0
	v_rcp_f32_e32 v147, v122
	s_nop 0
	v_fma_f32 v149, -v122, v147, 1.0
	v_fmac_f32_e32 v147, v149, v147
	v_fma_f32 v151, -v122, v147, 1.0
	v_fma_f32 v150, v151, v147, v147
	v_fma_f32 v0, -v122, v150, 1.0
	v_fma_f32 v0, v0, v147, v150
	v_div_fixup_f32 v122, v0, v122, 1.0
	v_mul_f32_e32 v0, 0xbfb8aa3b, v126
	v_pk_mul_f32 v[150:151], v[122:123], s[20:21] op_sel_hi:[1,0]
	v_exp_f32_e32 v122, v0
	v_mul_f32_e32 v0, 0xbfb8aa3b, v127
	v_exp_f32_e32 v123, v0
	v_cvt_pk_bf16_f32 v162, v150, v151
	v_pk_add_f32 v[122:123], v[122:123], 1.0 op_sel_hi:[1,0]
	s_nop 0
	v_rcp_f32_e32 v126, v123
	s_nop 0
	v_fma_f32 v127, -v123, v126, 1.0
	v_fmac_f32_e32 v126, v127, v126
	v_fma_f32 v149, -v123, v126, 1.0
	v_fma_f32 v147, v149, v126, v126
	v_fma_f32 v0, -v123, v147, 1.0
	v_fma_f32 v0, v0, v126, v147
	v_div_fixup_f32 v123, v0, v123, 1.0
	v_rcp_f32_e32 v126, v122
	s_nop 0
	v_fma_f32 v127, -v122, v126, 1.0
	v_fmac_f32_e32 v126, v127, v126
	v_fma_f32 v149, -v122, v126, 1.0
	v_fma_f32 v147, v149, v126, v126
	v_fma_f32 v0, -v122, v147, 1.0
	v_fma_f32 v0, v0, v126, v147
	v_div_fixup_f32 v122, v0, v122, 1.0
	v_cmp_gt_i32_e32 vcc, s66, v148
	v_mov_b32_e32 v126, s72
	v_mov_b32_e32 v127, s39
	v_mov_b32_e32 v147, s62
	v_mov_b32_e32 v149, s18
	v_pk_mul_f32 v[164:165], v[122:123], s[20:21] op_sel_hi:[1,0]
	v_cndmask_b32_e32 v123, v126, v127, vcc
	v_cndmask_b32_e32 v122, v147, v149, vcc
	v_and_b32_e32 v0, 0x378, v148
	v_lshl_add_u64 v[160:161], v[122:123], 0, v[144:145]
	v_lshlrev_b32_e32 v0, 1, v0
	v_lshl_add_u64 v[166:167], v[160:161], 0, v[0:1]
	v_cvt_pk_bf16_f32 v160, v124, v125
	v_cvt_pk_bf16_f32 v161, v128, v129
	v_cvt_pk_bf16_f32 v163, v164, v165
	global_store_dwordx4 v[166:167], v[160:163], off
	global_load_dwordx4 v[160:163], v[142:143], off offset:528
	global_load_dwordx4 v[164:167], v[142:143], off offset:512
	v_or_b32_e32 v124, 0x80, v148
	s_waitcnt vmcnt(0)
; __device__ __forceinline__ u32x4 pack8(f32x4 v0, f32x4 v1) { u32x4 o; o.x = pkbf(v0.x, v0.y); o.y = pkbf(v0.z, v0.w); o.z = pkbf(v1.x, v1.y); o.w = pkbf(v1.z, v1.w); return o; }
;     __device__ __forceinline__ float f(float x) const { return -0.6065306597126334f * sigmoidf_(x); }
;     __device__ __forceinline__ void operator()(int row, int col, f32x4 v0, f32x4 v1) const { *(u32x4*)(G + (size_t)row * 1024 + col) = pack8(v0, v1); }
;     __device__ __forceinline__ void operator()(int row, int col, f32x4 v0, f32x4 v1) const {
;         const f32x4 b0 = *(const f32x4*)(w0 + col), b1 = *(const f32x4*)(w0 + col + 4);
;         v0 += b0; v1 += b1;
;         v0 = (f32x4){f(v0.x), f(v0.y), f(v0.z), f(v0.w)}; v1 = (f32x4){f(v1.x), f(v1.y), f(v1.z), f(v1.w)};
;         bf16_t* dst = (col < 1024 ? D0 : D1) + (size_t)row * 1024 + (col & 1023);
;         *(u32x4*)dst = pack8(v0, v1);
	v_pk_add_f32 v[114:115], v[114:115], v[160:161]
	v_pk_add_f32 v[118:119], v[118:119], v[164:165]
	v_pk_add_f32 v[120:121], v[120:121], v[166:167]
	v_mul_f32_e32 v118, 0xbfb8aa3b, v118
	v_mul_f32_e32 v119, 0xbfb8aa3b, v119
	v_exp_f32_e32 v118, v118
	v_exp_f32_e32 v119, v119
	v_mul_f32_e32 v120, 0xbfb8aa3b, v120
	v_mul_f32_e32 v121, 0xbfb8aa3b, v121
	v_exp_f32_e32 v120, v120
	v_pk_add_f32 v[118:119], v[118:119], 1.0 op_sel_hi:[1,0]
	v_exp_f32_e32 v121, v121
	v_rcp_f32_e32 v128, v119
	v_pk_add_f32 v[120:121], v[120:121], 1.0 op_sel_hi:[1,0]
	v_mul_f32_e32 v114, 0xbfb8aa3b, v114
	v_mul_f32_e32 v115, 0xbfb8aa3b, v115
	v_fma_f32 v129, -v119, v128, 1.0
	v_fmac_f32_e32 v128, v129, v128
	v_fma_f32 v151, -v119, v128, 1.0
	v_fma_f32 v150, v151, v128, v128
	v_fma_f32 v125, -v119, v150, 1.0
	v_fma_f32 v125, v125, v128, v150
	v_div_fixup_f32 v119, v125, v119, 1.0
	v_rcp_f32_e32 v128, v118
	v_exp_f32_e32 v114, v114
	v_exp_f32_e32 v115, v115
	v_pk_add_f32 v[116:117], v[116:117], v[162:163]
	v_fma_f32 v129, -v118, v128, 1.0
	v_fmac_f32_e32 v128, v129, v128
	v_fma_f32 v151, -v118, v128, 1.0
	v_fma_f32 v150, v151, v128, v128
	v_fma_f32 v125, -v118, v150, 1.0
	v_fma_f32 v125, v125, v128, v150
	v_div_fixup_f32 v118, v125, v118, 1.0
	v_rcp_f32_e32 v128, v121
	v_pk_add_f32 v[114:115], v[114:115], 1.0 op_sel_hi:[1,0]
	v_pk_mul_f32 v[118:119], v[118:119], s[20:21] op_sel_hi:[1,0]
	v_fma_f32 v129, -v121, v128, 1.0
	v_fmac_f32_e32 v128, v129, v128
	v_fma_f32 v151, -v121, v128, 1.0
	v_fma_f32 v150, v151, v128, v128
	v_fma_f32 v125, -v121, v150, 1.0
	v_fma_f32 v125, v125, v128, v150
	v_div_fixup_f32 v121, v125, v121, 1.0
	v_rcp_f32_e32 v128, v120
	v_cvt_pk_bf16_f32 v118, v118, v119
	v_fma_f32 v129, -v120, v128, 1.0
	v_fmac_f32_e32 v128, v129, v128
	v_fma_f32 v151, -v120, v128, 1.0
	v_fma_f32 v150, v151, v128, v128
	v_fma_f32 v125, -v120, v150, 1.0
	v_fma_f32 v125, v125, v128, v150
	v_div_fixup_f32 v120, v125, v120, 1.0
	v_rcp_f32_e32 v128, v115
	v_pk_mul_f32 v[120:121], v[120:121], s[20:21] op_sel_hi:[1,0]
	v_fma_f32 v129, -v115, v128, 1.0
	v_fmac_f32_e32 v128, v129, v128
	v_fma_f32 v151, -v115, v128, 1.0
	v_fma_f32 v150, v151, v128, v128
	v_fma_f32 v125, -v115, v150, 1.0
	v_fma_f32 v125, v125, v128, v150
	v_div_fixup_f32 v115, v125, v115, 1.0
	v_rcp_f32_e32 v128, v114
	v_cvt_pk_bf16_f32 v119, v120, v121
	v_fma_f32 v129, -v114, v128, 1.0
	v_fmac_f32_e32 v128, v129, v128
	v_fma_f32 v151, -v114, v128, 1.0
	v_fma_f32 v150, v151, v128, v128
	v_fma_f32 v125, -v114, v150, 1.0
	v_fma_f32 v125, v125, v128, v150
	v_div_fixup_f32 v114, v125, v114, 1.0
	v_pk_mul_f32 v[128:129], v[114:115], s[20:21] op_sel_hi:[1,0]
	v_mul_f32_e32 v114, 0xbfb8aa3b, v116
	v_mul_f32_e32 v115, 0xbfb8aa3b, v117
	v_exp_f32_e32 v114, v114
	v_exp_f32_e32 v115, v115
	v_cvt_pk_bf16_f32 v120, v128, v129
	v_pk_add_f32 v[114:115], v[114:115], 1.0 op_sel_hi:[1,0]
	s_nop 0
	v_rcp_f32_e32 v117, v115
	s_nop 0
	v_fma_f32 v125, -v115, v117, 1.0
	v_fmac_f32_e32 v117, v125, v117
	v_fma_f32 v151, -v115, v117, 1.0
	v_fma_f32 v150, v151, v117, v117
	v_fma_f32 v116, -v115, v150, 1.0
	v_fma_f32 v116, v116, v117, v150
	v_div_fixup_f32 v115, v116, v115, 1.0
	v_rcp_f32_e32 v117, v114
	s_nop 0
	v_fma_f32 v125, -v114, v117, 1.0
	v_fmac_f32_e32 v117, v125, v117
	v_fma_f32 v151, -v114, v117, 1.0
	v_fma_f32 v150, v151, v117, v117
	v_fma_f32 v116, -v114, v150, 1.0
	v_fma_f32 v116, v116, v117, v150
	v_div_fixup_f32 v114, v116, v114, 1.0
	v_cmp_gt_i32_e32 vcc, s66, v124
	v_pk_mul_f32 v[150:151], v[114:115], s[20:21] op_sel_hi:[1,0]
	v_bitop3_b32 v116, v148, s86, v192 bitop3:0xc8
	v_cndmask_b32_e32 v115, v126, v127, vcc
	v_cndmask_b32_e32 v114, v147, v149, vcc
	v_lshl_add_u64 v[124:125], v[114:115], 0, v[144:145]
	v_lshlrev_b32_e32 v116, 1, v116
	v_mov_b32_e32 v117, v1
	v_lshl_add_u64 v[124:125], v[124:125], 0, v[116:117]
	v_cvt_pk_bf16_f32 v121, v150, v151
	global_store_dwordx4 v[124:125], v[118:121], off
	global_load_dwordx4 v[124:127], v[142:143], off offset:16
	global_load_dwordx4 v[148:151], v[142:143], off
	v_or_b32_e32 v118, 16, v146
	v_ashrrev_i32_e32 v119, 31, v118
	v_lshlrev_b64 v[118:119], 11, v[118:119]
	s_waitcnt vmcnt(0)
	v_pk_add_f32 v[120:121], v[106:107], v[124:125]
	v_pk_add_f32 v[110:111], v[110:111], v[148:149]
	v_pk_add_f32 v[108:109], v[108:109], v[126:127]
	v_mul_f32_e32 v106, 0xbfb8aa3b, v110
	v_mul_f32_e32 v107, 0xbfb8aa3b, v111
	v_exp_f32_e32 v106, v106
	v_exp_f32_e32 v107, v107
	v_pk_add_f32 v[112:113], v[112:113], v[150:151]
	v_mul_f32_e32 v108, 0xbfb8aa3b, v108
	v_mul_f32_e32 v109, 0xbfb8aa3b, v109
	v_pk_add_f32 v[106:107], v[106:107], 1.0 op_sel_hi:[1,0]
	v_exp_f32_e32 v108, v108
	v_rcp_f32_e32 v111, v107
	v_exp_f32_e32 v109, v109
	v_fma_f32 v124, -v107, v111, 1.0
	v_fmac_f32_e32 v111, v124, v111
	v_fma_f32 v126, -v107, v111, 1.0
	v_fma_f32 v125, v126, v111, v111
	v_fma_f32 v110, -v107, v125, 1.0
	v_fma_f32 v110, v110, v111, v125
	v_div_fixup_f32 v107, v110, v107, 1.0
	v_rcp_f32_e32 v111, v106
	v_pk_add_f32 v[108:109], v[108:109], 1.0 op_sel_hi:[1,0]
	v_fma_f32 v124, -v106, v111, 1.0
	v_fmac_f32_e32 v111, v124, v111
	v_fma_f32 v126, -v106, v111, 1.0
	v_fma_f32 v125, v126, v111, v111
	v_fma_f32 v110, -v106, v125, 1.0
	v_fma_f32 v110, v110, v111, v125
	v_div_fixup_f32 v106, v110, v106, 1.0
	v_mul_f32_e32 v110, 0xbfb8aa3b, v112
	v_mul_f32_e32 v111, 0xbfb8aa3b, v113
	v_exp_f32_e32 v110, v110
	v_exp_f32_e32 v111, v111
	v_pk_mul_f32 v[106:107], v[106:107], s[20:21] op_sel_hi:[1,0]
	v_pk_add_f32 v[110:111], v[110:111], 1.0 op_sel_hi:[1,0]
	s_nop 0
	v_rcp_f32_e32 v113, v111
	v_cvt_pk_bf16_f32 v106, v106, v107
	v_fma_f32 v124, -v111, v113, 1.0
	v_fmac_f32_e32 v113, v124, v113
	v_fma_f32 v126, -v111, v113, 1.0
; __device__ __forceinline__ u32x4 pack8(f32x4 v0, f32x4 v1) { u32x4 o; o.x = pkbf(v0.x, v0.y); o.y = pkbf(v0.z, v0.w); o.z = pkbf(v1.x, v1.y); o.w = pkbf(v1.z, v1.w); return o; }
;     __device__ __forceinline__ float f(float x) const { return -0.6065306597126334f * sigmoidf_(x); }
;     __device__ __forceinline__ void operator()(int row, int col, f32x4 v0, f32x4 v1) const { *(u32x4*)(G + (size_t)row * 1024 + col) = pack8(v0, v1); }
;     __device__ __forceinline__ void operator()(int row, int col, f32x4 v0, f32x4 v1) const {
;         const f32x4 b0 = *(const f32x4*)(w0 + col), b1 = *(const f32x4*)(w0 + col + 4);
;         v0 += b0; v1 += b1;
;         v0 = (f32x4){f(v0.x), f(v0.y), f(v0.z), f(v0.w)}; v1 = (f32x4){f(v1.x), f(v1.y), f(v1.z), f(v1.w)};
;         bf16_t* dst = (col < 1024 ? D0 : D1) + (size_t)row * 1024 + (col & 1023);
;         *(u32x4*)dst = pack8(v0, v1);
	v_fma_f32 v125, v126, v113, v113
	v_fma_f32 v112, -v111, v125, 1.0
	v_fma_f32 v112, v112, v113, v125
	v_div_fixup_f32 v111, v112, v111, 1.0
	v_rcp_f32_e32 v113, v110
	s_nop 0
	v_fma_f32 v124, -v110, v113, 1.0
	v_fmac_f32_e32 v113, v124, v113
	v_fma_f32 v126, -v110, v113, 1.0
	v_fma_f32 v125, v126, v113, v113
	v_fma_f32 v112, -v110, v125, 1.0
	v_fma_f32 v112, v112, v113, v125
	v_div_fixup_f32 v110, v112, v110, 1.0
	v_mul_f32_e32 v112, 0xbfb8aa3b, v120
	v_mul_f32_e32 v113, 0xbfb8aa3b, v121
	v_exp_f32_e32 v112, v112
	v_exp_f32_e32 v113, v113
	v_pk_mul_f32 v[110:111], v[110:111], s[20:21] op_sel_hi:[1,0]
	v_pk_add_f32 v[112:113], v[112:113], 1.0 op_sel_hi:[1,0]
	s_nop 0
	v_rcp_f32_e32 v121, v113
	v_cvt_pk_bf16_f32 v107, v110, v111
	v_fma_f32 v124, -v113, v121, 1.0
	v_fmac_f32_e32 v121, v124, v121
	v_fma_f32 v126, -v113, v121, 1.0
	v_fma_f32 v125, v126, v121, v121
	v_fma_f32 v120, -v113, v125, 1.0
	v_fma_f32 v120, v120, v121, v125
	v_div_fixup_f32 v113, v120, v113, 1.0
	v_rcp_f32_e32 v121, v112
	s_nop 0
	v_fma_f32 v124, -v112, v121, 1.0
	v_fmac_f32_e32 v121, v124, v121
	v_fma_f32 v126, -v112, v121, 1.0
	v_fma_f32 v125, v126, v121, v121
	v_fma_f32 v120, -v112, v125, 1.0
	v_fma_f32 v120, v120, v121, v125
	v_div_fixup_f32 v112, v120, v112, 1.0
	v_rcp_f32_e32 v121, v109
	v_pk_mul_f32 v[112:113], v[112:113], s[20:21] op_sel_hi:[1,0]
	v_fma_f32 v124, -v109, v121, 1.0
	v_fmac_f32_e32 v121, v124, v121
	v_fma_f32 v126, -v109, v121, 1.0
	v_fma_f32 v125, v126, v121, v121
	v_fma_f32 v120, -v109, v125, 1.0
	v_fma_f32 v120, v120, v121, v125
	v_div_fixup_f32 v109, v120, v109, 1.0
	v_rcp_f32_e32 v121, v108
	s_nop 0
	v_fma_f32 v124, -v108, v121, 1.0
	v_fmac_f32_e32 v121, v124, v121
	v_fma_f32 v126, -v108, v121, 1.0
	v_fma_f32 v125, v126, v121, v121
	v_fma_f32 v120, -v108, v125, 1.0
	v_fma_f32 v120, v120, v121, v125
	v_div_fixup_f32 v108, v120, v108, 1.0
	v_pk_mul_f32 v[120:121], v[108:109], s[20:21] op_sel_hi:[1,0]
	v_lshl_add_u64 v[108:109], v[122:123], 0, v[118:119]
	v_lshl_add_u64 v[124:125], v[108:109], 0, v[0:1]
	v_cvt_pk_bf16_f32 v108, v112, v113
	v_cvt_pk_bf16_f32 v109, v120, v121
	global_store_dwordx4 v[124:125], v[106:109], off
	global_load_dwordx4 v[106:109], v[142:143], off offset:528
	global_load_dwordx4 v[110:113], v[142:143], off offset:512
	s_waitcnt vmcnt(0)
	v_pk_add_f32 v[106:107], v[98:99], v[106:107]
	v_pk_add_f32 v[102:103], v[102:103], v[110:111]
	v_pk_add_f32 v[100:101], v[100:101], v[108:109]
	v_mul_f32_e32 v98, 0xbfb8aa3b, v102
	v_mul_f32_e32 v99, 0xbfb8aa3b, v103
	v_exp_f32_e32 v98, v98
	v_exp_f32_e32 v99, v99
	v_pk_add_f32 v[104:105], v[104:105], v[112:113]
	v_mul_f32_e32 v100, 0xbfb8aa3b, v100
	v_mul_f32_e32 v101, 0xbfb8aa3b, v101
	v_pk_add_f32 v[98:99], v[98:99], 1.0 op_sel_hi:[1,0]
	v_exp_f32_e32 v100, v100
	v_rcp_f32_e32 v103, v99
	v_exp_f32_e32 v101, v101
	v_fma_f32 v108, -v99, v103, 1.0
	v_fmac_f32_e32 v103, v108, v103
	v_fma_f32 v110, -v99, v103, 1.0
	v_fma_f32 v109, v110, v103, v103
	v_fma_f32 v102, -v99, v109, 1.0
	v_fma_f32 v102, v102, v103, v109
	v_div_fixup_f32 v99, v102, v99, 1.0
	v_rcp_f32_e32 v103, v98
	v_pk_add_f32 v[100:101], v[100:101], 1.0 op_sel_hi:[1,0]
	v_fma_f32 v108, -v98, v103, 1.0
	v_fmac_f32_e32 v103, v108, v103
	v_fma_f32 v110, -v98, v103, 1.0
	v_fma_f32 v109, v110, v103, v103
	v_fma_f32 v102, -v98, v109, 1.0
	v_fma_f32 v102, v102, v103, v109
	v_div_fixup_f32 v98, v102, v98, 1.0
	v_mul_f32_e32 v102, 0xbfb8aa3b, v104
	v_mul_f32_e32 v103, 0xbfb8aa3b, v105
	v_exp_f32_e32 v102, v102
	v_exp_f32_e32 v103, v103
	v_pk_mul_f32 v[98:99], v[98:99], s[20:21] op_sel_hi:[1,0]
	v_pk_add_f32 v[102:103], v[102:103], 1.0 op_sel_hi:[1,0]
	s_nop 0
	v_rcp_f32_e32 v105, v103
	v_cvt_pk_bf16_f32 v98, v98, v99
	v_fma_f32 v108, -v103, v105, 1.0
	v_fmac_f32_e32 v105, v108, v105
	v_fma_f32 v110, -v103, v105, 1.0
	v_fma_f32 v109, v110, v105, v105
	v_fma_f32 v104, -v103, v109, 1.0
	v_fma_f32 v104, v104, v105, v109
	v_div_fixup_f32 v103, v104, v103, 1.0
	v_rcp_f32_e32 v105, v102
	s_nop 0
	v_fma_f32 v108, -v102, v105, 1.0
	v_fmac_f32_e32 v105, v108, v105
	v_fma_f32 v110, -v102, v105, 1.0
	v_fma_f32 v109, v110, v105, v105
	v_fma_f32 v104, -v102, v109, 1.0
	v_fma_f32 v104, v104, v105, v109
	v_div_fixup_f32 v102, v104, v102, 1.0
	v_mul_f32_e32 v104, 0xbfb8aa3b, v106
	v_mul_f32_e32 v105, 0xbfb8aa3b, v107
	v_exp_f32_e32 v104, v104
	v_exp_f32_e32 v105, v105
	v_pk_mul_f32 v[102:103], v[102:103], s[20:21] op_sel_hi:[1,0]
	v_pk_add_f32 v[104:105], v[104:105], 1.0 op_sel_hi:[1,0]
	s_nop 0
	v_rcp_f32_e32 v107, v105
	v_cvt_pk_bf16_f32 v99, v102, v103
	v_fma_f32 v108, -v105, v107, 1.0
	v_fmac_f32_e32 v107, v108, v107
	v_fma_f32 v110, -v105, v107, 1.0
	v_fma_f32 v109, v110, v107, v107
	v_fma_f32 v106, -v105, v109, 1.0
	v_fma_f32 v106, v106, v107, v109
	v_div_fixup_f32 v105, v106, v105, 1.0
	v_rcp_f32_e32 v107, v104
	s_nop 0
	v_fma_f32 v108, -v104, v107, 1.0
	v_fmac_f32_e32 v107, v108, v107
	v_fma_f32 v110, -v104, v107, 1.0
	v_fma_f32 v109, v110, v107, v107
	v_fma_f32 v106, -v104, v109, 1.0
	v_fma_f32 v106, v106, v107, v109
	v_div_fixup_f32 v104, v106, v104, 1.0
	v_rcp_f32_e32 v107, v101
	v_pk_mul_f32 v[104:105], v[104:105], s[20:21] op_sel_hi:[1,0]
	v_fma_f32 v108, -v101, v107, 1.0
	v_fmac_f32_e32 v107, v108, v107
	v_fma_f32 v110, -v101, v107, 1.0
	v_fma_f32 v109, v110, v107, v107
	v_fma_f32 v106, -v101, v109, 1.0
	v_fma_f32 v106, v106, v107, v109
	v_div_fixup_f32 v101, v106, v101, 1.0
	v_rcp_f32_e32 v107, v100
	s_nop 0
	v_fma_f32 v108, -v100, v107, 1.0
	v_fmac_f32_e32 v107, v108, v107
	v_fma_f32 v110, -v100, v107, 1.0
	v_fma_f32 v109, v110, v107, v107
	v_fma_f32 v106, -v100, v109, 1.0
	v_fma_f32 v106, v106, v107, v109
	v_div_fixup_f32 v100, v106, v100, 1.0
	v_pk_mul_f32 v[106:107], v[100:101], s[20:21] op_sel_hi:[1,0]
	v_lshl_add_u64 v[100:101], v[114:115], 0, v[118:119]
	v_lshl_add_u64 v[108:109], v[100:101], 0, v[116:117]
	v_cvt_pk_bf16_f32 v100, v104, v105
	v_cvt_pk_bf16_f32 v101, v106, v107
	global_store_dwordx4 v[108:109], v[98:101], off
	global_load_dwordx4 v[100:103], v[142:143], off offset:16
	global_load_dwordx4 v[104:107], v[142:143], off
	v_or_b32_e32 v98, 32, v146
	v_ashrrev_i32_e32 v99, 31, v98
	v_lshlrev_b64 v[98:99], 11, v[98:99]
	s_waitcnt vmcnt(0)
; __device__ __forceinline__ u32x4 pack8(f32x4 v0, f32x4 v1) { u32x4 o; o.x = pkbf(v0.x, v0.y); o.y = pkbf(v0.z, v0.w); o.z = pkbf(v1.x, v1.y); o.w = pkbf(v1.z, v1.w); return o; }
;     __device__ __forceinline__ float f(float x) const { return -0.6065306597126334f * sigmoidf_(x); }
;     __device__ __forceinline__ void operator()(int row, int col, f32x4 v0, f32x4 v1) const { *(u32x4*)(G + (size_t)row * 1024 + col) = pack8(v0, v1); }
;     __device__ __forceinline__ void operator()(int row, int col, f32x4 v0, f32x4 v1) const {
;         const f32x4 b0 = *(const f32x4*)(w0 + col), b1 = *(const f32x4*)(w0 + col + 4);
;         v0 += b0; v1 += b1;
;         v0 = (f32x4){f(v0.x), f(v0.y), f(v0.z), f(v0.w)}; v1 = (f32x4){f(v1.x), f(v1.y), f(v1.z), f(v1.w)};
;         bf16_t* dst = (col < 1024 ? D0 : D1) + (size_t)row * 1024 + (col & 1023);
;         *(u32x4*)dst = pack8(v0, v1);
	v_pk_add_f32 v[100:101], v[90:91], v[100:101]
	v_pk_add_f32 v[94:95], v[94:95], v[104:105]
	v_pk_add_f32 v[92:93], v[92:93], v[102:103]
	v_mul_f32_e32 v90, 0xbfb8aa3b, v94
	v_mul_f32_e32 v91, 0xbfb8aa3b, v95
	v_exp_f32_e32 v90, v90
	v_exp_f32_e32 v91, v91
	v_pk_add_f32 v[96:97], v[96:97], v[106:107]
	v_mul_f32_e32 v92, 0xbfb8aa3b, v92
	v_mul_f32_e32 v93, 0xbfb8aa3b, v93
	v_pk_add_f32 v[90:91], v[90:91], 1.0 op_sel_hi:[1,0]
	v_exp_f32_e32 v92, v92
	v_rcp_f32_e32 v95, v91
	v_exp_f32_e32 v93, v93
	v_fma_f32 v102, -v91, v95, 1.0
	v_fmac_f32_e32 v95, v102, v95
	v_fma_f32 v104, -v91, v95, 1.0
	v_fma_f32 v103, v104, v95, v95
	v_fma_f32 v94, -v91, v103, 1.0
	v_fma_f32 v94, v94, v95, v103
	v_div_fixup_f32 v91, v94, v91, 1.0
	v_rcp_f32_e32 v95, v90
	v_pk_add_f32 v[92:93], v[92:93], 1.0 op_sel_hi:[1,0]
	v_fma_f32 v102, -v90, v95, 1.0
	v_fmac_f32_e32 v95, v102, v95
	v_fma_f32 v104, -v90, v95, 1.0
	v_fma_f32 v103, v104, v95, v95
	v_fma_f32 v94, -v90, v103, 1.0
	v_fma_f32 v94, v94, v95, v103
	v_div_fixup_f32 v90, v94, v90, 1.0
	v_mul_f32_e32 v94, 0xbfb8aa3b, v96
	v_mul_f32_e32 v95, 0xbfb8aa3b, v97
	v_exp_f32_e32 v94, v94
	v_exp_f32_e32 v95, v95
	v_pk_mul_f32 v[90:91], v[90:91], s[20:21] op_sel_hi:[1,0]
	v_pk_add_f32 v[94:95], v[94:95], 1.0 op_sel_hi:[1,0]
	s_nop 0
	v_rcp_f32_e32 v97, v95
	v_cvt_pk_bf16_f32 v90, v90, v91
	v_fma_f32 v102, -v95, v97, 1.0
	v_fmac_f32_e32 v97, v102, v97
	v_fma_f32 v104, -v95, v97, 1.0
	v_fma_f32 v103, v104, v97, v97
	v_fma_f32 v96, -v95, v103, 1.0
	v_fma_f32 v96, v96, v97, v103
	v_div_fixup_f32 v95, v96, v95, 1.0
	v_rcp_f32_e32 v97, v94
	s_nop 0
	v_fma_f32 v102, -v94, v97, 1.0
	v_fmac_f32_e32 v97, v102, v97
	v_fma_f32 v104, -v94, v97, 1.0
	v_fma_f32 v103, v104, v97, v97
	v_fma_f32 v96, -v94, v103, 1.0
	v_fma_f32 v96, v96, v97, v103
	v_div_fixup_f32 v94, v96, v94, 1.0
	v_mul_f32_e32 v96, 0xbfb8aa3b, v100
	v_mul_f32_e32 v97, 0xbfb8aa3b, v101
	v_exp_f32_e32 v96, v96
	v_exp_f32_e32 v97, v97
	v_pk_mul_f32 v[94:95], v[94:95], s[20:21] op_sel_hi:[1,0]
	v_pk_add_f32 v[96:97], v[96:97], 1.0 op_sel_hi:[1,0]
	s_nop 0
	v_rcp_f32_e32 v101, v97
	v_cvt_pk_bf16_f32 v91, v94, v95
	v_fma_f32 v102, -v97, v101, 1.0
	v_fmac_f32_e32 v101, v102, v101
	v_fma_f32 v104, -v97, v101, 1.0
	v_fma_f32 v103, v104, v101, v101
	v_fma_f32 v100, -v97, v103, 1.0
	v_fma_f32 v100, v100, v101, v103
	v_div_fixup_f32 v97, v100, v97, 1.0
	v_rcp_f32_e32 v101, v96
	s_nop 0
	v_fma_f32 v102, -v96, v101, 1.0
	v_fmac_f32_e32 v101, v102, v101
	v_fma_f32 v104, -v96, v101, 1.0
	v_fma_f32 v103, v104, v101, v101
	v_fma_f32 v100, -v96, v103, 1.0
	v_fma_f32 v100, v100, v101, v103
	v_div_fixup_f32 v96, v100, v96, 1.0
	v_rcp_f32_e32 v101, v93
	v_pk_mul_f32 v[96:97], v[96:97], s[20:21] op_sel_hi:[1,0]
	v_fma_f32 v102, -v93, v101, 1.0
	v_fmac_f32_e32 v101, v102, v101
	v_fma_f32 v104, -v93, v101, 1.0
	v_fma_f32 v103, v104, v101, v101
	v_fma_f32 v100, -v93, v103, 1.0
	v_fma_f32 v100, v100, v101, v103
	v_div_fixup_f32 v93, v100, v93, 1.0
	v_rcp_f32_e32 v101, v92
	s_nop 0
	v_fma_f32 v102, -v92, v101, 1.0
	v_fmac_f32_e32 v101, v102, v101
	v_fma_f32 v104, -v92, v101, 1.0
	v_fma_f32 v103, v104, v101, v101
	v_fma_f32 v100, -v92, v103, 1.0
	v_fma_f32 v100, v100, v101, v103
	v_div_fixup_f32 v92, v100, v92, 1.0
	v_pk_mul_f32 v[100:101], v[92:93], s[20:21] op_sel_hi:[1,0]
	v_lshl_add_u64 v[92:93], v[122:123], 0, v[98:99]
	v_lshl_add_u64 v[102:103], v[92:93], 0, v[0:1]
	v_cvt_pk_bf16_f32 v92, v96, v97
	v_cvt_pk_bf16_f32 v93, v100, v101
	global_store_dwordx4 v[102:103], v[90:93], off
	global_load_dwordx4 v[90:93], v[142:143], off offset:528
	global_load_dwordx4 v[94:97], v[142:143], off offset:512
	s_waitcnt vmcnt(0)
	v_pk_add_f32 v[90:91], v[82:83], v[90:91]
	v_pk_add_f32 v[86:87], v[86:87], v[94:95]
	v_pk_add_f32 v[84:85], v[84:85], v[92:93]
	v_mul_f32_e32 v82, 0xbfb8aa3b, v86
	v_mul_f32_e32 v83, 0xbfb8aa3b, v87
	v_exp_f32_e32 v82, v82
	v_exp_f32_e32 v83, v83
	v_pk_add_f32 v[88:89], v[88:89], v[96:97]
	v_mul_f32_e32 v84, 0xbfb8aa3b, v84
	v_mul_f32_e32 v85, 0xbfb8aa3b, v85
	v_pk_add_f32 v[82:83], v[82:83], 1.0 op_sel_hi:[1,0]
	v_exp_f32_e32 v84, v84
	v_rcp_f32_e32 v87, v83
	v_exp_f32_e32 v85, v85
	v_fma_f32 v92, -v83, v87, 1.0
	v_fmac_f32_e32 v87, v92, v87
	v_fma_f32 v94, -v83, v87, 1.0
	v_fma_f32 v93, v94, v87, v87
	v_fma_f32 v86, -v83, v93, 1.0
	v_fma_f32 v86, v86, v87, v93
	v_div_fixup_f32 v83, v86, v83, 1.0
	v_rcp_f32_e32 v87, v82
	v_pk_add_f32 v[84:85], v[84:85], 1.0 op_sel_hi:[1,0]
	v_fma_f32 v92, -v82, v87, 1.0
	v_fmac_f32_e32 v87, v92, v87
	v_fma_f32 v94, -v82, v87, 1.0
	v_fma_f32 v93, v94, v87, v87
	v_fma_f32 v86, -v82, v93, 1.0
	v_fma_f32 v86, v86, v87, v93
	v_div_fixup_f32 v82, v86, v82, 1.0
	v_mul_f32_e32 v86, 0xbfb8aa3b, v88
	v_mul_f32_e32 v87, 0xbfb8aa3b, v89
	v_exp_f32_e32 v86, v86
	v_exp_f32_e32 v87, v87
	v_pk_mul_f32 v[82:83], v[82:83], s[20:21] op_sel_hi:[1,0]
	v_pk_add_f32 v[86:87], v[86:87], 1.0 op_sel_hi:[1,0]
	s_nop 0
	v_rcp_f32_e32 v89, v87
	v_cvt_pk_bf16_f32 v82, v82, v83
	v_fma_f32 v92, -v87, v89, 1.0
	v_fmac_f32_e32 v89, v92, v89
	v_fma_f32 v94, -v87, v89, 1.0
	v_fma_f32 v93, v94, v89, v89
	v_fma_f32 v88, -v87, v93, 1.0
	v_fma_f32 v88, v88, v89, v93
	v_div_fixup_f32 v87, v88, v87, 1.0
	v_rcp_f32_e32 v89, v86
	s_nop 0
	v_fma_f32 v92, -v86, v89, 1.0
	v_fmac_f32_e32 v89, v92, v89
	v_fma_f32 v94, -v86, v89, 1.0
	v_fma_f32 v93, v94, v89, v89
	v_fma_f32 v88, -v86, v93, 1.0
	v_fma_f32 v88, v88, v89, v93
	v_div_fixup_f32 v86, v88, v86, 1.0
	v_mul_f32_e32 v88, 0xbfb8aa3b, v90
	v_mul_f32_e32 v89, 0xbfb8aa3b, v91
	v_exp_f32_e32 v88, v88
	v_exp_f32_e32 v89, v89
	v_pk_mul_f32 v[86:87], v[86:87], s[20:21] op_sel_hi:[1,0]
	v_pk_add_f32 v[88:89], v[88:89], 1.0 op_sel_hi:[1,0]
; __device__ __forceinline__ u32x4 pack8(f32x4 v0, f32x4 v1) { u32x4 o; o.x = pkbf(v0.x, v0.y); o.y = pkbf(v0.z, v0.w); o.z = pkbf(v1.x, v1.y); o.w = pkbf(v1.z, v1.w); return o; }
;     __device__ __forceinline__ float f(float x) const { return -0.6065306597126334f * sigmoidf_(x); }
;     __device__ __forceinline__ void operator()(int row, int col, f32x4 v0, f32x4 v1) const { *(u32x4*)(G + (size_t)row * 1024 + col) = pack8(v0, v1); }
;     __device__ __forceinline__ void operator()(int row, int col, f32x4 v0, f32x4 v1) const {
;         const f32x4 b0 = *(const f32x4*)(w0 + col), b1 = *(const f32x4*)(w0 + col + 4);
;         v0 += b0; v1 += b1;
;         v0 = (f32x4){f(v0.x), f(v0.y), f(v0.z), f(v0.w)}; v1 = (f32x4){f(v1.x), f(v1.y), f(v1.z), f(v1.w)};
;         bf16_t* dst = (col < 1024 ? D0 : D1) + (size_t)row * 1024 + (col & 1023);
;         *(u32x4*)dst = pack8(v0, v1);
	s_nop 0
	v_rcp_f32_e32 v91, v89
	v_cvt_pk_bf16_f32 v83, v86, v87
	v_fma_f32 v92, -v89, v91, 1.0
	v_fmac_f32_e32 v91, v92, v91
	v_fma_f32 v94, -v89, v91, 1.0
	v_fma_f32 v93, v94, v91, v91
	v_fma_f32 v90, -v89, v93, 1.0
	v_fma_f32 v90, v90, v91, v93
	v_div_fixup_f32 v89, v90, v89, 1.0
	v_rcp_f32_e32 v91, v88
	s_nop 0
	v_fma_f32 v92, -v88, v91, 1.0
	v_fmac_f32_e32 v91, v92, v91
	v_fma_f32 v94, -v88, v91, 1.0
	v_fma_f32 v93, v94, v91, v91
	v_fma_f32 v90, -v88, v93, 1.0
	v_fma_f32 v90, v90, v91, v93
	v_div_fixup_f32 v88, v90, v88, 1.0
	v_rcp_f32_e32 v91, v85
	v_pk_mul_f32 v[88:89], v[88:89], s[20:21] op_sel_hi:[1,0]
	v_fma_f32 v92, -v85, v91, 1.0
	v_fmac_f32_e32 v91, v92, v91
	v_fma_f32 v94, -v85, v91, 1.0
	v_fma_f32 v93, v94, v91, v91
	v_fma_f32 v90, -v85, v93, 1.0
	v_fma_f32 v90, v90, v91, v93
	v_div_fixup_f32 v85, v90, v85, 1.0
	v_rcp_f32_e32 v91, v84
	s_nop 0
	v_fma_f32 v92, -v84, v91, 1.0
	v_fmac_f32_e32 v91, v92, v91
	v_fma_f32 v94, -v84, v91, 1.0
	v_fma_f32 v93, v94, v91, v91
	v_fma_f32 v90, -v84, v93, 1.0
	v_fma_f32 v90, v90, v91, v93
	v_div_fixup_f32 v84, v90, v84, 1.0
	v_pk_mul_f32 v[90:91], v[84:85], s[20:21] op_sel_hi:[1,0]
	v_lshl_add_u64 v[84:85], v[114:115], 0, v[98:99]
	v_lshl_add_u64 v[92:93], v[84:85], 0, v[116:117]
	v_cvt_pk_bf16_f32 v84, v88, v89
	v_cvt_pk_bf16_f32 v85, v90, v91
	global_store_dwordx4 v[92:93], v[82:85], off
	global_load_dwordx4 v[84:87], v[142:143], off offset:16
	global_load_dwordx4 v[88:91], v[142:143], off
	v_or_b32_e32 v82, 48, v146
	v_ashrrev_i32_e32 v83, 31, v82
	v_lshlrev_b64 v[82:83], 11, v[82:83]
	s_waitcnt vmcnt(0)
	v_pk_add_f32 v[84:85], v[74:75], v[84:85]
	v_pk_add_f32 v[78:79], v[78:79], v[88:89]
	v_pk_add_f32 v[76:77], v[76:77], v[86:87]
	v_mul_f32_e32 v74, 0xbfb8aa3b, v78
	v_mul_f32_e32 v75, 0xbfb8aa3b, v79
	v_exp_f32_e32 v74, v74
	v_exp_f32_e32 v75, v75
	v_pk_add_f32 v[80:81], v[80:81], v[90:91]
	v_mul_f32_e32 v76, 0xbfb8aa3b, v76
	v_mul_f32_e32 v77, 0xbfb8aa3b, v77
	v_pk_add_f32 v[74:75], v[74:75], 1.0 op_sel_hi:[1,0]
	v_exp_f32_e32 v76, v76
	v_rcp_f32_e32 v79, v75
	v_exp_f32_e32 v77, v77
	v_fma_f32 v86, -v75, v79, 1.0
	v_fmac_f32_e32 v79, v86, v79
	v_fma_f32 v88, -v75, v79, 1.0
	v_fma_f32 v87, v88, v79, v79
	v_fma_f32 v78, -v75, v87, 1.0
	v_fma_f32 v78, v78, v79, v87
	v_div_fixup_f32 v75, v78, v75, 1.0
	v_rcp_f32_e32 v79, v74
	v_pk_add_f32 v[76:77], v[76:77], 1.0 op_sel_hi:[1,0]
	v_fma_f32 v86, -v74, v79, 1.0
	v_fmac_f32_e32 v79, v86, v79
	v_fma_f32 v88, -v74, v79, 1.0
	v_fma_f32 v87, v88, v79, v79
	v_fma_f32 v78, -v74, v87, 1.0
	v_fma_f32 v78, v78, v79, v87
	v_div_fixup_f32 v74, v78, v74, 1.0
	v_mul_f32_e32 v78, 0xbfb8aa3b, v80
	v_mul_f32_e32 v79, 0xbfb8aa3b, v81
	v_exp_f32_e32 v78, v78
	v_exp_f32_e32 v79, v79
	v_pk_mul_f32 v[74:75], v[74:75], s[20:21] op_sel_hi:[1,0]
	v_pk_add_f32 v[78:79], v[78:79], 1.0 op_sel_hi:[1,0]
	s_nop 0
	v_rcp_f32_e32 v81, v79
	v_cvt_pk_bf16_f32 v74, v74, v75
	v_fma_f32 v86, -v79, v81, 1.0
	v_fmac_f32_e32 v81, v86, v81
	v_fma_f32 v88, -v79, v81, 1.0
	v_fma_f32 v87, v88, v81, v81
	v_fma_f32 v80, -v79, v87, 1.0
	v_fma_f32 v80, v80, v81, v87
	v_div_fixup_f32 v79, v80, v79, 1.0
	v_rcp_f32_e32 v81, v78
	s_nop 0
	v_fma_f32 v86, -v78, v81, 1.0
	v_fmac_f32_e32 v81, v86, v81
	v_fma_f32 v88, -v78, v81, 1.0
	v_fma_f32 v87, v88, v81, v81
	v_fma_f32 v80, -v78, v87, 1.0
	v_fma_f32 v80, v80, v81, v87
	v_div_fixup_f32 v78, v80, v78, 1.0
	v_mul_f32_e32 v80, 0xbfb8aa3b, v84
	v_mul_f32_e32 v81, 0xbfb8aa3b, v85
	v_exp_f32_e32 v80, v80
	v_exp_f32_e32 v81, v81
	v_pk_mul_f32 v[78:79], v[78:79], s[20:21] op_sel_hi:[1,0]
	v_pk_add_f32 v[80:81], v[80:81], 1.0 op_sel_hi:[1,0]
	s_nop 0
	v_rcp_f32_e32 v85, v81
	v_cvt_pk_bf16_f32 v75, v78, v79
	v_fma_f32 v86, -v81, v85, 1.0
	v_fmac_f32_e32 v85, v86, v85
	v_fma_f32 v88, -v81, v85, 1.0
	v_fma_f32 v87, v88, v85, v85
	v_fma_f32 v84, -v81, v87, 1.0
	v_fma_f32 v84, v84, v85, v87
	v_div_fixup_f32 v81, v84, v81, 1.0
	v_rcp_f32_e32 v85, v80
	s_nop 0
	v_fma_f32 v86, -v80, v85, 1.0
	v_fmac_f32_e32 v85, v86, v85
	v_fma_f32 v88, -v80, v85, 1.0
	v_fma_f32 v87, v88, v85, v85
	v_fma_f32 v84, -v80, v87, 1.0
	v_fma_f32 v84, v84, v85, v87
	v_div_fixup_f32 v80, v84, v80, 1.0
	v_rcp_f32_e32 v85, v77
	v_pk_mul_f32 v[80:81], v[80:81], s[20:21] op_sel_hi:[1,0]
	v_fma_f32 v86, -v77, v85, 1.0
	v_fmac_f32_e32 v85, v86, v85
	v_fma_f32 v88, -v77, v85, 1.0
	v_fma_f32 v87, v88, v85, v85
	v_fma_f32 v84, -v77, v87, 1.0
	v_fma_f32 v84, v84, v85, v87
	v_div_fixup_f32 v77, v84, v77, 1.0
	v_rcp_f32_e32 v85, v76
	s_nop 0
	v_fma_f32 v86, -v76, v85, 1.0
	v_fmac_f32_e32 v85, v86, v85
	v_fma_f32 v88, -v76, v85, 1.0
	v_fma_f32 v87, v88, v85, v85
	v_fma_f32 v84, -v76, v87, 1.0
	v_fma_f32 v84, v84, v85, v87
	v_div_fixup_f32 v76, v84, v76, 1.0
	v_pk_mul_f32 v[84:85], v[76:77], s[20:21] op_sel_hi:[1,0]
	v_lshl_add_u64 v[76:77], v[122:123], 0, v[82:83]
	v_lshl_add_u64 v[86:87], v[76:77], 0, v[0:1]
	v_cvt_pk_bf16_f32 v76, v80, v81
	v_cvt_pk_bf16_f32 v77, v84, v85
	global_store_dwordx4 v[86:87], v[74:77], off
	global_load_dwordx4 v[74:77], v[142:143], off offset:528
	global_load_dwordx4 v[78:81], v[142:143], off offset:512
	s_waitcnt vmcnt(0)
; __device__ __forceinline__ u32x4 pack8(f32x4 v0, f32x4 v1) { u32x4 o; o.x = pkbf(v0.x, v0.y); o.y = pkbf(v0.z, v0.w); o.z = pkbf(v1.x, v1.y); o.w = pkbf(v1.z, v1.w); return o; }
;     __device__ __forceinline__ float f(float x) const { return -0.6065306597126334f * sigmoidf_(x); }
;     __device__ __forceinline__ void operator()(int row, int col, f32x4 v0, f32x4 v1) const { *(u32x4*)(G + (size_t)row * 1024 + col) = pack8(v0, v1); }
;     __device__ __forceinline__ void operator()(int row, int col, f32x4 v0, f32x4 v1) const {
;         const f32x4 b0 = *(const f32x4*)(w0 + col), b1 = *(const f32x4*)(w0 + col + 4);
;         v0 += b0; v1 += b1;
;         v0 = (f32x4){f(v0.x), f(v0.y), f(v0.z), f(v0.w)}; v1 = (f32x4){f(v1.x), f(v1.y), f(v1.z), f(v1.w)};
;         bf16_t* dst = (col < 1024 ? D0 : D1) + (size_t)row * 1024 + (col & 1023);
;         *(u32x4*)dst = pack8(v0, v1);
	v_pk_add_f32 v[74:75], v[66:67], v[74:75]
	v_pk_add_f32 v[70:71], v[70:71], v[78:79]
	v_pk_add_f32 v[68:69], v[68:69], v[76:77]
	v_mul_f32_e32 v66, 0xbfb8aa3b, v70
	v_mul_f32_e32 v67, 0xbfb8aa3b, v71
	v_exp_f32_e32 v66, v66
	v_exp_f32_e32 v67, v67
	v_pk_add_f32 v[72:73], v[72:73], v[80:81]
	v_mul_f32_e32 v68, 0xbfb8aa3b, v68
	v_mul_f32_e32 v69, 0xbfb8aa3b, v69
	v_pk_add_f32 v[66:67], v[66:67], 1.0 op_sel_hi:[1,0]
	v_exp_f32_e32 v68, v68
	v_rcp_f32_e32 v71, v67
	v_exp_f32_e32 v69, v69
	v_fma_f32 v76, -v67, v71, 1.0
	v_fmac_f32_e32 v71, v76, v71
	v_fma_f32 v78, -v67, v71, 1.0
	v_fma_f32 v77, v78, v71, v71
	v_fma_f32 v70, -v67, v77, 1.0
	v_fma_f32 v70, v70, v71, v77
	v_div_fixup_f32 v67, v70, v67, 1.0
	v_rcp_f32_e32 v71, v66
	v_pk_add_f32 v[68:69], v[68:69], 1.0 op_sel_hi:[1,0]
	v_fma_f32 v76, -v66, v71, 1.0
	v_fmac_f32_e32 v71, v76, v71
	v_fma_f32 v78, -v66, v71, 1.0
	v_fma_f32 v77, v78, v71, v71
	v_fma_f32 v70, -v66, v77, 1.0
	v_fma_f32 v70, v70, v71, v77
	v_div_fixup_f32 v66, v70, v66, 1.0
	v_mul_f32_e32 v70, 0xbfb8aa3b, v72
	v_mul_f32_e32 v71, 0xbfb8aa3b, v73
	v_exp_f32_e32 v70, v70
	v_exp_f32_e32 v71, v71
	v_pk_mul_f32 v[66:67], v[66:67], s[20:21] op_sel_hi:[1,0]
	v_pk_add_f32 v[70:71], v[70:71], 1.0 op_sel_hi:[1,0]
	s_nop 0
	v_rcp_f32_e32 v73, v71
	v_cvt_pk_bf16_f32 v66, v66, v67
	v_fma_f32 v76, -v71, v73, 1.0
	v_fmac_f32_e32 v73, v76, v73
	v_fma_f32 v78, -v71, v73, 1.0
	v_fma_f32 v77, v78, v73, v73
	v_fma_f32 v72, -v71, v77, 1.0
	v_fma_f32 v72, v72, v73, v77
	v_div_fixup_f32 v71, v72, v71, 1.0
	v_rcp_f32_e32 v73, v70
	s_nop 0
	v_fma_f32 v76, -v70, v73, 1.0
	v_fmac_f32_e32 v73, v76, v73
	v_fma_f32 v78, -v70, v73, 1.0
	v_fma_f32 v77, v78, v73, v73
	v_fma_f32 v72, -v70, v77, 1.0
	v_fma_f32 v72, v72, v73, v77
	v_div_fixup_f32 v70, v72, v70, 1.0
	v_mul_f32_e32 v72, 0xbfb8aa3b, v74
	v_mul_f32_e32 v73, 0xbfb8aa3b, v75
	v_exp_f32_e32 v72, v72
	v_exp_f32_e32 v73, v73
	v_pk_mul_f32 v[70:71], v[70:71], s[20:21] op_sel_hi:[1,0]
	v_pk_add_f32 v[72:73], v[72:73], 1.0 op_sel_hi:[1,0]
	s_nop 0
	v_rcp_f32_e32 v75, v73
	v_cvt_pk_bf16_f32 v67, v70, v71
	v_fma_f32 v76, -v73, v75, 1.0
	v_fmac_f32_e32 v75, v76, v75
	v_fma_f32 v78, -v73, v75, 1.0
	v_fma_f32 v77, v78, v75, v75
	v_fma_f32 v74, -v73, v77, 1.0
	v_fma_f32 v74, v74, v75, v77
	v_div_fixup_f32 v73, v74, v73, 1.0
	v_rcp_f32_e32 v75, v72
	s_nop 0
	v_fma_f32 v76, -v72, v75, 1.0
	v_fmac_f32_e32 v75, v76, v75
	v_fma_f32 v78, -v72, v75, 1.0
	v_fma_f32 v77, v78, v75, v75
	v_fma_f32 v74, -v72, v77, 1.0
	v_fma_f32 v74, v74, v75, v77
	v_div_fixup_f32 v72, v74, v72, 1.0
	v_rcp_f32_e32 v75, v69
	v_pk_mul_f32 v[72:73], v[72:73], s[20:21] op_sel_hi:[1,0]
	v_fma_f32 v76, -v69, v75, 1.0
	v_fmac_f32_e32 v75, v76, v75
	v_fma_f32 v78, -v69, v75, 1.0
	v_fma_f32 v77, v78, v75, v75
	v_fma_f32 v74, -v69, v77, 1.0
	v_fma_f32 v74, v74, v75, v77
	v_div_fixup_f32 v69, v74, v69, 1.0
	v_rcp_f32_e32 v75, v68
	s_nop 0
	v_fma_f32 v76, -v68, v75, 1.0
	v_fmac_f32_e32 v75, v76, v75
	v_fma_f32 v78, -v68, v75, 1.0
	v_fma_f32 v77, v78, v75, v75
	v_fma_f32 v74, -v68, v77, 1.0
	v_fma_f32 v74, v74, v75, v77
	v_div_fixup_f32 v68, v74, v68, 1.0
	v_pk_mul_f32 v[74:75], v[68:69], s[20:21] op_sel_hi:[1,0]
	v_lshl_add_u64 v[68:69], v[114:115], 0, v[82:83]
	v_lshl_add_u64 v[76:77], v[68:69], 0, v[116:117]
	v_cvt_pk_bf16_f32 v68, v72, v73
	v_cvt_pk_bf16_f32 v69, v74, v75
	global_store_dwordx4 v[76:77], v[66:69], off
	global_load_dwordx4 v[68:71], v[142:143], off offset:16
	global_load_dwordx4 v[72:75], v[142:143], off
	v_lshl_add_u64 v[66:67], v[144:145], 0, s[90:91]
	s_waitcnt vmcnt(0)
	v_pk_add_f32 v[68:69], v[58:59], v[68:69]
	v_pk_add_f32 v[62:63], v[62:63], v[72:73]
	v_pk_add_f32 v[60:61], v[60:61], v[70:71]
	v_mul_f32_e32 v58, 0xbfb8aa3b, v62
	v_mul_f32_e32 v59, 0xbfb8aa3b, v63
	v_exp_f32_e32 v58, v58
	v_exp_f32_e32 v59, v59
	v_pk_add_f32 v[64:65], v[64:65], v[74:75]
	v_mul_f32_e32 v60, 0xbfb8aa3b, v60
	v_mul_f32_e32 v61, 0xbfb8aa3b, v61
	v_pk_add_f32 v[58:59], v[58:59], 1.0 op_sel_hi:[1,0]
	v_exp_f32_e32 v60, v60
	v_rcp_f32_e32 v63, v59
	v_exp_f32_e32 v61, v61
	v_fma_f32 v70, -v59, v63, 1.0
	v_fmac_f32_e32 v63, v70, v63
	v_fma_f32 v72, -v59, v63, 1.0
	v_fma_f32 v71, v72, v63, v63
	v_fma_f32 v62, -v59, v71, 1.0
	v_fma_f32 v62, v62, v63, v71
	v_div_fixup_f32 v59, v62, v59, 1.0
	v_rcp_f32_e32 v63, v58
	v_pk_add_f32 v[60:61], v[60:61], 1.0 op_sel_hi:[1,0]
	v_fma_f32 v70, -v58, v63, 1.0
	v_fmac_f32_e32 v63, v70, v63
	v_fma_f32 v72, -v58, v63, 1.0
	v_fma_f32 v71, v72, v63, v63
	v_fma_f32 v62, -v58, v71, 1.0
	v_fma_f32 v62, v62, v63, v71
	v_div_fixup_f32 v58, v62, v58, 1.0
	v_mul_f32_e32 v62, 0xbfb8aa3b, v64
	v_mul_f32_e32 v63, 0xbfb8aa3b, v65
	v_exp_f32_e32 v62, v62
	v_exp_f32_e32 v63, v63
	v_pk_mul_f32 v[58:59], v[58:59], s[20:21] op_sel_hi:[1,0]
	v_pk_add_f32 v[62:63], v[62:63], 1.0 op_sel_hi:[1,0]
	s_nop 0
	v_rcp_f32_e32 v65, v63
	v_cvt_pk_bf16_f32 v58, v58, v59
	v_fma_f32 v70, -v63, v65, 1.0
	v_fmac_f32_e32 v65, v70, v65
	v_fma_f32 v72, -v63, v65, 1.0
	v_fma_f32 v71, v72, v65, v65
	v_fma_f32 v64, -v63, v71, 1.0
	v_fma_f32 v64, v64, v65, v71
	v_div_fixup_f32 v63, v64, v63, 1.0
	v_rcp_f32_e32 v65, v62
	s_nop 0
	v_fma_f32 v70, -v62, v65, 1.0
	v_fmac_f32_e32 v65, v70, v65
	v_fma_f32 v72, -v62, v65, 1.0
	v_fma_f32 v71, v72, v65, v65
	v_fma_f32 v64, -v62, v71, 1.0
	v_fma_f32 v64, v64, v65, v71
	v_div_fixup_f32 v62, v64, v62, 1.0
	v_mul_f32_e32 v64, 0xbfb8aa3b, v68
	v_mul_f32_e32 v65, 0xbfb8aa3b, v69
	v_exp_f32_e32 v64, v64
	v_exp_f32_e32 v65, v65
	v_pk_mul_f32 v[62:63], v[62:63], s[20:21] op_sel_hi:[1,0]
	v_pk_add_f32 v[64:65], v[64:65], 1.0 op_sel_hi:[1,0]
	s_nop 0
	v_rcp_f32_e32 v69, v65
	v_cvt_pk_bf16_f32 v59, v62, v63
	v_fma_f32 v70, -v65, v69, 1.0
	v_fmac_f32_e32 v69, v70, v69
	v_fma_f32 v72, -v65, v69, 1.0
	v_fma_f32 v71, v72, v69, v69
	v_fma_f32 v68, -v65, v71, 1.0
	v_fma_f32 v68, v68, v69, v71
	v_div_fixup_f32 v65, v68, v65, 1.0
	v_rcp_f32_e32 v69, v64
	s_nop 0
	v_fma_f32 v70, -v64, v69, 1.0
	v_fmac_f32_e32 v69, v70, v69
	v_fma_f32 v72, -v64, v69, 1.0
	v_fma_f32 v71, v72, v69, v69
	v_fma_f32 v68, -v64, v71, 1.0
	v_fma_f32 v68, v68, v69, v71
	v_div_fixup_f32 v64, v68, v64, 1.0
	v_rcp_f32_e32 v69, v61
	v_pk_mul_f32 v[64:65], v[64:65], s[20:21] op_sel_hi:[1,0]
	v_fma_f32 v70, -v61, v69, 1.0
	v_fmac_f32_e32 v69, v70, v69
	v_fma_f32 v72, -v61, v69, 1.0
	v_fma_f32 v71, v72, v69, v69
	v_fma_f32 v68, -v61, v71, 1.0
	v_fma_f32 v68, v68, v69, v71
	v_div_fixup_f32 v61, v68, v61, 1.0
	v_rcp_f32_e32 v69, v60
	s_nop 0
	v_fma_f32 v70, -v60, v69, 1.0
	v_fmac_f32_e32 v69, v70, v69
	v_fma_f32 v72, -v60, v69, 1.0
	v_fma_f32 v71, v72, v69, v69
	v_fma_f32 v68, -v60, v71, 1.0
	v_fma_f32 v68, v68, v69, v71
	v_div_fixup_f32 v60, v68, v60, 1.0
	v_pk_mul_f32 v[68:69], v[60:61], s[20:21] op_sel_hi:[1,0]
	v_lshl_add_u64 v[60:61], v[122:123], 0, v[66:67]
	v_lshl_add_u64 v[70:71], v[60:61], 0, v[0:1]
	v_cvt_pk_bf16_f32 v60, v64, v65
	v_cvt_pk_bf16_f32 v61, v68, v69
	global_store_dwordx4 v[70:71], v[58:61], off
	global_load_dwordx4 v[58:61], v[142:143], off offset:528
	global_load_dwordx4 v[62:65], v[142:143], off offset:512
	s_waitcnt vmcnt(0)
; __device__ __forceinline__ u32x4 pack8(f32x4 v0, f32x4 v1) { u32x4 o; o.x = pkbf(v0.x, v0.y); o.y = pkbf(v0.z, v0.w); o.z = pkbf(v1.x, v1.y); o.w = pkbf(v1.z, v1.w); return o; }
;     __device__ __forceinline__ float f(float x) const { return -0.6065306597126334f * sigmoidf_(x); }
;     __device__ __forceinline__ void operator()(int row, int col, f32x4 v0, f32x4 v1) const { *(u32x4*)(G + (size_t)row * 1024 + col) = pack8(v0, v1); }
;     __device__ __forceinline__ void operator()(int row, int col, f32x4 v0, f32x4 v1) const {
;         const f32x4 b0 = *(const f32x4*)(w0 + col), b1 = *(const f32x4*)(w0 + col + 4);
;         v0 += b0; v1 += b1;
;         v0 = (f32x4){f(v0.x), f(v0.y), f(v0.z), f(v0.w)}; v1 = (f32x4){f(v1.x), f(v1.y), f(v1.z), f(v1.w)};
;         bf16_t* dst = (col < 1024 ? D0 : D1) + (size_t)row * 1024 + (col & 1023);
;         *(u32x4*)dst = pack8(v0, v1);
	v_pk_add_f32 v[58:59], v[50:51], v[58:59]
	v_pk_add_f32 v[54:55], v[54:55], v[62:63]
	v_pk_add_f32 v[52:53], v[52:53], v[60:61]
	v_mul_f32_e32 v50, 0xbfb8aa3b, v54
	v_mul_f32_e32 v51, 0xbfb8aa3b, v55
	v_exp_f32_e32 v50, v50
	v_exp_f32_e32 v51, v51
	v_pk_add_f32 v[56:57], v[56:57], v[64:65]
	v_mul_f32_e32 v52, 0xbfb8aa3b, v52
	v_mul_f32_e32 v53, 0xbfb8aa3b, v53
	v_pk_add_f32 v[50:51], v[50:51], 1.0 op_sel_hi:[1,0]
	v_exp_f32_e32 v52, v52
	v_rcp_f32_e32 v55, v51
	v_exp_f32_e32 v53, v53
	v_fma_f32 v60, -v51, v55, 1.0
	v_fmac_f32_e32 v55, v60, v55
	v_fma_f32 v62, -v51, v55, 1.0
	v_fma_f32 v61, v62, v55, v55
	v_fma_f32 v54, -v51, v61, 1.0
	v_fma_f32 v54, v54, v55, v61
	v_div_fixup_f32 v51, v54, v51, 1.0
	v_rcp_f32_e32 v55, v50
	v_pk_add_f32 v[52:53], v[52:53], 1.0 op_sel_hi:[1,0]
	v_fma_f32 v60, -v50, v55, 1.0
	v_fmac_f32_e32 v55, v60, v55
	v_fma_f32 v62, -v50, v55, 1.0
	v_fma_f32 v61, v62, v55, v55
	v_fma_f32 v54, -v50, v61, 1.0
	v_fma_f32 v54, v54, v55, v61
	v_div_fixup_f32 v50, v54, v50, 1.0
	v_mul_f32_e32 v54, 0xbfb8aa3b, v56
	v_mul_f32_e32 v55, 0xbfb8aa3b, v57
	v_exp_f32_e32 v54, v54
	v_exp_f32_e32 v55, v55
	v_pk_mul_f32 v[50:51], v[50:51], s[20:21] op_sel_hi:[1,0]
	v_pk_add_f32 v[54:55], v[54:55], 1.0 op_sel_hi:[1,0]
	s_nop 0
	v_rcp_f32_e32 v57, v55
	v_cvt_pk_bf16_f32 v50, v50, v51
	v_fma_f32 v60, -v55, v57, 1.0
	v_fmac_f32_e32 v57, v60, v57
	v_fma_f32 v62, -v55, v57, 1.0
	v_fma_f32 v61, v62, v57, v57
	v_fma_f32 v56, -v55, v61, 1.0
	v_fma_f32 v56, v56, v57, v61
	v_div_fixup_f32 v55, v56, v55, 1.0
	v_rcp_f32_e32 v57, v54
	s_nop 0
	v_fma_f32 v60, -v54, v57, 1.0
	v_fmac_f32_e32 v57, v60, v57
	v_fma_f32 v62, -v54, v57, 1.0
	v_fma_f32 v61, v62, v57, v57
	v_fma_f32 v56, -v54, v61, 1.0
	v_fma_f32 v56, v56, v57, v61
	v_div_fixup_f32 v54, v56, v54, 1.0
	v_mul_f32_e32 v56, 0xbfb8aa3b, v58
	v_mul_f32_e32 v57, 0xbfb8aa3b, v59
	v_exp_f32_e32 v56, v56
	v_exp_f32_e32 v57, v57
	v_pk_mul_f32 v[54:55], v[54:55], s[20:21] op_sel_hi:[1,0]
	v_pk_add_f32 v[56:57], v[56:57], 1.0 op_sel_hi:[1,0]
	s_nop 0
	v_rcp_f32_e32 v59, v57
	v_cvt_pk_bf16_f32 v51, v54, v55
	v_fma_f32 v60, -v57, v59, 1.0
	v_fmac_f32_e32 v59, v60, v59
	v_fma_f32 v62, -v57, v59, 1.0
	v_fma_f32 v61, v62, v59, v59
	v_fma_f32 v58, -v57, v61, 1.0
	v_fma_f32 v58, v58, v59, v61
	v_div_fixup_f32 v57, v58, v57, 1.0
	v_rcp_f32_e32 v59, v56
	s_nop 0
	v_fma_f32 v60, -v56, v59, 1.0
	v_fmac_f32_e32 v59, v60, v59
	v_fma_f32 v62, -v56, v59, 1.0
	v_fma_f32 v61, v62, v59, v59
	v_fma_f32 v58, -v56, v61, 1.0
	v_fma_f32 v58, v58, v59, v61
	v_div_fixup_f32 v56, v58, v56, 1.0
	v_rcp_f32_e32 v59, v53
	v_pk_mul_f32 v[56:57], v[56:57], s[20:21] op_sel_hi:[1,0]
	v_fma_f32 v60, -v53, v59, 1.0
	v_fmac_f32_e32 v59, v60, v59
	v_fma_f32 v62, -v53, v59, 1.0
	v_fma_f32 v61, v62, v59, v59
	v_fma_f32 v58, -v53, v61, 1.0
	v_fma_f32 v58, v58, v59, v61
	v_div_fixup_f32 v53, v58, v53, 1.0
	v_rcp_f32_e32 v59, v52
	s_mov_b64 s[4:5], 0x48000
	v_fma_f32 v60, -v52, v59, 1.0
	v_fmac_f32_e32 v59, v60, v59
	v_fma_f32 v62, -v52, v59, 1.0
	v_fma_f32 v61, v62, v59, v59
	v_fma_f32 v58, -v52, v61, 1.0
	v_fma_f32 v58, v58, v59, v61
	v_div_fixup_f32 v52, v58, v52, 1.0
	v_pk_mul_f32 v[58:59], v[52:53], s[20:21] op_sel_hi:[1,0]
	v_lshl_add_u64 v[52:53], v[114:115], 0, v[66:67]
	v_lshl_add_u64 v[60:61], v[52:53], 0, v[116:117]
	v_cvt_pk_bf16_f32 v52, v56, v57
	v_cvt_pk_bf16_f32 v53, v58, v59
	global_store_dwordx4 v[60:61], v[50:53], off
	global_load_dwordx4 v[52:55], v[142:143], off offset:16
	global_load_dwordx4 v[56:59], v[142:143], off
	v_lshl_add_u64 v[50:51], v[144:145], 0, s[4:5]
	s_waitcnt vmcnt(0)
	v_pk_add_f32 v[52:53], v[42:43], v[52:53]
	v_pk_add_f32 v[46:47], v[46:47], v[56:57]
	v_pk_add_f32 v[44:45], v[44:45], v[54:55]
	v_mul_f32_e32 v42, 0xbfb8aa3b, v46
	v_mul_f32_e32 v43, 0xbfb8aa3b, v47
	v_exp_f32_e32 v42, v42
	v_exp_f32_e32 v43, v43
	v_pk_add_f32 v[48:49], v[48:49], v[58:59]
	v_mul_f32_e32 v44, 0xbfb8aa3b, v44
	v_mul_f32_e32 v45, 0xbfb8aa3b, v45
	v_pk_add_f32 v[42:43], v[42:43], 1.0 op_sel_hi:[1,0]
	v_exp_f32_e32 v44, v44
	v_rcp_f32_e32 v47, v43
	v_exp_f32_e32 v45, v45
	v_fma_f32 v54, -v43, v47, 1.0
	v_fmac_f32_e32 v47, v54, v47
	v_fma_f32 v56, -v43, v47, 1.0
	v_fma_f32 v55, v56, v47, v47
	v_fma_f32 v46, -v43, v55, 1.0
	v_fma_f32 v46, v46, v47, v55
	v_div_fixup_f32 v43, v46, v43, 1.0
	v_rcp_f32_e32 v47, v42
	v_pk_add_f32 v[44:45], v[44:45], 1.0 op_sel_hi:[1,0]
	v_fma_f32 v54, -v42, v47, 1.0
	v_fmac_f32_e32 v47, v54, v47
	v_fma_f32 v56, -v42, v47, 1.0
	v_fma_f32 v55, v56, v47, v47
	v_fma_f32 v46, -v42, v55, 1.0
	v_fma_f32 v46, v46, v47, v55
	v_div_fixup_f32 v42, v46, v42, 1.0
	v_mul_f32_e32 v46, 0xbfb8aa3b, v48
	v_mul_f32_e32 v47, 0xbfb8aa3b, v49
	v_exp_f32_e32 v46, v46
	v_exp_f32_e32 v47, v47
	v_pk_mul_f32 v[42:43], v[42:43], s[20:21] op_sel_hi:[1,0]
	v_pk_add_f32 v[46:47], v[46:47], 1.0 op_sel_hi:[1,0]
	s_nop 0
	v_rcp_f32_e32 v49, v47
	v_cvt_pk_bf16_f32 v42, v42, v43
	v_fma_f32 v54, -v47, v49, 1.0
	v_fmac_f32_e32 v49, v54, v49
	v_fma_f32 v56, -v47, v49, 1.0
	v_fma_f32 v55, v56, v49, v49
	v_fma_f32 v48, -v47, v55, 1.0
	v_fma_f32 v48, v48, v49, v55
	v_div_fixup_f32 v47, v48, v47, 1.0
	v_rcp_f32_e32 v49, v46
	s_nop 0
	v_fma_f32 v54, -v46, v49, 1.0
	v_fmac_f32_e32 v49, v54, v49
	v_fma_f32 v56, -v46, v49, 1.0
	v_fma_f32 v55, v56, v49, v49
	v_fma_f32 v48, -v46, v55, 1.0
	v_fma_f32 v48, v48, v49, v55
	v_div_fixup_f32 v46, v48, v46, 1.0
	v_mul_f32_e32 v48, 0xbfb8aa3b, v52
	v_mul_f32_e32 v49, 0xbfb8aa3b, v53
	v_exp_f32_e32 v48, v48
	v_exp_f32_e32 v49, v49
	v_pk_mul_f32 v[46:47], v[46:47], s[20:21] op_sel_hi:[1,0]
	v_pk_add_f32 v[48:49], v[48:49], 1.0 op_sel_hi:[1,0]
	s_nop 0
	v_rcp_f32_e32 v53, v49
	v_cvt_pk_bf16_f32 v43, v46, v47
; __device__ __forceinline__ u32x4 pack8(f32x4 v0, f32x4 v1) { u32x4 o; o.x = pkbf(v0.x, v0.y); o.y = pkbf(v0.z, v0.w); o.z = pkbf(v1.x, v1.y); o.w = pkbf(v1.z, v1.w); return o; }
;     __device__ __forceinline__ float f(float x) const { return -0.6065306597126334f * sigmoidf_(x); }
;     __device__ __forceinline__ void operator()(int row, int col, f32x4 v0, f32x4 v1) const { *(u32x4*)(G + (size_t)row * 1024 + col) = pack8(v0, v1); }
;     __device__ __forceinline__ void operator()(const pg8::f32x4 (&acc)[2][2][4][2], const pg8::Unit& u, int wr, int wc, int fr, int fq) const {
;     ...
;         for (int ai = 0; ai < 2; ++ai)
; #pragma unroll
;             for (int m = 0; m < 4; ++m)
; #pragma unroll
;                 for (int bj = 0; bj < 2; ++bj) { op(row0 + ai * 128 + m * 16, col0 + bj * 128, acc[ai][bj][m][0], acc[ai][bj][m][1]); asm volatile("" ::: "memory"); }
;     __device__ __forceinline__ void operator()(int row, int col, f32x4 v0, f32x4 v1) const {
;         const f32x4 b0 = *(const f32x4*)(w0 + col), b1 = *(const f32x4*)(w0 + col + 4);
;         v0 += b0; v1 += b1;
;         v0 = (f32x4){f(v0.x), f(v0.y), f(v0.z), f(v0.w)}; v1 = (f32x4){f(v1.x), f(v1.y), f(v1.z), f(v1.w)};
;         bf16_t* dst = (col < 1024 ? D0 : D1) + (size_t)row * 1024 + (col & 1023);
;         *(u32x4*)dst = pack8(v0, v1);
	v_fma_f32 v54, -v49, v53, 1.0
	v_fmac_f32_e32 v53, v54, v53
	v_fma_f32 v56, -v49, v53, 1.0
	v_fma_f32 v55, v56, v53, v53
	v_fma_f32 v52, -v49, v55, 1.0
	v_fma_f32 v52, v52, v53, v55
	v_div_fixup_f32 v49, v52, v49, 1.0
	v_rcp_f32_e32 v53, v48
	s_nop 0
	v_fma_f32 v54, -v48, v53, 1.0
	v_fmac_f32_e32 v53, v54, v53
	v_fma_f32 v56, -v48, v53, 1.0
	v_fma_f32 v55, v56, v53, v53
	v_fma_f32 v52, -v48, v55, 1.0
	v_fma_f32 v52, v52, v53, v55
	v_div_fixup_f32 v48, v52, v48, 1.0
	v_rcp_f32_e32 v53, v45
	v_pk_mul_f32 v[48:49], v[48:49], s[20:21] op_sel_hi:[1,0]
	v_fma_f32 v54, -v45, v53, 1.0
	v_fmac_f32_e32 v53, v54, v53
	v_fma_f32 v56, -v45, v53, 1.0
	v_fma_f32 v55, v56, v53, v53
	v_fma_f32 v52, -v45, v55, 1.0
	v_fma_f32 v52, v52, v53, v55
	v_div_fixup_f32 v45, v52, v45, 1.0
	v_rcp_f32_e32 v53, v44
	s_nop 0
	v_fma_f32 v54, -v44, v53, 1.0
	v_fmac_f32_e32 v53, v54, v53
	v_fma_f32 v56, -v44, v53, 1.0
	v_fma_f32 v55, v56, v53, v53
	v_fma_f32 v52, -v44, v55, 1.0
	v_fma_f32 v52, v52, v53, v55
	v_div_fixup_f32 v44, v52, v44, 1.0
	v_pk_mul_f32 v[52:53], v[44:45], s[20:21] op_sel_hi:[1,0]
	v_lshl_add_u64 v[44:45], v[122:123], 0, v[50:51]
	v_lshl_add_u64 v[54:55], v[44:45], 0, v[0:1]
	v_cvt_pk_bf16_f32 v44, v48, v49
	v_cvt_pk_bf16_f32 v45, v52, v53
	global_store_dwordx4 v[54:55], v[42:45], off
	global_load_dwordx4 v[42:45], v[142:143], off offset:528
	global_load_dwordx4 v[46:49], v[142:143], off offset:512
	s_waitcnt vmcnt(0)
	v_pk_add_f32 v[42:43], v[34:35], v[42:43]
	v_pk_add_f32 v[38:39], v[38:39], v[46:47]
	v_pk_add_f32 v[36:37], v[36:37], v[44:45]
	v_mul_f32_e32 v34, 0xbfb8aa3b, v38
	v_mul_f32_e32 v35, 0xbfb8aa3b, v39
	v_exp_f32_e32 v34, v34
	v_exp_f32_e32 v35, v35
	v_pk_add_f32 v[40:41], v[40:41], v[48:49]
	v_mul_f32_e32 v36, 0xbfb8aa3b, v36
	v_mul_f32_e32 v37, 0xbfb8aa3b, v37
	v_pk_add_f32 v[34:35], v[34:35], 1.0 op_sel_hi:[1,0]
	v_exp_f32_e32 v36, v36
	v_rcp_f32_e32 v39, v35
	v_exp_f32_e32 v37, v37
	v_fma_f32 v44, -v35, v39, 1.0
	v_fmac_f32_e32 v39, v44, v39
	v_fma_f32 v46, -v35, v39, 1.0
	v_fma_f32 v45, v46, v39, v39
	v_fma_f32 v38, -v35, v45, 1.0
	v_fma_f32 v38, v38, v39, v45
	v_div_fixup_f32 v35, v38, v35, 1.0
	v_rcp_f32_e32 v39, v34
	v_pk_add_f32 v[36:37], v[36:37], 1.0 op_sel_hi:[1,0]
	v_fma_f32 v44, -v34, v39, 1.0
	v_fmac_f32_e32 v39, v44, v39
	v_fma_f32 v46, -v34, v39, 1.0
	v_fma_f32 v45, v46, v39, v39
	v_fma_f32 v38, -v34, v45, 1.0
	v_fma_f32 v38, v38, v39, v45
	v_div_fixup_f32 v34, v38, v34, 1.0
	v_mul_f32_e32 v38, 0xbfb8aa3b, v40
	v_mul_f32_e32 v39, 0xbfb8aa3b, v41
	v_exp_f32_e32 v38, v38
	v_exp_f32_e32 v39, v39
	v_pk_mul_f32 v[34:35], v[34:35], s[20:21] op_sel_hi:[1,0]
	v_pk_add_f32 v[38:39], v[38:39], 1.0 op_sel_hi:[1,0]
	s_nop 0
	v_rcp_f32_e32 v41, v39
	v_cvt_pk_bf16_f32 v34, v34, v35
	v_fma_f32 v44, -v39, v41, 1.0
	v_fmac_f32_e32 v41, v44, v41
	v_fma_f32 v46, -v39, v41, 1.0
	v_fma_f32 v45, v46, v41, v41
	v_fma_f32 v40, -v39, v45, 1.0
	v_fma_f32 v40, v40, v41, v45
	v_div_fixup_f32 v39, v40, v39, 1.0
	v_rcp_f32_e32 v41, v38
	s_nop 0
	v_fma_f32 v44, -v38, v41, 1.0
	v_fmac_f32_e32 v41, v44, v41
	v_fma_f32 v46, -v38, v41, 1.0
	v_fma_f32 v45, v46, v41, v41
	v_fma_f32 v40, -v38, v45, 1.0
	v_fma_f32 v40, v40, v41, v45
	v_div_fixup_f32 v38, v40, v38, 1.0
	v_mul_f32_e32 v40, 0xbfb8aa3b, v42
	v_mul_f32_e32 v41, 0xbfb8aa3b, v43
	v_exp_f32_e32 v40, v40
	v_exp_f32_e32 v41, v41
	v_pk_mul_f32 v[38:39], v[38:39], s[20:21] op_sel_hi:[1,0]
	v_pk_add_f32 v[40:41], v[40:41], 1.0 op_sel_hi:[1,0]
	s_nop 0
	v_rcp_f32_e32 v43, v41
	v_cvt_pk_bf16_f32 v35, v38, v39
	v_fma_f32 v44, -v41, v43, 1.0
	v_fmac_f32_e32 v43, v44, v43
	v_fma_f32 v46, -v41, v43, 1.0
	v_fma_f32 v45, v46, v43, v43
	v_fma_f32 v42, -v41, v45, 1.0
	v_fma_f32 v42, v42, v43, v45
	v_div_fixup_f32 v41, v42, v41, 1.0
	v_rcp_f32_e32 v43, v40
	s_nop 0
	v_fma_f32 v44, -v40, v43, 1.0
	v_fmac_f32_e32 v43, v44, v43
	v_fma_f32 v46, -v40, v43, 1.0
	v_fma_f32 v45, v46, v43, v43
	v_fma_f32 v42, -v40, v45, 1.0
	v_fma_f32 v42, v42, v43, v45
	v_div_fixup_f32 v40, v42, v40, 1.0
	v_rcp_f32_e32 v43, v37
	v_pk_mul_f32 v[40:41], v[40:41], s[20:21] op_sel_hi:[1,0]
	v_fma_f32 v44, -v37, v43, 1.0
	v_fmac_f32_e32 v43, v44, v43
	v_fma_f32 v46, -v37, v43, 1.0
	v_fma_f32 v45, v46, v43, v43
	v_fma_f32 v42, -v37, v45, 1.0
	v_fma_f32 v42, v42, v43, v45
	v_div_fixup_f32 v37, v42, v37, 1.0
	v_rcp_f32_e32 v43, v36
	s_mov_b64 s[4:5], 0x50000
	v_fma_f32 v44, -v36, v43, 1.0
	v_fmac_f32_e32 v43, v44, v43
	v_fma_f32 v46, -v36, v43, 1.0
	v_fma_f32 v45, v46, v43, v43
	v_fma_f32 v42, -v36, v45, 1.0
	v_fma_f32 v42, v42, v43, v45
	v_div_fixup_f32 v36, v42, v36, 1.0
	v_pk_mul_f32 v[42:43], v[36:37], s[20:21] op_sel_hi:[1,0]
	v_lshl_add_u64 v[36:37], v[114:115], 0, v[50:51]
	v_lshl_add_u64 v[44:45], v[36:37], 0, v[116:117]
	v_cvt_pk_bf16_f32 v36, v40, v41
	v_cvt_pk_bf16_f32 v37, v42, v43
	global_store_dwordx4 v[44:45], v[34:37], off
	global_load_dwordx4 v[36:39], v[142:143], off offset:16
	global_load_dwordx4 v[40:43], v[142:143], off
	v_lshl_add_u64 v[34:35], v[144:145], 0, s[4:5]
	s_waitcnt vmcnt(0)
; __device__ __forceinline__ u32x4 pack8(f32x4 v0, f32x4 v1) { u32x4 o; o.x = pkbf(v0.x, v0.y); o.y = pkbf(v0.z, v0.w); o.z = pkbf(v1.x, v1.y); o.w = pkbf(v1.z, v1.w); return o; }
;     __device__ __forceinline__ float f(float x) const { return -0.6065306597126334f * sigmoidf_(x); }
;     __device__ __forceinline__ void operator()(int row, int col, f32x4 v0, f32x4 v1) const { *(u32x4*)(G + (size_t)row * 1024 + col) = pack8(v0, v1); }
;     __device__ __forceinline__ void operator()(const pg8::f32x4 (&acc)[2][2][4][2], const pg8::Unit& u, int wr, int wc, int fr, int fq) const {
;     ...
;         for (int ai = 0; ai < 2; ++ai)
; #pragma unroll
;             for (int m = 0; m < 4; ++m)
; #pragma unroll
;                 for (int bj = 0; bj < 2; ++bj) { op(row0 + ai * 128 + m * 16, col0 + bj * 128, acc[ai][bj][m][0], acc[ai][bj][m][1]); asm volatile("" ::: "memory"); }
;     __device__ __forceinline__ void operator()(int row, int col, f32x4 v0, f32x4 v1) const {
;         const f32x4 b0 = *(const f32x4*)(w0 + col), b1 = *(const f32x4*)(w0 + col + 4);
;         v0 += b0; v1 += b1;
;         v0 = (f32x4){f(v0.x), f(v0.y), f(v0.z), f(v0.w)}; v1 = (f32x4){f(v1.x), f(v1.y), f(v1.z), f(v1.w)};
;         bf16_t* dst = (col < 1024 ? D0 : D1) + (size_t)row * 1024 + (col & 1023);
;         *(u32x4*)dst = pack8(v0, v1);
	v_pk_add_f32 v[36:37], v[26:27], v[36:37]
	v_pk_add_f32 v[30:31], v[30:31], v[40:41]
	v_pk_add_f32 v[28:29], v[28:29], v[38:39]
	v_mul_f32_e32 v26, 0xbfb8aa3b, v30
	v_mul_f32_e32 v27, 0xbfb8aa3b, v31
	v_exp_f32_e32 v26, v26
	v_exp_f32_e32 v27, v27
	v_pk_add_f32 v[32:33], v[32:33], v[42:43]
	v_mul_f32_e32 v28, 0xbfb8aa3b, v28
	v_mul_f32_e32 v29, 0xbfb8aa3b, v29
	v_pk_add_f32 v[26:27], v[26:27], 1.0 op_sel_hi:[1,0]
	v_exp_f32_e32 v28, v28
	v_rcp_f32_e32 v31, v27
	v_exp_f32_e32 v29, v29
	v_fma_f32 v38, -v27, v31, 1.0
	v_fmac_f32_e32 v31, v38, v31
	v_fma_f32 v40, -v27, v31, 1.0
	v_fma_f32 v39, v40, v31, v31
	v_fma_f32 v30, -v27, v39, 1.0
	v_fma_f32 v30, v30, v31, v39
	v_div_fixup_f32 v27, v30, v27, 1.0
	v_rcp_f32_e32 v31, v26
	v_pk_add_f32 v[28:29], v[28:29], 1.0 op_sel_hi:[1,0]
	v_fma_f32 v38, -v26, v31, 1.0
	v_fmac_f32_e32 v31, v38, v31
	v_fma_f32 v40, -v26, v31, 1.0
	v_fma_f32 v39, v40, v31, v31
	v_fma_f32 v30, -v26, v39, 1.0
	v_fma_f32 v30, v30, v31, v39
	v_div_fixup_f32 v26, v30, v26, 1.0
	v_mul_f32_e32 v30, 0xbfb8aa3b, v32
	v_mul_f32_e32 v31, 0xbfb8aa3b, v33
	v_exp_f32_e32 v30, v30
	v_exp_f32_e32 v31, v31
	v_pk_mul_f32 v[26:27], v[26:27], s[20:21] op_sel_hi:[1,0]
	v_pk_add_f32 v[30:31], v[30:31], 1.0 op_sel_hi:[1,0]
	s_nop 0
	v_rcp_f32_e32 v33, v31
	v_cvt_pk_bf16_f32 v26, v26, v27
	v_fma_f32 v38, -v31, v33, 1.0
	v_fmac_f32_e32 v33, v38, v33
	v_fma_f32 v40, -v31, v33, 1.0
	v_fma_f32 v39, v40, v33, v33
	v_fma_f32 v32, -v31, v39, 1.0
	v_fma_f32 v32, v32, v33, v39
	v_div_fixup_f32 v31, v32, v31, 1.0
	v_rcp_f32_e32 v33, v30
	s_nop 0
	v_fma_f32 v38, -v30, v33, 1.0
	v_fmac_f32_e32 v33, v38, v33
	v_fma_f32 v40, -v30, v33, 1.0
	v_fma_f32 v39, v40, v33, v33
	v_fma_f32 v32, -v30, v39, 1.0
	v_fma_f32 v32, v32, v33, v39
	v_div_fixup_f32 v30, v32, v30, 1.0
	v_mul_f32_e32 v32, 0xbfb8aa3b, v36
	v_mul_f32_e32 v33, 0xbfb8aa3b, v37
	v_exp_f32_e32 v32, v32
	v_exp_f32_e32 v33, v33
	v_pk_mul_f32 v[30:31], v[30:31], s[20:21] op_sel_hi:[1,0]
	v_pk_add_f32 v[32:33], v[32:33], 1.0 op_sel_hi:[1,0]
	s_nop 0
	v_rcp_f32_e32 v37, v33
	v_cvt_pk_bf16_f32 v27, v30, v31
	v_fma_f32 v38, -v33, v37, 1.0
	v_fmac_f32_e32 v37, v38, v37
	v_fma_f32 v40, -v33, v37, 1.0
	v_fma_f32 v39, v40, v37, v37
	v_fma_f32 v36, -v33, v39, 1.0
	v_fma_f32 v36, v36, v37, v39
	v_div_fixup_f32 v33, v36, v33, 1.0
	v_rcp_f32_e32 v37, v32
	s_nop 0
	v_fma_f32 v38, -v32, v37, 1.0
	v_fmac_f32_e32 v37, v38, v37
	v_fma_f32 v40, -v32, v37, 1.0
	v_fma_f32 v39, v40, v37, v37
	v_fma_f32 v36, -v32, v39, 1.0
	v_fma_f32 v36, v36, v37, v39
	v_div_fixup_f32 v32, v36, v32, 1.0
	v_rcp_f32_e32 v37, v29
	v_pk_mul_f32 v[32:33], v[32:33], s[20:21] op_sel_hi:[1,0]
	v_fma_f32 v38, -v29, v37, 1.0
	v_fmac_f32_e32 v37, v38, v37
	v_fma_f32 v40, -v29, v37, 1.0
	v_fma_f32 v39, v40, v37, v37
	v_fma_f32 v36, -v29, v39, 1.0
	v_fma_f32 v36, v36, v37, v39
	v_div_fixup_f32 v29, v36, v29, 1.0
	v_rcp_f32_e32 v37, v28
	s_nop 0
	v_fma_f32 v38, -v28, v37, 1.0
	v_fmac_f32_e32 v37, v38, v37
	v_fma_f32 v40, -v28, v37, 1.0
	v_fma_f32 v39, v40, v37, v37
	v_fma_f32 v36, -v28, v39, 1.0
	v_fma_f32 v36, v36, v37, v39
	v_div_fixup_f32 v28, v36, v28, 1.0
	v_pk_mul_f32 v[36:37], v[28:29], s[20:21] op_sel_hi:[1,0]
	v_lshl_add_u64 v[28:29], v[122:123], 0, v[34:35]
	v_lshl_add_u64 v[38:39], v[28:29], 0, v[0:1]
	v_cvt_pk_bf16_f32 v28, v32, v33
	v_cvt_pk_bf16_f32 v29, v36, v37
	global_store_dwordx4 v[38:39], v[26:29], off
	global_load_dwordx4 v[26:29], v[142:143], off offset:528
	global_load_dwordx4 v[30:33], v[142:143], off offset:512
	s_waitcnt vmcnt(0)
	v_pk_add_f32 v[26:27], v[18:19], v[26:27]
	v_pk_add_f32 v[22:23], v[22:23], v[30:31]
	v_pk_add_f32 v[20:21], v[20:21], v[28:29]
	v_mul_f32_e32 v18, 0xbfb8aa3b, v22
	v_mul_f32_e32 v19, 0xbfb8aa3b, v23
	v_exp_f32_e32 v18, v18
	v_exp_f32_e32 v19, v19
	v_pk_add_f32 v[24:25], v[24:25], v[32:33]
	v_mul_f32_e32 v20, 0xbfb8aa3b, v20
	v_mul_f32_e32 v21, 0xbfb8aa3b, v21
	v_pk_add_f32 v[18:19], v[18:19], 1.0 op_sel_hi:[1,0]
	v_exp_f32_e32 v20, v20
	v_rcp_f32_e32 v23, v19
	v_exp_f32_e32 v21, v21
	v_fma_f32 v28, -v19, v23, 1.0
	v_fmac_f32_e32 v23, v28, v23
	v_fma_f32 v30, -v19, v23, 1.0
	v_fma_f32 v29, v30, v23, v23
	v_fma_f32 v22, -v19, v29, 1.0
	v_fma_f32 v22, v22, v23, v29
	v_div_fixup_f32 v19, v22, v19, 1.0
	v_rcp_f32_e32 v23, v18
	v_pk_add_f32 v[20:21], v[20:21], 1.0 op_sel_hi:[1,0]
	v_fma_f32 v28, -v18, v23, 1.0
	v_fmac_f32_e32 v23, v28, v23
	v_fma_f32 v30, -v18, v23, 1.0
	v_fma_f32 v29, v30, v23, v23
	v_fma_f32 v22, -v18, v29, 1.0
	v_fma_f32 v22, v22, v23, v29
	v_div_fixup_f32 v18, v22, v18, 1.0
	v_mul_f32_e32 v22, 0xbfb8aa3b, v24
	v_mul_f32_e32 v23, 0xbfb8aa3b, v25
	v_exp_f32_e32 v22, v22
	v_exp_f32_e32 v23, v23
	v_pk_mul_f32 v[18:19], v[18:19], s[20:21] op_sel_hi:[1,0]
	v_pk_add_f32 v[22:23], v[22:23], 1.0 op_sel_hi:[1,0]
	s_nop 0
	v_rcp_f32_e32 v25, v23
	v_cvt_pk_bf16_f32 v18, v18, v19
	v_fma_f32 v28, -v23, v25, 1.0
	v_fmac_f32_e32 v25, v28, v25
	v_fma_f32 v30, -v23, v25, 1.0
	v_fma_f32 v29, v30, v25, v25
	v_fma_f32 v24, -v23, v29, 1.0
	v_fma_f32 v24, v24, v25, v29
	v_div_fixup_f32 v23, v24, v23, 1.0
	v_rcp_f32_e32 v25, v22
	s_nop 0
	v_fma_f32 v28, -v22, v25, 1.0
	v_fmac_f32_e32 v25, v28, v25
	v_fma_f32 v30, -v22, v25, 1.0
	v_fma_f32 v29, v30, v25, v25
	v_fma_f32 v24, -v22, v29, 1.0
	v_fma_f32 v24, v24, v25, v29
	v_div_fixup_f32 v22, v24, v22, 1.0
	v_mul_f32_e32 v24, 0xbfb8aa3b, v26
	v_mul_f32_e32 v25, 0xbfb8aa3b, v27
	v_exp_f32_e32 v24, v24
	v_exp_f32_e32 v25, v25
	v_pk_mul_f32 v[22:23], v[22:23], s[20:21] op_sel_hi:[1,0]
	v_pk_add_f32 v[24:25], v[24:25], 1.0 op_sel_hi:[1,0]
	s_nop 0
	v_rcp_f32_e32 v27, v25
	v_cvt_pk_bf16_f32 v19, v22, v23
	v_fma_f32 v28, -v25, v27, 1.0
	v_fmac_f32_e32 v27, v28, v27
; __device__ __forceinline__ u32x4 pack8(f32x4 v0, f32x4 v1) { u32x4 o; o.x = pkbf(v0.x, v0.y); o.y = pkbf(v0.z, v0.w); o.z = pkbf(v1.x, v1.y); o.w = pkbf(v1.z, v1.w); return o; }
;     __device__ __forceinline__ float f(float x) const { return -0.6065306597126334f * sigmoidf_(x); }
;     __device__ __forceinline__ void operator()(int row, int col, f32x4 v0, f32x4 v1) const { *(u32x4*)(G + (size_t)row * 1024 + col) = pack8(v0, v1); }
;     __device__ __forceinline__ void operator()(const pg8::f32x4 (&acc)[2][2][4][2], const pg8::Unit& u, int wr, int wc, int fr, int fq) const {
;     ...
;         for (int ai = 0; ai < 2; ++ai)
; #pragma unroll
;             for (int m = 0; m < 4; ++m)
; #pragma unroll
;                 for (int bj = 0; bj < 2; ++bj) { op(row0 + ai * 128 + m * 16, col0 + bj * 128, acc[ai][bj][m][0], acc[ai][bj][m][1]); asm volatile("" ::: "memory"); }
;     __device__ __forceinline__ void operator()(int row, int col, f32x4 v0, f32x4 v1) const {
;         const f32x4 b0 = *(const f32x4*)(w0 + col), b1 = *(const f32x4*)(w0 + col + 4);
;         v0 += b0; v1 += b1;
;         v0 = (f32x4){f(v0.x), f(v0.y), f(v0.z), f(v0.w)}; v1 = (f32x4){f(v1.x), f(v1.y), f(v1.z), f(v1.w)};
;         bf16_t* dst = (col < 1024 ? D0 : D1) + (size_t)row * 1024 + (col & 1023);
;         *(u32x4*)dst = pack8(v0, v1);
	v_fma_f32 v30, -v25, v27, 1.0
	v_fma_f32 v29, v30, v27, v27
	v_fma_f32 v26, -v25, v29, 1.0
	v_fma_f32 v26, v26, v27, v29
	v_div_fixup_f32 v25, v26, v25, 1.0
	v_rcp_f32_e32 v27, v24
	s_nop 0
	v_fma_f32 v28, -v24, v27, 1.0
	v_fmac_f32_e32 v27, v28, v27
	v_fma_f32 v30, -v24, v27, 1.0
	v_fma_f32 v29, v30, v27, v27
	v_fma_f32 v26, -v24, v29, 1.0
	v_fma_f32 v26, v26, v27, v29
	v_div_fixup_f32 v24, v26, v24, 1.0
	v_rcp_f32_e32 v27, v21
	v_pk_mul_f32 v[24:25], v[24:25], s[20:21] op_sel_hi:[1,0]
	v_fma_f32 v28, -v21, v27, 1.0
	v_fmac_f32_e32 v27, v28, v27
	v_fma_f32 v30, -v21, v27, 1.0
	v_fma_f32 v29, v30, v27, v27
	v_fma_f32 v26, -v21, v29, 1.0
	v_fma_f32 v26, v26, v27, v29
	v_div_fixup_f32 v21, v26, v21, 1.0
	v_rcp_f32_e32 v27, v20
	s_mov_b64 s[4:5], 0x58000
	v_fma_f32 v28, -v20, v27, 1.0
	v_fmac_f32_e32 v27, v28, v27
	v_fma_f32 v30, -v20, v27, 1.0
	v_fma_f32 v29, v30, v27, v27
	v_fma_f32 v26, -v20, v29, 1.0
	v_fma_f32 v26, v26, v27, v29
	v_div_fixup_f32 v20, v26, v20, 1.0
	v_pk_mul_f32 v[26:27], v[20:21], s[20:21] op_sel_hi:[1,0]
	v_lshl_add_u64 v[20:21], v[114:115], 0, v[34:35]
	v_lshl_add_u64 v[28:29], v[20:21], 0, v[116:117]
	v_cvt_pk_bf16_f32 v20, v24, v25
	v_cvt_pk_bf16_f32 v21, v26, v27
	global_store_dwordx4 v[28:29], v[18:21], off
	global_load_dwordx4 v[20:23], v[142:143], off offset:16
	global_load_dwordx4 v[24:27], v[142:143], off
	v_lshl_add_u64 v[18:19], v[144:145], 0, s[4:5]
	s_waitcnt vmcnt(0)
	v_pk_add_f32 v[20:21], v[10:11], v[20:21]
	v_pk_add_f32 v[14:15], v[14:15], v[24:25]
	v_pk_add_f32 v[12:13], v[12:13], v[22:23]
	v_mul_f32_e32 v10, 0xbfb8aa3b, v14
	v_mul_f32_e32 v11, 0xbfb8aa3b, v15
	v_exp_f32_e32 v10, v10
	v_exp_f32_e32 v11, v11
	v_pk_add_f32 v[16:17], v[16:17], v[26:27]
	v_mul_f32_e32 v12, 0xbfb8aa3b, v12
	v_mul_f32_e32 v13, 0xbfb8aa3b, v13
	v_pk_add_f32 v[10:11], v[10:11], 1.0 op_sel_hi:[1,0]
	v_exp_f32_e32 v12, v12
	v_rcp_f32_e32 v15, v11
	v_exp_f32_e32 v13, v13
	v_fma_f32 v22, -v11, v15, 1.0
	v_fmac_f32_e32 v15, v22, v15
	v_fma_f32 v24, -v11, v15, 1.0
	v_fma_f32 v23, v24, v15, v15
	v_fma_f32 v14, -v11, v23, 1.0
	v_fma_f32 v14, v14, v15, v23
	v_div_fixup_f32 v11, v14, v11, 1.0
	v_rcp_f32_e32 v15, v10
	v_pk_add_f32 v[12:13], v[12:13], 1.0 op_sel_hi:[1,0]
	v_fma_f32 v22, -v10, v15, 1.0
	v_fmac_f32_e32 v15, v22, v15
	v_fma_f32 v24, -v10, v15, 1.0
	v_fma_f32 v23, v24, v15, v15
	v_fma_f32 v14, -v10, v23, 1.0
	v_fma_f32 v14, v14, v15, v23
	v_div_fixup_f32 v10, v14, v10, 1.0
	v_mul_f32_e32 v14, 0xbfb8aa3b, v16
	v_mul_f32_e32 v15, 0xbfb8aa3b, v17
	v_exp_f32_e32 v14, v14
	v_exp_f32_e32 v15, v15
	v_pk_mul_f32 v[10:11], v[10:11], s[20:21] op_sel_hi:[1,0]
	v_pk_add_f32 v[14:15], v[14:15], 1.0 op_sel_hi:[1,0]
	s_nop 0
	v_rcp_f32_e32 v17, v15
	v_cvt_pk_bf16_f32 v10, v10, v11
	v_fma_f32 v22, -v15, v17, 1.0
	v_fmac_f32_e32 v17, v22, v17
	v_fma_f32 v24, -v15, v17, 1.0
	v_fma_f32 v23, v24, v17, v17
	v_fma_f32 v16, -v15, v23, 1.0
	v_fma_f32 v16, v16, v17, v23
	v_div_fixup_f32 v15, v16, v15, 1.0
	v_rcp_f32_e32 v17, v14
	s_nop 0
	v_fma_f32 v22, -v14, v17, 1.0
	v_fmac_f32_e32 v17, v22, v17
	v_fma_f32 v24, -v14, v17, 1.0
	v_fma_f32 v23, v24, v17, v17
	v_fma_f32 v16, -v14, v23, 1.0
	v_fma_f32 v16, v16, v17, v23
	v_div_fixup_f32 v14, v16, v14, 1.0
	v_mul_f32_e32 v16, 0xbfb8aa3b, v20
	v_mul_f32_e32 v17, 0xbfb8aa3b, v21
	v_exp_f32_e32 v16, v16
	v_exp_f32_e32 v17, v17
	v_pk_mul_f32 v[14:15], v[14:15], s[20:21] op_sel_hi:[1,0]
	v_pk_add_f32 v[16:17], v[16:17], 1.0 op_sel_hi:[1,0]
	s_nop 0
	v_rcp_f32_e32 v21, v17
	v_cvt_pk_bf16_f32 v11, v14, v15
	v_fma_f32 v22, -v17, v21, 1.0
	v_fmac_f32_e32 v21, v22, v21
	v_fma_f32 v24, -v17, v21, 1.0
	v_fma_f32 v23, v24, v21, v21
	v_fma_f32 v20, -v17, v23, 1.0
	v_fma_f32 v20, v20, v21, v23
	v_div_fixup_f32 v17, v20, v17, 1.0
	v_rcp_f32_e32 v21, v16
	s_nop 0
	v_fma_f32 v22, -v16, v21, 1.0
	v_fmac_f32_e32 v21, v22, v21
	v_fma_f32 v24, -v16, v21, 1.0
	v_fma_f32 v23, v24, v21, v21
	v_fma_f32 v20, -v16, v23, 1.0
	v_fma_f32 v20, v20, v21, v23
	v_div_fixup_f32 v16, v20, v16, 1.0
	v_rcp_f32_e32 v21, v13
	v_pk_mul_f32 v[16:17], v[16:17], s[20:21] op_sel_hi:[1,0]
	v_fma_f32 v22, -v13, v21, 1.0
	v_fmac_f32_e32 v21, v22, v21
	v_fma_f32 v24, -v13, v21, 1.0
	v_fma_f32 v23, v24, v21, v21
	v_fma_f32 v20, -v13, v23, 1.0
	v_fma_f32 v20, v20, v21, v23
	v_div_fixup_f32 v13, v20, v13, 1.0
	v_rcp_f32_e32 v21, v12
	s_nop 0
	v_fma_f32 v22, -v12, v21, 1.0
	v_fmac_f32_e32 v21, v22, v21
	v_fma_f32 v24, -v12, v21, 1.0
	v_fma_f32 v23, v24, v21, v21
	v_fma_f32 v20, -v12, v23, 1.0
	v_fma_f32 v20, v20, v21, v23
	v_div_fixup_f32 v12, v20, v12, 1.0
	v_pk_mul_f32 v[20:21], v[12:13], s[20:21] op_sel_hi:[1,0]
	v_lshl_add_u64 v[12:13], v[122:123], 0, v[18:19]
	v_lshl_add_u64 v[22:23], v[12:13], 0, v[0:1]
	v_cvt_pk_bf16_f32 v12, v16, v17
	v_cvt_pk_bf16_f32 v13, v20, v21
	global_store_dwordx4 v[22:23], v[10:13], off
	global_load_dwordx4 v[10:13], v[142:143], off offset:528
	global_load_dwordx4 v[14:17], v[142:143], off offset:512
	s_waitcnt vmcnt(0)
; #define PG8_BAR __builtin_amdgcn_s_barrier()
; __device__ __forceinline__ u32x4 pack8(f32x4 v0, f32x4 v1) { u32x4 o; o.x = pkbf(v0.x, v0.y); o.y = pkbf(v0.z, v0.w); o.z = pkbf(v1.x, v1.y); o.w = pkbf(v1.z, v1.w); return o; }
;     __device__ __forceinline__ float f(float x) const { return -0.6065306597126334f * sigmoidf_(x); }
;     __device__ __forceinline__ void operator()(int row, int col, f32x4 v0, f32x4 v1) const { *(u32x4*)(G + (size_t)row * 1024 + col) = pack8(v0, v1); }
; template <class Epi, class Sched, bool ALIGN_EPI = false, bool SP2 = false>
; __device__ __forceinline__ void gemm_phase(PG8_LAS unsigned char* lds, const Gemm g, const Sched& S, const Epi& E, const int tid_in) {
;     ...
;         if constexpr (!Epi::AFTER_DRAIN) { E(acc, cur, wr, wc, fr, fq); S.done(cur); }
;         if (!has_next) break;
; #pragma unroll
;         for (int a = 0; a < 2; ++a)
; #pragma unroll
;             for (int b = 0; b < 2; ++b)
; #pragma unroll
;                 for (int m = 0; m < 4; ++m)
; #pragma unroll
;                     for (int n = 0; n < 2; ++n) acc[a][b][m][n] = (f32x4){0.f, 0.f, 0.f, 0.f};
;         cur = nxt; cA = nA; cB = nB; ++ui;
;         if constexpr (ALIGN_EPI) { if (wr == 1) PG8_BAR; }
;     __device__ __forceinline__ void operator()(int row, int col, f32x4 v0, f32x4 v1) const {
;         const f32x4 b0 = *(const f32x4*)(w0 + col), b1 = *(const f32x4*)(w0 + col + 4);
;         v0 += b0; v1 += b1;
;         v0 = (f32x4){f(v0.x), f(v0.y), f(v0.z), f(v0.w)}; v1 = (f32x4){f(v1.x), f(v1.y), f(v1.z), f(v1.w)};
;         bf16_t* dst = (col < 1024 ? D0 : D1) + (size_t)row * 1024 + (col & 1023);
;         *(u32x4*)dst = pack8(v0, v1);
	v_pk_add_f32 v[10:11], v[2:3], v[10:11]
	v_pk_add_f32 v[6:7], v[6:7], v[14:15]
	v_pk_add_f32 v[4:5], v[4:5], v[12:13]
	v_mul_f32_e32 v0, 0xbfb8aa3b, v6
	v_exp_f32_e32 v2, v0
	v_mul_f32_e32 v0, 0xbfb8aa3b, v7
	v_exp_f32_e32 v3, v0
	v_pk_add_f32 v[8:9], v[8:9], v[16:17]
	v_pk_add_f32 v[2:3], v[2:3], 1.0 op_sel_hi:[1,0]
	s_nop 0
	v_rcp_f32_e32 v6, v3
	s_nop 0
	v_fma_f32 v7, -v3, v6, 1.0
	v_fmac_f32_e32 v6, v7, v6
	v_fma_f32 v13, -v3, v6, 1.0
	v_fma_f32 v12, v13, v6, v6
	v_fma_f32 v0, -v3, v12, 1.0
	v_fma_f32 v0, v0, v6, v12
	v_div_fixup_f32 v3, v0, v3, 1.0
	v_rcp_f32_e32 v6, v2
	s_nop 0
	v_fma_f32 v7, -v2, v6, 1.0
	v_fmac_f32_e32 v6, v7, v6
	v_fma_f32 v13, -v2, v6, 1.0
	v_fma_f32 v12, v13, v6, v6
	v_fma_f32 v0, -v2, v12, 1.0
	v_fma_f32 v0, v0, v6, v12
	v_div_fixup_f32 v2, v0, v2, 1.0
	v_mul_f32_e32 v0, 0xbfb8aa3b, v8
	v_exp_f32_e32 v6, v0
	v_mul_f32_e32 v0, 0xbfb8aa3b, v9
	v_exp_f32_e32 v7, v0
	v_pk_mul_f32 v[2:3], v[2:3], s[20:21] op_sel_hi:[1,0]
	v_pk_add_f32 v[6:7], v[6:7], 1.0 op_sel_hi:[1,0]
	s_nop 0
	v_rcp_f32_e32 v8, v7
	v_cvt_pk_bf16_f32 v2, v2, v3
	v_fma_f32 v9, -v7, v8, 1.0
	v_fmac_f32_e32 v8, v9, v8
	v_fma_f32 v13, -v7, v8, 1.0
	v_fma_f32 v12, v13, v8, v8
	v_fma_f32 v0, -v7, v12, 1.0
	v_fma_f32 v0, v0, v8, v12
	v_div_fixup_f32 v7, v0, v7, 1.0
	v_rcp_f32_e32 v8, v6
	s_nop 0
	v_fma_f32 v9, -v6, v8, 1.0
	v_fmac_f32_e32 v8, v9, v8
	v_fma_f32 v13, -v6, v8, 1.0
	v_fma_f32 v12, v13, v8, v8
	v_fma_f32 v0, -v6, v12, 1.0
	v_fma_f32 v0, v0, v8, v12
	v_div_fixup_f32 v6, v0, v6, 1.0
	v_mul_f32_e32 v0, 0xbfb8aa3b, v10
	v_exp_f32_e32 v8, v0
	v_mul_f32_e32 v0, 0xbfb8aa3b, v11
	v_exp_f32_e32 v9, v0
	v_pk_mul_f32 v[6:7], v[6:7], s[20:21] op_sel_hi:[1,0]
	v_pk_add_f32 v[8:9], v[8:9], 1.0 op_sel_hi:[1,0]
	s_nop 0
	v_rcp_f32_e32 v10, v9
	v_cvt_pk_bf16_f32 v3, v6, v7
	v_fma_f32 v11, -v9, v10, 1.0
	v_fmac_f32_e32 v10, v11, v10
	v_fma_f32 v13, -v9, v10, 1.0
	v_fma_f32 v12, v13, v10, v10
	v_fma_f32 v0, -v9, v12, 1.0
	v_fma_f32 v0, v0, v10, v12
	v_div_fixup_f32 v9, v0, v9, 1.0
	v_rcp_f32_e32 v10, v8
	s_nop 0
	v_fma_f32 v11, -v8, v10, 1.0
	v_fmac_f32_e32 v10, v11, v10
	v_fma_f32 v13, -v8, v10, 1.0
	v_fma_f32 v12, v13, v10, v10
	v_fma_f32 v0, -v8, v12, 1.0
	v_fma_f32 v0, v0, v10, v12
	v_div_fixup_f32 v8, v0, v8, 1.0
	v_mul_f32_e32 v0, 0xbfb8aa3b, v4
	v_exp_f32_e32 v4, v0
	v_mul_f32_e32 v0, 0xbfb8aa3b, v5
	v_exp_f32_e32 v5, v0
	v_pk_mul_f32 v[8:9], v[8:9], s[20:21] op_sel_hi:[1,0]
	v_pk_add_f32 v[4:5], v[4:5], 1.0 op_sel_hi:[1,0]
	s_nop 0
	v_rcp_f32_e32 v10, v5
	s_nop 0
	v_fma_f32 v11, -v5, v10, 1.0
	v_fmac_f32_e32 v10, v11, v10
	v_fma_f32 v13, -v5, v10, 1.0
	v_fma_f32 v12, v13, v10, v10
	v_fma_f32 v0, -v5, v12, 1.0
	v_fma_f32 v0, v0, v10, v12
	v_div_fixup_f32 v5, v0, v5, 1.0
	v_rcp_f32_e32 v10, v4
	s_mov_b64 s[4:5], -1
	v_fma_f32 v11, -v4, v10, 1.0
	v_fmac_f32_e32 v10, v11, v10
	v_fma_f32 v13, -v4, v10, 1.0
	v_fma_f32 v12, v13, v10, v10
	v_fma_f32 v0, -v4, v12, 1.0
	v_fma_f32 v0, v0, v10, v12
	v_div_fixup_f32 v4, v0, v4, 1.0
	v_pk_mul_f32 v[10:11], v[4:5], s[20:21] op_sel_hi:[1,0]
	v_lshl_add_u64 v[4:5], v[114:115], 0, v[18:19]
	v_lshl_add_u64 v[12:13], v[4:5], 0, v[116:117]
	v_cvt_pk_bf16_f32 v4, v8, v9
	v_cvt_pk_bf16_f32 v5, v10, v11
	global_store_dwordx4 v[12:13], v[2:5], off
	s_and_b64 vcc, exec, s[40:41]
	s_cbranch_vccnz .LBB0_371
	s_andn2_b64 vcc, exec, s[52:53]
	s_cbranch_vccnz .LBB0_370
	s_barrier
	s_branch .LBB0_370

; __device__ __forceinline__ u32x4 pack8(f32x4 v0, f32x4 v1) { u32x4 o; o.x = pkbf(v0.x, v0.y); o.y = pkbf(v0.z, v0.w); o.z = pkbf(v1.x, v1.y); o.w = pkbf(v1.z, v1.w); return o; }
; __device__ __forceinline__ f32x4 sig4(f32x4 v) { return (f32x4){sigmoidf_(v.x), sigmoidf_(v.y), sigmoidf_(v.z), sigmoidf_(v.w)}; }
;     __device__ __forceinline__ void operator()(int row, int col, f32x4 v0, f32x4 v1) const { *(u32x4*)(G + (size_t)row * 1024 + col) = pack8(v0, v1); }
;     __device__ __forceinline__ void operator()(const pg8::f32x4 (&acc)[2][2][4][2], const pg8::Unit& u, int wr, int wc, int fr, int fq) const {
;     ...
;         for (int ai = 0; ai < 2; ++ai)
; #pragma unroll
;             for (int m = 0; m < 4; ++m)
; #pragma unroll
;                 for (int bj = 0; bj < 2; ++bj) { op(row0 + ai * 128 + m * 16, col0 + bj * 128, acc[ai][bj][m][0], acc[ai][bj][m][1]); asm volatile("" ::: "memory"); }
;     __device__ __forceinline__ void operator()(int row, int col, f32x4 v0, f32x4 v1) const {
;         const f32x4 b0 = *(const f32x4*)(a0 + col), b1 = *(const f32x4*)(a0 + col + 4);
;         v0 = sig4(v0 + b0); v1 = sig4(v1 + b1);
;         bf16_t* dst = (col < 1024 ? A0 : A1) + (size_t)row * 1024 + (col & 1023);
;         *(u32x4*)dst = pack8(v0, v1);
.LBB0_406:
	v_lshl_or_b32 v152, s78, 8, v160
	v_ashrrev_i32_e32 v153, 31, v152
	v_lshl_add_u64 v[146:147], v[152:153], 2, s[44:45]
	global_load_dwordx4 v[130:133], v[146:147], off offset:16
	global_load_dwordx4 v[162:165], v[146:147], off
	v_lshl_add_u32 v150, s27, 8, v158
	v_ashrrev_i32_e32 v151, 31, v150
	v_lshlrev_b64 v[148:149], 11, v[150:151]
	s_waitcnt vmcnt(0)
	v_pk_add_f32 v[122:123], v[122:123], v[130:131]
	v_pk_add_f32 v[126:127], v[126:127], v[162:163]
	v_pk_add_f32 v[164:165], v[128:129], v[164:165]
	v_mul_f32_e32 v0, 0xbfb8aa3b, v126
	v_exp_f32_e32 v126, v0
	v_mul_f32_e32 v0, 0xbfb8aa3b, v127
	v_exp_f32_e32 v127, v0
	v_pk_add_f32 v[124:125], v[124:125], v[132:133]
	v_mov_b32_e32 v132, s60
	v_mov_b32_e32 v133, s18
	v_pk_add_f32 v[126:127], v[126:127], 1.0 op_sel_hi:[1,0]
	s_nop 0
	v_rcp_f32_e32 v128, v127
	s_nop 0
	v_fma_f32 v129, -v127, v128, 1.0
	v_fmac_f32_e32 v128, v129, v128
	v_fma_f32 v153, -v127, v128, 1.0
	v_fma_f32 v151, v153, v128, v128
	v_fma_f32 v0, -v127, v151, 1.0
	v_fma_f32 v0, v0, v128, v151
	v_div_fixup_f32 v128, v0, v127, 1.0
	v_rcp_f32_e32 v127, v126
	s_nop 0
	v_fma_f32 v129, -v126, v127, 1.0
	v_fmac_f32_e32 v127, v129, v127
	v_fma_f32 v153, -v126, v127, 1.0
	v_fma_f32 v151, v153, v127, v127
	v_fma_f32 v0, -v126, v151, 1.0
	v_fma_f32 v0, v0, v127, v151
	v_div_fixup_f32 v129, v0, v126, 1.0
	v_mul_f32_e32 v0, 0xbfb8aa3b, v164
	v_exp_f32_e32 v126, v0
	v_mul_f32_e32 v0, 0xbfb8aa3b, v165
	v_exp_f32_e32 v127, v0
	s_nop 0
	v_pk_add_f32 v[126:127], v[126:127], 1.0 op_sel_hi:[1,0]
	s_nop 0
	v_rcp_f32_e32 v151, v127
	s_nop 0
	v_fma_f32 v153, -v127, v151, 1.0
	v_fmac_f32_e32 v151, v153, v151
	v_fma_f32 v163, -v127, v151, 1.0
	v_fma_f32 v162, v163, v151, v151
	v_fma_f32 v0, -v127, v162, 1.0
	v_fma_f32 v0, v0, v151, v162
	v_div_fixup_f32 v151, v0, v127, 1.0
	v_rcp_f32_e32 v127, v126
	s_nop 0
	v_fma_f32 v153, -v126, v127, 1.0
	v_fmac_f32_e32 v127, v153, v127
	v_fma_f32 v163, -v126, v127, 1.0
	v_fma_f32 v162, v163, v127, v127
	v_fma_f32 v0, -v126, v162, 1.0
	v_fma_f32 v0, v0, v127, v162
	v_div_fixup_f32 v153, v0, v126, 1.0
	v_mul_f32_e32 v0, 0xbfb8aa3b, v122
	v_exp_f32_e32 v122, v0
	v_mul_f32_e32 v0, 0xbfb8aa3b, v123
	v_exp_f32_e32 v123, v0
	s_nop 0
	v_pk_add_f32 v[122:123], v[122:123], 1.0 op_sel_hi:[1,0]
	s_nop 0
	v_rcp_f32_e32 v126, v123
	s_nop 0
	v_fma_f32 v127, -v123, v126, 1.0
	v_fmac_f32_e32 v126, v127, v126
	v_fma_f32 v131, -v123, v126, 1.0
	v_fma_f32 v130, v131, v126, v126
	v_fma_f32 v0, -v123, v130, 1.0
	v_fma_f32 v0, v0, v126, v130
	v_div_fixup_f32 v162, v0, v123, 1.0
	v_rcp_f32_e32 v123, v122
	v_mov_b32_e32 v131, s39
	v_fma_f32 v126, -v122, v123, 1.0
	v_fmac_f32_e32 v123, v126, v123
	v_fma_f32 v130, -v122, v123, 1.0
	v_fma_f32 v127, v130, v123, v123
	v_fma_f32 v0, -v122, v127, 1.0
	v_fma_f32 v0, v0, v123, v127
	v_div_fixup_f32 v163, v0, v122, 1.0
	v_mul_f32_e32 v0, 0xbfb8aa3b, v124
	v_exp_f32_e32 v122, v0
	v_mul_f32_e32 v0, 0xbfb8aa3b, v125
	v_exp_f32_e32 v123, v0
	v_mov_b32_e32 v130, s61
	v_pk_add_f32 v[122:123], v[122:123], 1.0 op_sel_hi:[1,0]
	s_nop 0
	v_rcp_f32_e32 v124, v123
	s_nop 0
	v_fma_f32 v125, -v123, v124, 1.0
	v_fmac_f32_e32 v124, v125, v124
	v_fma_f32 v127, -v123, v124, 1.0
	v_fma_f32 v126, v127, v124, v124
	v_fma_f32 v0, -v123, v126, 1.0
	v_fma_f32 v0, v0, v124, v126
	v_div_fixup_f32 v125, v0, v123, 1.0
	v_div_scale_f32 v0, s[4:5], v122, v122, 1.0
	v_rcp_f32_e32 v123, v0
	s_nop 0
	v_fma_f32 v124, -v0, v123, 1.0
	v_fmac_f32_e32 v123, v124, v123
	v_div_scale_f32 v124, vcc, 1.0, v122, 1.0
	v_mul_f32_e32 v126, v124, v123
	v_fma_f32 v127, -v0, v126, v124
	v_fmac_f32_e32 v126, v127, v123
	v_fma_f32 v0, -v0, v126, v124
	v_div_fmas_f32 v0, v0, v123, v126
	v_cmp_gt_i32_e32 vcc, s66, v152
	v_div_fixup_f32 v166, v0, v122, 1.0
	v_and_b32_e32 v0, 0x378, v152
	v_cndmask_b32_e32 v127, v130, v131, vcc
	v_cndmask_b32_e32 v126, v132, v133, vcc
	v_lshl_add_u64 v[122:123], v[126:127], 0, v[148:149]
	v_lshlrev_b32_e32 v0, 1, v0
	v_lshl_add_u64 v[164:165], v[122:123], 0, v[0:1]
	v_cvt_pk_bf16_f32 v122, v129, v128
	v_cvt_pk_bf16_f32 v123, v153, v151
	v_cvt_pk_bf16_f32 v124, v163, v162
	v_cvt_pk_bf16_f32 v125, v166, v125
	global_store_dwordx4 v[164:165], v[122:125], off
	global_load_dwordx4 v[122:125], v[146:147], off offset:528
	global_load_dwordx4 v[162:165], v[146:147], off offset:512
	v_or_b32_e32 v128, 0x80, v152
	s_waitcnt vmcnt(0)
; __device__ __forceinline__ u32x4 pack8(f32x4 v0, f32x4 v1) { u32x4 o; o.x = pkbf(v0.x, v0.y); o.y = pkbf(v0.z, v0.w); o.z = pkbf(v1.x, v1.y); o.w = pkbf(v1.z, v1.w); return o; }
; __device__ __forceinline__ f32x4 sig4(f32x4 v) { return (f32x4){sigmoidf_(v.x), sigmoidf_(v.y), sigmoidf_(v.z), sigmoidf_(v.w)}; }
;     __device__ __forceinline__ void operator()(int row, int col, f32x4 v0, f32x4 v1) const { *(u32x4*)(G + (size_t)row * 1024 + col) = pack8(v0, v1); }
;     __device__ __forceinline__ void operator()(const pg8::f32x4 (&acc)[2][2][4][2], const pg8::Unit& u, int wr, int wc, int fr, int fq) const {
;     ...
;         for (int ai = 0; ai < 2; ++ai)
; #pragma unroll
;             for (int m = 0; m < 4; ++m)
; #pragma unroll
;                 for (int bj = 0; bj < 2; ++bj) { op(row0 + ai * 128 + m * 16, col0 + bj * 128, acc[ai][bj][m][0], acc[ai][bj][m][1]); asm volatile("" ::: "memory"); }
;     __device__ __forceinline__ void operator()(int row, int col, f32x4 v0, f32x4 v1) const {
;         const f32x4 b0 = *(const f32x4*)(a0 + col), b1 = *(const f32x4*)(a0 + col + 4);
;         v0 = sig4(v0 + b0); v1 = sig4(v1 + b1);
;         bf16_t* dst = (col < 1024 ? A0 : A1) + (size_t)row * 1024 + (col & 1023);
;         *(u32x4*)dst = pack8(v0, v1);
	v_pk_add_f32 v[114:115], v[114:115], v[122:123]
	v_pk_add_f32 v[118:119], v[118:119], v[162:163]
	v_pk_add_f32 v[120:121], v[120:121], v[164:165]
	v_mul_f32_e32 v118, 0xbfb8aa3b, v118
	v_mul_f32_e32 v119, 0xbfb8aa3b, v119
	v_exp_f32_e32 v118, v118
	v_exp_f32_e32 v119, v119
	v_mul_f32_e32 v114, 0xbfb8aa3b, v114
	v_mul_f32_e32 v115, 0xbfb8aa3b, v115
	v_exp_f32_e32 v114, v114
	v_pk_add_f32 v[118:119], v[118:119], 1.0 op_sel_hi:[1,0]
	v_exp_f32_e32 v115, v115
	v_rcp_f32_e32 v151, v119
	v_pk_add_f32 v[114:115], v[114:115], 1.0 op_sel_hi:[1,0]
	v_pk_add_f32 v[116:117], v[116:117], v[124:125]
	v_fma_f32 v153, -v119, v151, 1.0
	v_fmac_f32_e32 v151, v153, v151
	v_fma_f32 v163, -v119, v151, 1.0
	v_fma_f32 v162, v163, v151, v151
	v_fma_f32 v129, -v119, v162, 1.0
	v_fma_f32 v129, v129, v151, v162
	v_div_fixup_f32 v129, v129, v119, 1.0
	v_rcp_f32_e32 v151, v118
	s_nop 0
	v_fma_f32 v153, -v118, v151, 1.0
	v_fmac_f32_e32 v151, v153, v151
	v_fma_f32 v163, -v118, v151, 1.0
	v_fma_f32 v162, v163, v151, v151
	v_fma_f32 v119, -v118, v162, 1.0
	v_fma_f32 v119, v119, v151, v162
	v_div_fixup_f32 v151, v119, v118, 1.0
	v_mul_f32_e32 v118, 0xbfb8aa3b, v120
	v_mul_f32_e32 v119, 0xbfb8aa3b, v121
	v_exp_f32_e32 v118, v118
	v_exp_f32_e32 v119, v119
	s_nop 0
	v_pk_add_f32 v[118:119], v[118:119], 1.0 op_sel_hi:[1,0]
	s_nop 0
	v_rcp_f32_e32 v121, v119
	s_nop 0
	v_fma_f32 v153, -v119, v121, 1.0
	v_fmac_f32_e32 v121, v153, v121
	v_fma_f32 v163, -v119, v121, 1.0
	v_fma_f32 v162, v163, v121, v121
	v_fma_f32 v120, -v119, v162, 1.0
	v_fma_f32 v120, v120, v121, v162
	v_div_fixup_f32 v153, v120, v119, 1.0
	v_rcp_f32_e32 v120, v118
	s_nop 0
	v_fma_f32 v121, -v118, v120, 1.0
	v_fmac_f32_e32 v120, v121, v120
	v_fma_f32 v163, -v118, v120, 1.0
	v_fma_f32 v162, v163, v120, v120
	v_fma_f32 v119, -v118, v162, 1.0
	v_fma_f32 v119, v119, v120, v162
	v_div_fixup_f32 v162, v119, v118, 1.0
	v_rcp_f32_e32 v119, v115
	s_nop 0
	v_fma_f32 v120, -v115, v119, 1.0
	v_fmac_f32_e32 v119, v120, v119
	v_fma_f32 v122, -v115, v119, 1.0
	v_fma_f32 v121, v122, v119, v119
	v_fma_f32 v118, -v115, v121, 1.0
	v_fma_f32 v118, v118, v119, v121
	v_div_fixup_f32 v124, v118, v115, 1.0
	v_rcp_f32_e32 v118, v114
	s_nop 0
	v_fma_f32 v119, -v114, v118, 1.0
	v_fmac_f32_e32 v118, v119, v118
	v_fma_f32 v121, -v114, v118, 1.0
	v_fma_f32 v120, v121, v118, v118
	v_fma_f32 v115, -v114, v120, 1.0
	v_fma_f32 v115, v115, v118, v120
	v_div_fixup_f32 v125, v115, v114, 1.0
	v_mul_f32_e32 v114, 0xbfb8aa3b, v116
	v_mul_f32_e32 v115, 0xbfb8aa3b, v117
	v_exp_f32_e32 v114, v114
	v_exp_f32_e32 v115, v115
	v_mov_b32_e32 v121, v1
	v_pk_add_f32 v[114:115], v[114:115], 1.0 op_sel_hi:[1,0]
	s_nop 0
	v_rcp_f32_e32 v117, v115
	s_nop 0
	v_fma_f32 v118, -v115, v117, 1.0
	v_fmac_f32_e32 v117, v118, v117
	v_fma_f32 v120, -v115, v117, 1.0
	v_fma_f32 v119, v120, v117, v117
	v_fma_f32 v116, -v115, v119, 1.0
	v_fma_f32 v116, v116, v117, v119
	v_div_fixup_f32 v117, v116, v115, 1.0
	v_div_scale_f32 v115, s[4:5], v114, v114, 1.0
	v_rcp_f32_e32 v116, v115
	s_nop 0
	v_fma_f32 v118, -v115, v116, 1.0
	v_fmac_f32_e32 v116, v118, v116
	v_div_scale_f32 v118, vcc, 1.0, v114, 1.0
	v_mul_f32_e32 v119, v118, v116
	v_fma_f32 v120, -v115, v119, v118
	v_fmac_f32_e32 v119, v120, v116
	v_fma_f32 v115, -v115, v119, v118
	v_div_fmas_f32 v115, v115, v116, v119
	v_cmp_gt_i32_e32 vcc, s66, v128
	v_bitop3_b32 v116, v152, s86, v192 bitop3:0xc8
	v_div_fixup_f32 v163, v115, v114, 1.0
	v_cndmask_b32_e32 v119, v130, v131, vcc
	v_cndmask_b32_e32 v118, v132, v133, vcc
	v_lshl_add_u64 v[114:115], v[118:119], 0, v[148:149]
	v_lshlrev_b32_e32 v120, 1, v116
	v_lshl_add_u64 v[122:123], v[114:115], 0, v[120:121]
	v_cvt_pk_bf16_f32 v114, v151, v129
	v_cvt_pk_bf16_f32 v115, v162, v153
	v_cvt_pk_bf16_f32 v116, v125, v124
	v_cvt_pk_bf16_f32 v117, v163, v117
	global_store_dwordx4 v[122:123], v[114:117], off
	s_nop 1
	v_or_b32_e32 v114, 16, v150
	v_ashrrev_i32_e32 v115, 31, v114
	v_lshlrev_b64 v[122:123], 11, v[114:115]
	global_load_dwordx4 v[114:117], v[146:147], off offset:16
	global_load_dwordx4 v[128:131], v[146:147], off
	s_waitcnt vmcnt(0)
	v_pk_add_f32 v[106:107], v[106:107], v[114:115]
	v_pk_add_f32 v[110:111], v[110:111], v[128:129]
	v_pk_add_f32 v[112:113], v[112:113], v[130:131]
	v_mul_f32_e32 v110, 0xbfb8aa3b, v110
	v_mul_f32_e32 v111, 0xbfb8aa3b, v111
	v_exp_f32_e32 v110, v110
	v_exp_f32_e32 v111, v111
	v_mul_f32_e32 v106, 0xbfb8aa3b, v106
	v_mul_f32_e32 v107, 0xbfb8aa3b, v107
	v_exp_f32_e32 v106, v106
	v_pk_add_f32 v[110:111], v[110:111], 1.0 op_sel_hi:[1,0]
	v_exp_f32_e32 v107, v107
	v_rcp_f32_e32 v125, v111
	v_pk_add_f32 v[106:107], v[106:107], 1.0 op_sel_hi:[1,0]
	v_pk_add_f32 v[108:109], v[108:109], v[116:117]
	v_fma_f32 v128, -v111, v125, 1.0
	v_fmac_f32_e32 v125, v128, v125
	v_fma_f32 v130, -v111, v125, 1.0
	v_fma_f32 v129, v130, v125, v125
	v_fma_f32 v124, -v111, v129, 1.0
	v_fma_f32 v124, v124, v125, v129
	v_div_fixup_f32 v124, v124, v111, 1.0
	v_rcp_f32_e32 v125, v110
	s_nop 0
	v_fma_f32 v128, -v110, v125, 1.0
	v_fmac_f32_e32 v125, v128, v125
	v_fma_f32 v130, -v110, v125, 1.0
	v_fma_f32 v129, v130, v125, v125
	v_fma_f32 v111, -v110, v129, 1.0
	v_fma_f32 v111, v111, v125, v129
	v_div_fixup_f32 v125, v111, v110, 1.0
	v_mul_f32_e32 v110, 0xbfb8aa3b, v112
	v_mul_f32_e32 v111, 0xbfb8aa3b, v113
	v_exp_f32_e32 v110, v110
	v_exp_f32_e32 v111, v111
	s_nop 0
	v_pk_add_f32 v[110:111], v[110:111], 1.0 op_sel_hi:[1,0]
	s_nop 0
	v_rcp_f32_e32 v113, v111
	s_nop 0
	v_fma_f32 v128, -v111, v113, 1.0
	v_fmac_f32_e32 v113, v128, v113
	v_fma_f32 v130, -v111, v113, 1.0
	v_fma_f32 v129, v130, v113, v113
	v_fma_f32 v112, -v111, v129, 1.0
	v_fma_f32 v112, v112, v113, v129
; __device__ __forceinline__ u32x4 pack8(f32x4 v0, f32x4 v1) { u32x4 o; o.x = pkbf(v0.x, v0.y); o.y = pkbf(v0.z, v0.w); o.z = pkbf(v1.x, v1.y); o.w = pkbf(v1.z, v1.w); return o; }
; __device__ __forceinline__ f32x4 sig4(f32x4 v) { return (f32x4){sigmoidf_(v.x), sigmoidf_(v.y), sigmoidf_(v.z), sigmoidf_(v.w)}; }
;     __device__ __forceinline__ void operator()(int row, int col, f32x4 v0, f32x4 v1) const { *(u32x4*)(G + (size_t)row * 1024 + col) = pack8(v0, v1); }
;     __device__ __forceinline__ void operator()(const pg8::f32x4 (&acc)[2][2][4][2], const pg8::Unit& u, int wr, int wc, int fr, int fq) const {
;     ...
;         for (int ai = 0; ai < 2; ++ai)
; #pragma unroll
;             for (int m = 0; m < 4; ++m)
; #pragma unroll
;                 for (int bj = 0; bj < 2; ++bj) { op(row0 + ai * 128 + m * 16, col0 + bj * 128, acc[ai][bj][m][0], acc[ai][bj][m][1]); asm volatile("" ::: "memory"); }
;     __device__ __forceinline__ void operator()(int row, int col, f32x4 v0, f32x4 v1) const {
;         const f32x4 b0 = *(const f32x4*)(a0 + col), b1 = *(const f32x4*)(a0 + col + 4);
;         v0 = sig4(v0 + b0); v1 = sig4(v1 + b1);
;         bf16_t* dst = (col < 1024 ? A0 : A1) + (size_t)row * 1024 + (col & 1023);
;         *(u32x4*)dst = pack8(v0, v1);
	v_div_fixup_f32 v112, v112, v111, 1.0
	v_rcp_f32_e32 v113, v110
	s_nop 0
	v_fma_f32 v128, -v110, v113, 1.0
	v_fmac_f32_e32 v113, v128, v113
	v_fma_f32 v130, -v110, v113, 1.0
	v_fma_f32 v129, v130, v113, v113
	v_fma_f32 v111, -v110, v129, 1.0
	v_fma_f32 v111, v111, v113, v129
	v_div_fixup_f32 v113, v111, v110, 1.0
	v_rcp_f32_e32 v111, v107
	s_nop 0
	v_fma_f32 v114, -v107, v111, 1.0
	v_fmac_f32_e32 v111, v114, v111
	v_fma_f32 v116, -v107, v111, 1.0
	v_fma_f32 v115, v116, v111, v111
	v_fma_f32 v110, -v107, v115, 1.0
	v_fma_f32 v110, v110, v111, v115
	v_div_fixup_f32 v114, v110, v107, 1.0
	v_rcp_f32_e32 v110, v106
	s_nop 0
	v_fma_f32 v111, -v106, v110, 1.0
	v_fmac_f32_e32 v110, v111, v110
	v_fma_f32 v116, -v106, v110, 1.0
	v_fma_f32 v115, v116, v110, v110
	v_fma_f32 v107, -v106, v115, 1.0
	v_fma_f32 v107, v107, v110, v115
	v_div_fixup_f32 v115, v107, v106, 1.0
	v_mul_f32_e32 v106, 0xbfb8aa3b, v108
	v_mul_f32_e32 v107, 0xbfb8aa3b, v109
	v_exp_f32_e32 v106, v106
	v_exp_f32_e32 v107, v107
	s_nop 0
	v_pk_add_f32 v[106:107], v[106:107], 1.0 op_sel_hi:[1,0]
	s_nop 0
	v_rcp_f32_e32 v109, v107
	s_nop 0
	v_fma_f32 v110, -v107, v109, 1.0
	v_fmac_f32_e32 v109, v110, v109
	v_fma_f32 v116, -v107, v109, 1.0
	v_fma_f32 v111, v116, v109, v109
	v_fma_f32 v108, -v107, v111, 1.0
	v_fma_f32 v108, v108, v109, v111
	v_div_fixup_f32 v109, v108, v107, 1.0
	v_rcp_f32_e32 v108, v106
	s_nop 0
	v_fma_f32 v110, -v106, v108, 1.0
	v_fmac_f32_e32 v108, v110, v108
	v_fma_f32 v116, -v106, v108, 1.0
	v_fma_f32 v111, v116, v108, v108
	v_fma_f32 v107, -v106, v111, 1.0
	v_fma_f32 v107, v107, v108, v111
	v_div_fixup_f32 v116, v107, v106, 1.0
	v_lshl_add_u64 v[106:107], v[126:127], 0, v[122:123]
	v_lshl_add_u64 v[110:111], v[106:107], 0, v[0:1]
	v_cvt_pk_bf16_f32 v106, v125, v124
	v_cvt_pk_bf16_f32 v107, v113, v112
	v_cvt_pk_bf16_f32 v108, v115, v114
	v_cvt_pk_bf16_f32 v109, v116, v109
	global_store_dwordx4 v[110:111], v[106:109], off
	global_load_dwordx4 v[106:109], v[146:147], off offset:528
	global_load_dwordx4 v[110:113], v[146:147], off offset:512
	s_waitcnt vmcnt(0)
	v_pk_add_f32 v[98:99], v[98:99], v[106:107]
	v_pk_add_f32 v[102:103], v[102:103], v[110:111]
	v_pk_add_f32 v[104:105], v[104:105], v[112:113]
	v_mul_f32_e32 v102, 0xbfb8aa3b, v102
	v_mul_f32_e32 v103, 0xbfb8aa3b, v103
	v_exp_f32_e32 v102, v102
	v_exp_f32_e32 v103, v103
	v_mul_f32_e32 v98, 0xbfb8aa3b, v98
	v_mul_f32_e32 v99, 0xbfb8aa3b, v99
	v_exp_f32_e32 v98, v98
	v_pk_add_f32 v[102:103], v[102:103], 1.0 op_sel_hi:[1,0]
	v_exp_f32_e32 v99, v99
	v_rcp_f32_e32 v111, v103
	v_pk_add_f32 v[98:99], v[98:99], 1.0 op_sel_hi:[1,0]
	v_pk_add_f32 v[100:101], v[100:101], v[108:109]
	v_fma_f32 v112, -v103, v111, 1.0
	v_fmac_f32_e32 v111, v112, v111
	v_fma_f32 v114, -v103, v111, 1.0
	v_fma_f32 v113, v114, v111, v111
	v_fma_f32 v110, -v103, v113, 1.0
	v_fma_f32 v110, v110, v111, v113
	v_div_fixup_f32 v110, v110, v103, 1.0
	v_rcp_f32_e32 v111, v102
	s_nop 0
	v_fma_f32 v112, -v102, v111, 1.0
	v_fmac_f32_e32 v111, v112, v111
	v_fma_f32 v114, -v102, v111, 1.0
	v_fma_f32 v113, v114, v111, v111
	v_fma_f32 v103, -v102, v113, 1.0
	v_fma_f32 v103, v103, v111, v113
	v_div_fixup_f32 v111, v103, v102, 1.0
	v_mul_f32_e32 v102, 0xbfb8aa3b, v104
	v_mul_f32_e32 v103, 0xbfb8aa3b, v105
	v_exp_f32_e32 v102, v102
	v_exp_f32_e32 v103, v103
	s_nop 0
	v_pk_add_f32 v[102:103], v[102:103], 1.0 op_sel_hi:[1,0]
	s_nop 0
	v_rcp_f32_e32 v105, v103
	s_nop 0
	v_fma_f32 v112, -v103, v105, 1.0
	v_fmac_f32_e32 v105, v112, v105
	v_fma_f32 v114, -v103, v105, 1.0
	v_fma_f32 v113, v114, v105, v105
	v_fma_f32 v104, -v103, v113, 1.0
	v_fma_f32 v104, v104, v105, v113
	v_div_fixup_f32 v104, v104, v103, 1.0
	v_rcp_f32_e32 v105, v102
	s_nop 0
	v_fma_f32 v112, -v102, v105, 1.0
	v_fmac_f32_e32 v105, v112, v105
	v_fma_f32 v114, -v102, v105, 1.0
	v_fma_f32 v113, v114, v105, v105
	v_fma_f32 v103, -v102, v113, 1.0
	v_fma_f32 v103, v103, v105, v113
	v_div_fixup_f32 v105, v103, v102, 1.0
	v_rcp_f32_e32 v103, v99
	s_nop 0
	v_fma_f32 v106, -v99, v103, 1.0
	v_fmac_f32_e32 v103, v106, v103
	v_fma_f32 v108, -v99, v103, 1.0
	v_fma_f32 v107, v108, v103, v103
	v_fma_f32 v102, -v99, v107, 1.0
	v_fma_f32 v102, v102, v103, v107
	v_div_fixup_f32 v106, v102, v99, 1.0
	v_rcp_f32_e32 v102, v98
	s_nop 0
	v_fma_f32 v103, -v98, v102, 1.0
	v_fmac_f32_e32 v102, v103, v102
	v_fma_f32 v108, -v98, v102, 1.0
	v_fma_f32 v107, v108, v102, v102
	v_fma_f32 v99, -v98, v107, 1.0
	v_fma_f32 v99, v99, v102, v107
	v_div_fixup_f32 v107, v99, v98, 1.0
	v_mul_f32_e32 v98, 0xbfb8aa3b, v100
	v_mul_f32_e32 v99, 0xbfb8aa3b, v101
	v_exp_f32_e32 v98, v98
	v_exp_f32_e32 v99, v99
	s_nop 0
	v_pk_add_f32 v[98:99], v[98:99], 1.0 op_sel_hi:[1,0]
	s_nop 0
	v_rcp_f32_e32 v101, v99
	s_nop 0
	v_fma_f32 v102, -v99, v101, 1.0
	v_fmac_f32_e32 v101, v102, v101
	v_fma_f32 v108, -v99, v101, 1.0
	v_fma_f32 v103, v108, v101, v101
	v_fma_f32 v100, -v99, v103, 1.0
	v_fma_f32 v100, v100, v101, v103
	v_div_fixup_f32 v101, v100, v99, 1.0
	v_rcp_f32_e32 v100, v98
	s_nop 0
	v_fma_f32 v102, -v98, v100, 1.0
	v_fmac_f32_e32 v100, v102, v100
	v_fma_f32 v108, -v98, v100, 1.0
	v_fma_f32 v103, v108, v100, v100
	v_fma_f32 v99, -v98, v103, 1.0
	v_fma_f32 v99, v99, v100, v103
	v_div_fixup_f32 v108, v99, v98, 1.0
	v_lshl_add_u64 v[98:99], v[118:119], 0, v[122:123]
	v_lshl_add_u64 v[102:103], v[98:99], 0, v[120:121]
	v_cvt_pk_bf16_f32 v98, v111, v110
	v_cvt_pk_bf16_f32 v99, v105, v104
	v_cvt_pk_bf16_f32 v100, v107, v106
	v_cvt_pk_bf16_f32 v101, v108, v101
	global_store_dwordx4 v[102:103], v[98:101], off
	s_nop 1
	v_or_b32_e32 v98, 32, v150
	v_ashrrev_i32_e32 v99, 31, v98
	v_lshlrev_b64 v[102:103], 11, v[98:99]
	global_load_dwordx4 v[98:101], v[146:147], off offset:16
	global_load_dwordx4 v[104:107], v[146:147], off
	s_waitcnt vmcnt(0)
; __device__ __forceinline__ u32x4 pack8(f32x4 v0, f32x4 v1) { u32x4 o; o.x = pkbf(v0.x, v0.y); o.y = pkbf(v0.z, v0.w); o.z = pkbf(v1.x, v1.y); o.w = pkbf(v1.z, v1.w); return o; }
; __device__ __forceinline__ f32x4 sig4(f32x4 v) { return (f32x4){sigmoidf_(v.x), sigmoidf_(v.y), sigmoidf_(v.z), sigmoidf_(v.w)}; }
;     __device__ __forceinline__ void operator()(int row, int col, f32x4 v0, f32x4 v1) const { *(u32x4*)(G + (size_t)row * 1024 + col) = pack8(v0, v1); }
;     __device__ __forceinline__ void operator()(const pg8::f32x4 (&acc)[2][2][4][2], const pg8::Unit& u, int wr, int wc, int fr, int fq) const {
;     ...
;         for (int ai = 0; ai < 2; ++ai)
; #pragma unroll
;             for (int m = 0; m < 4; ++m)
; #pragma unroll
;                 for (int bj = 0; bj < 2; ++bj) { op(row0 + ai * 128 + m * 16, col0 + bj * 128, acc[ai][bj][m][0], acc[ai][bj][m][1]); asm volatile("" ::: "memory"); }
;     __device__ __forceinline__ void operator()(int row, int col, f32x4 v0, f32x4 v1) const {
;         const f32x4 b0 = *(const f32x4*)(a0 + col), b1 = *(const f32x4*)(a0 + col + 4);
;         v0 = sig4(v0 + b0); v1 = sig4(v1 + b1);
;         bf16_t* dst = (col < 1024 ? A0 : A1) + (size_t)row * 1024 + (col & 1023);
;         *(u32x4*)dst = pack8(v0, v1);
	v_pk_add_f32 v[90:91], v[90:91], v[98:99]
	v_pk_add_f32 v[94:95], v[94:95], v[104:105]
	v_pk_add_f32 v[96:97], v[96:97], v[106:107]
	v_mul_f32_e32 v94, 0xbfb8aa3b, v94
	v_mul_f32_e32 v95, 0xbfb8aa3b, v95
	v_exp_f32_e32 v94, v94
	v_exp_f32_e32 v95, v95
	v_mul_f32_e32 v90, 0xbfb8aa3b, v90
	v_mul_f32_e32 v91, 0xbfb8aa3b, v91
	v_exp_f32_e32 v90, v90
	v_pk_add_f32 v[94:95], v[94:95], 1.0 op_sel_hi:[1,0]
	v_exp_f32_e32 v91, v91
	v_rcp_f32_e32 v105, v95
	v_pk_add_f32 v[90:91], v[90:91], 1.0 op_sel_hi:[1,0]
	v_pk_add_f32 v[92:93], v[92:93], v[100:101]
	v_fma_f32 v106, -v95, v105, 1.0
	v_fmac_f32_e32 v105, v106, v105
	v_fma_f32 v108, -v95, v105, 1.0
	v_fma_f32 v107, v108, v105, v105
	v_fma_f32 v104, -v95, v107, 1.0
	v_fma_f32 v104, v104, v105, v107
	v_div_fixup_f32 v104, v104, v95, 1.0
	v_rcp_f32_e32 v105, v94
	s_nop 0
	v_fma_f32 v106, -v94, v105, 1.0
	v_fmac_f32_e32 v105, v106, v105
	v_fma_f32 v108, -v94, v105, 1.0
	v_fma_f32 v107, v108, v105, v105
	v_fma_f32 v95, -v94, v107, 1.0
	v_fma_f32 v95, v95, v105, v107
	v_div_fixup_f32 v105, v95, v94, 1.0
	v_mul_f32_e32 v94, 0xbfb8aa3b, v96
	v_mul_f32_e32 v95, 0xbfb8aa3b, v97
	v_exp_f32_e32 v94, v94
	v_exp_f32_e32 v95, v95
	s_nop 0
	v_pk_add_f32 v[94:95], v[94:95], 1.0 op_sel_hi:[1,0]
	s_nop 0
	v_rcp_f32_e32 v97, v95
	s_nop 0
	v_fma_f32 v106, -v95, v97, 1.0
	v_fmac_f32_e32 v97, v106, v97
	v_fma_f32 v108, -v95, v97, 1.0
	v_fma_f32 v107, v108, v97, v97
	v_fma_f32 v96, -v95, v107, 1.0
	v_fma_f32 v96, v96, v97, v107
	v_div_fixup_f32 v96, v96, v95, 1.0
	v_rcp_f32_e32 v97, v94
	s_nop 0
	v_fma_f32 v106, -v94, v97, 1.0
	v_fmac_f32_e32 v97, v106, v97
	v_fma_f32 v108, -v94, v97, 1.0
	v_fma_f32 v107, v108, v97, v97
	v_fma_f32 v95, -v94, v107, 1.0
	v_fma_f32 v95, v95, v97, v107
	v_div_fixup_f32 v97, v95, v94, 1.0
	v_rcp_f32_e32 v95, v91
	s_nop 0
	v_fma_f32 v98, -v91, v95, 1.0
	v_fmac_f32_e32 v95, v98, v95
	v_fma_f32 v100, -v91, v95, 1.0
	v_fma_f32 v99, v100, v95, v95
	v_fma_f32 v94, -v91, v99, 1.0
	v_fma_f32 v94, v94, v95, v99
	v_div_fixup_f32 v98, v94, v91, 1.0
	v_rcp_f32_e32 v94, v90
	s_nop 0
	v_fma_f32 v95, -v90, v94, 1.0
	v_fmac_f32_e32 v94, v95, v94
	v_fma_f32 v100, -v90, v94, 1.0
	v_fma_f32 v99, v100, v94, v94
	v_fma_f32 v91, -v90, v99, 1.0
	v_fma_f32 v91, v91, v94, v99
	v_div_fixup_f32 v99, v91, v90, 1.0
	v_mul_f32_e32 v90, 0xbfb8aa3b, v92
	v_mul_f32_e32 v91, 0xbfb8aa3b, v93
	v_exp_f32_e32 v90, v90
	v_exp_f32_e32 v91, v91
	s_nop 0
	v_pk_add_f32 v[90:91], v[90:91], 1.0 op_sel_hi:[1,0]
	s_nop 0
	v_rcp_f32_e32 v93, v91
	s_nop 0
	v_fma_f32 v94, -v91, v93, 1.0
	v_fmac_f32_e32 v93, v94, v93
	v_fma_f32 v100, -v91, v93, 1.0
	v_fma_f32 v95, v100, v93, v93
	v_fma_f32 v92, -v91, v95, 1.0
	v_fma_f32 v92, v92, v93, v95
	v_div_fixup_f32 v93, v92, v91, 1.0
	v_rcp_f32_e32 v92, v90
	s_nop 0
	v_fma_f32 v94, -v90, v92, 1.0
	v_fmac_f32_e32 v92, v94, v92
	v_fma_f32 v100, -v90, v92, 1.0
	v_fma_f32 v95, v100, v92, v92
	v_fma_f32 v91, -v90, v95, 1.0
	v_fma_f32 v91, v91, v92, v95
	v_div_fixup_f32 v100, v91, v90, 1.0
	v_lshl_add_u64 v[90:91], v[126:127], 0, v[102:103]
	v_lshl_add_u64 v[94:95], v[90:91], 0, v[0:1]
	v_cvt_pk_bf16_f32 v90, v105, v104
	v_cvt_pk_bf16_f32 v91, v97, v96
	v_cvt_pk_bf16_f32 v92, v99, v98
	v_cvt_pk_bf16_f32 v93, v100, v93
	global_store_dwordx4 v[94:95], v[90:93], off
	global_load_dwordx4 v[90:93], v[146:147], off offset:528
	global_load_dwordx4 v[94:97], v[146:147], off offset:512
	s_waitcnt vmcnt(0)
	v_pk_add_f32 v[82:83], v[82:83], v[90:91]
	v_pk_add_f32 v[86:87], v[86:87], v[94:95]
	v_pk_add_f32 v[88:89], v[88:89], v[96:97]
	v_mul_f32_e32 v86, 0xbfb8aa3b, v86
	v_mul_f32_e32 v87, 0xbfb8aa3b, v87
	v_exp_f32_e32 v86, v86
	v_exp_f32_e32 v87, v87
	v_mul_f32_e32 v82, 0xbfb8aa3b, v82
	v_mul_f32_e32 v83, 0xbfb8aa3b, v83
	v_exp_f32_e32 v82, v82
	v_pk_add_f32 v[86:87], v[86:87], 1.0 op_sel_hi:[1,0]
	v_exp_f32_e32 v83, v83
	v_rcp_f32_e32 v95, v87
	v_pk_add_f32 v[82:83], v[82:83], 1.0 op_sel_hi:[1,0]
	v_pk_add_f32 v[84:85], v[84:85], v[92:93]
	v_fma_f32 v96, -v87, v95, 1.0
	v_fmac_f32_e32 v95, v96, v95
	v_fma_f32 v98, -v87, v95, 1.0
	v_fma_f32 v97, v98, v95, v95
	v_fma_f32 v94, -v87, v97, 1.0
	v_fma_f32 v94, v94, v95, v97
	v_div_fixup_f32 v94, v94, v87, 1.0
	v_rcp_f32_e32 v95, v86
	s_nop 0
	v_fma_f32 v96, -v86, v95, 1.0
	v_fmac_f32_e32 v95, v96, v95
	v_fma_f32 v98, -v86, v95, 1.0
	v_fma_f32 v97, v98, v95, v95
	v_fma_f32 v87, -v86, v97, 1.0
	v_fma_f32 v87, v87, v95, v97
	v_div_fixup_f32 v95, v87, v86, 1.0
	v_mul_f32_e32 v86, 0xbfb8aa3b, v88
	v_mul_f32_e32 v87, 0xbfb8aa3b, v89
	v_exp_f32_e32 v86, v86
	v_exp_f32_e32 v87, v87
	s_nop 0
	v_pk_add_f32 v[86:87], v[86:87], 1.0 op_sel_hi:[1,0]
	s_nop 0
	v_rcp_f32_e32 v89, v87
	s_nop 0
	v_fma_f32 v96, -v87, v89, 1.0
	v_fmac_f32_e32 v89, v96, v89
	v_fma_f32 v98, -v87, v89, 1.0
	v_fma_f32 v97, v98, v89, v89
	v_fma_f32 v88, -v87, v97, 1.0
	v_fma_f32 v88, v88, v89, v97
	v_div_fixup_f32 v88, v88, v87, 1.0
	v_rcp_f32_e32 v89, v86
	s_nop 0
	v_fma_f32 v96, -v86, v89, 1.0
	v_fmac_f32_e32 v89, v96, v89
	v_fma_f32 v98, -v86, v89, 1.0
	v_fma_f32 v97, v98, v89, v89
	v_fma_f32 v87, -v86, v97, 1.0
	v_fma_f32 v87, v87, v89, v97
	v_div_fixup_f32 v89, v87, v86, 1.0
	v_rcp_f32_e32 v87, v83
	s_nop 0
	v_fma_f32 v90, -v83, v87, 1.0
	v_fmac_f32_e32 v87, v90, v87
	v_fma_f32 v92, -v83, v87, 1.0
	v_fma_f32 v91, v92, v87, v87
	v_fma_f32 v86, -v83, v91, 1.0
	v_fma_f32 v86, v86, v87, v91
	v_div_fixup_f32 v90, v86, v83, 1.0
	v_rcp_f32_e32 v86, v82
	s_nop 0
	v_fma_f32 v87, -v82, v86, 1.0
	v_fmac_f32_e32 v86, v87, v86
	v_fma_f32 v92, -v82, v86, 1.0
	v_fma_f32 v91, v92, v86, v86
	v_fma_f32 v83, -v82, v91, 1.0
	v_fma_f32 v83, v83, v86, v91
	v_div_fixup_f32 v91, v83, v82, 1.0
	v_mul_f32_e32 v82, 0xbfb8aa3b, v84
	v_mul_f32_e32 v83, 0xbfb8aa3b, v85
	v_exp_f32_e32 v82, v82
	v_exp_f32_e32 v83, v83
	s_nop 0
	v_pk_add_f32 v[82:83], v[82:83], 1.0 op_sel_hi:[1,0]
	s_nop 0
	v_rcp_f32_e32 v85, v83
	s_nop 0
	v_fma_f32 v86, -v83, v85, 1.0
	v_fmac_f32_e32 v85, v86, v85
	v_fma_f32 v92, -v83, v85, 1.0
	v_fma_f32 v87, v92, v85, v85
	v_fma_f32 v84, -v83, v87, 1.0
	v_fma_f32 v84, v84, v85, v87
	v_div_fixup_f32 v85, v84, v83, 1.0
	v_rcp_f32_e32 v84, v82
	s_nop 0
	v_fma_f32 v86, -v82, v84, 1.0
	v_fmac_f32_e32 v84, v86, v84
	v_fma_f32 v92, -v82, v84, 1.0
	v_fma_f32 v87, v92, v84, v84
	v_fma_f32 v83, -v82, v87, 1.0
	v_fma_f32 v83, v83, v84, v87
	v_div_fixup_f32 v92, v83, v82, 1.0
	v_lshl_add_u64 v[82:83], v[118:119], 0, v[102:103]
	v_lshl_add_u64 v[86:87], v[82:83], 0, v[120:121]
	v_cvt_pk_bf16_f32 v82, v95, v94
	v_cvt_pk_bf16_f32 v83, v89, v88
	v_cvt_pk_bf16_f32 v84, v91, v90
	v_cvt_pk_bf16_f32 v85, v92, v85
	global_store_dwordx4 v[86:87], v[82:85], off
	s_nop 1
	v_or_b32_e32 v82, 48, v150
	v_ashrrev_i32_e32 v83, 31, v82
	v_lshlrev_b64 v[86:87], 11, v[82:83]
	global_load_dwordx4 v[82:85], v[146:147], off offset:16
	global_load_dwordx4 v[88:91], v[146:147], off
	s_waitcnt vmcnt(0)
; __device__ __forceinline__ u32x4 pack8(f32x4 v0, f32x4 v1) { u32x4 o; o.x = pkbf(v0.x, v0.y); o.y = pkbf(v0.z, v0.w); o.z = pkbf(v1.x, v1.y); o.w = pkbf(v1.z, v1.w); return o; }
; __device__ __forceinline__ f32x4 sig4(f32x4 v) { return (f32x4){sigmoidf_(v.x), sigmoidf_(v.y), sigmoidf_(v.z), sigmoidf_(v.w)}; }
;     __device__ __forceinline__ void operator()(int row, int col, f32x4 v0, f32x4 v1) const { *(u32x4*)(G + (size_t)row * 1024 + col) = pack8(v0, v1); }
;     __device__ __forceinline__ void operator()(const pg8::f32x4 (&acc)[2][2][4][2], const pg8::Unit& u, int wr, int wc, int fr, int fq) const {
;     ...
;         for (int ai = 0; ai < 2; ++ai)
; #pragma unroll
;             for (int m = 0; m < 4; ++m)
; #pragma unroll
;                 for (int bj = 0; bj < 2; ++bj) { op(row0 + ai * 128 + m * 16, col0 + bj * 128, acc[ai][bj][m][0], acc[ai][bj][m][1]); asm volatile("" ::: "memory"); }
;     __device__ __forceinline__ void operator()(int row, int col, f32x4 v0, f32x4 v1) const {
;         const f32x4 b0 = *(const f32x4*)(a0 + col), b1 = *(const f32x4*)(a0 + col + 4);
;         v0 = sig4(v0 + b0); v1 = sig4(v1 + b1);
;         bf16_t* dst = (col < 1024 ? A0 : A1) + (size_t)row * 1024 + (col & 1023);
;         *(u32x4*)dst = pack8(v0, v1);
	v_pk_add_f32 v[74:75], v[74:75], v[82:83]
	v_pk_add_f32 v[78:79], v[78:79], v[88:89]
	v_pk_add_f32 v[80:81], v[80:81], v[90:91]
	v_mul_f32_e32 v78, 0xbfb8aa3b, v78
	v_mul_f32_e32 v79, 0xbfb8aa3b, v79
	v_exp_f32_e32 v78, v78
	v_exp_f32_e32 v79, v79
	v_mul_f32_e32 v74, 0xbfb8aa3b, v74
	v_mul_f32_e32 v75, 0xbfb8aa3b, v75
	v_exp_f32_e32 v74, v74
	v_pk_add_f32 v[78:79], v[78:79], 1.0 op_sel_hi:[1,0]
	v_exp_f32_e32 v75, v75
	v_rcp_f32_e32 v89, v79
	v_pk_add_f32 v[74:75], v[74:75], 1.0 op_sel_hi:[1,0]
	v_pk_add_f32 v[76:77], v[76:77], v[84:85]
	v_fma_f32 v90, -v79, v89, 1.0
	v_fmac_f32_e32 v89, v90, v89
	v_fma_f32 v92, -v79, v89, 1.0
	v_fma_f32 v91, v92, v89, v89
	v_fma_f32 v88, -v79, v91, 1.0
	v_fma_f32 v88, v88, v89, v91
	v_div_fixup_f32 v88, v88, v79, 1.0
	v_rcp_f32_e32 v89, v78
	s_nop 0
	v_fma_f32 v90, -v78, v89, 1.0
	v_fmac_f32_e32 v89, v90, v89
	v_fma_f32 v92, -v78, v89, 1.0
	v_fma_f32 v91, v92, v89, v89
	v_fma_f32 v79, -v78, v91, 1.0
	v_fma_f32 v79, v79, v89, v91
	v_div_fixup_f32 v89, v79, v78, 1.0
	v_mul_f32_e32 v78, 0xbfb8aa3b, v80
	v_mul_f32_e32 v79, 0xbfb8aa3b, v81
	v_exp_f32_e32 v78, v78
	v_exp_f32_e32 v79, v79
	s_nop 0
	v_pk_add_f32 v[78:79], v[78:79], 1.0 op_sel_hi:[1,0]
	s_nop 0
	v_rcp_f32_e32 v81, v79
	s_nop 0
	v_fma_f32 v90, -v79, v81, 1.0
	v_fmac_f32_e32 v81, v90, v81
	v_fma_f32 v92, -v79, v81, 1.0
	v_fma_f32 v91, v92, v81, v81
	v_fma_f32 v80, -v79, v91, 1.0
	v_fma_f32 v80, v80, v81, v91
	v_div_fixup_f32 v80, v80, v79, 1.0
	v_rcp_f32_e32 v81, v78
	s_nop 0
	v_fma_f32 v90, -v78, v81, 1.0
	v_fmac_f32_e32 v81, v90, v81
	v_fma_f32 v92, -v78, v81, 1.0
	v_fma_f32 v91, v92, v81, v81
	v_fma_f32 v79, -v78, v91, 1.0
	v_fma_f32 v79, v79, v81, v91
	v_div_fixup_f32 v81, v79, v78, 1.0
	v_rcp_f32_e32 v79, v75
	s_nop 0
	v_fma_f32 v82, -v75, v79, 1.0
	v_fmac_f32_e32 v79, v82, v79
	v_fma_f32 v84, -v75, v79, 1.0
	v_fma_f32 v83, v84, v79, v79
	v_fma_f32 v78, -v75, v83, 1.0
	v_fma_f32 v78, v78, v79, v83
	v_div_fixup_f32 v82, v78, v75, 1.0
	v_rcp_f32_e32 v78, v74
	s_nop 0
	v_fma_f32 v79, -v74, v78, 1.0
	v_fmac_f32_e32 v78, v79, v78
	v_fma_f32 v84, -v74, v78, 1.0
	v_fma_f32 v83, v84, v78, v78
	v_fma_f32 v75, -v74, v83, 1.0
	v_fma_f32 v75, v75, v78, v83
	v_div_fixup_f32 v83, v75, v74, 1.0
	v_mul_f32_e32 v74, 0xbfb8aa3b, v76
	v_mul_f32_e32 v75, 0xbfb8aa3b, v77
	v_exp_f32_e32 v74, v74
	v_exp_f32_e32 v75, v75
	s_nop 0
	v_pk_add_f32 v[74:75], v[74:75], 1.0 op_sel_hi:[1,0]
	s_nop 0
	v_rcp_f32_e32 v77, v75
	s_nop 0
	v_fma_f32 v78, -v75, v77, 1.0
	v_fmac_f32_e32 v77, v78, v77
	v_fma_f32 v84, -v75, v77, 1.0
	v_fma_f32 v79, v84, v77, v77
	v_fma_f32 v76, -v75, v79, 1.0
	v_fma_f32 v76, v76, v77, v79
	v_div_fixup_f32 v77, v76, v75, 1.0
	v_rcp_f32_e32 v76, v74
	s_nop 0
	v_fma_f32 v78, -v74, v76, 1.0
	v_fmac_f32_e32 v76, v78, v76
	v_fma_f32 v84, -v74, v76, 1.0
	v_fma_f32 v79, v84, v76, v76
	v_fma_f32 v75, -v74, v79, 1.0
	v_fma_f32 v75, v75, v76, v79
	v_div_fixup_f32 v84, v75, v74, 1.0
	v_lshl_add_u64 v[74:75], v[126:127], 0, v[86:87]
	v_lshl_add_u64 v[78:79], v[74:75], 0, v[0:1]
	v_cvt_pk_bf16_f32 v74, v89, v88
	v_cvt_pk_bf16_f32 v75, v81, v80
	v_cvt_pk_bf16_f32 v76, v83, v82
	v_cvt_pk_bf16_f32 v77, v84, v77
	global_store_dwordx4 v[78:79], v[74:77], off
	global_load_dwordx4 v[74:77], v[146:147], off offset:528
	global_load_dwordx4 v[78:81], v[146:147], off offset:512
	s_waitcnt vmcnt(0)
	v_pk_add_f32 v[66:67], v[66:67], v[74:75]
	v_pk_add_f32 v[70:71], v[70:71], v[78:79]
	v_pk_add_f32 v[72:73], v[72:73], v[80:81]
	v_mul_f32_e32 v70, 0xbfb8aa3b, v70
	v_mul_f32_e32 v71, 0xbfb8aa3b, v71
	v_exp_f32_e32 v70, v70
	v_exp_f32_e32 v71, v71
	v_mul_f32_e32 v66, 0xbfb8aa3b, v66
	v_mul_f32_e32 v67, 0xbfb8aa3b, v67
	v_exp_f32_e32 v66, v66
	v_pk_add_f32 v[70:71], v[70:71], 1.0 op_sel_hi:[1,0]
	v_exp_f32_e32 v67, v67
	v_rcp_f32_e32 v79, v71
	v_pk_add_f32 v[66:67], v[66:67], 1.0 op_sel_hi:[1,0]
	v_pk_add_f32 v[68:69], v[68:69], v[76:77]
	v_fma_f32 v80, -v71, v79, 1.0
	v_fmac_f32_e32 v79, v80, v79
	v_fma_f32 v82, -v71, v79, 1.0
	v_fma_f32 v81, v82, v79, v79
	v_fma_f32 v78, -v71, v81, 1.0
	v_fma_f32 v78, v78, v79, v81
	v_div_fixup_f32 v78, v78, v71, 1.0
	v_rcp_f32_e32 v79, v70
	s_nop 0
	v_fma_f32 v80, -v70, v79, 1.0
	v_fmac_f32_e32 v79, v80, v79
	v_fma_f32 v82, -v70, v79, 1.0
	v_fma_f32 v81, v82, v79, v79
	v_fma_f32 v71, -v70, v81, 1.0
	v_fma_f32 v71, v71, v79, v81
	v_div_fixup_f32 v79, v71, v70, 1.0
	v_mul_f32_e32 v70, 0xbfb8aa3b, v72
	v_mul_f32_e32 v71, 0xbfb8aa3b, v73
	v_exp_f32_e32 v70, v70
	v_exp_f32_e32 v71, v71
	s_nop 0
	v_pk_add_f32 v[70:71], v[70:71], 1.0 op_sel_hi:[1,0]
	s_nop 0
	v_rcp_f32_e32 v73, v71
	s_nop 0
	v_fma_f32 v80, -v71, v73, 1.0
	v_fmac_f32_e32 v73, v80, v73
	v_fma_f32 v82, -v71, v73, 1.0
	v_fma_f32 v81, v82, v73, v73
	v_fma_f32 v72, -v71, v81, 1.0
	v_fma_f32 v72, v72, v73, v81
	v_div_fixup_f32 v72, v72, v71, 1.0
	v_rcp_f32_e32 v73, v70
	s_nop 0
	v_fma_f32 v80, -v70, v73, 1.0
	v_fmac_f32_e32 v73, v80, v73
	v_fma_f32 v82, -v70, v73, 1.0
	v_fma_f32 v81, v82, v73, v73
	v_fma_f32 v71, -v70, v81, 1.0
	v_fma_f32 v71, v71, v73, v81
	v_div_fixup_f32 v73, v71, v70, 1.0
	v_rcp_f32_e32 v71, v67
	s_nop 0
	v_fma_f32 v74, -v67, v71, 1.0
	v_fmac_f32_e32 v71, v74, v71
	v_fma_f32 v76, -v67, v71, 1.0
	v_fma_f32 v75, v76, v71, v71
	v_fma_f32 v70, -v67, v75, 1.0
	v_fma_f32 v70, v70, v71, v75
	v_div_fixup_f32 v74, v70, v67, 1.0
	v_rcp_f32_e32 v70, v66
	s_nop 0
	v_fma_f32 v71, -v66, v70, 1.0
	v_fmac_f32_e32 v70, v71, v70
	v_fma_f32 v76, -v66, v70, 1.0
	v_fma_f32 v75, v76, v70, v70
	v_fma_f32 v67, -v66, v75, 1.0
	v_fma_f32 v67, v67, v70, v75
	v_div_fixup_f32 v75, v67, v66, 1.0
	v_mul_f32_e32 v66, 0xbfb8aa3b, v68
	v_mul_f32_e32 v67, 0xbfb8aa3b, v69
	v_exp_f32_e32 v66, v66
	v_exp_f32_e32 v67, v67
	s_nop 0
	v_pk_add_f32 v[66:67], v[66:67], 1.0 op_sel_hi:[1,0]
	s_nop 0
	v_rcp_f32_e32 v69, v67
	s_nop 0
	v_fma_f32 v70, -v67, v69, 1.0
	v_fmac_f32_e32 v69, v70, v69
	v_fma_f32 v76, -v67, v69, 1.0
	v_fma_f32 v71, v76, v69, v69
	v_fma_f32 v68, -v67, v71, 1.0
	v_fma_f32 v68, v68, v69, v71
	v_div_fixup_f32 v69, v68, v67, 1.0
	v_rcp_f32_e32 v68, v66
	s_nop 0
	v_fma_f32 v70, -v66, v68, 1.0
	v_fmac_f32_e32 v68, v70, v68
	v_fma_f32 v76, -v66, v68, 1.0
	v_fma_f32 v71, v76, v68, v68
	v_fma_f32 v67, -v66, v71, 1.0
	v_fma_f32 v67, v67, v68, v71
	v_div_fixup_f32 v76, v67, v66, 1.0
	v_lshl_add_u64 v[66:67], v[118:119], 0, v[86:87]
	v_lshl_add_u64 v[70:71], v[66:67], 0, v[120:121]
	v_cvt_pk_bf16_f32 v66, v79, v78
	v_cvt_pk_bf16_f32 v67, v73, v72
	v_cvt_pk_bf16_f32 v68, v75, v74
	v_cvt_pk_bf16_f32 v69, v76, v69
	global_store_dwordx4 v[70:71], v[66:69], off
	global_load_dwordx4 v[68:71], v[146:147], off offset:16
	global_load_dwordx4 v[72:75], v[146:147], off
	v_lshl_add_u64 v[66:67], v[148:149], 0, s[90:91]
	s_waitcnt vmcnt(0)
; __device__ __forceinline__ u32x4 pack8(f32x4 v0, f32x4 v1) { u32x4 o; o.x = pkbf(v0.x, v0.y); o.y = pkbf(v0.z, v0.w); o.z = pkbf(v1.x, v1.y); o.w = pkbf(v1.z, v1.w); return o; }
; __device__ __forceinline__ f32x4 sig4(f32x4 v) { return (f32x4){sigmoidf_(v.x), sigmoidf_(v.y), sigmoidf_(v.z), sigmoidf_(v.w)}; }
;     __device__ __forceinline__ void operator()(int row, int col, f32x4 v0, f32x4 v1) const { *(u32x4*)(G + (size_t)row * 1024 + col) = pack8(v0, v1); }
;     __device__ __forceinline__ void operator()(const pg8::f32x4 (&acc)[2][2][4][2], const pg8::Unit& u, int wr, int wc, int fr, int fq) const {
;     ...
;         for (int ai = 0; ai < 2; ++ai)
; #pragma unroll
;             for (int m = 0; m < 4; ++m)
; #pragma unroll
;                 for (int bj = 0; bj < 2; ++bj) { op(row0 + ai * 128 + m * 16, col0 + bj * 128, acc[ai][bj][m][0], acc[ai][bj][m][1]); asm volatile("" ::: "memory"); }
;     __device__ __forceinline__ void operator()(int row, int col, f32x4 v0, f32x4 v1) const {
;         const f32x4 b0 = *(const f32x4*)(a0 + col), b1 = *(const f32x4*)(a0 + col + 4);
;         v0 = sig4(v0 + b0); v1 = sig4(v1 + b1);
;         bf16_t* dst = (col < 1024 ? A0 : A1) + (size_t)row * 1024 + (col & 1023);
;         *(u32x4*)dst = pack8(v0, v1);
	v_pk_add_f32 v[58:59], v[58:59], v[68:69]
	v_pk_add_f32 v[62:63], v[62:63], v[72:73]
	v_pk_add_f32 v[64:65], v[64:65], v[74:75]
	v_mul_f32_e32 v62, 0xbfb8aa3b, v62
	v_mul_f32_e32 v63, 0xbfb8aa3b, v63
	v_exp_f32_e32 v62, v62
	v_exp_f32_e32 v63, v63
	v_mul_f32_e32 v58, 0xbfb8aa3b, v58
	v_mul_f32_e32 v59, 0xbfb8aa3b, v59
	v_exp_f32_e32 v58, v58
	v_pk_add_f32 v[62:63], v[62:63], 1.0 op_sel_hi:[1,0]
	v_exp_f32_e32 v59, v59
	v_rcp_f32_e32 v73, v63
	v_pk_add_f32 v[58:59], v[58:59], 1.0 op_sel_hi:[1,0]
	v_pk_add_f32 v[60:61], v[60:61], v[70:71]
	v_fma_f32 v74, -v63, v73, 1.0
	v_fmac_f32_e32 v73, v74, v73
	v_fma_f32 v76, -v63, v73, 1.0
	v_fma_f32 v75, v76, v73, v73
	v_fma_f32 v72, -v63, v75, 1.0
	v_fma_f32 v72, v72, v73, v75
	v_div_fixup_f32 v72, v72, v63, 1.0
	v_rcp_f32_e32 v73, v62
	s_nop 0
	v_fma_f32 v74, -v62, v73, 1.0
	v_fmac_f32_e32 v73, v74, v73
	v_fma_f32 v76, -v62, v73, 1.0
	v_fma_f32 v75, v76, v73, v73
	v_fma_f32 v63, -v62, v75, 1.0
	v_fma_f32 v63, v63, v73, v75
	v_div_fixup_f32 v73, v63, v62, 1.0
	v_mul_f32_e32 v62, 0xbfb8aa3b, v64
	v_mul_f32_e32 v63, 0xbfb8aa3b, v65
	v_exp_f32_e32 v62, v62
	v_exp_f32_e32 v63, v63
	s_nop 0
	v_pk_add_f32 v[62:63], v[62:63], 1.0 op_sel_hi:[1,0]
	s_nop 0
	v_rcp_f32_e32 v65, v63
	s_nop 0
	v_fma_f32 v74, -v63, v65, 1.0
	v_fmac_f32_e32 v65, v74, v65
	v_fma_f32 v76, -v63, v65, 1.0
	v_fma_f32 v75, v76, v65, v65
	v_fma_f32 v64, -v63, v75, 1.0
	v_fma_f32 v64, v64, v65, v75
	v_div_fixup_f32 v64, v64, v63, 1.0
	v_rcp_f32_e32 v65, v62
	s_nop 0
	v_fma_f32 v74, -v62, v65, 1.0
	v_fmac_f32_e32 v65, v74, v65
	v_fma_f32 v76, -v62, v65, 1.0
	v_fma_f32 v75, v76, v65, v65
	v_fma_f32 v63, -v62, v75, 1.0
	v_fma_f32 v63, v63, v65, v75
	v_div_fixup_f32 v65, v63, v62, 1.0
	v_rcp_f32_e32 v63, v59
	s_nop 0
	v_fma_f32 v68, -v59, v63, 1.0
	v_fmac_f32_e32 v63, v68, v63
	v_fma_f32 v70, -v59, v63, 1.0
	v_fma_f32 v69, v70, v63, v63
	v_fma_f32 v62, -v59, v69, 1.0
	v_fma_f32 v62, v62, v63, v69
	v_div_fixup_f32 v68, v62, v59, 1.0
	v_rcp_f32_e32 v62, v58
	s_nop 0
	v_fma_f32 v63, -v58, v62, 1.0
	v_fmac_f32_e32 v62, v63, v62
	v_fma_f32 v70, -v58, v62, 1.0
	v_fma_f32 v69, v70, v62, v62
	v_fma_f32 v59, -v58, v69, 1.0
	v_fma_f32 v59, v59, v62, v69
	v_div_fixup_f32 v69, v59, v58, 1.0
	v_mul_f32_e32 v58, 0xbfb8aa3b, v60
	v_mul_f32_e32 v59, 0xbfb8aa3b, v61
	v_exp_f32_e32 v58, v58
	v_exp_f32_e32 v59, v59
	s_nop 0
	v_pk_add_f32 v[58:59], v[58:59], 1.0 op_sel_hi:[1,0]
	s_nop 0
	v_rcp_f32_e32 v61, v59
	s_nop 0
	v_fma_f32 v62, -v59, v61, 1.0
	v_fmac_f32_e32 v61, v62, v61
	v_fma_f32 v70, -v59, v61, 1.0
	v_fma_f32 v63, v70, v61, v61
	v_fma_f32 v60, -v59, v63, 1.0
	v_fma_f32 v60, v60, v61, v63
	v_div_fixup_f32 v61, v60, v59, 1.0
	v_rcp_f32_e32 v60, v58
	s_nop 0
	v_fma_f32 v62, -v58, v60, 1.0
	v_fmac_f32_e32 v60, v62, v60
	v_fma_f32 v70, -v58, v60, 1.0
	v_fma_f32 v63, v70, v60, v60
	v_fma_f32 v59, -v58, v63, 1.0
	v_fma_f32 v59, v59, v60, v63
	v_div_fixup_f32 v70, v59, v58, 1.0
	v_lshl_add_u64 v[58:59], v[126:127], 0, v[66:67]
	v_lshl_add_u64 v[62:63], v[58:59], 0, v[0:1]
	v_cvt_pk_bf16_f32 v58, v73, v72
	v_cvt_pk_bf16_f32 v59, v65, v64
	v_cvt_pk_bf16_f32 v60, v69, v68
	v_cvt_pk_bf16_f32 v61, v70, v61
	global_store_dwordx4 v[62:63], v[58:61], off
	global_load_dwordx4 v[58:61], v[146:147], off offset:528
	global_load_dwordx4 v[62:65], v[146:147], off offset:512
	s_waitcnt vmcnt(0)
	v_pk_add_f32 v[50:51], v[50:51], v[58:59]
	v_pk_add_f32 v[54:55], v[54:55], v[62:63]
	v_pk_add_f32 v[56:57], v[56:57], v[64:65]
	v_mul_f32_e32 v54, 0xbfb8aa3b, v54
	v_mul_f32_e32 v55, 0xbfb8aa3b, v55
	v_exp_f32_e32 v54, v54
	v_exp_f32_e32 v55, v55
	v_mul_f32_e32 v50, 0xbfb8aa3b, v50
	v_mul_f32_e32 v51, 0xbfb8aa3b, v51
	v_exp_f32_e32 v50, v50
	v_pk_add_f32 v[54:55], v[54:55], 1.0 op_sel_hi:[1,0]
	v_exp_f32_e32 v51, v51
	v_rcp_f32_e32 v63, v55
	v_pk_add_f32 v[50:51], v[50:51], 1.0 op_sel_hi:[1,0]
	v_pk_add_f32 v[52:53], v[52:53], v[60:61]
	v_fma_f32 v64, -v55, v63, 1.0
	v_fmac_f32_e32 v63, v64, v63
	v_fma_f32 v68, -v55, v63, 1.0
	v_fma_f32 v65, v68, v63, v63
	v_fma_f32 v62, -v55, v65, 1.0
	v_fma_f32 v62, v62, v63, v65
	v_div_fixup_f32 v62, v62, v55, 1.0
	v_rcp_f32_e32 v63, v54
	s_nop 0
	v_fma_f32 v64, -v54, v63, 1.0
	v_fmac_f32_e32 v63, v64, v63
	v_fma_f32 v68, -v54, v63, 1.0
	v_fma_f32 v65, v68, v63, v63
	v_fma_f32 v55, -v54, v65, 1.0
	v_fma_f32 v55, v55, v63, v65
	v_div_fixup_f32 v63, v55, v54, 1.0
	v_mul_f32_e32 v54, 0xbfb8aa3b, v56
	v_mul_f32_e32 v55, 0xbfb8aa3b, v57
	v_exp_f32_e32 v54, v54
	v_exp_f32_e32 v55, v55
	s_nop 0
	v_pk_add_f32 v[54:55], v[54:55], 1.0 op_sel_hi:[1,0]
	s_nop 0
	v_rcp_f32_e32 v57, v55
	s_nop 0
	v_fma_f32 v64, -v55, v57, 1.0
	v_fmac_f32_e32 v57, v64, v57
	v_fma_f32 v68, -v55, v57, 1.0
	v_fma_f32 v65, v68, v57, v57
	v_fma_f32 v56, -v55, v65, 1.0
	v_fma_f32 v56, v56, v57, v65
	v_div_fixup_f32 v56, v56, v55, 1.0
	v_rcp_f32_e32 v57, v54
	s_nop 0
	v_fma_f32 v64, -v54, v57, 1.0
	v_fmac_f32_e32 v57, v64, v57
	v_fma_f32 v68, -v54, v57, 1.0
	v_fma_f32 v65, v68, v57, v57
	v_fma_f32 v55, -v54, v65, 1.0
	v_fma_f32 v55, v55, v57, v65
	v_div_fixup_f32 v57, v55, v54, 1.0
	v_rcp_f32_e32 v55, v51
	s_nop 0
	v_fma_f32 v58, -v51, v55, 1.0
	v_fmac_f32_e32 v55, v58, v55
	v_fma_f32 v60, -v51, v55, 1.0
	v_fma_f32 v59, v60, v55, v55
	v_fma_f32 v54, -v51, v59, 1.0
	v_fma_f32 v54, v54, v55, v59
	v_div_fixup_f32 v58, v54, v51, 1.0
	v_rcp_f32_e32 v54, v50
	s_nop 0
	v_fma_f32 v55, -v50, v54, 1.0
	v_fmac_f32_e32 v54, v55, v54
	v_fma_f32 v60, -v50, v54, 1.0
	v_fma_f32 v59, v60, v54, v54
	v_fma_f32 v51, -v50, v59, 1.0
	v_fma_f32 v51, v51, v54, v59
	v_div_fixup_f32 v59, v51, v50, 1.0
	v_mul_f32_e32 v50, 0xbfb8aa3b, v52
	v_mul_f32_e32 v51, 0xbfb8aa3b, v53
	v_exp_f32_e32 v50, v50
	v_exp_f32_e32 v51, v51
	s_nop 0
	v_pk_add_f32 v[50:51], v[50:51], 1.0 op_sel_hi:[1,0]
	s_nop 0
	v_rcp_f32_e32 v53, v51
	s_nop 0
	v_fma_f32 v54, -v51, v53, 1.0
	v_fmac_f32_e32 v53, v54, v53
	v_fma_f32 v60, -v51, v53, 1.0
	v_fma_f32 v55, v60, v53, v53
	v_fma_f32 v52, -v51, v55, 1.0
	v_fma_f32 v52, v52, v53, v55
	v_div_fixup_f32 v53, v52, v51, 1.0
	v_rcp_f32_e32 v52, v50
	s_mov_b64 s[4:5], 0x48000
	v_fma_f32 v54, -v50, v52, 1.0
	v_fmac_f32_e32 v52, v54, v52
	v_fma_f32 v60, -v50, v52, 1.0
	v_fma_f32 v55, v60, v52, v52
	v_fma_f32 v51, -v50, v55, 1.0
	v_fma_f32 v51, v51, v52, v55
	v_div_fixup_f32 v60, v51, v50, 1.0
	v_lshl_add_u64 v[50:51], v[118:119], 0, v[66:67]
	v_lshl_add_u64 v[54:55], v[50:51], 0, v[120:121]
	v_cvt_pk_bf16_f32 v50, v63, v62
	v_cvt_pk_bf16_f32 v51, v57, v56
	v_cvt_pk_bf16_f32 v52, v59, v58
	v_cvt_pk_bf16_f32 v53, v60, v53
	global_store_dwordx4 v[54:55], v[50:53], off
	global_load_dwordx4 v[52:55], v[146:147], off offset:16
	global_load_dwordx4 v[56:59], v[146:147], off
	v_lshl_add_u64 v[50:51], v[148:149], 0, s[4:5]
	s_waitcnt vmcnt(0)
; __device__ __forceinline__ u32x4 pack8(f32x4 v0, f32x4 v1) { u32x4 o; o.x = pkbf(v0.x, v0.y); o.y = pkbf(v0.z, v0.w); o.z = pkbf(v1.x, v1.y); o.w = pkbf(v1.z, v1.w); return o; }
; __device__ __forceinline__ f32x4 sig4(f32x4 v) { return (f32x4){sigmoidf_(v.x), sigmoidf_(v.y), sigmoidf_(v.z), sigmoidf_(v.w)}; }
;     __device__ __forceinline__ void operator()(int row, int col, f32x4 v0, f32x4 v1) const { *(u32x4*)(G + (size_t)row * 1024 + col) = pack8(v0, v1); }
;     __device__ __forceinline__ void operator()(const pg8::f32x4 (&acc)[2][2][4][2], const pg8::Unit& u, int wr, int wc, int fr, int fq) const {
;     ...
;         for (int ai = 0; ai < 2; ++ai)
; #pragma unroll
;             for (int m = 0; m < 4; ++m)
; #pragma unroll
;                 for (int bj = 0; bj < 2; ++bj) { op(row0 + ai * 128 + m * 16, col0 + bj * 128, acc[ai][bj][m][0], acc[ai][bj][m][1]); asm volatile("" ::: "memory"); }
;     __device__ __forceinline__ void operator()(int row, int col, f32x4 v0, f32x4 v1) const {
;         const f32x4 b0 = *(const f32x4*)(a0 + col), b1 = *(const f32x4*)(a0 + col + 4);
;         v0 = sig4(v0 + b0); v1 = sig4(v1 + b1);
;         bf16_t* dst = (col < 1024 ? A0 : A1) + (size_t)row * 1024 + (col & 1023);
;         *(u32x4*)dst = pack8(v0, v1);
	v_pk_add_f32 v[42:43], v[42:43], v[52:53]
	v_pk_add_f32 v[46:47], v[46:47], v[56:57]
	v_pk_add_f32 v[48:49], v[48:49], v[58:59]
	v_mul_f32_e32 v46, 0xbfb8aa3b, v46
	v_mul_f32_e32 v47, 0xbfb8aa3b, v47
	v_exp_f32_e32 v46, v46
	v_exp_f32_e32 v47, v47
	v_mul_f32_e32 v42, 0xbfb8aa3b, v42
	v_mul_f32_e32 v43, 0xbfb8aa3b, v43
	v_exp_f32_e32 v42, v42
	v_pk_add_f32 v[46:47], v[46:47], 1.0 op_sel_hi:[1,0]
	v_exp_f32_e32 v43, v43
	v_rcp_f32_e32 v57, v47
	v_pk_add_f32 v[42:43], v[42:43], 1.0 op_sel_hi:[1,0]
	v_pk_add_f32 v[44:45], v[44:45], v[54:55]
	v_fma_f32 v58, -v47, v57, 1.0
	v_fmac_f32_e32 v57, v58, v57
	v_fma_f32 v60, -v47, v57, 1.0
	v_fma_f32 v59, v60, v57, v57
	v_fma_f32 v56, -v47, v59, 1.0
	v_fma_f32 v56, v56, v57, v59
	v_div_fixup_f32 v56, v56, v47, 1.0
	v_rcp_f32_e32 v57, v46
	s_nop 0
	v_fma_f32 v58, -v46, v57, 1.0
	v_fmac_f32_e32 v57, v58, v57
	v_fma_f32 v60, -v46, v57, 1.0
	v_fma_f32 v59, v60, v57, v57
	v_fma_f32 v47, -v46, v59, 1.0
	v_fma_f32 v47, v47, v57, v59
	v_div_fixup_f32 v57, v47, v46, 1.0
	v_mul_f32_e32 v46, 0xbfb8aa3b, v48
	v_mul_f32_e32 v47, 0xbfb8aa3b, v49
	v_exp_f32_e32 v46, v46
	v_exp_f32_e32 v47, v47
	s_nop 0
	v_pk_add_f32 v[46:47], v[46:47], 1.0 op_sel_hi:[1,0]
	s_nop 0
	v_rcp_f32_e32 v49, v47
	s_nop 0
	v_fma_f32 v58, -v47, v49, 1.0
	v_fmac_f32_e32 v49, v58, v49
	v_fma_f32 v60, -v47, v49, 1.0
	v_fma_f32 v59, v60, v49, v49
	v_fma_f32 v48, -v47, v59, 1.0
	v_fma_f32 v48, v48, v49, v59
	v_div_fixup_f32 v48, v48, v47, 1.0
	v_rcp_f32_e32 v49, v46
	s_nop 0
	v_fma_f32 v58, -v46, v49, 1.0
	v_fmac_f32_e32 v49, v58, v49
	v_fma_f32 v60, -v46, v49, 1.0
	v_fma_f32 v59, v60, v49, v49
	v_fma_f32 v47, -v46, v59, 1.0
	v_fma_f32 v47, v47, v49, v59
	v_div_fixup_f32 v49, v47, v46, 1.0
	v_rcp_f32_e32 v47, v43
	s_nop 0
	v_fma_f32 v52, -v43, v47, 1.0
	v_fmac_f32_e32 v47, v52, v47
	v_fma_f32 v54, -v43, v47, 1.0
	v_fma_f32 v53, v54, v47, v47
	v_fma_f32 v46, -v43, v53, 1.0
	v_fma_f32 v46, v46, v47, v53
	v_div_fixup_f32 v52, v46, v43, 1.0
	v_rcp_f32_e32 v46, v42
	s_nop 0
	v_fma_f32 v47, -v42, v46, 1.0
	v_fmac_f32_e32 v46, v47, v46
	v_fma_f32 v54, -v42, v46, 1.0
	v_fma_f32 v53, v54, v46, v46
	v_fma_f32 v43, -v42, v53, 1.0
	v_fma_f32 v43, v43, v46, v53
	v_div_fixup_f32 v53, v43, v42, 1.0
	v_mul_f32_e32 v42, 0xbfb8aa3b, v44
	v_mul_f32_e32 v43, 0xbfb8aa3b, v45
	v_exp_f32_e32 v42, v42
	v_exp_f32_e32 v43, v43
	s_nop 0
	v_pk_add_f32 v[42:43], v[42:43], 1.0 op_sel_hi:[1,0]
	s_nop 0
	v_rcp_f32_e32 v45, v43
	s_nop 0
	v_fma_f32 v46, -v43, v45, 1.0
	v_fmac_f32_e32 v45, v46, v45
	v_fma_f32 v54, -v43, v45, 1.0
	v_fma_f32 v47, v54, v45, v45
	v_fma_f32 v44, -v43, v47, 1.0
	v_fma_f32 v44, v44, v45, v47
	v_div_fixup_f32 v45, v44, v43, 1.0
	v_rcp_f32_e32 v44, v42
	s_nop 0
	v_fma_f32 v46, -v42, v44, 1.0
	v_fmac_f32_e32 v44, v46, v44
	v_fma_f32 v54, -v42, v44, 1.0
	v_fma_f32 v47, v54, v44, v44
	v_fma_f32 v43, -v42, v47, 1.0
	v_fma_f32 v43, v43, v44, v47
	v_div_fixup_f32 v54, v43, v42, 1.0
	v_lshl_add_u64 v[42:43], v[126:127], 0, v[50:51]
	v_lshl_add_u64 v[46:47], v[42:43], 0, v[0:1]
	v_cvt_pk_bf16_f32 v42, v57, v56
	v_cvt_pk_bf16_f32 v43, v49, v48
	v_cvt_pk_bf16_f32 v44, v53, v52
	v_cvt_pk_bf16_f32 v45, v54, v45
	global_store_dwordx4 v[46:47], v[42:45], off
	global_load_dwordx4 v[42:45], v[146:147], off offset:528
	global_load_dwordx4 v[46:49], v[146:147], off offset:512
	s_waitcnt vmcnt(0)
	v_pk_add_f32 v[34:35], v[34:35], v[42:43]
	v_pk_add_f32 v[38:39], v[38:39], v[46:47]
	v_pk_add_f32 v[40:41], v[40:41], v[48:49]
	v_mul_f32_e32 v38, 0xbfb8aa3b, v38
	v_mul_f32_e32 v39, 0xbfb8aa3b, v39
	v_exp_f32_e32 v38, v38
	v_exp_f32_e32 v39, v39
	v_mul_f32_e32 v34, 0xbfb8aa3b, v34
	v_mul_f32_e32 v35, 0xbfb8aa3b, v35
	v_exp_f32_e32 v34, v34
	v_pk_add_f32 v[38:39], v[38:39], 1.0 op_sel_hi:[1,0]
	v_exp_f32_e32 v35, v35
	v_rcp_f32_e32 v47, v39
	v_pk_add_f32 v[34:35], v[34:35], 1.0 op_sel_hi:[1,0]
	v_pk_add_f32 v[36:37], v[36:37], v[44:45]
	v_fma_f32 v48, -v39, v47, 1.0
	v_fmac_f32_e32 v47, v48, v47
	v_fma_f32 v52, -v39, v47, 1.0
	v_fma_f32 v49, v52, v47, v47
	v_fma_f32 v46, -v39, v49, 1.0
	v_fma_f32 v46, v46, v47, v49
	v_div_fixup_f32 v46, v46, v39, 1.0
	v_rcp_f32_e32 v47, v38
	s_nop 0
	v_fma_f32 v48, -v38, v47, 1.0
	v_fmac_f32_e32 v47, v48, v47
	v_fma_f32 v52, -v38, v47, 1.0
	v_fma_f32 v49, v52, v47, v47
	v_fma_f32 v39, -v38, v49, 1.0
	v_fma_f32 v39, v39, v47, v49
	v_div_fixup_f32 v47, v39, v38, 1.0
	v_mul_f32_e32 v38, 0xbfb8aa3b, v40
	v_mul_f32_e32 v39, 0xbfb8aa3b, v41
	v_exp_f32_e32 v38, v38
	v_exp_f32_e32 v39, v39
	s_nop 0
	v_pk_add_f32 v[38:39], v[38:39], 1.0 op_sel_hi:[1,0]
	s_nop 0
	v_rcp_f32_e32 v41, v39
	s_nop 0
	v_fma_f32 v48, -v39, v41, 1.0
	v_fmac_f32_e32 v41, v48, v41
	v_fma_f32 v52, -v39, v41, 1.0
	v_fma_f32 v49, v52, v41, v41
	v_fma_f32 v40, -v39, v49, 1.0
	v_fma_f32 v40, v40, v41, v49
	v_div_fixup_f32 v40, v40, v39, 1.0
	v_rcp_f32_e32 v41, v38
	s_nop 0
	v_fma_f32 v48, -v38, v41, 1.0
	v_fmac_f32_e32 v41, v48, v41
	v_fma_f32 v52, -v38, v41, 1.0
	v_fma_f32 v49, v52, v41, v41
	v_fma_f32 v39, -v38, v49, 1.0
	v_fma_f32 v39, v39, v41, v49
	v_div_fixup_f32 v41, v39, v38, 1.0
	v_rcp_f32_e32 v39, v35
	s_nop 0
	v_fma_f32 v42, -v35, v39, 1.0
	v_fmac_f32_e32 v39, v42, v39
	v_fma_f32 v44, -v35, v39, 1.0
	v_fma_f32 v43, v44, v39, v39
	v_fma_f32 v38, -v35, v43, 1.0
	v_fma_f32 v38, v38, v39, v43
	v_div_fixup_f32 v42, v38, v35, 1.0
	v_rcp_f32_e32 v38, v34
	s_nop 0
	v_fma_f32 v39, -v34, v38, 1.0
	v_fmac_f32_e32 v38, v39, v38
	v_fma_f32 v44, -v34, v38, 1.0
	v_fma_f32 v43, v44, v38, v38
	v_fma_f32 v35, -v34, v43, 1.0
	v_fma_f32 v35, v35, v38, v43
	v_div_fixup_f32 v43, v35, v34, 1.0
	v_mul_f32_e32 v34, 0xbfb8aa3b, v36
	v_mul_f32_e32 v35, 0xbfb8aa3b, v37
	v_exp_f32_e32 v34, v34
	v_exp_f32_e32 v35, v35
	s_nop 0
	v_pk_add_f32 v[34:35], v[34:35], 1.0 op_sel_hi:[1,0]
	s_nop 0
	v_rcp_f32_e32 v37, v35
	s_nop 0
	v_fma_f32 v38, -v35, v37, 1.0
	v_fmac_f32_e32 v37, v38, v37
	v_fma_f32 v44, -v35, v37, 1.0
	v_fma_f32 v39, v44, v37, v37
	v_fma_f32 v36, -v35, v39, 1.0
	v_fma_f32 v36, v36, v37, v39
	v_div_fixup_f32 v37, v36, v35, 1.0
	v_rcp_f32_e32 v36, v34
	s_mov_b64 s[4:5], 0x50000
	v_fma_f32 v38, -v34, v36, 1.0
	v_fmac_f32_e32 v36, v38, v36
	v_fma_f32 v44, -v34, v36, 1.0
	v_fma_f32 v39, v44, v36, v36
	v_fma_f32 v35, -v34, v39, 1.0
	v_fma_f32 v35, v35, v36, v39
	v_div_fixup_f32 v44, v35, v34, 1.0
	v_lshl_add_u64 v[34:35], v[118:119], 0, v[50:51]
	v_lshl_add_u64 v[38:39], v[34:35], 0, v[120:121]
	v_cvt_pk_bf16_f32 v34, v47, v46
	v_cvt_pk_bf16_f32 v35, v41, v40
	v_cvt_pk_bf16_f32 v36, v43, v42
	v_cvt_pk_bf16_f32 v37, v44, v37
	global_store_dwordx4 v[38:39], v[34:37], off
	global_load_dwordx4 v[36:39], v[146:147], off offset:16
	global_load_dwordx4 v[40:43], v[146:147], off
	v_lshl_add_u64 v[34:35], v[148:149], 0, s[4:5]
	s_waitcnt vmcnt(0)
; __device__ __forceinline__ u32x4 pack8(f32x4 v0, f32x4 v1) { u32x4 o; o.x = pkbf(v0.x, v0.y); o.y = pkbf(v0.z, v0.w); o.z = pkbf(v1.x, v1.y); o.w = pkbf(v1.z, v1.w); return o; }
; __device__ __forceinline__ f32x4 sig4(f32x4 v) { return (f32x4){sigmoidf_(v.x), sigmoidf_(v.y), sigmoidf_(v.z), sigmoidf_(v.w)}; }
;     __device__ __forceinline__ void operator()(int row, int col, f32x4 v0, f32x4 v1) const { *(u32x4*)(G + (size_t)row * 1024 + col) = pack8(v0, v1); }
;     __device__ __forceinline__ void operator()(const pg8::f32x4 (&acc)[2][2][4][2], const pg8::Unit& u, int wr, int wc, int fr, int fq) const {
;     ...
;         for (int ai = 0; ai < 2; ++ai)
; #pragma unroll
;             for (int m = 0; m < 4; ++m)
; #pragma unroll
;                 for (int bj = 0; bj < 2; ++bj) { op(row0 + ai * 128 + m * 16, col0 + bj * 128, acc[ai][bj][m][0], acc[ai][bj][m][1]); asm volatile("" ::: "memory"); }
;     __device__ __forceinline__ void operator()(int row, int col, f32x4 v0, f32x4 v1) const {
;         const f32x4 b0 = *(const f32x4*)(a0 + col), b1 = *(const f32x4*)(a0 + col + 4);
;         v0 = sig4(v0 + b0); v1 = sig4(v1 + b1);
;         bf16_t* dst = (col < 1024 ? A0 : A1) + (size_t)row * 1024 + (col & 1023);
;         *(u32x4*)dst = pack8(v0, v1);
	v_pk_add_f32 v[26:27], v[26:27], v[36:37]
	v_pk_add_f32 v[30:31], v[30:31], v[40:41]
	v_pk_add_f32 v[32:33], v[32:33], v[42:43]
	v_mul_f32_e32 v30, 0xbfb8aa3b, v30
	v_mul_f32_e32 v31, 0xbfb8aa3b, v31
	v_exp_f32_e32 v30, v30
	v_exp_f32_e32 v31, v31
	v_mul_f32_e32 v26, 0xbfb8aa3b, v26
	v_mul_f32_e32 v27, 0xbfb8aa3b, v27
	v_exp_f32_e32 v26, v26
	v_pk_add_f32 v[30:31], v[30:31], 1.0 op_sel_hi:[1,0]
	v_exp_f32_e32 v27, v27
	v_rcp_f32_e32 v41, v31
	v_pk_add_f32 v[26:27], v[26:27], 1.0 op_sel_hi:[1,0]
	v_pk_add_f32 v[28:29], v[28:29], v[38:39]
	v_fma_f32 v42, -v31, v41, 1.0
	v_fmac_f32_e32 v41, v42, v41
	v_fma_f32 v44, -v31, v41, 1.0
	v_fma_f32 v43, v44, v41, v41
	v_fma_f32 v40, -v31, v43, 1.0
	v_fma_f32 v40, v40, v41, v43
	v_div_fixup_f32 v40, v40, v31, 1.0
	v_rcp_f32_e32 v41, v30
	s_nop 0
	v_fma_f32 v42, -v30, v41, 1.0
	v_fmac_f32_e32 v41, v42, v41
	v_fma_f32 v44, -v30, v41, 1.0
	v_fma_f32 v43, v44, v41, v41
	v_fma_f32 v31, -v30, v43, 1.0
	v_fma_f32 v31, v31, v41, v43
	v_div_fixup_f32 v41, v31, v30, 1.0
	v_mul_f32_e32 v30, 0xbfb8aa3b, v32
	v_mul_f32_e32 v31, 0xbfb8aa3b, v33
	v_exp_f32_e32 v30, v30
	v_exp_f32_e32 v31, v31
	s_nop 0
	v_pk_add_f32 v[30:31], v[30:31], 1.0 op_sel_hi:[1,0]
	s_nop 0
	v_rcp_f32_e32 v33, v31
	s_nop 0
	v_fma_f32 v42, -v31, v33, 1.0
	v_fmac_f32_e32 v33, v42, v33
	v_fma_f32 v44, -v31, v33, 1.0
	v_fma_f32 v43, v44, v33, v33
	v_fma_f32 v32, -v31, v43, 1.0
	v_fma_f32 v32, v32, v33, v43
	v_div_fixup_f32 v32, v32, v31, 1.0
	v_rcp_f32_e32 v33, v30
	s_nop 0
	v_fma_f32 v42, -v30, v33, 1.0
	v_fmac_f32_e32 v33, v42, v33
	v_fma_f32 v44, -v30, v33, 1.0
	v_fma_f32 v43, v44, v33, v33
	v_fma_f32 v31, -v30, v43, 1.0
	v_fma_f32 v31, v31, v33, v43
	v_div_fixup_f32 v33, v31, v30, 1.0
	v_rcp_f32_e32 v31, v27
	s_nop 0
	v_fma_f32 v36, -v27, v31, 1.0
	v_fmac_f32_e32 v31, v36, v31
	v_fma_f32 v38, -v27, v31, 1.0
	v_fma_f32 v37, v38, v31, v31
	v_fma_f32 v30, -v27, v37, 1.0
	v_fma_f32 v30, v30, v31, v37
	v_div_fixup_f32 v36, v30, v27, 1.0
	v_rcp_f32_e32 v30, v26
	s_nop 0
	v_fma_f32 v31, -v26, v30, 1.0
	v_fmac_f32_e32 v30, v31, v30
	v_fma_f32 v38, -v26, v30, 1.0
	v_fma_f32 v37, v38, v30, v30
	v_fma_f32 v27, -v26, v37, 1.0
	v_fma_f32 v27, v27, v30, v37
	v_div_fixup_f32 v37, v27, v26, 1.0
	v_mul_f32_e32 v26, 0xbfb8aa3b, v28
	v_mul_f32_e32 v27, 0xbfb8aa3b, v29
	v_exp_f32_e32 v26, v26
	v_exp_f32_e32 v27, v27
	s_nop 0
	v_pk_add_f32 v[26:27], v[26:27], 1.0 op_sel_hi:[1,0]
	s_nop 0
	v_rcp_f32_e32 v29, v27
	s_nop 0
	v_fma_f32 v30, -v27, v29, 1.0
	v_fmac_f32_e32 v29, v30, v29
	v_fma_f32 v38, -v27, v29, 1.0
	v_fma_f32 v31, v38, v29, v29
	v_fma_f32 v28, -v27, v31, 1.0
	v_fma_f32 v28, v28, v29, v31
	v_div_fixup_f32 v29, v28, v27, 1.0
	v_rcp_f32_e32 v28, v26
	s_nop 0
	v_fma_f32 v30, -v26, v28, 1.0
	v_fmac_f32_e32 v28, v30, v28
	v_fma_f32 v38, -v26, v28, 1.0
	v_fma_f32 v31, v38, v28, v28
	v_fma_f32 v27, -v26, v31, 1.0
	v_fma_f32 v27, v27, v28, v31
	v_div_fixup_f32 v38, v27, v26, 1.0
	v_lshl_add_u64 v[26:27], v[126:127], 0, v[34:35]
	v_lshl_add_u64 v[30:31], v[26:27], 0, v[0:1]
	v_cvt_pk_bf16_f32 v26, v41, v40
	v_cvt_pk_bf16_f32 v27, v33, v32
	v_cvt_pk_bf16_f32 v28, v37, v36
	v_cvt_pk_bf16_f32 v29, v38, v29
	global_store_dwordx4 v[30:31], v[26:29], off
	global_load_dwordx4 v[26:29], v[146:147], off offset:528
	global_load_dwordx4 v[30:33], v[146:147], off offset:512
	s_waitcnt vmcnt(0)
	v_pk_add_f32 v[18:19], v[18:19], v[26:27]
	v_pk_add_f32 v[22:23], v[22:23], v[30:31]
	v_pk_add_f32 v[24:25], v[24:25], v[32:33]
	v_mul_f32_e32 v22, 0xbfb8aa3b, v22
	v_mul_f32_e32 v23, 0xbfb8aa3b, v23
	v_exp_f32_e32 v22, v22
	v_exp_f32_e32 v23, v23
	v_mul_f32_e32 v18, 0xbfb8aa3b, v18
	v_mul_f32_e32 v19, 0xbfb8aa3b, v19
	v_exp_f32_e32 v18, v18
	v_pk_add_f32 v[22:23], v[22:23], 1.0 op_sel_hi:[1,0]
	v_exp_f32_e32 v19, v19
	v_rcp_f32_e32 v31, v23
	v_pk_add_f32 v[18:19], v[18:19], 1.0 op_sel_hi:[1,0]
	v_pk_add_f32 v[20:21], v[20:21], v[28:29]
	v_fma_f32 v32, -v23, v31, 1.0
	v_fmac_f32_e32 v31, v32, v31
	v_fma_f32 v36, -v23, v31, 1.0
	v_fma_f32 v33, v36, v31, v31
	v_fma_f32 v30, -v23, v33, 1.0
	v_fma_f32 v30, v30, v31, v33
	v_div_fixup_f32 v30, v30, v23, 1.0
	v_rcp_f32_e32 v31, v22
	s_nop 0
	v_fma_f32 v32, -v22, v31, 1.0
	v_fmac_f32_e32 v31, v32, v31
	v_fma_f32 v36, -v22, v31, 1.0
	v_fma_f32 v33, v36, v31, v31
	v_fma_f32 v23, -v22, v33, 1.0
	v_fma_f32 v23, v23, v31, v33
	v_div_fixup_f32 v31, v23, v22, 1.0
	v_mul_f32_e32 v22, 0xbfb8aa3b, v24
	v_mul_f32_e32 v23, 0xbfb8aa3b, v25
	v_exp_f32_e32 v22, v22
	v_exp_f32_e32 v23, v23
	s_nop 0
	v_pk_add_f32 v[22:23], v[22:23], 1.0 op_sel_hi:[1,0]
	s_nop 0
	v_rcp_f32_e32 v25, v23
	s_nop 0
	v_fma_f32 v32, -v23, v25, 1.0
	v_fmac_f32_e32 v25, v32, v25
	v_fma_f32 v36, -v23, v25, 1.0
	v_fma_f32 v33, v36, v25, v25
	v_fma_f32 v24, -v23, v33, 1.0
	v_fma_f32 v24, v24, v25, v33
	v_div_fixup_f32 v24, v24, v23, 1.0
	v_rcp_f32_e32 v25, v22
	s_nop 0
	v_fma_f32 v32, -v22, v25, 1.0
	v_fmac_f32_e32 v25, v32, v25
	v_fma_f32 v36, -v22, v25, 1.0
	v_fma_f32 v33, v36, v25, v25
	v_fma_f32 v23, -v22, v33, 1.0
	v_fma_f32 v23, v23, v25, v33
	v_div_fixup_f32 v25, v23, v22, 1.0
	v_rcp_f32_e32 v23, v19
	s_nop 0
	v_fma_f32 v26, -v19, v23, 1.0
	v_fmac_f32_e32 v23, v26, v23
	v_fma_f32 v28, -v19, v23, 1.0
	v_fma_f32 v27, v28, v23, v23
	v_fma_f32 v22, -v19, v27, 1.0
	v_fma_f32 v22, v22, v23, v27
	v_div_fixup_f32 v26, v22, v19, 1.0
	v_rcp_f32_e32 v22, v18
	s_nop 0
	v_fma_f32 v23, -v18, v22, 1.0
	v_fmac_f32_e32 v22, v23, v22
	v_fma_f32 v28, -v18, v22, 1.0
	v_fma_f32 v27, v28, v22, v22
	v_fma_f32 v19, -v18, v27, 1.0
	v_fma_f32 v19, v19, v22, v27
	v_div_fixup_f32 v27, v19, v18, 1.0
	v_mul_f32_e32 v18, 0xbfb8aa3b, v20
	v_mul_f32_e32 v19, 0xbfb8aa3b, v21
	v_exp_f32_e32 v18, v18
	v_exp_f32_e32 v19, v19
	s_nop 0
	v_pk_add_f32 v[18:19], v[18:19], 1.0 op_sel_hi:[1,0]
	s_nop 0
	v_rcp_f32_e32 v21, v19
	s_nop 0
	v_fma_f32 v22, -v19, v21, 1.0
	v_fmac_f32_e32 v21, v22, v21
	v_fma_f32 v28, -v19, v21, 1.0
	v_fma_f32 v23, v28, v21, v21
	v_fma_f32 v20, -v19, v23, 1.0
	v_fma_f32 v20, v20, v21, v23
	v_div_fixup_f32 v21, v20, v19, 1.0
	v_rcp_f32_e32 v20, v18
	s_mov_b64 s[4:5], 0x58000
	v_fma_f32 v22, -v18, v20, 1.0
	v_fmac_f32_e32 v20, v22, v20
	v_fma_f32 v28, -v18, v20, 1.0
	v_fma_f32 v23, v28, v20, v20
	v_fma_f32 v19, -v18, v23, 1.0
	v_fma_f32 v19, v19, v20, v23
	v_div_fixup_f32 v28, v19, v18, 1.0
	v_lshl_add_u64 v[18:19], v[118:119], 0, v[34:35]
	v_lshl_add_u64 v[22:23], v[18:19], 0, v[120:121]
	v_cvt_pk_bf16_f32 v18, v31, v30
	v_cvt_pk_bf16_f32 v19, v25, v24
	v_cvt_pk_bf16_f32 v20, v27, v26
	v_cvt_pk_bf16_f32 v21, v28, v21
	global_store_dwordx4 v[22:23], v[18:21], off
	global_load_dwordx4 v[20:23], v[146:147], off offset:16
	global_load_dwordx4 v[24:27], v[146:147], off
	v_lshl_add_u64 v[18:19], v[148:149], 0, s[4:5]
	s_waitcnt vmcnt(0)
; __device__ __forceinline__ float sigmoidf_(float x) { return 1.f / (1.f + __expf(-x)); }
; __device__ __forceinline__ u32x4 pack8(f32x4 v0, f32x4 v1) { u32x4 o; o.x = pkbf(v0.x, v0.y); o.y = pkbf(v0.z, v0.w); o.z = pkbf(v1.x, v1.y); o.w = pkbf(v1.z, v1.w); return o; }
;     __device__ __forceinline__ void operator()(int row, int col, f32x4 v0, f32x4 v1) const { *(u32x4*)(G + (size_t)row * 1024 + col) = pack8(v0, v1); }
; __device__ __forceinline__ f32x4 sig4(f32x4 v) { return (f32x4){sigmoidf_(v.x), sigmoidf_(v.y), sigmoidf_(v.z), sigmoidf_(v.w)}; }
;     __device__ __forceinline__ void operator()(int row, int col, f32x4 v0, f32x4 v1) const {
;         const f32x4 b0 = *(const f32x4*)(a0 + col), b1 = *(const f32x4*)(a0 + col + 4);
;         v0 = sig4(v0 + b0); v1 = sig4(v1 + b1);
;         bf16_t* dst = (col < 1024 ? A0 : A1) + (size_t)row * 1024 + (col & 1023);
;         *(u32x4*)dst = pack8(v0, v1);
;     }
	v_pk_add_f32 v[10:11], v[10:11], v[20:21]
	v_pk_add_f32 v[14:15], v[14:15], v[24:25]
	v_pk_add_f32 v[16:17], v[16:17], v[26:27]
	v_mul_f32_e32 v14, 0xbfb8aa3b, v14
	v_mul_f32_e32 v15, 0xbfb8aa3b, v15
	v_exp_f32_e32 v14, v14
	v_exp_f32_e32 v15, v15
	v_mul_f32_e32 v10, 0xbfb8aa3b, v10
	v_mul_f32_e32 v11, 0xbfb8aa3b, v11
	v_exp_f32_e32 v10, v10
	v_pk_add_f32 v[14:15], v[14:15], 1.0 op_sel_hi:[1,0]
	v_exp_f32_e32 v11, v11
	v_rcp_f32_e32 v25, v15
	v_pk_add_f32 v[10:11], v[10:11], 1.0 op_sel_hi:[1,0]
	v_pk_add_f32 v[12:13], v[12:13], v[22:23]
	v_fma_f32 v26, -v15, v25, 1.0
	v_fmac_f32_e32 v25, v26, v25
	v_fma_f32 v28, -v15, v25, 1.0
	v_fma_f32 v27, v28, v25, v25
	v_fma_f32 v24, -v15, v27, 1.0
	v_fma_f32 v24, v24, v25, v27
	v_div_fixup_f32 v24, v24, v15, 1.0
	v_rcp_f32_e32 v25, v14
	s_nop 0
	v_fma_f32 v26, -v14, v25, 1.0
	v_fmac_f32_e32 v25, v26, v25
	v_fma_f32 v28, -v14, v25, 1.0
	v_fma_f32 v27, v28, v25, v25
	v_fma_f32 v15, -v14, v27, 1.0
	v_fma_f32 v15, v15, v25, v27
	v_div_fixup_f32 v25, v15, v14, 1.0
	v_mul_f32_e32 v14, 0xbfb8aa3b, v16
	v_mul_f32_e32 v15, 0xbfb8aa3b, v17
	v_exp_f32_e32 v14, v14
	v_exp_f32_e32 v15, v15
	s_nop 0
	v_pk_add_f32 v[14:15], v[14:15], 1.0 op_sel_hi:[1,0]
	s_nop 0
	v_rcp_f32_e32 v17, v15
	s_nop 0
	v_fma_f32 v26, -v15, v17, 1.0
	v_fmac_f32_e32 v17, v26, v17
	v_fma_f32 v28, -v15, v17, 1.0
	v_fma_f32 v27, v28, v17, v17
	v_fma_f32 v16, -v15, v27, 1.0
	v_fma_f32 v16, v16, v17, v27
	v_div_fixup_f32 v16, v16, v15, 1.0
	v_rcp_f32_e32 v17, v14
	s_nop 0
	v_fma_f32 v26, -v14, v17, 1.0
	v_fmac_f32_e32 v17, v26, v17
	v_fma_f32 v28, -v14, v17, 1.0
	v_fma_f32 v27, v28, v17, v17
	v_fma_f32 v15, -v14, v27, 1.0
	v_fma_f32 v15, v15, v17, v27
	v_div_fixup_f32 v17, v15, v14, 1.0
	v_rcp_f32_e32 v15, v11
	s_nop 0
	v_fma_f32 v20, -v11, v15, 1.0
	v_fmac_f32_e32 v15, v20, v15
	v_fma_f32 v22, -v11, v15, 1.0
	v_fma_f32 v21, v22, v15, v15
	v_fma_f32 v14, -v11, v21, 1.0
	v_fma_f32 v14, v14, v15, v21
	v_div_fixup_f32 v20, v14, v11, 1.0
	v_rcp_f32_e32 v14, v10
	s_nop 0
	v_fma_f32 v15, -v10, v14, 1.0
	v_fmac_f32_e32 v14, v15, v14
	v_fma_f32 v22, -v10, v14, 1.0
	v_fma_f32 v21, v22, v14, v14
	v_fma_f32 v11, -v10, v21, 1.0
	v_fma_f32 v11, v11, v14, v21
	v_div_fixup_f32 v21, v11, v10, 1.0
	v_mul_f32_e32 v10, 0xbfb8aa3b, v12
	v_mul_f32_e32 v11, 0xbfb8aa3b, v13
	v_exp_f32_e32 v10, v10
	v_exp_f32_e32 v11, v11
	s_nop 0
	v_pk_add_f32 v[10:11], v[10:11], 1.0 op_sel_hi:[1,0]
	s_nop 0
	v_rcp_f32_e32 v13, v11
	s_nop 0
	v_fma_f32 v14, -v11, v13, 1.0
	v_fmac_f32_e32 v13, v14, v13
	v_fma_f32 v22, -v11, v13, 1.0
	v_fma_f32 v15, v22, v13, v13
	v_fma_f32 v12, -v11, v15, 1.0
	v_fma_f32 v12, v12, v13, v15
	v_div_fixup_f32 v13, v12, v11, 1.0
	v_rcp_f32_e32 v12, v10
	s_nop 0
	v_fma_f32 v14, -v10, v12, 1.0
	v_fmac_f32_e32 v12, v14, v12
	v_fma_f32 v22, -v10, v12, 1.0
	v_fma_f32 v15, v22, v12, v12
	v_fma_f32 v11, -v10, v15, 1.0
	v_fma_f32 v11, v11, v12, v15
	v_div_fixup_f32 v22, v11, v10, 1.0
	v_lshl_add_u64 v[10:11], v[126:127], 0, v[18:19]
	v_lshl_add_u64 v[14:15], v[10:11], 0, v[0:1]
	v_cvt_pk_bf16_f32 v10, v25, v24
	v_cvt_pk_bf16_f32 v11, v17, v16
	v_cvt_pk_bf16_f32 v12, v21, v20
	v_cvt_pk_bf16_f32 v13, v22, v13
	global_store_dwordx4 v[14:15], v[10:13], off
	global_load_dwordx4 v[10:13], v[146:147], off offset:528
	global_load_dwordx4 v[14:17], v[146:147], off offset:512
	s_waitcnt vmcnt(0)
	v_pk_add_f32 v[2:3], v[2:3], v[10:11]
	v_pk_add_f32 v[6:7], v[6:7], v[14:15]
	v_pk_add_f32 v[8:9], v[8:9], v[16:17]
	v_mul_f32_e32 v0, 0xbfb8aa3b, v6
	v_exp_f32_e32 v6, v0
	v_mul_f32_e32 v0, 0xbfb8aa3b, v7
	v_exp_f32_e32 v7, v0
	v_mul_f32_e32 v2, 0xbfb8aa3b, v2
	v_mul_f32_e32 v3, 0xbfb8aa3b, v3
	v_exp_f32_e32 v2, v2
	v_pk_add_f32 v[6:7], v[6:7], 1.0 op_sel_hi:[1,0]
	v_exp_f32_e32 v3, v3
	v_rcp_f32_e32 v14, v7
	v_pk_add_f32 v[2:3], v[2:3], 1.0 op_sel_hi:[1,0]
	v_pk_add_f32 v[4:5], v[4:5], v[12:13]
	v_fma_f32 v15, -v7, v14, 1.0
	v_fmac_f32_e32 v14, v15, v14
	v_fma_f32 v17, -v7, v14, 1.0
	v_fma_f32 v16, v17, v14, v14
	v_fma_f32 v0, -v7, v16, 1.0
	v_fma_f32 v0, v0, v14, v16
	v_div_fixup_f32 v0, v0, v7, 1.0
	v_rcp_f32_e32 v14, v6
	s_nop 0
	v_fma_f32 v15, -v6, v14, 1.0
	v_fmac_f32_e32 v14, v15, v14
	v_fma_f32 v17, -v6, v14, 1.0
	v_fma_f32 v16, v17, v14, v14
	v_fma_f32 v7, -v6, v16, 1.0
	v_fma_f32 v7, v7, v14, v16
	v_div_fixup_f32 v14, v7, v6, 1.0
	v_mul_f32_e32 v6, 0xbfb8aa3b, v8
	v_mul_f32_e32 v7, 0xbfb8aa3b, v9
	v_exp_f32_e32 v6, v6
	v_exp_f32_e32 v7, v7
	s_nop 0
	v_pk_add_f32 v[6:7], v[6:7], 1.0 op_sel_hi:[1,0]
	s_nop 0
	v_rcp_f32_e32 v9, v7
	s_nop 0
	v_fma_f32 v15, -v7, v9, 1.0
	v_fmac_f32_e32 v9, v15, v9
	v_fma_f32 v17, -v7, v9, 1.0
	v_fma_f32 v16, v17, v9, v9
	v_fma_f32 v8, -v7, v16, 1.0
	v_fma_f32 v8, v8, v9, v16
	v_div_fixup_f32 v8, v8, v7, 1.0
	v_rcp_f32_e32 v9, v6
	s_nop 0
	v_fma_f32 v15, -v6, v9, 1.0
	v_fmac_f32_e32 v9, v15, v9
	v_fma_f32 v17, -v6, v9, 1.0
	v_fma_f32 v16, v17, v9, v9
	v_fma_f32 v7, -v6, v16, 1.0
	v_fma_f32 v7, v7, v9, v16
	v_div_fixup_f32 v9, v7, v6, 1.0
	v_rcp_f32_e32 v7, v3
	s_nop 0
	v_fma_f32 v10, -v3, v7, 1.0
	v_fmac_f32_e32 v7, v10, v7
	v_fma_f32 v12, -v3, v7, 1.0
	v_fma_f32 v11, v12, v7, v7
	v_fma_f32 v6, -v3, v11, 1.0
	v_fma_f32 v6, v6, v7, v11
	v_div_fixup_f32 v10, v6, v3, 1.0
	v_rcp_f32_e32 v6, v2
	s_nop 0
	v_fma_f32 v7, -v2, v6, 1.0
	v_fmac_f32_e32 v6, v7, v6
	v_fma_f32 v12, -v2, v6, 1.0
	v_fma_f32 v11, v12, v6, v6
	v_fma_f32 v3, -v2, v11, 1.0
	v_fma_f32 v3, v3, v6, v11
	v_div_fixup_f32 v11, v3, v2, 1.0
	v_mul_f32_e32 v2, 0xbfb8aa3b, v4
	v_mul_f32_e32 v3, 0xbfb8aa3b, v5
	v_exp_f32_e32 v2, v2
	v_exp_f32_e32 v3, v3
	s_nop 0
	v_pk_add_f32 v[2:3], v[2:3], 1.0 op_sel_hi:[1,0]
	s_nop 0
	v_rcp_f32_e32 v5, v3
	s_nop 0
	v_fma_f32 v6, -v3, v5, 1.0
	v_fmac_f32_e32 v5, v6, v5
	v_fma_f32 v12, -v3, v5, 1.0
	v_fma_f32 v7, v12, v5, v5
	v_fma_f32 v4, -v3, v7, 1.0
	v_fma_f32 v4, v4, v5, v7
	v_div_fixup_f32 v5, v4, v3, 1.0
	v_rcp_f32_e32 v4, v2
	s_mov_b64 s[4:5], -1
	v_fma_f32 v6, -v2, v4, 1.0
	v_fmac_f32_e32 v4, v6, v4
	v_fma_f32 v12, -v2, v4, 1.0
	v_fma_f32 v7, v12, v4, v4
	v_fma_f32 v3, -v2, v7, 1.0
	v_fma_f32 v3, v3, v4, v7
	v_div_fixup_f32 v12, v3, v2, 1.0
	v_lshl_add_u64 v[2:3], v[118:119], 0, v[18:19]
	v_lshl_add_u64 v[6:7], v[2:3], 0, v[120:121]
	v_cvt_pk_bf16_f32 v2, v14, v0
	v_cvt_pk_bf16_f32 v3, v9, v8
	v_cvt_pk_bf16_f32 v4, v11, v10
	v_cvt_pk_bf16_f32 v5, v12, v5
	global_store_dwordx4 v[6:7], v[2:5], off
	s_and_b64 vcc, exec, s[40:41]
	s_cbranch_vccnz .LBB0_393
	s_andn2_b64 vcc, exec, s[50:51]
	s_cbranch_vccnz .LBB0_392
	s_barrier
	s_branch .LBB0_392

; __device__ __forceinline__ u32x4 pack8(f32x4 v0, f32x4 v1) { u32x4 o; o.x = pkbf(v0.x, v0.y); o.y = pkbf(v0.z, v0.w); o.z = pkbf(v1.x, v1.y); o.w = pkbf(v1.z, v1.w); return o; }
; __device__ __forceinline__ f32x4 sig4(f32x4 v) { return (f32x4){sigmoidf_(v.x), sigmoidf_(v.y), sigmoidf_(v.z), sigmoidf_(v.w)}; }
; __device__ __forceinline__ void lora_in_rows(CArgs& a, int l, int gw, int ngw, int lane) {
;     ...
;     for (int row = gw; row < M; row += ngw) {
;         int t, Tn; if (row < ML) { t = row & 2047; Tn = 2048; } else { t = (row - ML) & 255; Tn = 256; }
;         const bool hp = t > 0, hn = t < Tn - 1;
;         if (lane < 52) {
;             const bf16_t* p = RW + (size_t)row * RWP + 3072 + 8 * lane;
;             f32x4 x0, x1, p0 = {0.f, 0.f, 0.f, 0.f}, p1 = p0, n0 = p0, n1 = p0;
;             unpack8(*(const u32x4*)p, x0, x1);
;             if (hp) unpack8(*(const u32x4*)(p - RWP), p0, p1);
;             if (hn) unpack8(*(const u32x4*)(p + RWP), n0, n1);
;             f32x4 z0 = x0 + m0 * (0.5f * (p0 + n0) - x0), z1 = x1 + m1 * (0.5f * (p1 + n1) - x1);
;             const int j = 8 * lane;
;             if (j < 128) { z0 = (f32x4){tanhf(z0.x), tanhf(z0.y), tanhf(z0.z), tanhf(z0.w)}; z1 = (f32x4){tanhf(z1.x), tanhf(z1.y), tanhf(z1.z), tanhf(z1.w)}; *(u32x4*)(LW + (size_t)row * 128 + j) = pack8(z0, z1); }
;             else if (j < 256) { *(u32x4*)(LA + (size_t)row * 128 + j - 128) = pack8(z0, z1); }
;             else { *(u32x4*)(LG + (size_t)row * 256 + j - 256) = pack8(sig4(z0), sig4(z1)); }
.LBB0_471:
	s_waitcnt vmcnt(0)
	v_lshlrev_b32_e32 v24, 16, v10
	v_and_b32_e32 v25, 0xffff0000, v10
	v_lshlrev_b32_e32 v10, 16, v11
	v_and_b32_e32 v11, 0xffff0000, v11
	v_pk_add_f32 v[14:15], v[14:15], v[28:29]
	v_xor_b32_e32 v29, 0x80000000, v25
	v_xor_b32_e32 v28, 0x80000000, v24
	v_lshlrev_b32_e32 v32, 16, v12
	v_and_b32_e32 v33, 0xffff0000, v12
	v_pk_add_f32 v[16:17], v[16:17], v[30:31]
	v_pk_fma_f32 v[28:29], v[14:15], 0.5, v[28:29] op_sel_hi:[1,0,1]
	v_xor_b32_e32 v15, 0x80000000, v11
	v_xor_b32_e32 v14, 0x80000000, v10
	v_lshlrev_b32_e32 v12, 16, v13
	v_and_b32_e32 v13, 0xffff0000, v13
	v_pk_fma_f32 v[14:15], v[16:17], 0.5, v[14:15] op_sel_hi:[1,0,1]
	v_pk_add_f32 v[18:19], v[20:21], v[18:19]
	v_xor_b32_e32 v21, 0x80000000, v33
	v_xor_b32_e32 v20, 0x80000000, v32
	v_pk_fma_f32 v[14:15], v[8:9], v[14:15], v[10:11]
	v_pk_add_f32 v[10:11], v[22:23], v[26:27]
	v_pk_fma_f32 v[18:19], v[18:19], 0.5, v[20:21] op_sel_hi:[1,0,1]
	v_xor_b32_e32 v21, 0x80000000, v13
	v_xor_b32_e32 v20, 0x80000000, v12
	v_pk_fma_f32 v[10:11], v[10:11], 0.5, v[20:21] op_sel_hi:[1,0,1]
	v_pk_fma_f32 v[16:17], v[6:7], v[28:29], v[24:25]
	v_pk_fma_f32 v[10:11], v[4:5], v[10:11], v[12:13]
	v_pk_fma_f32 v[12:13], v[2:3], v[18:19], v[32:33]
	s_and_saveexec_b64 s[4:5], s[42:43]
	s_xor_b64 s[4:5], exec, s[4:5]
	s_cbranch_execz .LBB0_477
	s_and_saveexec_b64 s[6:7], s[44:45]
	s_xor_b64 s[6:7], exec, s[6:7]
	s_cbranch_execz .LBB0_474
	v_mul_f32_e32 v16, 0xbfb8aa3b, v16
	v_mul_f32_e32 v17, 0xbfb8aa3b, v17
	v_exp_f32_e32 v16, v16
	v_exp_f32_e32 v17, v17
	v_mul_f32_e32 v14, 0xbfb8aa3b, v14
	v_mul_f32_e32 v15, 0xbfb8aa3b, v15
	v_exp_f32_e32 v14, v14
	v_pk_add_f32 v[16:17], v[16:17], 1.0 op_sel_hi:[1,0]
	v_exp_f32_e32 v15, v15
	v_rcp_f32_e32 v19, v17
	v_pk_add_f32 v[14:15], v[14:15], 1.0 op_sel_hi:[1,0]
	v_mul_f32_e32 v12, 0xbfb8aa3b, v12
	v_mul_f32_e32 v13, 0xbfb8aa3b, v13
	v_fma_f32 v20, -v17, v19, 1.0
	v_fmac_f32_e32 v19, v20, v19
	v_fma_f32 v22, -v17, v19, 1.0
	v_fma_f32 v21, v22, v19, v19
	v_fma_f32 v18, -v17, v21, 1.0
	v_fma_f32 v18, v18, v19, v21
	v_div_fixup_f32 v17, v18, v17, 1.0
	v_rcp_f32_e32 v19, v16
	v_exp_f32_e32 v12, v12
	v_exp_f32_e32 v13, v13
	v_mul_f32_e32 v10, 0xbfb8aa3b, v10
	v_fma_f32 v20, -v16, v19, 1.0
	v_fmac_f32_e32 v19, v20, v19
	v_fma_f32 v22, -v16, v19, 1.0
	v_fma_f32 v21, v22, v19, v19
	v_fma_f32 v18, -v16, v21, 1.0
	v_fma_f32 v18, v18, v19, v21
	v_div_fixup_f32 v16, v18, v16, 1.0
	v_rcp_f32_e32 v19, v15
	v_pk_add_f32 v[12:13], v[12:13], 1.0 op_sel_hi:[1,0]
	v_mul_f32_e32 v11, 0xbfb8aa3b, v11
	v_exp_f32_e32 v10, v10
	v_fma_f32 v20, -v15, v19, 1.0
	v_fmac_f32_e32 v19, v20, v19
	v_fma_f32 v22, -v15, v19, 1.0
	v_fma_f32 v21, v22, v19, v19
	v_fma_f32 v18, -v15, v21, 1.0
	v_fma_f32 v18, v18, v19, v21
	v_div_fixup_f32 v15, v18, v15, 1.0
	v_rcp_f32_e32 v19, v14
	v_exp_f32_e32 v11, v11
	v_fma_f32 v20, -v14, v19, 1.0
	v_fmac_f32_e32 v19, v20, v19
	v_fma_f32 v22, -v14, v19, 1.0
	v_fma_f32 v21, v22, v19, v19
	v_fma_f32 v18, -v14, v21, 1.0
	v_fma_f32 v18, v18, v19, v21
	v_div_fixup_f32 v14, v18, v14, 1.0
	v_rcp_f32_e32 v19, v13
	v_pk_add_f32 v[10:11], v[10:11], 1.0 op_sel_hi:[1,0]
	v_fma_f32 v20, -v13, v19, 1.0
	v_fmac_f32_e32 v19, v20, v19
	v_fma_f32 v22, -v13, v19, 1.0
	v_fma_f32 v21, v22, v19, v19
	v_fma_f32 v18, -v13, v21, 1.0
	v_fma_f32 v18, v18, v19, v21
	v_div_fixup_f32 v13, v18, v13, 1.0
	v_rcp_f32_e32 v19, v12
	s_nop 0
	v_fma_f32 v20, -v12, v19, 1.0
	v_fmac_f32_e32 v19, v20, v19
	v_fma_f32 v22, -v12, v19, 1.0
	v_fma_f32 v21, v22, v19, v19
	v_fma_f32 v18, -v12, v21, 1.0
	v_fma_f32 v18, v18, v19, v21
	v_div_fixup_f32 v12, v18, v12, 1.0
	v_rcp_f32_e32 v19, v11
	v_cvt_pk_bf16_f32 v12, v12, v13
	v_fma_f32 v20, -v11, v19, 1.0
	v_fmac_f32_e32 v19, v20, v19
	v_fma_f32 v22, -v11, v19, 1.0
	v_fma_f32 v21, v22, v19, v19
	v_fma_f32 v18, -v11, v21, 1.0
	v_fma_f32 v18, v18, v19, v21
	v_div_fixup_f32 v18, v18, v11, 1.0
	v_rcp_f32_e32 v19, v10
	s_nop 0
	v_fma_f32 v20, -v10, v19, 1.0
	v_fmac_f32_e32 v19, v20, v19
	v_fma_f32 v22, -v10, v19, 1.0
	v_fma_f32 v21, v22, v19, v19
	v_fma_f32 v11, -v10, v21, 1.0
	v_fma_f32 v11, v11, v19, v21
	v_div_fixup_f32 v19, v11, v10, 1.0
	v_cvt_pk_bf16_f32 v10, v16, v17
	v_cvt_pk_bf16_f32 v11, v14, v15
	v_cvt_pk_bf16_f32 v13, v19, v18
	v_lshl_add_u64 v[14:15], s[50:51], 0, v[0:1]
	global_store_dwordx4 v[14:15], v[10:13], off

; __device__ __forceinline__ float sigmoidf_(float x) { return 1.f / (1.f + __expf(-x)); }
; __device__ __forceinline__ u32x4 pack8(f32x4 v0, f32x4 v1) { u32x4 o; o.x = pkbf(v0.x, v0.y); o.y = pkbf(v0.z, v0.w); o.z = pkbf(v1.x, v1.y); o.w = pkbf(v1.z, v1.w); return o; }
; __device__ __forceinline__ f32x4 gelu4(f32x4 v) { pg8::f32x2 a = pg8::gelu_pk((pg8::f32x2){v.x, v.y}), b = pg8::gelu_pk((pg8::f32x2){v.z, v.w}); return (f32x4){a.x, a.y, b.x, b.y}; }
;     __device__ __forceinline__ void operator()(int row, int col, f32x4 v0, f32x4 v1) const { *(u32x4*)(G + (size_t)row * 1024 + col) = pack8(v0, v1); }
; __device__ __forceinline__ f32x4 sig4(f32x4 v) { return (f32x4){sigmoidf_(v.x), sigmoidf_(v.y), sigmoidf_(v.z), sigmoidf_(v.w)}; }
;     __device__ __forceinline__ void operator()(int row, int col, f32x4 v0, f32x4 v1) const {
;         bf16_t* dst;
;         if (col < 2048) { v0 = gelu4(v0); v1 = gelu4(v1); dst = (col < 1024 ? GU : GV) + (size_t)row * 1024 + (col & 1023); }
;         else if (col < 5120) { const int q = col - 2048; dst = Q + (size_t)(q >> 10) * (size_t)(18 * MiB) + (size_t)row * 1024 + (q & 1023); }
;         else if (col < 8704) { dst = RW + (size_t)row * RWP + (col - 5120); }
;         else { v0 = sig4(v0); v1 = sig4(v1); dst = GT + (size_t)row * 3072 + (col - 8704); }
;         *(u32x4*)dst = pack8(v0, v1);
;     }
.LBB0_532:
	s_lshl_b32 s73, s27, 8
	v_lshl_add_u32 v144, s35, 8, v154
	s_add_i32 s4, s73, 0xfffff800
	s_lshr_b32 s72, s4, 10
	v_mad_i64_i32 v[150:151], s[4:5], v144, s21, 0
	v_mad_i64_i32 v[148:149], s[4:5], v144, s67, 0
	v_or_b32_e32 v142, s73, v156
	v_ashrrev_i32_e32 v145, 31, v144
	s_movk_i32 s4, 0x7ff
	s_mul_hi_u32 s35, s72, 0x2400000
	s_mul_i32 s72, s72, 0x2400000
	v_lshlrev_b64 v[146:147], 11, v[144:145]
	v_cmp_lt_i32_e64 s[42:43], s4, v142
	s_and_saveexec_b64 s[4:5], s[42:43]
	s_xor_b64 s[4:5], exec, s[4:5]
	s_cbranch_execz .LBB0_542
	s_cmpk_gt_u32 s73, 0x13ff
	s_mov_b64 s[6:7], -1
	s_cbranch_scc0 .LBB0_539
	s_cmpk_gt_u32 s73, 0x21ff
	s_cbranch_scc0 .LBB0_536
	v_mul_f32_e32 v0, 0xbfb8aa3b, v126
	v_exp_f32_e32 v152, v0
	v_mul_f32_e32 v0, 0xbfb8aa3b, v127
	v_exp_f32_e32 v153, v0
	v_mul_f32_e32 v0, 0xbfb8aa3b, v128
	v_exp_f32_e32 v158, v0
	v_mul_f32_e32 v0, 0xbfb8aa3b, v129
	v_pk_add_f32 v[152:153], v[152:153], 1.0 op_sel_hi:[1,0]
	v_exp_f32_e32 v159, v0
	v_div_scale_f32 v0, s[6:7], v152, v152, 1.0
	v_rcp_f32_e32 v143, v0
	v_pk_add_f32 v[160:161], v[158:159], 1.0 op_sel_hi:[1,0]
	v_fma_f32 v145, -v0, v143, 1.0
	v_fmac_f32_e32 v143, v145, v143
	v_div_scale_f32 v145, vcc, 1.0, v152, 1.0
	v_mul_f32_e32 v158, v145, v143
	v_fma_f32 v159, -v0, v158, v145
	v_fmac_f32_e32 v158, v159, v143
	v_fma_f32 v0, -v0, v158, v145
	v_div_fmas_f32 v0, v0, v143, v158
	v_div_fixup_f32 v145, v0, v152, 1.0
	v_rcp_f32_e32 v143, v153
	s_nop 0
	v_fma_f32 v152, -v153, v143, 1.0
	v_fmac_f32_e32 v143, v152, v143
	v_fma_f32 v159, -v153, v143, 1.0
	v_fma_f32 v158, v159, v143, v143
	v_fma_f32 v0, -v153, v158, 1.0
	v_fma_f32 v0, v0, v143, v158
	v_div_fixup_f32 v158, v0, v153, 1.0
	v_rcp_f32_e32 v143, v160
	s_nop 0
	v_fma_f32 v152, -v160, v143, 1.0
	v_fmac_f32_e32 v143, v152, v143
	v_fma_f32 v159, -v160, v143, 1.0
	v_fma_f32 v153, v159, v143, v143
	v_fma_f32 v0, -v160, v153, 1.0
	v_fma_f32 v0, v0, v143, v153
	v_div_fixup_f32 v159, v0, v160, 1.0
	v_rcp_f32_e32 v143, v161
	s_nop 0
	v_fma_f32 v152, -v161, v143, 1.0
	v_fmac_f32_e32 v143, v152, v143
	v_fma_f32 v160, -v161, v143, 1.0
	v_fma_f32 v153, v160, v143, v143
	v_fma_f32 v0, -v161, v153, 1.0
	v_fma_f32 v0, v0, v143, v153
	v_div_fixup_f32 v160, v0, v161, 1.0
	v_mul_f32_e32 v0, 0xbfb8aa3b, v122
	v_exp_f32_e32 v152, v0
	v_mul_f32_e32 v0, 0xbfb8aa3b, v123
	v_exp_f32_e32 v153, v0
	v_mul_f32_e32 v0, 0xbfb8aa3b, v124
	v_exp_f32_e32 v162, v0
	v_mul_f32_e32 v0, 0xbfb8aa3b, v125
	v_pk_add_f32 v[152:153], v[152:153], 1.0 op_sel_hi:[1,0]
	v_exp_f32_e32 v163, v0
	v_div_scale_f32 v0, s[6:7], v152, v152, 1.0
	v_rcp_f32_e32 v143, v0
	v_pk_add_f32 v[164:165], v[162:163], 1.0 op_sel_hi:[1,0]
	v_fma_f32 v161, -v0, v143, 1.0
	v_fmac_f32_e32 v143, v161, v143
	v_div_scale_f32 v161, vcc, 1.0, v152, 1.0
	v_mul_f32_e32 v162, v161, v143
	v_fma_f32 v163, -v0, v162, v161
	v_fmac_f32_e32 v162, v163, v143
	v_fma_f32 v0, -v0, v162, v161
	v_div_fmas_f32 v0, v0, v143, v162
	v_div_fixup_f32 v161, v0, v152, 1.0
	v_rcp_f32_e32 v143, v153
	s_nop 0
	v_fma_f32 v152, -v153, v143, 1.0
	v_fmac_f32_e32 v143, v152, v143
	v_fma_f32 v163, -v153, v143, 1.0
	v_fma_f32 v162, v163, v143, v143
	v_fma_f32 v0, -v153, v162, 1.0
	v_fma_f32 v0, v0, v143, v162
	v_div_fixup_f32 v162, v0, v153, 1.0
	v_rcp_f32_e32 v143, v164
	s_nop 0
	v_fma_f32 v152, -v164, v143, 1.0
	v_fmac_f32_e32 v143, v152, v143
	v_fma_f32 v163, -v164, v143, 1.0
	v_fma_f32 v153, v163, v143, v143
	v_fma_f32 v0, -v164, v153, 1.0
	v_fma_f32 v0, v0, v143, v153
	v_div_fixup_f32 v163, v0, v164, 1.0
	v_div_scale_f32 v0, s[6:7], v165, v165, 1.0
	v_rcp_f32_e32 v143, v0
	s_mov_b64 s[6:7], 0
	v_fma_f32 v152, -v0, v143, 1.0
	v_fmac_f32_e32 v143, v152, v143
	v_div_scale_f32 v152, vcc, 1.0, v165, 1.0
	v_mul_f32_e32 v153, v152, v143
	v_fma_f32 v164, -v0, v153, v152
	v_fmac_f32_e32 v153, v164, v143
	v_fma_f32 v0, -v0, v153, v152
	v_div_fmas_f32 v0, v0, v143, v153
	v_lshl_add_u64 v[152:153], s[54:55], 0, v[150:151]
	v_mov_b32_e32 v143, v1
	v_lshl_add_u64 v[152:153], v[142:143], 1, v[152:153]
	v_div_fixup_f32 v164, v0, v165, 1.0
	v_lshl_add_u64 v[152:153], v[152:153], 0, s[86:87]

; __device__ __forceinline__ float sigmoidf_(float x) { return 1.f / (1.f + __expf(-x)); }
; __device__ __forceinline__ u32x4 pack8(f32x4 v0, f32x4 v1) { u32x4 o; o.x = pkbf(v0.x, v0.y); o.y = pkbf(v0.z, v0.w); o.z = pkbf(v1.x, v1.y); o.w = pkbf(v1.z, v1.w); return o; }
; __device__ __forceinline__ f32x4 gelu4(f32x4 v) { pg8::f32x2 a = pg8::gelu_pk((pg8::f32x2){v.x, v.y}), b = pg8::gelu_pk((pg8::f32x2){v.z, v.w}); return (f32x4){a.x, a.y, b.x, b.y}; }
;     __device__ __forceinline__ void operator()(int row, int col, f32x4 v0, f32x4 v1) const { *(u32x4*)(G + (size_t)row * 1024 + col) = pack8(v0, v1); }
; __device__ __forceinline__ f32x4 sig4(f32x4 v) { return (f32x4){sigmoidf_(v.x), sigmoidf_(v.y), sigmoidf_(v.z), sigmoidf_(v.w)}; }
;     __device__ __forceinline__ void operator()(int row, int col, f32x4 v0, f32x4 v1) const {
;         bf16_t* dst;
;         if (col < 2048) { v0 = gelu4(v0); v1 = gelu4(v1); dst = (col < 1024 ? GU : GV) + (size_t)row * 1024 + (col & 1023); }
;         else if (col < 5120) { const int q = col - 2048; dst = Q + (size_t)(q >> 10) * (size_t)(18 * MiB) + (size_t)row * 1024 + (q & 1023); }
;         else if (col < 8704) { dst = RW + (size_t)row * RWP + (col - 5120); }
;         else { v0 = sig4(v0); v1 = sig4(v1); dst = GT + (size_t)row * 3072 + (col - 8704); }
;         *(u32x4*)dst = pack8(v0, v1);
;     }
.LBB0_544:
	s_or_b64 exec, exec, s[4:5]
	v_cvt_pk_bf16_f32 v122, v145, v158
	v_cvt_pk_bf16_f32 v123, v159, v160
	v_cvt_pk_bf16_f32 v124, v161, v162
	v_cvt_pk_bf16_f32 v125, v163, v164
	global_store_dwordx4 v[152:153], v[122:125], off
	v_or_b32_e32 v126, 0x80, v142
	s_movk_i32 s4, 0x7ff
	v_cmp_lt_i32_e64 s[44:45], s4, v126
	s_and_saveexec_b64 s[4:5], s[44:45]
	s_xor_b64 s[4:5], exec, s[4:5]
	s_cbranch_execz .LBB0_554
	s_cmpk_lt_u32 s73, 0x1400
	s_mov_b64 s[6:7], -1
	s_cbranch_scc1 .LBB0_551
	s_cmpk_lt_u32 s73, 0x2200
	s_cbranch_scc1 .LBB0_548
	v_mul_f32_e32 v122, 0xbfb8aa3b, v118
	v_mul_f32_e32 v123, 0xbfb8aa3b, v119
	v_exp_f32_e32 v122, v122
	v_exp_f32_e32 v123, v123
	v_mul_f32_e32 v124, 0xbfb8aa3b, v120
	v_mul_f32_e32 v125, 0xbfb8aa3b, v121
	v_exp_f32_e32 v124, v124
	v_pk_add_f32 v[122:123], v[122:123], 1.0 op_sel_hi:[1,0]
	v_exp_f32_e32 v125, v125
	v_rcp_f32_e32 v128, v122
	v_pk_add_f32 v[124:125], v[124:125], 1.0 op_sel_hi:[1,0]
	v_fma_f32 v129, -v122, v128, 1.0
	v_fmac_f32_e32 v128, v129, v128
	v_fma_f32 v145, -v122, v128, 1.0
	v_fma_f32 v143, v145, v128, v128
	v_fma_f32 v127, -v122, v143, 1.0
	v_fma_f32 v127, v127, v128, v143
	v_div_fixup_f32 v127, v127, v122, 1.0
	v_rcp_f32_e32 v128, v123
	s_nop 0
	v_fma_f32 v129, -v123, v128, 1.0
	v_fmac_f32_e32 v128, v129, v128
	v_fma_f32 v145, -v123, v128, 1.0
	v_fma_f32 v143, v145, v128, v128
	v_fma_f32 v122, -v123, v143, 1.0
	v_fma_f32 v122, v122, v128, v143
	v_div_fixup_f32 v128, v122, v123, 1.0
	v_rcp_f32_e32 v123, v124
	s_nop 0
	v_fma_f32 v129, -v124, v123, 1.0
	v_fmac_f32_e32 v123, v129, v123
	v_fma_f32 v145, -v124, v123, 1.0
	v_fma_f32 v143, v145, v123, v123
	v_fma_f32 v122, -v124, v143, 1.0
	v_fma_f32 v122, v122, v123, v143
	v_div_fixup_f32 v129, v122, v124, 1.0
	v_rcp_f32_e32 v123, v125
	s_nop 0
	v_fma_f32 v124, -v125, v123, 1.0
	v_fmac_f32_e32 v123, v124, v123
	v_fma_f32 v145, -v125, v123, 1.0
	v_fma_f32 v143, v145, v123, v123
	v_fma_f32 v122, -v125, v143, 1.0
	v_fma_f32 v122, v122, v123, v143
	v_div_fixup_f32 v145, v122, v125, 1.0
	v_mul_f32_e32 v122, 0xbfb8aa3b, v114
	v_mul_f32_e32 v123, 0xbfb8aa3b, v115
	v_exp_f32_e32 v122, v122
	v_exp_f32_e32 v123, v123
	v_mul_f32_e32 v124, 0xbfb8aa3b, v116
	v_mul_f32_e32 v125, 0xbfb8aa3b, v117
	v_exp_f32_e32 v124, v124
	v_pk_add_f32 v[122:123], v[122:123], 1.0 op_sel_hi:[1,0]
	v_exp_f32_e32 v125, v125
	v_rcp_f32_e32 v152, v122
	v_pk_add_f32 v[124:125], v[124:125], 1.0 op_sel_hi:[1,0]
	v_fma_f32 v153, -v122, v152, 1.0
	v_fmac_f32_e32 v152, v153, v152
	v_fma_f32 v159, -v122, v152, 1.0
	v_fma_f32 v158, v159, v152, v152
	v_fma_f32 v143, -v122, v158, 1.0
	v_fma_f32 v143, v143, v152, v158
	v_div_fixup_f32 v152, v143, v122, 1.0
	v_rcp_f32_e32 v143, v123
	s_nop 0
	v_fma_f32 v153, -v123, v143, 1.0
	v_fmac_f32_e32 v143, v153, v143
	v_fma_f32 v159, -v123, v143, 1.0
	v_fma_f32 v158, v159, v143, v143
	v_fma_f32 v122, -v123, v158, 1.0
	v_fma_f32 v122, v122, v143, v158
	v_div_fixup_f32 v153, v122, v123, 1.0
	v_rcp_f32_e32 v123, v124
	s_nop 0
	v_fma_f32 v143, -v124, v123, 1.0
	v_fmac_f32_e32 v123, v143, v123
	v_fma_f32 v159, -v124, v123, 1.0
	v_fma_f32 v158, v159, v123, v123
	v_fma_f32 v122, -v124, v158, 1.0
	v_fma_f32 v122, v122, v123, v158
	v_div_fixup_f32 v158, v122, v124, 1.0
	v_rcp_f32_e32 v123, v125
	s_movk_i32 s6, 0xbd00
	s_mov_b32 s7, -1
	v_fma_f32 v124, -v125, v123, 1.0
	v_fmac_f32_e32 v123, v124, v123
	v_fma_f32 v159, -v125, v123, 1.0
	v_fma_f32 v143, v159, v123, v123
	v_fma_f32 v122, -v125, v143, 1.0
	v_fma_f32 v122, v122, v123, v143
	v_div_fixup_f32 v159, v122, v125, 1.0
	v_lshl_add_u64 v[122:123], s[54:55], 0, v[150:151]
	v_mov_b32_e32 v143, v1
	v_lshl_add_u64 v[122:123], v[142:143], 1, v[122:123]
	v_lshl_add_u64 v[124:125], v[122:123], 0, s[6:7]
	s_mov_b64 s[6:7], 0

; __device__ __forceinline__ float sigmoidf_(float x) { return 1.f / (1.f + __expf(-x)); }
; __device__ __forceinline__ u32x4 pack8(f32x4 v0, f32x4 v1) { u32x4 o; o.x = pkbf(v0.x, v0.y); o.y = pkbf(v0.z, v0.w); o.z = pkbf(v1.x, v1.y); o.w = pkbf(v1.z, v1.w); return o; }
; __device__ __forceinline__ f32x4 gelu4(f32x4 v) { pg8::f32x2 a = pg8::gelu_pk((pg8::f32x2){v.x, v.y}), b = pg8::gelu_pk((pg8::f32x2){v.z, v.w}); return (f32x4){a.x, a.y, b.x, b.y}; }
;     __device__ __forceinline__ void operator()(int row, int col, f32x4 v0, f32x4 v1) const { *(u32x4*)(G + (size_t)row * 1024 + col) = pack8(v0, v1); }
; __device__ __forceinline__ f32x4 sig4(f32x4 v) { return (f32x4){sigmoidf_(v.x), sigmoidf_(v.y), sigmoidf_(v.z), sigmoidf_(v.w)}; }
;     __device__ __forceinline__ void operator()(int row, int col, f32x4 v0, f32x4 v1) const {
;         bf16_t* dst;
;         if (col < 2048) { v0 = gelu4(v0); v1 = gelu4(v1); dst = (col < 1024 ? GU : GV) + (size_t)row * 1024 + (col & 1023); }
;         else if (col < 5120) { const int q = col - 2048; dst = Q + (size_t)(q >> 10) * (size_t)(18 * MiB) + (size_t)row * 1024 + (q & 1023); }
;         else if (col < 8704) { dst = RW + (size_t)row * RWP + (col - 5120); }
;         else { v0 = sig4(v0); v1 = sig4(v1); dst = GT + (size_t)row * 3072 + (col - 8704); }
;         *(u32x4*)dst = pack8(v0, v1);
;     }
.LBB0_556:
	s_or_b64 exec, exec, s[4:5]
	v_cvt_pk_bf16_f32 v114, v127, v128
	v_cvt_pk_bf16_f32 v115, v129, v145
	v_cvt_pk_bf16_f32 v116, v152, v153
	v_cvt_pk_bf16_f32 v117, v158, v159
	global_store_dwordx4 v[124:125], v[114:117], off
	s_nop 1
	v_or_b32_e32 v114, 16, v144
	v_ashrrev_i32_e32 v115, 31, v114
	v_mad_i64_i32 v[118:119], s[4:5], v114, s21, 0
	v_mad_i64_i32 v[116:117], s[4:5], v114, s67, 0
	v_lshlrev_b64 v[114:115], 11, v[114:115]
	s_and_saveexec_b64 s[4:5], s[42:43]
	s_xor_b64 s[4:5], exec, s[4:5]
	s_cbranch_execz .LBB0_566
	s_cmpk_lt_u32 s73, 0x1400
	s_mov_b64 s[6:7], -1
	s_cbranch_scc1 .LBB0_563
	s_cmpk_lt_u32 s73, 0x2200
	s_cbranch_scc1 .LBB0_560
	v_mul_f32_e32 v120, 0xbfb8aa3b, v110
	v_mul_f32_e32 v121, 0xbfb8aa3b, v111
	v_exp_f32_e32 v120, v120
	v_exp_f32_e32 v121, v121
	v_mul_f32_e32 v123, 0xbfb8aa3b, v112
	v_exp_f32_e32 v124, v123
	v_mul_f32_e32 v123, 0xbfb8aa3b, v113
	v_exp_f32_e32 v125, v123
	v_pk_add_f32 v[120:121], v[120:121], 1.0 op_sel_hi:[1,0]
	v_pk_add_f32 v[128:129], v[124:125], 1.0 op_sel_hi:[1,0]
	v_rcp_f32_e32 v124, v120
	s_nop 0
	v_fma_f32 v125, -v120, v124, 1.0
	v_fmac_f32_e32 v124, v125, v124
	v_fma_f32 v143, -v120, v124, 1.0
	v_fma_f32 v127, v143, v124, v124
	v_fma_f32 v123, -v120, v127, 1.0
	v_fma_f32 v123, v123, v124, v127
	v_div_fixup_f32 v123, v123, v120, 1.0
	v_rcp_f32_e32 v124, v121
	s_nop 0
	v_fma_f32 v125, -v121, v124, 1.0
	v_fmac_f32_e32 v124, v125, v124
	v_fma_f32 v143, -v121, v124, 1.0
	v_fma_f32 v127, v143, v124, v124
	v_fma_f32 v120, -v121, v127, 1.0
	v_fma_f32 v120, v120, v124, v127
	v_div_fixup_f32 v124, v120, v121, 1.0
	v_rcp_f32_e32 v121, v128
	s_nop 0
	v_fma_f32 v125, -v128, v121, 1.0
	v_fmac_f32_e32 v121, v125, v121
	v_fma_f32 v143, -v128, v121, 1.0
	v_fma_f32 v127, v143, v121, v121
	v_fma_f32 v120, -v128, v127, 1.0
	v_fma_f32 v120, v120, v121, v127
	v_div_fixup_f32 v125, v120, v128, 1.0
	v_rcp_f32_e32 v121, v129
	s_nop 0
	v_fma_f32 v127, -v129, v121, 1.0
	v_fmac_f32_e32 v121, v127, v121
	v_fma_f32 v143, -v129, v121, 1.0
	v_fma_f32 v128, v143, v121, v121
	v_fma_f32 v120, -v129, v128, 1.0
	v_fma_f32 v120, v120, v121, v128
	v_div_fixup_f32 v127, v120, v129, 1.0
	v_mul_f32_e32 v120, 0xbfb8aa3b, v106
	v_mul_f32_e32 v121, 0xbfb8aa3b, v107
	v_exp_f32_e32 v120, v120
	v_exp_f32_e32 v121, v121
	v_mul_f32_e32 v128, 0xbfb8aa3b, v108
	v_mul_f32_e32 v129, 0xbfb8aa3b, v109
	v_exp_f32_e32 v128, v128
	v_exp_f32_e32 v129, v129
	v_pk_add_f32 v[120:121], v[120:121], 1.0 op_sel_hi:[1,0]
	v_pk_add_f32 v[146:147], v[128:129], 1.0 op_sel_hi:[1,0]
	v_rcp_f32_e32 v129, v120
	s_nop 0
	v_fma_f32 v143, -v120, v129, 1.0
	v_fmac_f32_e32 v129, v143, v129
	v_fma_f32 v148, -v120, v129, 1.0
	v_fma_f32 v145, v148, v129, v129
	v_fma_f32 v128, -v120, v145, 1.0
	v_fma_f32 v128, v128, v129, v145
	v_div_fixup_f32 v128, v128, v120, 1.0
	v_rcp_f32_e32 v129, v121
	s_nop 0
	v_fma_f32 v143, -v121, v129, 1.0
	v_fmac_f32_e32 v129, v143, v129
	v_fma_f32 v148, -v121, v129, 1.0
	v_fma_f32 v145, v148, v129, v129
	v_fma_f32 v120, -v121, v145, 1.0
	v_fma_f32 v120, v120, v129, v145
	v_div_fixup_f32 v129, v120, v121, 1.0
	v_rcp_f32_e32 v121, v146
	s_nop 0
	v_fma_f32 v143, -v146, v121, 1.0
	v_fmac_f32_e32 v121, v143, v121
	v_fma_f32 v148, -v146, v121, 1.0
	v_fma_f32 v145, v148, v121, v121
	v_fma_f32 v120, -v146, v145, 1.0
	v_fma_f32 v120, v120, v121, v145
	v_div_fixup_f32 v145, v120, v146, 1.0
	v_rcp_f32_e32 v121, v147
	s_mov_b64 s[6:7], 0
	v_fma_f32 v143, -v147, v121, 1.0
	v_fmac_f32_e32 v121, v143, v121
	v_fma_f32 v148, -v147, v121, 1.0
	v_fma_f32 v146, v148, v121, v121
	v_fma_f32 v120, -v147, v146, 1.0
	v_fma_f32 v120, v120, v121, v146
	v_div_fixup_f32 v146, v120, v147, 1.0
	v_lshl_add_u64 v[120:121], s[54:55], 0, v[118:119]
	v_mov_b32_e32 v143, v1
	v_lshl_add_u64 v[120:121], v[142:143], 1, v[120:121]
	v_lshl_add_u64 v[120:121], v[120:121], 0, s[86:87]

; __device__ __forceinline__ float sigmoidf_(float x) { return 1.f / (1.f + __expf(-x)); }
; __device__ __forceinline__ u32x4 pack8(f32x4 v0, f32x4 v1) { u32x4 o; o.x = pkbf(v0.x, v0.y); o.y = pkbf(v0.z, v0.w); o.z = pkbf(v1.x, v1.y); o.w = pkbf(v1.z, v1.w); return o; }
; __device__ __forceinline__ f32x4 gelu4(f32x4 v) { pg8::f32x2 a = pg8::gelu_pk((pg8::f32x2){v.x, v.y}), b = pg8::gelu_pk((pg8::f32x2){v.z, v.w}); return (f32x4){a.x, a.y, b.x, b.y}; }
;     __device__ __forceinline__ void operator()(int row, int col, f32x4 v0, f32x4 v1) const { *(u32x4*)(G + (size_t)row * 1024 + col) = pack8(v0, v1); }
; __device__ __forceinline__ f32x4 sig4(f32x4 v) { return (f32x4){sigmoidf_(v.x), sigmoidf_(v.y), sigmoidf_(v.z), sigmoidf_(v.w)}; }
;     __device__ __forceinline__ void operator()(int row, int col, f32x4 v0, f32x4 v1) const {
;         bf16_t* dst;
;         if (col < 2048) { v0 = gelu4(v0); v1 = gelu4(v1); dst = (col < 1024 ? GU : GV) + (size_t)row * 1024 + (col & 1023); }
;         else if (col < 5120) { const int q = col - 2048; dst = Q + (size_t)(q >> 10) * (size_t)(18 * MiB) + (size_t)row * 1024 + (q & 1023); }
;         else if (col < 8704) { dst = RW + (size_t)row * RWP + (col - 5120); }
;         else { v0 = sig4(v0); v1 = sig4(v1); dst = GT + (size_t)row * 3072 + (col - 8704); }
;         *(u32x4*)dst = pack8(v0, v1);
;     }
.LBB0_568:
	s_or_b64 exec, exec, s[4:5]
	v_cvt_pk_bf16_f32 v106, v123, v124
	v_cvt_pk_bf16_f32 v107, v125, v127
	v_cvt_pk_bf16_f32 v108, v128, v129
	v_cvt_pk_bf16_f32 v109, v145, v146
	global_store_dwordx4 v[120:121], v[106:109], off
	s_and_saveexec_b64 s[4:5], s[44:45]
	s_xor_b64 s[4:5], exec, s[4:5]
	s_cbranch_execz .LBB0_578
	s_cmpk_lt_u32 s73, 0x1400
	s_mov_b64 s[6:7], -1
	s_cbranch_scc1 .LBB0_575
	s_cmpk_lt_u32 s73, 0x2200
	s_cbranch_scc1 .LBB0_572
	v_mul_f32_e32 v106, 0xbfb8aa3b, v102
	v_mul_f32_e32 v107, 0xbfb8aa3b, v103
	v_exp_f32_e32 v106, v106
	v_exp_f32_e32 v107, v107
	v_mul_f32_e32 v108, 0xbfb8aa3b, v104
	v_mul_f32_e32 v109, 0xbfb8aa3b, v105
	v_exp_f32_e32 v108, v108
	v_exp_f32_e32 v109, v109
	v_pk_add_f32 v[106:107], v[106:107], 1.0 op_sel_hi:[1,0]
	v_mov_b32_e32 v143, v1
	v_pk_add_f32 v[110:111], v[108:109], 1.0 op_sel_hi:[1,0]
	v_rcp_f32_e32 v109, v106
	s_nop 0
	v_fma_f32 v112, -v106, v109, 1.0
	v_fmac_f32_e32 v109, v112, v109
	v_fma_f32 v120, -v106, v109, 1.0
	v_fma_f32 v113, v120, v109, v109
	v_fma_f32 v108, -v106, v113, 1.0
	v_fma_f32 v108, v108, v109, v113
	v_div_fixup_f32 v108, v108, v106, 1.0
	v_rcp_f32_e32 v109, v107
	s_nop 0
	v_fma_f32 v112, -v107, v109, 1.0
	v_fmac_f32_e32 v109, v112, v109
	v_fma_f32 v120, -v107, v109, 1.0
	v_fma_f32 v113, v120, v109, v109
	v_fma_f32 v106, -v107, v113, 1.0
	v_fma_f32 v106, v106, v109, v113
	v_div_fixup_f32 v109, v106, v107, 1.0
	v_rcp_f32_e32 v107, v110
	s_nop 0
	v_fma_f32 v112, -v110, v107, 1.0
	v_fmac_f32_e32 v107, v112, v107
	v_fma_f32 v120, -v110, v107, 1.0
	v_fma_f32 v113, v120, v107, v107
	v_fma_f32 v106, -v110, v113, 1.0
	v_fma_f32 v106, v106, v107, v113
	v_div_fixup_f32 v110, v106, v110, 1.0
	v_rcp_f32_e32 v107, v111
	s_nop 0
	v_fma_f32 v112, -v111, v107, 1.0
	v_fmac_f32_e32 v107, v112, v107
	v_fma_f32 v120, -v111, v107, 1.0
	v_fma_f32 v113, v120, v107, v107
	v_fma_f32 v106, -v111, v113, 1.0
	v_fma_f32 v106, v106, v107, v113
	v_div_fixup_f32 v111, v106, v111, 1.0
	v_mul_f32_e32 v106, 0xbfb8aa3b, v98
	v_mul_f32_e32 v107, 0xbfb8aa3b, v99
	v_exp_f32_e32 v106, v106
	v_exp_f32_e32 v107, v107
	v_mul_f32_e32 v112, 0xbfb8aa3b, v100
	v_mul_f32_e32 v113, 0xbfb8aa3b, v101
	v_exp_f32_e32 v112, v112
	v_exp_f32_e32 v113, v113
	v_pk_add_f32 v[106:107], v[106:107], 1.0 op_sel_hi:[1,0]
	v_pk_add_f32 v[120:121], v[112:113], 1.0 op_sel_hi:[1,0]
	v_rcp_f32_e32 v113, v106
	s_nop 0
	v_fma_f32 v123, -v106, v113, 1.0
	v_fmac_f32_e32 v113, v123, v113
	v_fma_f32 v125, -v106, v113, 1.0
	v_fma_f32 v124, v125, v113, v113
	v_fma_f32 v112, -v106, v124, 1.0
	v_fma_f32 v112, v112, v113, v124
	v_div_fixup_f32 v112, v112, v106, 1.0
	v_rcp_f32_e32 v113, v107
	s_nop 0
	v_fma_f32 v123, -v107, v113, 1.0
	v_fmac_f32_e32 v113, v123, v113
	v_fma_f32 v125, -v107, v113, 1.0
	v_fma_f32 v124, v125, v113, v113
	v_fma_f32 v106, -v107, v124, 1.0
	v_fma_f32 v106, v106, v113, v124
	v_div_fixup_f32 v113, v106, v107, 1.0
	v_rcp_f32_e32 v107, v120
	s_nop 0
	v_fma_f32 v123, -v120, v107, 1.0
	v_fmac_f32_e32 v107, v123, v107
	v_fma_f32 v125, -v120, v107, 1.0
	v_fma_f32 v124, v125, v107, v107
	v_fma_f32 v106, -v120, v124, 1.0
	v_fma_f32 v106, v106, v107, v124
	v_div_fixup_f32 v120, v106, v120, 1.0
	v_rcp_f32_e32 v107, v121
	s_movk_i32 s6, 0xbd00
	s_mov_b32 s7, -1
	v_fma_f32 v123, -v121, v107, 1.0
	v_fmac_f32_e32 v107, v123, v107
	v_fma_f32 v125, -v121, v107, 1.0
	v_fma_f32 v124, v125, v107, v107
	v_fma_f32 v106, -v121, v124, 1.0
	v_fma_f32 v106, v106, v107, v124
	v_div_fixup_f32 v121, v106, v121, 1.0
	v_lshl_add_u64 v[106:107], s[54:55], 0, v[118:119]
	v_lshl_add_u64 v[106:107], v[142:143], 1, v[106:107]
	v_lshl_add_u64 v[106:107], v[106:107], 0, s[6:7]
	s_mov_b64 s[6:7], 0

; __device__ __forceinline__ float sigmoidf_(float x) { return 1.f / (1.f + __expf(-x)); }
; __device__ __forceinline__ u32x4 pack8(f32x4 v0, f32x4 v1) { u32x4 o; o.x = pkbf(v0.x, v0.y); o.y = pkbf(v0.z, v0.w); o.z = pkbf(v1.x, v1.y); o.w = pkbf(v1.z, v1.w); return o; }
; __device__ __forceinline__ f32x4 gelu4(f32x4 v) { pg8::f32x2 a = pg8::gelu_pk((pg8::f32x2){v.x, v.y}), b = pg8::gelu_pk((pg8::f32x2){v.z, v.w}); return (f32x4){a.x, a.y, b.x, b.y}; }
;     __device__ __forceinline__ void operator()(int row, int col, f32x4 v0, f32x4 v1) const { *(u32x4*)(G + (size_t)row * 1024 + col) = pack8(v0, v1); }
; __device__ __forceinline__ f32x4 sig4(f32x4 v) { return (f32x4){sigmoidf_(v.x), sigmoidf_(v.y), sigmoidf_(v.z), sigmoidf_(v.w)}; }
;     __device__ __forceinline__ void operator()(int row, int col, f32x4 v0, f32x4 v1) const {
;         bf16_t* dst;
;         if (col < 2048) { v0 = gelu4(v0); v1 = gelu4(v1); dst = (col < 1024 ? GU : GV) + (size_t)row * 1024 + (col & 1023); }
;         else if (col < 5120) { const int q = col - 2048; dst = Q + (size_t)(q >> 10) * (size_t)(18 * MiB) + (size_t)row * 1024 + (q & 1023); }
;         else if (col < 8704) { dst = RW + (size_t)row * RWP + (col - 5120); }
;         else { v0 = sig4(v0); v1 = sig4(v1); dst = GT + (size_t)row * 3072 + (col - 8704); }
;         *(u32x4*)dst = pack8(v0, v1);
;     }
.LBB0_580:
	s_or_b64 exec, exec, s[4:5]
	v_cvt_pk_bf16_f32 v98, v108, v109
	v_cvt_pk_bf16_f32 v99, v110, v111
	v_cvt_pk_bf16_f32 v100, v112, v113
	v_cvt_pk_bf16_f32 v101, v120, v121
	global_store_dwordx4 v[106:107], v[98:101], off
	s_nop 1
	v_or_b32_e32 v98, 32, v144
	v_ashrrev_i32_e32 v99, 31, v98
	v_mad_i64_i32 v[102:103], s[4:5], v98, s21, 0
	v_mad_i64_i32 v[100:101], s[4:5], v98, s67, 0
	v_lshlrev_b64 v[98:99], 11, v[98:99]
	s_and_saveexec_b64 s[4:5], s[42:43]
	s_xor_b64 s[4:5], exec, s[4:5]
	s_cbranch_execz .LBB0_590
	s_cmpk_lt_u32 s73, 0x1400
	s_mov_b64 s[6:7], -1
	s_cbranch_scc1 .LBB0_587
	s_cmpk_lt_u32 s73, 0x2200
	s_cbranch_scc1 .LBB0_584
	v_mul_f32_e32 v104, 0xbfb8aa3b, v94
	v_mul_f32_e32 v105, 0xbfb8aa3b, v95
	v_exp_f32_e32 v104, v104
	v_exp_f32_e32 v105, v105
	v_mul_f32_e32 v106, 0xbfb8aa3b, v96
	v_mul_f32_e32 v107, 0xbfb8aa3b, v97
	v_exp_f32_e32 v106, v106
	v_exp_f32_e32 v107, v107
	v_pk_add_f32 v[104:105], v[104:105], 1.0 op_sel_hi:[1,0]
	v_mov_b32_e32 v143, v1
	v_pk_add_f32 v[108:109], v[106:107], 1.0 op_sel_hi:[1,0]
	v_rcp_f32_e32 v107, v104
	s_nop 0
	v_fma_f32 v110, -v104, v107, 1.0
	v_fmac_f32_e32 v107, v110, v107
	v_fma_f32 v112, -v104, v107, 1.0
	v_fma_f32 v111, v112, v107, v107
	v_fma_f32 v106, -v104, v111, 1.0
	v_fma_f32 v106, v106, v107, v111
	v_div_fixup_f32 v106, v106, v104, 1.0
	v_rcp_f32_e32 v107, v105
	s_nop 0
	v_fma_f32 v110, -v105, v107, 1.0
	v_fmac_f32_e32 v107, v110, v107
	v_fma_f32 v112, -v105, v107, 1.0
	v_fma_f32 v111, v112, v107, v107
	v_fma_f32 v104, -v105, v111, 1.0
	v_fma_f32 v104, v104, v107, v111
	v_div_fixup_f32 v107, v104, v105, 1.0
	v_rcp_f32_e32 v105, v108
	s_nop 0
	v_fma_f32 v110, -v108, v105, 1.0
	v_fmac_f32_e32 v105, v110, v105
	v_fma_f32 v112, -v108, v105, 1.0
	v_fma_f32 v111, v112, v105, v105
	v_fma_f32 v104, -v108, v111, 1.0
	v_fma_f32 v104, v104, v105, v111
	v_div_fixup_f32 v108, v104, v108, 1.0
	v_rcp_f32_e32 v105, v109
	s_nop 0
	v_fma_f32 v110, -v109, v105, 1.0
	v_fmac_f32_e32 v105, v110, v105
	v_fma_f32 v112, -v109, v105, 1.0
	v_fma_f32 v111, v112, v105, v105
	v_fma_f32 v104, -v109, v111, 1.0
	v_fma_f32 v104, v104, v105, v111
	v_div_fixup_f32 v109, v104, v109, 1.0
	v_mul_f32_e32 v104, 0xbfb8aa3b, v90
	v_mul_f32_e32 v105, 0xbfb8aa3b, v91
	v_exp_f32_e32 v104, v104
	v_exp_f32_e32 v105, v105
	v_mul_f32_e32 v110, 0xbfb8aa3b, v92
	v_mul_f32_e32 v111, 0xbfb8aa3b, v93
	v_exp_f32_e32 v110, v110
	v_exp_f32_e32 v111, v111
	v_pk_add_f32 v[104:105], v[104:105], 1.0 op_sel_hi:[1,0]
	v_pk_add_f32 v[112:113], v[110:111], 1.0 op_sel_hi:[1,0]
	v_rcp_f32_e32 v111, v104
	s_nop 0
	v_fma_f32 v114, -v104, v111, 1.0
	v_fmac_f32_e32 v111, v114, v111
	v_fma_f32 v116, -v104, v111, 1.0
	v_fma_f32 v115, v116, v111, v111
	v_fma_f32 v110, -v104, v115, 1.0
	v_fma_f32 v110, v110, v111, v115
	v_div_fixup_f32 v110, v110, v104, 1.0
	v_rcp_f32_e32 v111, v105
	s_nop 0
	v_fma_f32 v114, -v105, v111, 1.0
	v_fmac_f32_e32 v111, v114, v111
	v_fma_f32 v116, -v105, v111, 1.0
	v_fma_f32 v115, v116, v111, v111
	v_fma_f32 v104, -v105, v115, 1.0
	v_fma_f32 v104, v104, v111, v115
	v_div_fixup_f32 v111, v104, v105, 1.0
	v_rcp_f32_e32 v105, v112
	s_nop 0
	v_fma_f32 v114, -v112, v105, 1.0
	v_fmac_f32_e32 v105, v114, v105
	v_fma_f32 v116, -v112, v105, 1.0
	v_fma_f32 v115, v116, v105, v105
	v_fma_f32 v104, -v112, v115, 1.0
	v_fma_f32 v104, v104, v105, v115
	v_div_fixup_f32 v112, v104, v112, 1.0
	v_rcp_f32_e32 v105, v113
	s_mov_b64 s[6:7], 0
	v_fma_f32 v114, -v113, v105, 1.0
	v_fmac_f32_e32 v105, v114, v105
	v_fma_f32 v116, -v113, v105, 1.0
	v_fma_f32 v115, v116, v105, v105
	v_fma_f32 v104, -v113, v115, 1.0
	v_fma_f32 v104, v104, v105, v115
	v_div_fixup_f32 v113, v104, v113, 1.0
	v_lshl_add_u64 v[104:105], s[54:55], 0, v[102:103]
	v_lshl_add_u64 v[104:105], v[142:143], 1, v[104:105]
	v_lshl_add_u64 v[104:105], v[104:105], 0, s[86:87]

; __device__ __forceinline__ float sigmoidf_(float x) { return 1.f / (1.f + __expf(-x)); }
; __device__ __forceinline__ u32x4 pack8(f32x4 v0, f32x4 v1) { u32x4 o; o.x = pkbf(v0.x, v0.y); o.y = pkbf(v0.z, v0.w); o.z = pkbf(v1.x, v1.y); o.w = pkbf(v1.z, v1.w); return o; }
; __device__ __forceinline__ f32x4 gelu4(f32x4 v) { pg8::f32x2 a = pg8::gelu_pk((pg8::f32x2){v.x, v.y}), b = pg8::gelu_pk((pg8::f32x2){v.z, v.w}); return (f32x4){a.x, a.y, b.x, b.y}; }
;     __device__ __forceinline__ void operator()(int row, int col, f32x4 v0, f32x4 v1) const { *(u32x4*)(G + (size_t)row * 1024 + col) = pack8(v0, v1); }
; __device__ __forceinline__ f32x4 sig4(f32x4 v) { return (f32x4){sigmoidf_(v.x), sigmoidf_(v.y), sigmoidf_(v.z), sigmoidf_(v.w)}; }
;     __device__ __forceinline__ void operator()(int row, int col, f32x4 v0, f32x4 v1) const {
;         bf16_t* dst;
;         if (col < 2048) { v0 = gelu4(v0); v1 = gelu4(v1); dst = (col < 1024 ? GU : GV) + (size_t)row * 1024 + (col & 1023); }
;         else if (col < 5120) { const int q = col - 2048; dst = Q + (size_t)(q >> 10) * (size_t)(18 * MiB) + (size_t)row * 1024 + (q & 1023); }
;         else if (col < 8704) { dst = RW + (size_t)row * RWP + (col - 5120); }
;         else { v0 = sig4(v0); v1 = sig4(v1); dst = GT + (size_t)row * 3072 + (col - 8704); }
;         *(u32x4*)dst = pack8(v0, v1);
;     }
.LBB0_592:
	s_or_b64 exec, exec, s[4:5]
	v_cvt_pk_bf16_f32 v90, v106, v107
	v_cvt_pk_bf16_f32 v91, v108, v109
	v_cvt_pk_bf16_f32 v92, v110, v111
	v_cvt_pk_bf16_f32 v93, v112, v113
	global_store_dwordx4 v[104:105], v[90:93], off
	s_and_saveexec_b64 s[4:5], s[44:45]
	s_xor_b64 s[4:5], exec, s[4:5]
	s_cbranch_execz .LBB0_602
	s_cmpk_lt_u32 s73, 0x1400
	s_mov_b64 s[6:7], -1
	s_cbranch_scc1 .LBB0_599
	s_cmpk_lt_u32 s73, 0x2200
	s_cbranch_scc1 .LBB0_596
	v_mul_f32_e32 v90, 0xbfb8aa3b, v86
	v_mul_f32_e32 v91, 0xbfb8aa3b, v87
	v_exp_f32_e32 v90, v90
	v_exp_f32_e32 v91, v91
	v_mul_f32_e32 v92, 0xbfb8aa3b, v88
	v_mul_f32_e32 v93, 0xbfb8aa3b, v89
	v_exp_f32_e32 v92, v92
	v_exp_f32_e32 v93, v93
	v_pk_add_f32 v[90:91], v[90:91], 1.0 op_sel_hi:[1,0]
	v_mov_b32_e32 v143, v1
	v_pk_add_f32 v[94:95], v[92:93], 1.0 op_sel_hi:[1,0]
	v_rcp_f32_e32 v93, v90
	s_nop 0
	v_fma_f32 v96, -v90, v93, 1.0
	v_fmac_f32_e32 v93, v96, v93
	v_fma_f32 v104, -v90, v93, 1.0
	v_fma_f32 v97, v104, v93, v93
	v_fma_f32 v92, -v90, v97, 1.0
	v_fma_f32 v92, v92, v93, v97
	v_div_fixup_f32 v92, v92, v90, 1.0
	v_rcp_f32_e32 v93, v91
	s_nop 0
	v_fma_f32 v96, -v91, v93, 1.0
	v_fmac_f32_e32 v93, v96, v93
	v_fma_f32 v104, -v91, v93, 1.0
	v_fma_f32 v97, v104, v93, v93
	v_fma_f32 v90, -v91, v97, 1.0
	v_fma_f32 v90, v90, v93, v97
	v_div_fixup_f32 v93, v90, v91, 1.0
	v_rcp_f32_e32 v91, v94
	s_nop 0
	v_fma_f32 v96, -v94, v91, 1.0
	v_fmac_f32_e32 v91, v96, v91
	v_fma_f32 v104, -v94, v91, 1.0
	v_fma_f32 v97, v104, v91, v91
	v_fma_f32 v90, -v94, v97, 1.0
	v_fma_f32 v90, v90, v91, v97
	v_div_fixup_f32 v94, v90, v94, 1.0
	v_rcp_f32_e32 v91, v95
	s_nop 0
	v_fma_f32 v96, -v95, v91, 1.0
	v_fmac_f32_e32 v91, v96, v91
	v_fma_f32 v104, -v95, v91, 1.0
	v_fma_f32 v97, v104, v91, v91
	v_fma_f32 v90, -v95, v97, 1.0
	v_fma_f32 v90, v90, v91, v97
	v_div_fixup_f32 v95, v90, v95, 1.0
	v_mul_f32_e32 v90, 0xbfb8aa3b, v82
	v_mul_f32_e32 v91, 0xbfb8aa3b, v83
	v_exp_f32_e32 v90, v90
	v_exp_f32_e32 v91, v91
	v_mul_f32_e32 v96, 0xbfb8aa3b, v84
	v_mul_f32_e32 v97, 0xbfb8aa3b, v85
	v_exp_f32_e32 v96, v96
	v_exp_f32_e32 v97, v97
	v_pk_add_f32 v[90:91], v[90:91], 1.0 op_sel_hi:[1,0]
	v_pk_add_f32 v[104:105], v[96:97], 1.0 op_sel_hi:[1,0]
	v_rcp_f32_e32 v97, v90
	s_nop 0
	v_fma_f32 v106, -v90, v97, 1.0
	v_fmac_f32_e32 v97, v106, v97
	v_fma_f32 v108, -v90, v97, 1.0
	v_fma_f32 v107, v108, v97, v97
	v_fma_f32 v96, -v90, v107, 1.0
	v_fma_f32 v96, v96, v97, v107
	v_div_fixup_f32 v96, v96, v90, 1.0
	v_rcp_f32_e32 v97, v91
	s_nop 0
	v_fma_f32 v106, -v91, v97, 1.0
	v_fmac_f32_e32 v97, v106, v97
	v_fma_f32 v108, -v91, v97, 1.0
	v_fma_f32 v107, v108, v97, v97
	v_fma_f32 v90, -v91, v107, 1.0
	v_fma_f32 v90, v90, v97, v107
	v_div_fixup_f32 v97, v90, v91, 1.0
	v_rcp_f32_e32 v91, v104
	s_nop 0
	v_fma_f32 v106, -v104, v91, 1.0
	v_fmac_f32_e32 v91, v106, v91
	v_fma_f32 v108, -v104, v91, 1.0
	v_fma_f32 v107, v108, v91, v91
	v_fma_f32 v90, -v104, v107, 1.0
	v_fma_f32 v90, v90, v91, v107
	v_div_fixup_f32 v104, v90, v104, 1.0
	v_rcp_f32_e32 v91, v105
	s_movk_i32 s6, 0xbd00
	s_mov_b32 s7, -1
	v_fma_f32 v106, -v105, v91, 1.0
	v_fmac_f32_e32 v91, v106, v91
	v_fma_f32 v108, -v105, v91, 1.0
	v_fma_f32 v107, v108, v91, v91
	v_fma_f32 v90, -v105, v107, 1.0
	v_fma_f32 v90, v90, v91, v107
	v_div_fixup_f32 v105, v90, v105, 1.0
	v_lshl_add_u64 v[90:91], s[54:55], 0, v[102:103]
	v_lshl_add_u64 v[90:91], v[142:143], 1, v[90:91]
	v_lshl_add_u64 v[90:91], v[90:91], 0, s[6:7]
	s_mov_b64 s[6:7], 0

; __device__ __forceinline__ float sigmoidf_(float x) { return 1.f / (1.f + __expf(-x)); }
; __device__ __forceinline__ u32x4 pack8(f32x4 v0, f32x4 v1) { u32x4 o; o.x = pkbf(v0.x, v0.y); o.y = pkbf(v0.z, v0.w); o.z = pkbf(v1.x, v1.y); o.w = pkbf(v1.z, v1.w); return o; }
; __device__ __forceinline__ f32x4 gelu4(f32x4 v) { pg8::f32x2 a = pg8::gelu_pk((pg8::f32x2){v.x, v.y}), b = pg8::gelu_pk((pg8::f32x2){v.z, v.w}); return (f32x4){a.x, a.y, b.x, b.y}; }
;     __device__ __forceinline__ void operator()(int row, int col, f32x4 v0, f32x4 v1) const { *(u32x4*)(G + (size_t)row * 1024 + col) = pack8(v0, v1); }
; __device__ __forceinline__ f32x4 sig4(f32x4 v) { return (f32x4){sigmoidf_(v.x), sigmoidf_(v.y), sigmoidf_(v.z), sigmoidf_(v.w)}; }
;     __device__ __forceinline__ void operator()(int row, int col, f32x4 v0, f32x4 v1) const {
;         bf16_t* dst;
;         if (col < 2048) { v0 = gelu4(v0); v1 = gelu4(v1); dst = (col < 1024 ? GU : GV) + (size_t)row * 1024 + (col & 1023); }
;         else if (col < 5120) { const int q = col - 2048; dst = Q + (size_t)(q >> 10) * (size_t)(18 * MiB) + (size_t)row * 1024 + (q & 1023); }
;         else if (col < 8704) { dst = RW + (size_t)row * RWP + (col - 5120); }
;         else { v0 = sig4(v0); v1 = sig4(v1); dst = GT + (size_t)row * 3072 + (col - 8704); }
;         *(u32x4*)dst = pack8(v0, v1);
;     }
.LBB0_604:
	s_or_b64 exec, exec, s[4:5]
	v_cvt_pk_bf16_f32 v82, v92, v93
	v_cvt_pk_bf16_f32 v83, v94, v95
	v_cvt_pk_bf16_f32 v84, v96, v97
	v_cvt_pk_bf16_f32 v85, v104, v105
	global_store_dwordx4 v[90:91], v[82:85], off
	s_nop 1
	v_or_b32_e32 v82, 48, v144
	v_ashrrev_i32_e32 v83, 31, v82
	v_mad_i64_i32 v[86:87], s[4:5], v82, s21, 0
	v_mad_i64_i32 v[84:85], s[4:5], v82, s67, 0
	v_lshlrev_b64 v[82:83], 11, v[82:83]
	s_and_saveexec_b64 s[4:5], s[42:43]
	s_xor_b64 s[4:5], exec, s[4:5]
	s_cbranch_execz .LBB0_614
	s_cmpk_lt_u32 s73, 0x1400
	s_mov_b64 s[6:7], -1
	s_cbranch_scc1 .LBB0_611
	s_cmpk_lt_u32 s73, 0x2200
	s_cbranch_scc1 .LBB0_608
	v_mul_f32_e32 v88, 0xbfb8aa3b, v78
	v_mul_f32_e32 v89, 0xbfb8aa3b, v79
	v_exp_f32_e32 v88, v88
	v_exp_f32_e32 v89, v89
	v_mul_f32_e32 v90, 0xbfb8aa3b, v80
	v_mul_f32_e32 v91, 0xbfb8aa3b, v81
	v_exp_f32_e32 v90, v90
	v_exp_f32_e32 v91, v91
	v_pk_add_f32 v[88:89], v[88:89], 1.0 op_sel_hi:[1,0]
	v_mov_b32_e32 v143, v1
	v_pk_add_f32 v[92:93], v[90:91], 1.0 op_sel_hi:[1,0]
	v_rcp_f32_e32 v91, v88
	s_nop 0
	v_fma_f32 v94, -v88, v91, 1.0
	v_fmac_f32_e32 v91, v94, v91
	v_fma_f32 v96, -v88, v91, 1.0
	v_fma_f32 v95, v96, v91, v91
	v_fma_f32 v90, -v88, v95, 1.0
	v_fma_f32 v90, v90, v91, v95
	v_div_fixup_f32 v90, v90, v88, 1.0
	v_rcp_f32_e32 v91, v89
	s_nop 0
	v_fma_f32 v94, -v89, v91, 1.0
	v_fmac_f32_e32 v91, v94, v91
	v_fma_f32 v96, -v89, v91, 1.0
	v_fma_f32 v95, v96, v91, v91
	v_fma_f32 v88, -v89, v95, 1.0
	v_fma_f32 v88, v88, v91, v95
	v_div_fixup_f32 v91, v88, v89, 1.0
	v_rcp_f32_e32 v89, v92
	s_nop 0
	v_fma_f32 v94, -v92, v89, 1.0
	v_fmac_f32_e32 v89, v94, v89
	v_fma_f32 v96, -v92, v89, 1.0
	v_fma_f32 v95, v96, v89, v89
	v_fma_f32 v88, -v92, v95, 1.0
	v_fma_f32 v88, v88, v89, v95
	v_div_fixup_f32 v92, v88, v92, 1.0
	v_rcp_f32_e32 v89, v93
	s_nop 0
	v_fma_f32 v94, -v93, v89, 1.0
	v_fmac_f32_e32 v89, v94, v89
	v_fma_f32 v96, -v93, v89, 1.0
	v_fma_f32 v95, v96, v89, v89
	v_fma_f32 v88, -v93, v95, 1.0
	v_fma_f32 v88, v88, v89, v95
	v_div_fixup_f32 v93, v88, v93, 1.0
	v_mul_f32_e32 v88, 0xbfb8aa3b, v74
	v_mul_f32_e32 v89, 0xbfb8aa3b, v75
	v_exp_f32_e32 v88, v88
	v_exp_f32_e32 v89, v89
	v_mul_f32_e32 v94, 0xbfb8aa3b, v76
	v_mul_f32_e32 v95, 0xbfb8aa3b, v77
	v_exp_f32_e32 v94, v94
	v_exp_f32_e32 v95, v95
	v_pk_add_f32 v[88:89], v[88:89], 1.0 op_sel_hi:[1,0]
	v_pk_add_f32 v[96:97], v[94:95], 1.0 op_sel_hi:[1,0]
	v_rcp_f32_e32 v95, v88
	s_nop 0
	v_fma_f32 v98, -v88, v95, 1.0
	v_fmac_f32_e32 v95, v98, v95
	v_fma_f32 v100, -v88, v95, 1.0
	v_fma_f32 v99, v100, v95, v95
	v_fma_f32 v94, -v88, v99, 1.0
	v_fma_f32 v94, v94, v95, v99
	v_div_fixup_f32 v94, v94, v88, 1.0
	v_rcp_f32_e32 v95, v89
	s_nop 0
	v_fma_f32 v98, -v89, v95, 1.0
	v_fmac_f32_e32 v95, v98, v95
	v_fma_f32 v100, -v89, v95, 1.0
	v_fma_f32 v99, v100, v95, v95
	v_fma_f32 v88, -v89, v99, 1.0
	v_fma_f32 v88, v88, v95, v99
	v_div_fixup_f32 v95, v88, v89, 1.0
	v_rcp_f32_e32 v89, v96
	s_nop 0
	v_fma_f32 v98, -v96, v89, 1.0
	v_fmac_f32_e32 v89, v98, v89
	v_fma_f32 v100, -v96, v89, 1.0
	v_fma_f32 v99, v100, v89, v89
	v_fma_f32 v88, -v96, v99, 1.0
	v_fma_f32 v88, v88, v89, v99
	v_div_fixup_f32 v96, v88, v96, 1.0
	v_rcp_f32_e32 v89, v97
	s_mov_b64 s[6:7], 0
	v_fma_f32 v98, -v97, v89, 1.0
	v_fmac_f32_e32 v89, v98, v89
	v_fma_f32 v100, -v97, v89, 1.0
	v_fma_f32 v99, v100, v89, v89
	v_fma_f32 v88, -v97, v99, 1.0
	v_fma_f32 v88, v88, v89, v99
	v_div_fixup_f32 v97, v88, v97, 1.0
	v_lshl_add_u64 v[88:89], s[54:55], 0, v[86:87]
	v_lshl_add_u64 v[88:89], v[142:143], 1, v[88:89]
	v_lshl_add_u64 v[88:89], v[88:89], 0, s[86:87]

; __device__ __forceinline__ float sigmoidf_(float x) { return 1.f / (1.f + __expf(-x)); }
; __device__ __forceinline__ u32x4 pack8(f32x4 v0, f32x4 v1) { u32x4 o; o.x = pkbf(v0.x, v0.y); o.y = pkbf(v0.z, v0.w); o.z = pkbf(v1.x, v1.y); o.w = pkbf(v1.z, v1.w); return o; }
; __device__ __forceinline__ f32x4 gelu4(f32x4 v) { pg8::f32x2 a = pg8::gelu_pk((pg8::f32x2){v.x, v.y}), b = pg8::gelu_pk((pg8::f32x2){v.z, v.w}); return (f32x4){a.x, a.y, b.x, b.y}; }
;     __device__ __forceinline__ void operator()(int row, int col, f32x4 v0, f32x4 v1) const { *(u32x4*)(G + (size_t)row * 1024 + col) = pack8(v0, v1); }
; __device__ __forceinline__ f32x4 sig4(f32x4 v) { return (f32x4){sigmoidf_(v.x), sigmoidf_(v.y), sigmoidf_(v.z), sigmoidf_(v.w)}; }
;     __device__ __forceinline__ void operator()(int row, int col, f32x4 v0, f32x4 v1) const {
;         bf16_t* dst;
;         if (col < 2048) { v0 = gelu4(v0); v1 = gelu4(v1); dst = (col < 1024 ? GU : GV) + (size_t)row * 1024 + (col & 1023); }
;         else if (col < 5120) { const int q = col - 2048; dst = Q + (size_t)(q >> 10) * (size_t)(18 * MiB) + (size_t)row * 1024 + (q & 1023); }
;         else if (col < 8704) { dst = RW + (size_t)row * RWP + (col - 5120); }
;         else { v0 = sig4(v0); v1 = sig4(v1); dst = GT + (size_t)row * 3072 + (col - 8704); }
;         *(u32x4*)dst = pack8(v0, v1);
;     }
.LBB0_616:
	s_or_b64 exec, exec, s[4:5]
	v_cvt_pk_bf16_f32 v74, v90, v91
	v_cvt_pk_bf16_f32 v75, v92, v93
	v_cvt_pk_bf16_f32 v76, v94, v95
	v_cvt_pk_bf16_f32 v77, v96, v97
	global_store_dwordx4 v[88:89], v[74:77], off
	s_and_saveexec_b64 s[4:5], s[44:45]
	s_xor_b64 s[4:5], exec, s[4:5]
	s_cbranch_execz .LBB0_626
	s_cmpk_lt_u32 s73, 0x1400
	s_mov_b64 s[6:7], -1
	s_cbranch_scc1 .LBB0_623
	s_cmpk_lt_u32 s73, 0x2200
	s_cbranch_scc1 .LBB0_620
	v_mul_f32_e32 v74, 0xbfb8aa3b, v70
	v_mul_f32_e32 v75, 0xbfb8aa3b, v71
	v_exp_f32_e32 v74, v74
	v_exp_f32_e32 v75, v75
	v_mul_f32_e32 v76, 0xbfb8aa3b, v72
	v_mul_f32_e32 v77, 0xbfb8aa3b, v73
	v_exp_f32_e32 v76, v76
	v_exp_f32_e32 v77, v77
	v_pk_add_f32 v[74:75], v[74:75], 1.0 op_sel_hi:[1,0]
	v_mov_b32_e32 v143, v1
	v_pk_add_f32 v[78:79], v[76:77], 1.0 op_sel_hi:[1,0]
	v_rcp_f32_e32 v77, v74
	s_nop 0
	v_fma_f32 v80, -v74, v77, 1.0
	v_fmac_f32_e32 v77, v80, v77
	v_fma_f32 v88, -v74, v77, 1.0
	v_fma_f32 v81, v88, v77, v77
	v_fma_f32 v76, -v74, v81, 1.0
	v_fma_f32 v76, v76, v77, v81
	v_div_fixup_f32 v76, v76, v74, 1.0
	v_rcp_f32_e32 v77, v75
	s_nop 0
	v_fma_f32 v80, -v75, v77, 1.0
	v_fmac_f32_e32 v77, v80, v77
	v_fma_f32 v88, -v75, v77, 1.0
	v_fma_f32 v81, v88, v77, v77
	v_fma_f32 v74, -v75, v81, 1.0
	v_fma_f32 v74, v74, v77, v81
	v_div_fixup_f32 v77, v74, v75, 1.0
	v_rcp_f32_e32 v75, v78
	s_nop 0
	v_fma_f32 v80, -v78, v75, 1.0
	v_fmac_f32_e32 v75, v80, v75
	v_fma_f32 v88, -v78, v75, 1.0
	v_fma_f32 v81, v88, v75, v75
	v_fma_f32 v74, -v78, v81, 1.0
	v_fma_f32 v74, v74, v75, v81
	v_div_fixup_f32 v78, v74, v78, 1.0
	v_rcp_f32_e32 v75, v79
	s_nop 0
	v_fma_f32 v80, -v79, v75, 1.0
	v_fmac_f32_e32 v75, v80, v75
	v_fma_f32 v88, -v79, v75, 1.0
	v_fma_f32 v81, v88, v75, v75
	v_fma_f32 v74, -v79, v81, 1.0
	v_fma_f32 v74, v74, v75, v81
	v_div_fixup_f32 v79, v74, v79, 1.0
	v_mul_f32_e32 v74, 0xbfb8aa3b, v66
	v_mul_f32_e32 v75, 0xbfb8aa3b, v67
	v_exp_f32_e32 v74, v74
	v_exp_f32_e32 v75, v75
	v_mul_f32_e32 v80, 0xbfb8aa3b, v68
	v_mul_f32_e32 v81, 0xbfb8aa3b, v69
	v_exp_f32_e32 v80, v80
	v_exp_f32_e32 v81, v81
	v_pk_add_f32 v[74:75], v[74:75], 1.0 op_sel_hi:[1,0]
	v_pk_add_f32 v[88:89], v[80:81], 1.0 op_sel_hi:[1,0]
	v_rcp_f32_e32 v81, v74
	s_nop 0
	v_fma_f32 v90, -v74, v81, 1.0
	v_fmac_f32_e32 v81, v90, v81
	v_fma_f32 v92, -v74, v81, 1.0
	v_fma_f32 v91, v92, v81, v81
	v_fma_f32 v80, -v74, v91, 1.0
	v_fma_f32 v80, v80, v81, v91
	v_div_fixup_f32 v80, v80, v74, 1.0
	v_rcp_f32_e32 v81, v75
	s_nop 0
	v_fma_f32 v90, -v75, v81, 1.0
	v_fmac_f32_e32 v81, v90, v81
	v_fma_f32 v92, -v75, v81, 1.0
	v_fma_f32 v91, v92, v81, v81
	v_fma_f32 v74, -v75, v91, 1.0
	v_fma_f32 v74, v74, v81, v91
	v_div_fixup_f32 v81, v74, v75, 1.0
	v_rcp_f32_e32 v75, v88
	s_nop 0
	v_fma_f32 v90, -v88, v75, 1.0
	v_fmac_f32_e32 v75, v90, v75
	v_fma_f32 v92, -v88, v75, 1.0
	v_fma_f32 v91, v92, v75, v75
	v_fma_f32 v74, -v88, v91, 1.0
	v_fma_f32 v74, v74, v75, v91
	v_div_fixup_f32 v88, v74, v88, 1.0
	v_rcp_f32_e32 v75, v89
	s_movk_i32 s6, 0xbd00
	s_mov_b32 s7, -1
	v_fma_f32 v90, -v89, v75, 1.0
	v_fmac_f32_e32 v75, v90, v75
	v_fma_f32 v92, -v89, v75, 1.0
	v_fma_f32 v91, v92, v75, v75
	v_fma_f32 v74, -v89, v91, 1.0
	v_fma_f32 v74, v74, v75, v91
	v_div_fixup_f32 v89, v74, v89, 1.0
	v_lshl_add_u64 v[74:75], s[54:55], 0, v[86:87]
	v_lshl_add_u64 v[74:75], v[142:143], 1, v[74:75]
	v_lshl_add_u64 v[74:75], v[74:75], 0, s[6:7]
	s_mov_b64 s[6:7], 0

; __device__ __forceinline__ float sigmoidf_(float x) { return 1.f / (1.f + __expf(-x)); }
; __device__ __forceinline__ u32x4 pack8(f32x4 v0, f32x4 v1) { u32x4 o; o.x = pkbf(v0.x, v0.y); o.y = pkbf(v0.z, v0.w); o.z = pkbf(v1.x, v1.y); o.w = pkbf(v1.z, v1.w); return o; }
; __device__ __forceinline__ f32x4 gelu4(f32x4 v) { pg8::f32x2 a = pg8::gelu_pk((pg8::f32x2){v.x, v.y}), b = pg8::gelu_pk((pg8::f32x2){v.z, v.w}); return (f32x4){a.x, a.y, b.x, b.y}; }
;     __device__ __forceinline__ void operator()(int row, int col, f32x4 v0, f32x4 v1) const { *(u32x4*)(G + (size_t)row * 1024 + col) = pack8(v0, v1); }
; __device__ __forceinline__ f32x4 sig4(f32x4 v) { return (f32x4){sigmoidf_(v.x), sigmoidf_(v.y), sigmoidf_(v.z), sigmoidf_(v.w)}; }
;     __device__ __forceinline__ void operator()(int row, int col, f32x4 v0, f32x4 v1) const {
;         bf16_t* dst;
;         if (col < 2048) { v0 = gelu4(v0); v1 = gelu4(v1); dst = (col < 1024 ? GU : GV) + (size_t)row * 1024 + (col & 1023); }
;         else if (col < 5120) { const int q = col - 2048; dst = Q + (size_t)(q >> 10) * (size_t)(18 * MiB) + (size_t)row * 1024 + (q & 1023); }
;         else if (col < 8704) { dst = RW + (size_t)row * RWP + (col - 5120); }
;         else { v0 = sig4(v0); v1 = sig4(v1); dst = GT + (size_t)row * 3072 + (col - 8704); }
;         *(u32x4*)dst = pack8(v0, v1);
;     }
.LBB0_628:
	s_or_b64 exec, exec, s[4:5]
	v_cvt_pk_bf16_f32 v66, v76, v77
	v_cvt_pk_bf16_f32 v67, v78, v79
	v_cvt_pk_bf16_f32 v68, v80, v81
	v_cvt_pk_bf16_f32 v69, v88, v89
	global_store_dwordx4 v[74:75], v[66:69], off
	s_nop 1
	v_add_u32_e32 v66, 0x80, v144
	v_ashrrev_i32_e32 v67, 31, v66
	v_mad_i64_i32 v[70:71], s[4:5], v66, s21, 0
	v_mad_i64_i32 v[68:69], s[4:5], v66, s67, 0
	v_lshlrev_b64 v[66:67], 11, v[66:67]
	s_and_saveexec_b64 s[4:5], s[42:43]
	s_xor_b64 s[4:5], exec, s[4:5]
	s_cbranch_execz .LBB0_638
	s_cmpk_lt_u32 s73, 0x1400
	s_mov_b64 s[6:7], -1
	s_cbranch_scc1 .LBB0_635
	s_cmpk_lt_u32 s73, 0x2200
	s_cbranch_scc1 .LBB0_632
	v_mul_f32_e32 v72, 0xbfb8aa3b, v62
	v_mul_f32_e32 v73, 0xbfb8aa3b, v63
	v_exp_f32_e32 v72, v72
	v_exp_f32_e32 v73, v73
	v_mul_f32_e32 v74, 0xbfb8aa3b, v64
	v_mul_f32_e32 v75, 0xbfb8aa3b, v65
	v_exp_f32_e32 v74, v74
	v_exp_f32_e32 v75, v75
	v_pk_add_f32 v[72:73], v[72:73], 1.0 op_sel_hi:[1,0]
	v_mov_b32_e32 v143, v1
	v_pk_add_f32 v[76:77], v[74:75], 1.0 op_sel_hi:[1,0]
	v_rcp_f32_e32 v75, v72
	s_nop 0
	v_fma_f32 v78, -v72, v75, 1.0
	v_fmac_f32_e32 v75, v78, v75
	v_fma_f32 v80, -v72, v75, 1.0
	v_fma_f32 v79, v80, v75, v75
	v_fma_f32 v74, -v72, v79, 1.0
	v_fma_f32 v74, v74, v75, v79
	v_div_fixup_f32 v74, v74, v72, 1.0
	v_rcp_f32_e32 v75, v73
	s_nop 0
	v_fma_f32 v78, -v73, v75, 1.0
	v_fmac_f32_e32 v75, v78, v75
	v_fma_f32 v80, -v73, v75, 1.0
	v_fma_f32 v79, v80, v75, v75
	v_fma_f32 v72, -v73, v79, 1.0
	v_fma_f32 v72, v72, v75, v79
	v_div_fixup_f32 v75, v72, v73, 1.0
	v_rcp_f32_e32 v73, v76
	s_nop 0
	v_fma_f32 v78, -v76, v73, 1.0
	v_fmac_f32_e32 v73, v78, v73
	v_fma_f32 v80, -v76, v73, 1.0
	v_fma_f32 v79, v80, v73, v73
	v_fma_f32 v72, -v76, v79, 1.0
	v_fma_f32 v72, v72, v73, v79
	v_div_fixup_f32 v76, v72, v76, 1.0
	v_rcp_f32_e32 v73, v77
	s_nop 0
	v_fma_f32 v78, -v77, v73, 1.0
	v_fmac_f32_e32 v73, v78, v73
	v_fma_f32 v80, -v77, v73, 1.0
	v_fma_f32 v79, v80, v73, v73
	v_fma_f32 v72, -v77, v79, 1.0
	v_fma_f32 v72, v72, v73, v79
	v_div_fixup_f32 v77, v72, v77, 1.0
	v_mul_f32_e32 v72, 0xbfb8aa3b, v58
	v_mul_f32_e32 v73, 0xbfb8aa3b, v59
	v_exp_f32_e32 v72, v72
	v_exp_f32_e32 v73, v73
	v_mul_f32_e32 v78, 0xbfb8aa3b, v60
	v_mul_f32_e32 v79, 0xbfb8aa3b, v61
	v_exp_f32_e32 v78, v78
	v_exp_f32_e32 v79, v79
	v_pk_add_f32 v[72:73], v[72:73], 1.0 op_sel_hi:[1,0]
	v_pk_add_f32 v[80:81], v[78:79], 1.0 op_sel_hi:[1,0]
	v_rcp_f32_e32 v79, v72
	s_nop 0
	v_fma_f32 v82, -v72, v79, 1.0
	v_fmac_f32_e32 v79, v82, v79
	v_fma_f32 v84, -v72, v79, 1.0
	v_fma_f32 v83, v84, v79, v79
	v_fma_f32 v78, -v72, v83, 1.0
	v_fma_f32 v78, v78, v79, v83
	v_div_fixup_f32 v78, v78, v72, 1.0
	v_rcp_f32_e32 v79, v73
	s_nop 0
	v_fma_f32 v82, -v73, v79, 1.0
	v_fmac_f32_e32 v79, v82, v79
	v_fma_f32 v84, -v73, v79, 1.0
	v_fma_f32 v83, v84, v79, v79
	v_fma_f32 v72, -v73, v83, 1.0
	v_fma_f32 v72, v72, v79, v83
	v_div_fixup_f32 v79, v72, v73, 1.0
	v_rcp_f32_e32 v73, v80
	s_nop 0
	v_fma_f32 v82, -v80, v73, 1.0
	v_fmac_f32_e32 v73, v82, v73
	v_fma_f32 v84, -v80, v73, 1.0
	v_fma_f32 v83, v84, v73, v73
	v_fma_f32 v72, -v80, v83, 1.0
	v_fma_f32 v72, v72, v73, v83
	v_div_fixup_f32 v80, v72, v80, 1.0
	v_rcp_f32_e32 v73, v81
	s_mov_b64 s[6:7], 0
	v_fma_f32 v82, -v81, v73, 1.0
	v_fmac_f32_e32 v73, v82, v73
	v_fma_f32 v84, -v81, v73, 1.0
	v_fma_f32 v83, v84, v73, v73
	v_fma_f32 v72, -v81, v83, 1.0
	v_fma_f32 v72, v72, v73, v83
	v_div_fixup_f32 v81, v72, v81, 1.0
	v_lshl_add_u64 v[72:73], s[54:55], 0, v[70:71]
	v_lshl_add_u64 v[72:73], v[142:143], 1, v[72:73]
	v_lshl_add_u64 v[72:73], v[72:73], 0, s[86:87]

; __device__ __forceinline__ float sigmoidf_(float x) { return 1.f / (1.f + __expf(-x)); }
; __device__ __forceinline__ u32x4 pack8(f32x4 v0, f32x4 v1) { u32x4 o; o.x = pkbf(v0.x, v0.y); o.y = pkbf(v0.z, v0.w); o.z = pkbf(v1.x, v1.y); o.w = pkbf(v1.z, v1.w); return o; }
; __device__ __forceinline__ f32x4 gelu4(f32x4 v) { pg8::f32x2 a = pg8::gelu_pk((pg8::f32x2){v.x, v.y}), b = pg8::gelu_pk((pg8::f32x2){v.z, v.w}); return (f32x4){a.x, a.y, b.x, b.y}; }
;     __device__ __forceinline__ void operator()(int row, int col, f32x4 v0, f32x4 v1) const { *(u32x4*)(G + (size_t)row * 1024 + col) = pack8(v0, v1); }
; __device__ __forceinline__ f32x4 sig4(f32x4 v) { return (f32x4){sigmoidf_(v.x), sigmoidf_(v.y), sigmoidf_(v.z), sigmoidf_(v.w)}; }
;     __device__ __forceinline__ void operator()(int row, int col, f32x4 v0, f32x4 v1) const {
;         bf16_t* dst;
;         if (col < 2048) { v0 = gelu4(v0); v1 = gelu4(v1); dst = (col < 1024 ? GU : GV) + (size_t)row * 1024 + (col & 1023); }
;         else if (col < 5120) { const int q = col - 2048; dst = Q + (size_t)(q >> 10) * (size_t)(18 * MiB) + (size_t)row * 1024 + (q & 1023); }
;         else if (col < 8704) { dst = RW + (size_t)row * RWP + (col - 5120); }
;         else { v0 = sig4(v0); v1 = sig4(v1); dst = GT + (size_t)row * 3072 + (col - 8704); }
;         *(u32x4*)dst = pack8(v0, v1);
;     }
.LBB0_640:
	s_or_b64 exec, exec, s[4:5]
	v_cvt_pk_bf16_f32 v58, v74, v75
	v_cvt_pk_bf16_f32 v59, v76, v77
	v_cvt_pk_bf16_f32 v60, v78, v79
	v_cvt_pk_bf16_f32 v61, v80, v81
	global_store_dwordx4 v[72:73], v[58:61], off
	s_and_saveexec_b64 s[4:5], s[44:45]
	s_xor_b64 s[4:5], exec, s[4:5]
	s_cbranch_execz .LBB0_650
	s_cmpk_lt_u32 s73, 0x1400
	s_mov_b64 s[6:7], -1
	s_cbranch_scc1 .LBB0_647
	s_cmpk_lt_u32 s73, 0x2200
	s_cbranch_scc1 .LBB0_644
	v_mul_f32_e32 v58, 0xbfb8aa3b, v54
	v_mul_f32_e32 v59, 0xbfb8aa3b, v55
	v_exp_f32_e32 v58, v58
	v_exp_f32_e32 v59, v59
	v_mul_f32_e32 v60, 0xbfb8aa3b, v56
	v_mul_f32_e32 v61, 0xbfb8aa3b, v57
	v_exp_f32_e32 v60, v60
	v_exp_f32_e32 v61, v61
	v_pk_add_f32 v[58:59], v[58:59], 1.0 op_sel_hi:[1,0]
	v_mov_b32_e32 v143, v1
	v_pk_add_f32 v[62:63], v[60:61], 1.0 op_sel_hi:[1,0]
	v_rcp_f32_e32 v61, v58
	s_nop 0
	v_fma_f32 v64, -v58, v61, 1.0
	v_fmac_f32_e32 v61, v64, v61
	v_fma_f32 v72, -v58, v61, 1.0
	v_fma_f32 v65, v72, v61, v61
	v_fma_f32 v60, -v58, v65, 1.0
	v_fma_f32 v60, v60, v61, v65
	v_div_fixup_f32 v60, v60, v58, 1.0
	v_rcp_f32_e32 v61, v59
	s_nop 0
	v_fma_f32 v64, -v59, v61, 1.0
	v_fmac_f32_e32 v61, v64, v61
	v_fma_f32 v72, -v59, v61, 1.0
	v_fma_f32 v65, v72, v61, v61
	v_fma_f32 v58, -v59, v65, 1.0
	v_fma_f32 v58, v58, v61, v65
	v_div_fixup_f32 v61, v58, v59, 1.0
	v_rcp_f32_e32 v59, v62
	s_nop 0
	v_fma_f32 v64, -v62, v59, 1.0
	v_fmac_f32_e32 v59, v64, v59
	v_fma_f32 v72, -v62, v59, 1.0
	v_fma_f32 v65, v72, v59, v59
	v_fma_f32 v58, -v62, v65, 1.0
	v_fma_f32 v58, v58, v59, v65
	v_div_fixup_f32 v62, v58, v62, 1.0
	v_rcp_f32_e32 v59, v63
	s_nop 0
	v_fma_f32 v64, -v63, v59, 1.0
	v_fmac_f32_e32 v59, v64, v59
	v_fma_f32 v72, -v63, v59, 1.0
	v_fma_f32 v65, v72, v59, v59
	v_fma_f32 v58, -v63, v65, 1.0
	v_fma_f32 v58, v58, v59, v65
	v_div_fixup_f32 v63, v58, v63, 1.0
	v_mul_f32_e32 v58, 0xbfb8aa3b, v50
	v_mul_f32_e32 v59, 0xbfb8aa3b, v51
	v_exp_f32_e32 v58, v58
	v_exp_f32_e32 v59, v59
	v_mul_f32_e32 v64, 0xbfb8aa3b, v52
	v_mul_f32_e32 v65, 0xbfb8aa3b, v53
	v_exp_f32_e32 v64, v64
	v_exp_f32_e32 v65, v65
	v_pk_add_f32 v[58:59], v[58:59], 1.0 op_sel_hi:[1,0]
	v_pk_add_f32 v[72:73], v[64:65], 1.0 op_sel_hi:[1,0]
	v_rcp_f32_e32 v65, v58
	s_nop 0
	v_fma_f32 v74, -v58, v65, 1.0
	v_fmac_f32_e32 v65, v74, v65
	v_fma_f32 v76, -v58, v65, 1.0
	v_fma_f32 v75, v76, v65, v65
	v_fma_f32 v64, -v58, v75, 1.0
	v_fma_f32 v64, v64, v65, v75
	v_div_fixup_f32 v64, v64, v58, 1.0
	v_rcp_f32_e32 v65, v59
	s_nop 0
	v_fma_f32 v74, -v59, v65, 1.0
	v_fmac_f32_e32 v65, v74, v65
	v_fma_f32 v76, -v59, v65, 1.0
	v_fma_f32 v75, v76, v65, v65
	v_fma_f32 v58, -v59, v75, 1.0
	v_fma_f32 v58, v58, v65, v75
	v_div_fixup_f32 v65, v58, v59, 1.0
	v_rcp_f32_e32 v59, v72
	s_nop 0
	v_fma_f32 v74, -v72, v59, 1.0
	v_fmac_f32_e32 v59, v74, v59
	v_fma_f32 v76, -v72, v59, 1.0
	v_fma_f32 v75, v76, v59, v59
	v_fma_f32 v58, -v72, v75, 1.0
	v_fma_f32 v58, v58, v59, v75
	v_div_fixup_f32 v72, v58, v72, 1.0
	v_rcp_f32_e32 v59, v73
	s_movk_i32 s6, 0xbd00
	s_mov_b32 s7, -1
	v_fma_f32 v74, -v73, v59, 1.0
	v_fmac_f32_e32 v59, v74, v59
	v_fma_f32 v76, -v73, v59, 1.0
	v_fma_f32 v75, v76, v59, v59
	v_fma_f32 v58, -v73, v75, 1.0
	v_fma_f32 v58, v58, v59, v75
	v_div_fixup_f32 v73, v58, v73, 1.0
	v_lshl_add_u64 v[58:59], s[54:55], 0, v[70:71]
	v_lshl_add_u64 v[58:59], v[142:143], 1, v[58:59]
	v_lshl_add_u64 v[58:59], v[58:59], 0, s[6:7]
	s_mov_b64 s[6:7], 0

; __device__ __forceinline__ float sigmoidf_(float x) { return 1.f / (1.f + __expf(-x)); }
; __device__ __forceinline__ u32x4 pack8(f32x4 v0, f32x4 v1) { u32x4 o; o.x = pkbf(v0.x, v0.y); o.y = pkbf(v0.z, v0.w); o.z = pkbf(v1.x, v1.y); o.w = pkbf(v1.z, v1.w); return o; }
; __device__ __forceinline__ f32x4 gelu4(f32x4 v) { pg8::f32x2 a = pg8::gelu_pk((pg8::f32x2){v.x, v.y}), b = pg8::gelu_pk((pg8::f32x2){v.z, v.w}); return (f32x4){a.x, a.y, b.x, b.y}; }
;     __device__ __forceinline__ void operator()(int row, int col, f32x4 v0, f32x4 v1) const { *(u32x4*)(G + (size_t)row * 1024 + col) = pack8(v0, v1); }
; __device__ __forceinline__ f32x4 sig4(f32x4 v) { return (f32x4){sigmoidf_(v.x), sigmoidf_(v.y), sigmoidf_(v.z), sigmoidf_(v.w)}; }
;     __device__ __forceinline__ void operator()(int row, int col, f32x4 v0, f32x4 v1) const {
;         bf16_t* dst;
;         if (col < 2048) { v0 = gelu4(v0); v1 = gelu4(v1); dst = (col < 1024 ? GU : GV) + (size_t)row * 1024 + (col & 1023); }
;         else if (col < 5120) { const int q = col - 2048; dst = Q + (size_t)(q >> 10) * (size_t)(18 * MiB) + (size_t)row * 1024 + (q & 1023); }
;         else if (col < 8704) { dst = RW + (size_t)row * RWP + (col - 5120); }
;         else { v0 = sig4(v0); v1 = sig4(v1); dst = GT + (size_t)row * 3072 + (col - 8704); }
;         *(u32x4*)dst = pack8(v0, v1);
;     }
.LBB0_652:
	s_or_b64 exec, exec, s[4:5]
	v_cvt_pk_bf16_f32 v50, v60, v61
	v_cvt_pk_bf16_f32 v51, v62, v63
	v_cvt_pk_bf16_f32 v52, v64, v65
	v_cvt_pk_bf16_f32 v53, v72, v73
	global_store_dwordx4 v[58:59], v[50:53], off
	s_nop 1
	v_add_u32_e32 v50, 0x90, v144
	v_ashrrev_i32_e32 v51, 31, v50
	v_mad_i64_i32 v[54:55], s[4:5], v50, s21, 0
	v_mad_i64_i32 v[52:53], s[4:5], v50, s67, 0
	v_lshlrev_b64 v[50:51], 11, v[50:51]
	s_and_saveexec_b64 s[4:5], s[42:43]
	s_xor_b64 s[4:5], exec, s[4:5]
	s_cbranch_execz .LBB0_662
	s_cmpk_lt_u32 s73, 0x1400
	s_mov_b64 s[6:7], -1
	s_cbranch_scc1 .LBB0_659
	s_cmpk_lt_u32 s73, 0x2200
	s_cbranch_scc1 .LBB0_656
	v_mul_f32_e32 v56, 0xbfb8aa3b, v46
	v_mul_f32_e32 v57, 0xbfb8aa3b, v47
	v_exp_f32_e32 v56, v56
	v_exp_f32_e32 v57, v57
	v_mul_f32_e32 v58, 0xbfb8aa3b, v48
	v_mul_f32_e32 v59, 0xbfb8aa3b, v49
	v_exp_f32_e32 v58, v58
	v_exp_f32_e32 v59, v59
	v_pk_add_f32 v[56:57], v[56:57], 1.0 op_sel_hi:[1,0]
	v_mov_b32_e32 v143, v1
	v_pk_add_f32 v[60:61], v[58:59], 1.0 op_sel_hi:[1,0]
	v_rcp_f32_e32 v59, v56
	s_nop 0
	v_fma_f32 v62, -v56, v59, 1.0
	v_fmac_f32_e32 v59, v62, v59
	v_fma_f32 v64, -v56, v59, 1.0
	v_fma_f32 v63, v64, v59, v59
	v_fma_f32 v58, -v56, v63, 1.0
	v_fma_f32 v58, v58, v59, v63
	v_div_fixup_f32 v58, v58, v56, 1.0
	v_rcp_f32_e32 v59, v57
	s_nop 0
	v_fma_f32 v62, -v57, v59, 1.0
	v_fmac_f32_e32 v59, v62, v59
	v_fma_f32 v64, -v57, v59, 1.0
	v_fma_f32 v63, v64, v59, v59
	v_fma_f32 v56, -v57, v63, 1.0
	v_fma_f32 v56, v56, v59, v63
	v_div_fixup_f32 v59, v56, v57, 1.0
	v_rcp_f32_e32 v57, v60
	s_nop 0
	v_fma_f32 v62, -v60, v57, 1.0
	v_fmac_f32_e32 v57, v62, v57
	v_fma_f32 v64, -v60, v57, 1.0
	v_fma_f32 v63, v64, v57, v57
	v_fma_f32 v56, -v60, v63, 1.0
	v_fma_f32 v56, v56, v57, v63
	v_div_fixup_f32 v60, v56, v60, 1.0
	v_rcp_f32_e32 v57, v61
	s_nop 0
	v_fma_f32 v62, -v61, v57, 1.0
	v_fmac_f32_e32 v57, v62, v57
	v_fma_f32 v64, -v61, v57, 1.0
	v_fma_f32 v63, v64, v57, v57
	v_fma_f32 v56, -v61, v63, 1.0
	v_fma_f32 v56, v56, v57, v63
	v_div_fixup_f32 v61, v56, v61, 1.0
	v_mul_f32_e32 v56, 0xbfb8aa3b, v42
	v_mul_f32_e32 v57, 0xbfb8aa3b, v43
	v_exp_f32_e32 v56, v56
	v_exp_f32_e32 v57, v57
	v_mul_f32_e32 v62, 0xbfb8aa3b, v44
	v_mul_f32_e32 v63, 0xbfb8aa3b, v45
	v_exp_f32_e32 v62, v62
	v_exp_f32_e32 v63, v63
	v_pk_add_f32 v[56:57], v[56:57], 1.0 op_sel_hi:[1,0]
	v_pk_add_f32 v[64:65], v[62:63], 1.0 op_sel_hi:[1,0]
	v_rcp_f32_e32 v63, v56
	s_nop 0
	v_fma_f32 v66, -v56, v63, 1.0
	v_fmac_f32_e32 v63, v66, v63
	v_fma_f32 v68, -v56, v63, 1.0
	v_fma_f32 v67, v68, v63, v63
	v_fma_f32 v62, -v56, v67, 1.0
	v_fma_f32 v62, v62, v63, v67
	v_div_fixup_f32 v62, v62, v56, 1.0
	v_rcp_f32_e32 v63, v57
	s_nop 0
	v_fma_f32 v66, -v57, v63, 1.0
	v_fmac_f32_e32 v63, v66, v63
	v_fma_f32 v68, -v57, v63, 1.0
	v_fma_f32 v67, v68, v63, v63
	v_fma_f32 v56, -v57, v67, 1.0
	v_fma_f32 v56, v56, v63, v67
	v_div_fixup_f32 v63, v56, v57, 1.0
	v_rcp_f32_e32 v57, v64
	s_nop 0
	v_fma_f32 v66, -v64, v57, 1.0
	v_fmac_f32_e32 v57, v66, v57
	v_fma_f32 v68, -v64, v57, 1.0
	v_fma_f32 v67, v68, v57, v57
	v_fma_f32 v56, -v64, v67, 1.0
	v_fma_f32 v56, v56, v57, v67
	v_div_fixup_f32 v64, v56, v64, 1.0
	v_rcp_f32_e32 v57, v65
	s_mov_b64 s[6:7], 0
	v_fma_f32 v66, -v65, v57, 1.0
	v_fmac_f32_e32 v57, v66, v57
	v_fma_f32 v68, -v65, v57, 1.0
	v_fma_f32 v67, v68, v57, v57
	v_fma_f32 v56, -v65, v67, 1.0
	v_fma_f32 v56, v56, v57, v67
	v_div_fixup_f32 v65, v56, v65, 1.0
	v_lshl_add_u64 v[56:57], s[54:55], 0, v[54:55]
	v_lshl_add_u64 v[56:57], v[142:143], 1, v[56:57]
	v_lshl_add_u64 v[56:57], v[56:57], 0, s[86:87]

; __device__ __forceinline__ float sigmoidf_(float x) { return 1.f / (1.f + __expf(-x)); }
; __device__ __forceinline__ u32x4 pack8(f32x4 v0, f32x4 v1) { u32x4 o; o.x = pkbf(v0.x, v0.y); o.y = pkbf(v0.z, v0.w); o.z = pkbf(v1.x, v1.y); o.w = pkbf(v1.z, v1.w); return o; }
; __device__ __forceinline__ f32x4 gelu4(f32x4 v) { pg8::f32x2 a = pg8::gelu_pk((pg8::f32x2){v.x, v.y}), b = pg8::gelu_pk((pg8::f32x2){v.z, v.w}); return (f32x4){a.x, a.y, b.x, b.y}; }
;     __device__ __forceinline__ void operator()(int row, int col, f32x4 v0, f32x4 v1) const { *(u32x4*)(G + (size_t)row * 1024 + col) = pack8(v0, v1); }
; __device__ __forceinline__ f32x4 sig4(f32x4 v) { return (f32x4){sigmoidf_(v.x), sigmoidf_(v.y), sigmoidf_(v.z), sigmoidf_(v.w)}; }
;     __device__ __forceinline__ void operator()(int row, int col, f32x4 v0, f32x4 v1) const {
;         bf16_t* dst;
;         if (col < 2048) { v0 = gelu4(v0); v1 = gelu4(v1); dst = (col < 1024 ? GU : GV) + (size_t)row * 1024 + (col & 1023); }
;         else if (col < 5120) { const int q = col - 2048; dst = Q + (size_t)(q >> 10) * (size_t)(18 * MiB) + (size_t)row * 1024 + (q & 1023); }
;         else if (col < 8704) { dst = RW + (size_t)row * RWP + (col - 5120); }
;         else { v0 = sig4(v0); v1 = sig4(v1); dst = GT + (size_t)row * 3072 + (col - 8704); }
;         *(u32x4*)dst = pack8(v0, v1);
;     }
.LBB0_664:
	s_or_b64 exec, exec, s[4:5]
	v_cvt_pk_bf16_f32 v42, v58, v59
	v_cvt_pk_bf16_f32 v43, v60, v61
	v_cvt_pk_bf16_f32 v44, v62, v63
	v_cvt_pk_bf16_f32 v45, v64, v65
	global_store_dwordx4 v[56:57], v[42:45], off
	s_and_saveexec_b64 s[4:5], s[44:45]
	s_xor_b64 s[4:5], exec, s[4:5]
	s_cbranch_execz .LBB0_674
	s_cmpk_lt_u32 s73, 0x1400
	s_mov_b64 s[6:7], -1
	s_cbranch_scc1 .LBB0_671
	s_cmpk_lt_u32 s73, 0x2200
	s_cbranch_scc1 .LBB0_668
	v_mul_f32_e32 v42, 0xbfb8aa3b, v38
	v_mul_f32_e32 v43, 0xbfb8aa3b, v39
	v_exp_f32_e32 v42, v42
	v_exp_f32_e32 v43, v43
	v_mul_f32_e32 v44, 0xbfb8aa3b, v40
	v_mul_f32_e32 v45, 0xbfb8aa3b, v41
	v_exp_f32_e32 v44, v44
	v_exp_f32_e32 v45, v45
	v_pk_add_f32 v[42:43], v[42:43], 1.0 op_sel_hi:[1,0]
	v_mov_b32_e32 v143, v1
	v_pk_add_f32 v[46:47], v[44:45], 1.0 op_sel_hi:[1,0]
	v_rcp_f32_e32 v45, v42
	s_nop 0
	v_fma_f32 v48, -v42, v45, 1.0
	v_fmac_f32_e32 v45, v48, v45
	v_fma_f32 v56, -v42, v45, 1.0
	v_fma_f32 v49, v56, v45, v45
	v_fma_f32 v44, -v42, v49, 1.0
	v_fma_f32 v44, v44, v45, v49
	v_div_fixup_f32 v44, v44, v42, 1.0
	v_rcp_f32_e32 v45, v43
	s_nop 0
	v_fma_f32 v48, -v43, v45, 1.0
	v_fmac_f32_e32 v45, v48, v45
	v_fma_f32 v56, -v43, v45, 1.0
	v_fma_f32 v49, v56, v45, v45
	v_fma_f32 v42, -v43, v49, 1.0
	v_fma_f32 v42, v42, v45, v49
	v_div_fixup_f32 v45, v42, v43, 1.0
	v_rcp_f32_e32 v43, v46
	s_nop 0
	v_fma_f32 v48, -v46, v43, 1.0
	v_fmac_f32_e32 v43, v48, v43
	v_fma_f32 v56, -v46, v43, 1.0
	v_fma_f32 v49, v56, v43, v43
	v_fma_f32 v42, -v46, v49, 1.0
	v_fma_f32 v42, v42, v43, v49
	v_div_fixup_f32 v46, v42, v46, 1.0
	v_rcp_f32_e32 v43, v47
	s_nop 0
	v_fma_f32 v48, -v47, v43, 1.0
	v_fmac_f32_e32 v43, v48, v43
	v_fma_f32 v56, -v47, v43, 1.0
	v_fma_f32 v49, v56, v43, v43
	v_fma_f32 v42, -v47, v49, 1.0
	v_fma_f32 v42, v42, v43, v49
	v_div_fixup_f32 v47, v42, v47, 1.0
	v_mul_f32_e32 v42, 0xbfb8aa3b, v34
	v_mul_f32_e32 v43, 0xbfb8aa3b, v35
	v_exp_f32_e32 v42, v42
	v_exp_f32_e32 v43, v43
	v_mul_f32_e32 v48, 0xbfb8aa3b, v36
	v_mul_f32_e32 v49, 0xbfb8aa3b, v37
	v_exp_f32_e32 v48, v48
	v_exp_f32_e32 v49, v49
	v_pk_add_f32 v[42:43], v[42:43], 1.0 op_sel_hi:[1,0]
	v_pk_add_f32 v[56:57], v[48:49], 1.0 op_sel_hi:[1,0]
	v_rcp_f32_e32 v49, v42
	s_nop 0
	v_fma_f32 v58, -v42, v49, 1.0
	v_fmac_f32_e32 v49, v58, v49
	v_fma_f32 v60, -v42, v49, 1.0
	v_fma_f32 v59, v60, v49, v49
	v_fma_f32 v48, -v42, v59, 1.0
	v_fma_f32 v48, v48, v49, v59
	v_div_fixup_f32 v48, v48, v42, 1.0
	v_rcp_f32_e32 v49, v43
	s_nop 0
	v_fma_f32 v58, -v43, v49, 1.0
	v_fmac_f32_e32 v49, v58, v49
	v_fma_f32 v60, -v43, v49, 1.0
	v_fma_f32 v59, v60, v49, v49
	v_fma_f32 v42, -v43, v59, 1.0
	v_fma_f32 v42, v42, v49, v59
	v_div_fixup_f32 v49, v42, v43, 1.0
	v_rcp_f32_e32 v43, v56
	s_nop 0
	v_fma_f32 v58, -v56, v43, 1.0
	v_fmac_f32_e32 v43, v58, v43
	v_fma_f32 v60, -v56, v43, 1.0
	v_fma_f32 v59, v60, v43, v43
	v_fma_f32 v42, -v56, v59, 1.0
	v_fma_f32 v42, v42, v43, v59
	v_div_fixup_f32 v56, v42, v56, 1.0
	v_rcp_f32_e32 v43, v57
	s_movk_i32 s6, 0xbd00
	s_mov_b32 s7, -1
	v_fma_f32 v58, -v57, v43, 1.0
	v_fmac_f32_e32 v43, v58, v43
	v_fma_f32 v60, -v57, v43, 1.0
	v_fma_f32 v59, v60, v43, v43
	v_fma_f32 v42, -v57, v59, 1.0
	v_fma_f32 v42, v42, v43, v59
	v_div_fixup_f32 v57, v42, v57, 1.0
	v_lshl_add_u64 v[42:43], s[54:55], 0, v[54:55]
	v_lshl_add_u64 v[42:43], v[142:143], 1, v[42:43]
	v_lshl_add_u64 v[42:43], v[42:43], 0, s[6:7]
	s_mov_b64 s[6:7], 0

; __device__ __forceinline__ float sigmoidf_(float x) { return 1.f / (1.f + __expf(-x)); }
; __device__ __forceinline__ u32x4 pack8(f32x4 v0, f32x4 v1) { u32x4 o; o.x = pkbf(v0.x, v0.y); o.y = pkbf(v0.z, v0.w); o.z = pkbf(v1.x, v1.y); o.w = pkbf(v1.z, v1.w); return o; }
; __device__ __forceinline__ f32x4 gelu4(f32x4 v) { pg8::f32x2 a = pg8::gelu_pk((pg8::f32x2){v.x, v.y}), b = pg8::gelu_pk((pg8::f32x2){v.z, v.w}); return (f32x4){a.x, a.y, b.x, b.y}; }
;     __device__ __forceinline__ void operator()(int row, int col, f32x4 v0, f32x4 v1) const { *(u32x4*)(G + (size_t)row * 1024 + col) = pack8(v0, v1); }
; __device__ __forceinline__ f32x4 sig4(f32x4 v) { return (f32x4){sigmoidf_(v.x), sigmoidf_(v.y), sigmoidf_(v.z), sigmoidf_(v.w)}; }
;     __device__ __forceinline__ void operator()(int row, int col, f32x4 v0, f32x4 v1) const {
;         bf16_t* dst;
;         if (col < 2048) { v0 = gelu4(v0); v1 = gelu4(v1); dst = (col < 1024 ? GU : GV) + (size_t)row * 1024 + (col & 1023); }
;         else if (col < 5120) { const int q = col - 2048; dst = Q + (size_t)(q >> 10) * (size_t)(18 * MiB) + (size_t)row * 1024 + (q & 1023); }
;         else if (col < 8704) { dst = RW + (size_t)row * RWP + (col - 5120); }
;         else { v0 = sig4(v0); v1 = sig4(v1); dst = GT + (size_t)row * 3072 + (col - 8704); }
;         *(u32x4*)dst = pack8(v0, v1);
;     }
.LBB0_676:
	s_or_b64 exec, exec, s[4:5]
	v_cvt_pk_bf16_f32 v34, v44, v45
	v_cvt_pk_bf16_f32 v35, v46, v47
	v_cvt_pk_bf16_f32 v36, v48, v49
	v_cvt_pk_bf16_f32 v37, v56, v57
	global_store_dwordx4 v[42:43], v[34:37], off
	s_nop 1
	v_add_u32_e32 v34, 0xa0, v144
	v_ashrrev_i32_e32 v35, 31, v34
	v_mad_i64_i32 v[38:39], s[4:5], v34, s21, 0
	v_mad_i64_i32 v[36:37], s[4:5], v34, s67, 0
	v_lshlrev_b64 v[34:35], 11, v[34:35]
	s_and_saveexec_b64 s[4:5], s[42:43]
	s_xor_b64 s[4:5], exec, s[4:5]
	s_cbranch_execz .LBB0_686
	s_cmpk_lt_u32 s73, 0x1400
	s_mov_b64 s[6:7], -1
	s_cbranch_scc1 .LBB0_683
	s_cmpk_lt_u32 s73, 0x2200
	s_cbranch_scc1 .LBB0_680
	v_mul_f32_e32 v40, 0xbfb8aa3b, v30
	v_mul_f32_e32 v41, 0xbfb8aa3b, v31
	v_exp_f32_e32 v40, v40
	v_exp_f32_e32 v41, v41
	v_mul_f32_e32 v42, 0xbfb8aa3b, v32
	v_mul_f32_e32 v43, 0xbfb8aa3b, v33
	v_exp_f32_e32 v42, v42
	v_exp_f32_e32 v43, v43
	v_pk_add_f32 v[40:41], v[40:41], 1.0 op_sel_hi:[1,0]
	v_mov_b32_e32 v143, v1
	v_pk_add_f32 v[44:45], v[42:43], 1.0 op_sel_hi:[1,0]
	v_rcp_f32_e32 v43, v40
	s_nop 0
	v_fma_f32 v46, -v40, v43, 1.0
	v_fmac_f32_e32 v43, v46, v43
	v_fma_f32 v48, -v40, v43, 1.0
	v_fma_f32 v47, v48, v43, v43
	v_fma_f32 v42, -v40, v47, 1.0
	v_fma_f32 v42, v42, v43, v47
	v_div_fixup_f32 v42, v42, v40, 1.0
	v_rcp_f32_e32 v43, v41
	s_nop 0
	v_fma_f32 v46, -v41, v43, 1.0
	v_fmac_f32_e32 v43, v46, v43
	v_fma_f32 v48, -v41, v43, 1.0
	v_fma_f32 v47, v48, v43, v43
	v_fma_f32 v40, -v41, v47, 1.0
	v_fma_f32 v40, v40, v43, v47
	v_div_fixup_f32 v43, v40, v41, 1.0
	v_rcp_f32_e32 v41, v44
	s_nop 0
	v_fma_f32 v46, -v44, v41, 1.0
	v_fmac_f32_e32 v41, v46, v41
	v_fma_f32 v48, -v44, v41, 1.0
	v_fma_f32 v47, v48, v41, v41
	v_fma_f32 v40, -v44, v47, 1.0
	v_fma_f32 v40, v40, v41, v47
	v_div_fixup_f32 v44, v40, v44, 1.0
	v_rcp_f32_e32 v41, v45
	s_nop 0
	v_fma_f32 v46, -v45, v41, 1.0
	v_fmac_f32_e32 v41, v46, v41
	v_fma_f32 v48, -v45, v41, 1.0
	v_fma_f32 v47, v48, v41, v41
	v_fma_f32 v40, -v45, v47, 1.0
	v_fma_f32 v40, v40, v41, v47
	v_div_fixup_f32 v45, v40, v45, 1.0
	v_mul_f32_e32 v40, 0xbfb8aa3b, v26
	v_mul_f32_e32 v41, 0xbfb8aa3b, v27
	v_exp_f32_e32 v40, v40
	v_exp_f32_e32 v41, v41
	v_mul_f32_e32 v46, 0xbfb8aa3b, v28
	v_mul_f32_e32 v47, 0xbfb8aa3b, v29
	v_exp_f32_e32 v46, v46
	v_exp_f32_e32 v47, v47
	v_pk_add_f32 v[40:41], v[40:41], 1.0 op_sel_hi:[1,0]
	v_pk_add_f32 v[48:49], v[46:47], 1.0 op_sel_hi:[1,0]
	v_rcp_f32_e32 v47, v40
	s_nop 0
	v_fma_f32 v50, -v40, v47, 1.0
	v_fmac_f32_e32 v47, v50, v47
	v_fma_f32 v52, -v40, v47, 1.0
	v_fma_f32 v51, v52, v47, v47
	v_fma_f32 v46, -v40, v51, 1.0
	v_fma_f32 v46, v46, v47, v51
	v_div_fixup_f32 v46, v46, v40, 1.0
	v_rcp_f32_e32 v47, v41
	s_nop 0
	v_fma_f32 v50, -v41, v47, 1.0
	v_fmac_f32_e32 v47, v50, v47
	v_fma_f32 v52, -v41, v47, 1.0
	v_fma_f32 v51, v52, v47, v47
	v_fma_f32 v40, -v41, v51, 1.0
	v_fma_f32 v40, v40, v47, v51
	v_div_fixup_f32 v47, v40, v41, 1.0
	v_rcp_f32_e32 v41, v48
	s_nop 0
	v_fma_f32 v50, -v48, v41, 1.0
	v_fmac_f32_e32 v41, v50, v41
	v_fma_f32 v52, -v48, v41, 1.0
	v_fma_f32 v51, v52, v41, v41
	v_fma_f32 v40, -v48, v51, 1.0
	v_fma_f32 v40, v40, v41, v51
	v_div_fixup_f32 v48, v40, v48, 1.0
	v_rcp_f32_e32 v41, v49
	s_mov_b64 s[6:7], 0
	v_fma_f32 v50, -v49, v41, 1.0
	v_fmac_f32_e32 v41, v50, v41
	v_fma_f32 v52, -v49, v41, 1.0
	v_fma_f32 v51, v52, v41, v41
	v_fma_f32 v40, -v49, v51, 1.0
	v_fma_f32 v40, v40, v41, v51
	v_div_fixup_f32 v49, v40, v49, 1.0
	v_lshl_add_u64 v[40:41], s[54:55], 0, v[38:39]
	v_lshl_add_u64 v[40:41], v[142:143], 1, v[40:41]
	v_lshl_add_u64 v[40:41], v[40:41], 0, s[86:87]

; __device__ __forceinline__ float sigmoidf_(float x) { return 1.f / (1.f + __expf(-x)); }
; __device__ __forceinline__ u32x4 pack8(f32x4 v0, f32x4 v1) { u32x4 o; o.x = pkbf(v0.x, v0.y); o.y = pkbf(v0.z, v0.w); o.z = pkbf(v1.x, v1.y); o.w = pkbf(v1.z, v1.w); return o; }
; __device__ __forceinline__ f32x4 gelu4(f32x4 v) { pg8::f32x2 a = pg8::gelu_pk((pg8::f32x2){v.x, v.y}), b = pg8::gelu_pk((pg8::f32x2){v.z, v.w}); return (f32x4){a.x, a.y, b.x, b.y}; }
;     __device__ __forceinline__ void operator()(int row, int col, f32x4 v0, f32x4 v1) const { *(u32x4*)(G + (size_t)row * 1024 + col) = pack8(v0, v1); }
; __device__ __forceinline__ f32x4 sig4(f32x4 v) { return (f32x4){sigmoidf_(v.x), sigmoidf_(v.y), sigmoidf_(v.z), sigmoidf_(v.w)}; }
;     __device__ __forceinline__ void operator()(int row, int col, f32x4 v0, f32x4 v1) const {
;         bf16_t* dst;
;         if (col < 2048) { v0 = gelu4(v0); v1 = gelu4(v1); dst = (col < 1024 ? GU : GV) + (size_t)row * 1024 + (col & 1023); }
;         else if (col < 5120) { const int q = col - 2048; dst = Q + (size_t)(q >> 10) * (size_t)(18 * MiB) + (size_t)row * 1024 + (q & 1023); }
;         else if (col < 8704) { dst = RW + (size_t)row * RWP + (col - 5120); }
;         else { v0 = sig4(v0); v1 = sig4(v1); dst = GT + (size_t)row * 3072 + (col - 8704); }
;         *(u32x4*)dst = pack8(v0, v1);
;     }
.LBB0_688:
	s_or_b64 exec, exec, s[4:5]
	v_cvt_pk_bf16_f32 v26, v42, v43
	v_cvt_pk_bf16_f32 v27, v44, v45
	v_cvt_pk_bf16_f32 v28, v46, v47
	v_cvt_pk_bf16_f32 v29, v48, v49
	global_store_dwordx4 v[40:41], v[26:29], off
	s_and_saveexec_b64 s[4:5], s[44:45]
	s_xor_b64 s[4:5], exec, s[4:5]
	s_cbranch_execz .LBB0_698
	s_cmpk_lt_u32 s73, 0x1400
	s_mov_b64 s[6:7], -1
	s_cbranch_scc1 .LBB0_695
	s_cmpk_lt_u32 s73, 0x2200
	s_cbranch_scc1 .LBB0_692
	v_mul_f32_e32 v26, 0xbfb8aa3b, v22
	v_mul_f32_e32 v27, 0xbfb8aa3b, v23
	v_exp_f32_e32 v26, v26
	v_exp_f32_e32 v27, v27
	v_mul_f32_e32 v28, 0xbfb8aa3b, v24
	v_mul_f32_e32 v29, 0xbfb8aa3b, v25
	v_exp_f32_e32 v28, v28
	v_exp_f32_e32 v29, v29
	v_pk_add_f32 v[26:27], v[26:27], 1.0 op_sel_hi:[1,0]
	v_mov_b32_e32 v143, v1
	v_pk_add_f32 v[30:31], v[28:29], 1.0 op_sel_hi:[1,0]
	v_rcp_f32_e32 v29, v26
	s_nop 0
	v_fma_f32 v32, -v26, v29, 1.0
	v_fmac_f32_e32 v29, v32, v29
	v_fma_f32 v40, -v26, v29, 1.0
	v_fma_f32 v33, v40, v29, v29
	v_fma_f32 v28, -v26, v33, 1.0
	v_fma_f32 v28, v28, v29, v33
	v_div_fixup_f32 v28, v28, v26, 1.0
	v_rcp_f32_e32 v29, v27
	s_nop 0
	v_fma_f32 v32, -v27, v29, 1.0
	v_fmac_f32_e32 v29, v32, v29
	v_fma_f32 v40, -v27, v29, 1.0
	v_fma_f32 v33, v40, v29, v29
	v_fma_f32 v26, -v27, v33, 1.0
	v_fma_f32 v26, v26, v29, v33
	v_div_fixup_f32 v29, v26, v27, 1.0
	v_rcp_f32_e32 v27, v30
	s_nop 0
	v_fma_f32 v32, -v30, v27, 1.0
	v_fmac_f32_e32 v27, v32, v27
	v_fma_f32 v40, -v30, v27, 1.0
	v_fma_f32 v33, v40, v27, v27
	v_fma_f32 v26, -v30, v33, 1.0
	v_fma_f32 v26, v26, v27, v33
	v_div_fixup_f32 v30, v26, v30, 1.0
	v_rcp_f32_e32 v27, v31
	s_nop 0
	v_fma_f32 v32, -v31, v27, 1.0
	v_fmac_f32_e32 v27, v32, v27
	v_fma_f32 v40, -v31, v27, 1.0
	v_fma_f32 v33, v40, v27, v27
	v_fma_f32 v26, -v31, v33, 1.0
	v_fma_f32 v26, v26, v27, v33
	v_div_fixup_f32 v31, v26, v31, 1.0
	v_mul_f32_e32 v26, 0xbfb8aa3b, v18
	v_mul_f32_e32 v27, 0xbfb8aa3b, v19
	v_exp_f32_e32 v26, v26
	v_exp_f32_e32 v27, v27
	v_mul_f32_e32 v32, 0xbfb8aa3b, v20
	v_mul_f32_e32 v33, 0xbfb8aa3b, v21
	v_exp_f32_e32 v32, v32
	v_exp_f32_e32 v33, v33
	v_pk_add_f32 v[26:27], v[26:27], 1.0 op_sel_hi:[1,0]
	v_pk_add_f32 v[40:41], v[32:33], 1.0 op_sel_hi:[1,0]
	v_rcp_f32_e32 v33, v26
	s_nop 0
	v_fma_f32 v42, -v26, v33, 1.0
	v_fmac_f32_e32 v33, v42, v33
	v_fma_f32 v44, -v26, v33, 1.0
	v_fma_f32 v43, v44, v33, v33
	v_fma_f32 v32, -v26, v43, 1.0
	v_fma_f32 v32, v32, v33, v43
	v_div_fixup_f32 v32, v32, v26, 1.0
	v_rcp_f32_e32 v33, v27
	s_nop 0
	v_fma_f32 v42, -v27, v33, 1.0
	v_fmac_f32_e32 v33, v42, v33
	v_fma_f32 v44, -v27, v33, 1.0
	v_fma_f32 v43, v44, v33, v33
	v_fma_f32 v26, -v27, v43, 1.0
	v_fma_f32 v26, v26, v33, v43
	v_div_fixup_f32 v33, v26, v27, 1.0
	v_rcp_f32_e32 v27, v40
	s_nop 0
	v_fma_f32 v42, -v40, v27, 1.0
	v_fmac_f32_e32 v27, v42, v27
	v_fma_f32 v44, -v40, v27, 1.0
	v_fma_f32 v43, v44, v27, v27
	v_fma_f32 v26, -v40, v43, 1.0
	v_fma_f32 v26, v26, v27, v43
	v_div_fixup_f32 v40, v26, v40, 1.0
	v_rcp_f32_e32 v27, v41
	s_movk_i32 s6, 0xbd00
	s_mov_b32 s7, -1
	v_fma_f32 v42, -v41, v27, 1.0
	v_fmac_f32_e32 v27, v42, v27
	v_fma_f32 v44, -v41, v27, 1.0
	v_fma_f32 v43, v44, v27, v27
	v_fma_f32 v26, -v41, v43, 1.0
	v_fma_f32 v26, v26, v27, v43
	v_div_fixup_f32 v41, v26, v41, 1.0
	v_lshl_add_u64 v[26:27], s[54:55], 0, v[38:39]
	v_lshl_add_u64 v[26:27], v[142:143], 1, v[26:27]
	v_lshl_add_u64 v[26:27], v[26:27], 0, s[6:7]
	s_mov_b64 s[6:7], 0

; __device__ __forceinline__ float sigmoidf_(float x) { return 1.f / (1.f + __expf(-x)); }
; __device__ __forceinline__ u32x4 pack8(f32x4 v0, f32x4 v1) { u32x4 o; o.x = pkbf(v0.x, v0.y); o.y = pkbf(v0.z, v0.w); o.z = pkbf(v1.x, v1.y); o.w = pkbf(v1.z, v1.w); return o; }
; __device__ __forceinline__ f32x4 gelu4(f32x4 v) { pg8::f32x2 a = pg8::gelu_pk((pg8::f32x2){v.x, v.y}), b = pg8::gelu_pk((pg8::f32x2){v.z, v.w}); return (f32x4){a.x, a.y, b.x, b.y}; }
;     __device__ __forceinline__ void operator()(int row, int col, f32x4 v0, f32x4 v1) const { *(u32x4*)(G + (size_t)row * 1024 + col) = pack8(v0, v1); }
; __device__ __forceinline__ f32x4 sig4(f32x4 v) { return (f32x4){sigmoidf_(v.x), sigmoidf_(v.y), sigmoidf_(v.z), sigmoidf_(v.w)}; }
;     __device__ __forceinline__ void operator()(int row, int col, f32x4 v0, f32x4 v1) const {
;         bf16_t* dst;
;         if (col < 2048) { v0 = gelu4(v0); v1 = gelu4(v1); dst = (col < 1024 ? GU : GV) + (size_t)row * 1024 + (col & 1023); }
;         else if (col < 5120) { const int q = col - 2048; dst = Q + (size_t)(q >> 10) * (size_t)(18 * MiB) + (size_t)row * 1024 + (q & 1023); }
;         else if (col < 8704) { dst = RW + (size_t)row * RWP + (col - 5120); }
;         else { v0 = sig4(v0); v1 = sig4(v1); dst = GT + (size_t)row * 3072 + (col - 8704); }
;         *(u32x4*)dst = pack8(v0, v1);
;     }
.LBB0_700:
	s_or_b64 exec, exec, s[4:5]
	v_cvt_pk_bf16_f32 v18, v28, v29
	v_cvt_pk_bf16_f32 v19, v30, v31
	v_cvt_pk_bf16_f32 v20, v32, v33
	v_cvt_pk_bf16_f32 v21, v40, v41
	global_store_dwordx4 v[26:27], v[18:21], off
	s_nop 1
	v_add_u32_e32 v18, 0xb0, v144
	v_ashrrev_i32_e32 v19, 31, v18
	v_mad_i64_i32 v[22:23], s[4:5], v18, s21, 0
	v_mad_i64_i32 v[20:21], s[4:5], v18, s67, 0
	v_lshlrev_b64 v[18:19], 11, v[18:19]
	s_and_saveexec_b64 s[4:5], s[42:43]
	s_xor_b64 s[4:5], exec, s[4:5]
	s_cbranch_execz .LBB0_710
	s_cmpk_lt_u32 s73, 0x1400
	s_mov_b64 s[6:7], -1
	s_cbranch_scc1 .LBB0_707
	s_cmpk_lt_u32 s73, 0x2200
	s_cbranch_scc1 .LBB0_704
	v_mul_f32_e32 v24, 0xbfb8aa3b, v14
	v_mul_f32_e32 v25, 0xbfb8aa3b, v15
	v_exp_f32_e32 v24, v24
	v_exp_f32_e32 v25, v25
	v_mul_f32_e32 v26, 0xbfb8aa3b, v16
	v_mul_f32_e32 v27, 0xbfb8aa3b, v17
	v_exp_f32_e32 v26, v26
	v_exp_f32_e32 v27, v27
	v_pk_add_f32 v[24:25], v[24:25], 1.0 op_sel_hi:[1,0]
	v_mov_b32_e32 v143, v1
	v_pk_add_f32 v[28:29], v[26:27], 1.0 op_sel_hi:[1,0]
	v_rcp_f32_e32 v27, v24
	s_nop 0
	v_fma_f32 v30, -v24, v27, 1.0
	v_fmac_f32_e32 v27, v30, v27
	v_fma_f32 v32, -v24, v27, 1.0
	v_fma_f32 v31, v32, v27, v27
	v_fma_f32 v26, -v24, v31, 1.0
	v_fma_f32 v26, v26, v27, v31
	v_div_fixup_f32 v26, v26, v24, 1.0
	v_rcp_f32_e32 v27, v25
	s_nop 0
	v_fma_f32 v30, -v25, v27, 1.0
	v_fmac_f32_e32 v27, v30, v27
	v_fma_f32 v32, -v25, v27, 1.0
	v_fma_f32 v31, v32, v27, v27
	v_fma_f32 v24, -v25, v31, 1.0
	v_fma_f32 v24, v24, v27, v31
	v_div_fixup_f32 v27, v24, v25, 1.0
	v_rcp_f32_e32 v25, v28
	s_nop 0
	v_fma_f32 v30, -v28, v25, 1.0
	v_fmac_f32_e32 v25, v30, v25
	v_fma_f32 v32, -v28, v25, 1.0
	v_fma_f32 v31, v32, v25, v25
	v_fma_f32 v24, -v28, v31, 1.0
	v_fma_f32 v24, v24, v25, v31
	v_div_fixup_f32 v28, v24, v28, 1.0
	v_rcp_f32_e32 v25, v29
	s_nop 0
	v_fma_f32 v30, -v29, v25, 1.0
	v_fmac_f32_e32 v25, v30, v25
	v_fma_f32 v32, -v29, v25, 1.0
	v_fma_f32 v31, v32, v25, v25
	v_fma_f32 v24, -v29, v31, 1.0
	v_fma_f32 v24, v24, v25, v31
	v_div_fixup_f32 v29, v24, v29, 1.0
	v_mul_f32_e32 v24, 0xbfb8aa3b, v10
	v_mul_f32_e32 v25, 0xbfb8aa3b, v11
	v_exp_f32_e32 v24, v24
	v_exp_f32_e32 v25, v25
	v_mul_f32_e32 v30, 0xbfb8aa3b, v12
	v_mul_f32_e32 v31, 0xbfb8aa3b, v13
	v_exp_f32_e32 v30, v30
	v_exp_f32_e32 v31, v31
	v_pk_add_f32 v[24:25], v[24:25], 1.0 op_sel_hi:[1,0]
	v_pk_add_f32 v[32:33], v[30:31], 1.0 op_sel_hi:[1,0]
	v_rcp_f32_e32 v31, v24
	s_nop 0
	v_fma_f32 v34, -v24, v31, 1.0
	v_fmac_f32_e32 v31, v34, v31
	v_fma_f32 v36, -v24, v31, 1.0
	v_fma_f32 v35, v36, v31, v31
	v_fma_f32 v30, -v24, v35, 1.0
	v_fma_f32 v30, v30, v31, v35
	v_div_fixup_f32 v30, v30, v24, 1.0
	v_rcp_f32_e32 v31, v25
	s_nop 0
	v_fma_f32 v34, -v25, v31, 1.0
	v_fmac_f32_e32 v31, v34, v31
	v_fma_f32 v36, -v25, v31, 1.0
	v_fma_f32 v35, v36, v31, v31
	v_fma_f32 v24, -v25, v35, 1.0
	v_fma_f32 v24, v24, v31, v35
	v_div_fixup_f32 v31, v24, v25, 1.0
	v_rcp_f32_e32 v25, v32
	s_nop 0
	v_fma_f32 v34, -v32, v25, 1.0
	v_fmac_f32_e32 v25, v34, v25
	v_fma_f32 v36, -v32, v25, 1.0
	v_fma_f32 v35, v36, v25, v25
	v_fma_f32 v24, -v32, v35, 1.0
	v_fma_f32 v24, v24, v25, v35
	v_div_fixup_f32 v32, v24, v32, 1.0
	v_rcp_f32_e32 v25, v33
	s_mov_b64 s[6:7], 0
	v_fma_f32 v34, -v33, v25, 1.0
	v_fmac_f32_e32 v25, v34, v25
	v_fma_f32 v36, -v33, v25, 1.0
	v_fma_f32 v35, v36, v25, v25
	v_fma_f32 v24, -v33, v35, 1.0
	v_fma_f32 v24, v24, v25, v35
	v_div_fixup_f32 v33, v24, v33, 1.0
	v_lshl_add_u64 v[24:25], s[54:55], 0, v[22:23]
	v_lshl_add_u64 v[24:25], v[142:143], 1, v[24:25]
	v_lshl_add_u64 v[24:25], v[24:25], 0, s[86:87]

; __device__ __forceinline__ float sigmoidf_(float x) { return 1.f / (1.f + __expf(-x)); }
; __device__ __forceinline__ u32x4 pack8(f32x4 v0, f32x4 v1) { u32x4 o; o.x = pkbf(v0.x, v0.y); o.y = pkbf(v0.z, v0.w); o.z = pkbf(v1.x, v1.y); o.w = pkbf(v1.z, v1.w); return o; }
; __device__ __forceinline__ f32x4 gelu4(f32x4 v) { pg8::f32x2 a = pg8::gelu_pk((pg8::f32x2){v.x, v.y}), b = pg8::gelu_pk((pg8::f32x2){v.z, v.w}); return (f32x4){a.x, a.y, b.x, b.y}; }
;     __device__ __forceinline__ void operator()(int row, int col, f32x4 v0, f32x4 v1) const { *(u32x4*)(G + (size_t)row * 1024 + col) = pack8(v0, v1); }
; __device__ __forceinline__ f32x4 sig4(f32x4 v) { return (f32x4){sigmoidf_(v.x), sigmoidf_(v.y), sigmoidf_(v.z), sigmoidf_(v.w)}; }
;     __device__ __forceinline__ void operator()(int row, int col, f32x4 v0, f32x4 v1) const {
;         bf16_t* dst;
;         if (col < 2048) { v0 = gelu4(v0); v1 = gelu4(v1); dst = (col < 1024 ? GU : GV) + (size_t)row * 1024 + (col & 1023); }
;         else if (col < 5120) { const int q = col - 2048; dst = Q + (size_t)(q >> 10) * (size_t)(18 * MiB) + (size_t)row * 1024 + (q & 1023); }
;         else if (col < 8704) { dst = RW + (size_t)row * RWP + (col - 5120); }
;         else { v0 = sig4(v0); v1 = sig4(v1); dst = GT + (size_t)row * 3072 + (col - 8704); }
;         *(u32x4*)dst = pack8(v0, v1);
;     }
.LBB0_712:
	s_or_b64 exec, exec, s[4:5]
	v_cvt_pk_bf16_f32 v10, v26, v27
	v_cvt_pk_bf16_f32 v11, v28, v29
	v_cvt_pk_bf16_f32 v12, v30, v31
	v_cvt_pk_bf16_f32 v13, v32, v33
	global_store_dwordx4 v[24:25], v[10:13], off
	s_and_saveexec_b64 s[4:5], s[44:45]
	s_xor_b64 s[4:5], exec, s[4:5]
	s_cbranch_execz .LBB0_722
	s_cmpk_lt_u32 s73, 0x1400
	s_mov_b64 s[6:7], -1
	s_cbranch_scc1 .LBB0_719
	s_cmpk_lt_u32 s73, 0x2200
	s_cbranch_scc1 .LBB0_716
	v_mul_f32_e32 v0, 0xbfb8aa3b, v6
	v_exp_f32_e32 v10, v0
	v_mul_f32_e32 v0, 0xbfb8aa3b, v7
	v_exp_f32_e32 v11, v0
	v_mul_f32_e32 v0, 0xbfb8aa3b, v8
	v_exp_f32_e32 v12, v0
	v_mul_f32_e32 v0, 0xbfb8aa3b, v9
	v_exp_f32_e32 v13, v0
	v_pk_add_f32 v[10:11], v[10:11], 1.0 op_sel_hi:[1,0]
	v_mov_b32_e32 v143, v1
	v_div_scale_f32 v0, s[6:7], v10, v10, 1.0
	v_pk_add_f32 v[14:15], v[12:13], 1.0 op_sel_hi:[1,0]
	v_rcp_f32_e32 v12, v0
	s_nop 0
	v_fma_f32 v13, -v0, v12, 1.0
	v_fmac_f32_e32 v12, v13, v12
	v_div_scale_f32 v13, vcc, 1.0, v10, 1.0
	v_mul_f32_e32 v16, v13, v12
	v_fma_f32 v17, -v0, v16, v13
	v_fmac_f32_e32 v16, v17, v12
	v_fma_f32 v0, -v0, v16, v13
	v_div_fmas_f32 v0, v0, v12, v16
	v_div_fixup_f32 v0, v0, v10, 1.0
	v_rcp_f32_e32 v12, v11
	s_nop 0
	v_fma_f32 v13, -v11, v12, 1.0
	v_fmac_f32_e32 v12, v13, v12
	v_fma_f32 v17, -v11, v12, 1.0
	v_fma_f32 v16, v17, v12, v12
	v_fma_f32 v10, -v11, v16, 1.0
	v_fma_f32 v10, v10, v12, v16
	v_div_fixup_f32 v12, v10, v11, 1.0
	v_rcp_f32_e32 v11, v14
	s_nop 0
	v_fma_f32 v13, -v14, v11, 1.0
	v_fmac_f32_e32 v11, v13, v11
	v_fma_f32 v17, -v14, v11, 1.0
	v_fma_f32 v16, v17, v11, v11
	v_fma_f32 v10, -v14, v16, 1.0
	v_fma_f32 v10, v10, v11, v16
	v_div_fixup_f32 v13, v10, v14, 1.0
	v_rcp_f32_e32 v11, v15
	s_nop 0
	v_fma_f32 v14, -v15, v11, 1.0
	v_fmac_f32_e32 v11, v14, v11
	v_fma_f32 v17, -v15, v11, 1.0
	v_fma_f32 v16, v17, v11, v11
	v_fma_f32 v10, -v15, v16, 1.0
	v_fma_f32 v10, v10, v11, v16
	v_div_fixup_f32 v14, v10, v15, 1.0
	v_mul_f32_e32 v10, 0xbfb8aa3b, v2
	v_mul_f32_e32 v11, 0xbfb8aa3b, v3
	v_exp_f32_e32 v10, v10
	v_exp_f32_e32 v11, v11
	v_mul_f32_e32 v15, 0xbfb8aa3b, v4
	v_exp_f32_e32 v16, v15
	v_mul_f32_e32 v15, 0xbfb8aa3b, v5
	v_exp_f32_e32 v17, v15
	v_pk_add_f32 v[10:11], v[10:11], 1.0 op_sel_hi:[1,0]
	v_pk_add_f32 v[24:25], v[16:17], 1.0 op_sel_hi:[1,0]
	v_rcp_f32_e32 v16, v10
	s_nop 0
	v_fma_f32 v17, -v10, v16, 1.0
	v_fmac_f32_e32 v16, v17, v16
	v_fma_f32 v27, -v10, v16, 1.0
	v_fma_f32 v26, v27, v16, v16
	v_fma_f32 v15, -v10, v26, 1.0
	v_fma_f32 v15, v15, v16, v26
	v_div_fixup_f32 v15, v15, v10, 1.0
	v_rcp_f32_e32 v16, v11
	s_nop 0
	v_fma_f32 v17, -v11, v16, 1.0
	v_fmac_f32_e32 v16, v17, v16
	v_fma_f32 v27, -v11, v16, 1.0
	v_fma_f32 v26, v27, v16, v16
	v_fma_f32 v10, -v11, v26, 1.0
	v_fma_f32 v10, v10, v16, v26
	v_div_fixup_f32 v16, v10, v11, 1.0
	v_rcp_f32_e32 v11, v24
	s_nop 0
	v_fma_f32 v17, -v24, v11, 1.0
	v_fmac_f32_e32 v11, v17, v11
	v_fma_f32 v27, -v24, v11, 1.0
	v_fma_f32 v26, v27, v11, v11
	v_fma_f32 v10, -v24, v26, 1.0
	v_fma_f32 v10, v10, v11, v26
	v_div_fixup_f32 v17, v10, v24, 1.0
	v_rcp_f32_e32 v11, v25
	s_movk_i32 s6, 0xbd00
	s_mov_b32 s7, -1
	v_fma_f32 v24, -v25, v11, 1.0
	v_fmac_f32_e32 v11, v24, v11
	v_fma_f32 v27, -v25, v11, 1.0
	v_fma_f32 v26, v27, v11, v11
	v_fma_f32 v10, -v25, v26, 1.0
	v_fma_f32 v10, v10, v11, v26
	v_div_fixup_f32 v24, v10, v25, 1.0
	v_lshl_add_u64 v[10:11], s[54:55], 0, v[22:23]
	v_lshl_add_u64 v[10:11], v[142:143], 1, v[10:11]
	v_lshl_add_u64 v[10:11], v[10:11], 0, s[6:7]
	s_mov_b64 s[6:7], 0
